# v055 + nt cache policy on once-read load streams (f32 weights being converted, adaLN weights, norm1 x rows, residual rows of the fused epilogues, SGU u tiles)
# speedup vs baseline: 1.0320x; 1.0320x over previous
; __global__ void __launch_bounds__(512, 2) fwd_mega(Args a) {
;     ...
;             for (int i = tid; i < 4096; i += 512) { const float v = INF(1)[i]; cs[i] = v / (1.f + __expf(-v)); }
;             __syncthreads();
;             const int kg = tid >> 6, col = tid & 63, j = cb * 64 + col;
;             const float* w = INF(3) + (size_t)l * 1024 * 6144 + (size_t)(kg * 128) * 6144 + j;
;             float a0 = 0.f, a1 = 0.f, a2 = 0.f, a3 = 0.f;
; #pragma unroll 32
;             for (int k = 0; k < 128; ++k) { const float wv = w[(size_t)k * 6144]; const int kk = kg * 128 + k; a0 += cs[kk] * wv; a1 += cs[1024 + kk] * wv; a2 += cs[2048 + kk] * wv; a3 += cs[3072 + kk] * wv; }
.LBB0_9:
	global_load_dword v6, v[2:3], off nt
	v_add_u32_e32 v5, 0x200, v5
	v_cmp_lt_u32_e32 vcc, s16, v5
	s_or_b64 s[12:13], vcc, s[12:13]
	v_lshl_add_u64 v[2:3], v[2:3], 0, s[10:11]
	s_waitcnt vmcnt(0)
	v_mul_f32_e32 v7, 0xbfb8aa3b, v6
	v_exp_f32_e32 v7, v7
	s_nop 0
	v_add_f32_e32 v7, 1.0, v7
	v_div_scale_f32 v8, s[14:15], v7, v7, v6
	v_rcp_f32_e32 v9, v8
	v_div_scale_f32 v10, vcc, v6, v7, v6
	v_fma_f32 v11, -v8, v9, 1.0
	v_fmac_f32_e32 v9, v11, v9
	v_mul_f32_e32 v11, v10, v9
	v_fma_f32 v12, -v8, v11, v10
	v_fmac_f32_e32 v11, v12, v9
	v_fma_f32 v8, -v8, v11, v10
	v_div_fmas_f32 v8, v8, v9, v11
	v_div_fixup_f32 v6, v8, v7, v6
	ds_write_b32 v4, v6
	v_add_u32_e32 v4, 0x800, v4
	s_andn2_b64 exec, exec, s[12:13]
	s_cbranch_execnz .LBB0_9
	s_or_b64 exec, exec, s[12:13]
	s_mul_hi_i32 s12, s53, 0x2aaaaaab
	s_lshr_b32 s13, s12, 31
	s_ashr_i32 s12, s12, 4
	s_add_i32 s13, s12, s13
	s_mul_i32 s12, s13, 0x60
	s_sub_i32 s12, s53, s12
	s_lshl_b32 s12, s12, 6
	v_or_b32_e32 v2, s12, v114
	v_mad_i64_i32 v[4:5], s[14:15], s13, v133, v[118:119]
	v_ashrrev_i32_e32 v3, 31, v2
	v_mov_b32_e32 v124, 0
	v_lshl_add_u64 v[122:123], v[2:3], 2, v[4:5]
	s_mov_b64 s[14:15], 0
	v_mov_b32_e32 v135, v115
	v_mov_b32_e32 v125, v124
	v_mov_b32_e32 v126, v124
	v_mov_b32_e32 v127, v124
	s_waitcnt lgkmcnt(0)
	s_barrier
.LBB0_11:
	v_lshl_add_u64 v[128:129], v[122:123], 0, s[14:15]
	v_add_co_u32_e32 v152, vcc, s17, v128
	ds_read_b128 v[22:25], v135
	ds_read_b128 v[18:21], v135 offset:16
	ds_read_b128 v[2:5], v135 offset:4096
	ds_read_b128 v[6:9], v135 offset:4112
	ds_read_b128 v[34:37], v135 offset:8192
	ds_read_b128 v[26:29], v135 offset:8208
	ds_read_b128 v[14:17], v135 offset:12288
	ds_read_b128 v[10:13], v135 offset:12304
	ds_read_b128 v[54:57], v135 offset:32
	ds_read_b128 v[42:45], v135 offset:48
	ds_read_b128 v[30:33], v135 offset:4128
	ds_read_b128 v[38:41], v135 offset:4144
	ds_read_b128 v[62:65], v135 offset:8224
	ds_read_b128 v[58:61], v135 offset:8240
	ds_read_b128 v[50:53], v135 offset:12320
	ds_read_b128 v[46:49], v135 offset:12336
	ds_read_b128 v[82:85], v135 offset:64
	ds_read_b128 v[86:89], v135 offset:80
	ds_read_b128 v[70:73], v135 offset:4160
	ds_read_b128 v[66:69], v135 offset:4176
	ds_read_b128 v[94:97], v135 offset:8256
	ds_read_b128 v[90:93], v135 offset:8272
	ds_read_b128 v[78:81], v135 offset:12352
	ds_read_b128 v[74:77], v135 offset:12368
	ds_read_b128 v[136:139], v135 offset:96
	ds_read_b128 v[140:143], v135 offset:112
	ds_read_b128 v[102:105], v135 offset:4192
	ds_read_b128 v[98:101], v135 offset:4208
	ds_read_b128 v[144:147], v135 offset:8288
	ds_read_b128 v[148:151], v135 offset:8304
	ds_read_b128 v[110:113], v135 offset:12384
	ds_read_b128 v[106:109], v135 offset:12400
	v_addc_co_u32_e32 v153, vcc, 0, v129, vcc
	v_add_co_u32_e32 v154, vcc, s18, v128
	s_waitcnt lgkmcnt(14)
	v_mov_b32_e32 v214, v22
	v_addc_co_u32_e32 v155, vcc, 0, v129, vcc
	v_add_co_u32_e32 v156, vcc, s19, v128
	v_mov_b32_e32 v215, v2
	s_nop 0
	v_addc_co_u32_e32 v157, vcc, 0, v129, vcc
	v_add_co_u32_e32 v158, vcc, s20, v128
	v_mov_b32_e32 v2, v23
	s_nop 0
	v_addc_co_u32_e32 v159, vcc, 0, v129, vcc
	v_add_co_u32_e32 v160, vcc, s21, v128
	v_mov_b32_e32 v22, v24
	s_nop 0
	v_addc_co_u32_e32 v161, vcc, 0, v129, vcc
	v_add_co_u32_e32 v162, vcc, s22, v128
	v_mov_b32_e32 v23, v4
	s_nop 0
	v_addc_co_u32_e32 v163, vcc, 0, v129, vcc
	v_add_co_u32_e32 v164, vcc, s23, v128
	v_mov_b32_e32 v4, v25
	s_nop 0
	v_addc_co_u32_e32 v165, vcc, 0, v129, vcc
	v_add_co_u32_e32 v166, vcc, s25, v128
	v_mov_b32_e32 v24, v34
	s_nop 0
	v_addc_co_u32_e32 v167, vcc, 0, v129, vcc
	v_add_co_u32_e32 v168, vcc, s28, v128
	v_mov_b32_e32 v25, v14
	s_nop 0
	v_addc_co_u32_e32 v169, vcc, 0, v129, vcc
	v_add_co_u32_e32 v170, vcc, s29, v128
	v_mov_b32_e32 v14, v35
	s_nop 0
	v_addc_co_u32_e32 v171, vcc, 0, v129, vcc
	v_add_co_u32_e32 v172, vcc, s30, v128
	v_mov_b32_e32 v34, v36
	s_nop 0
	v_addc_co_u32_e32 v173, vcc, 0, v129, vcc
	v_add_co_u32_e32 v174, vcc, s31, v128
	v_mov_b32_e32 v35, v16
	s_nop 0
	v_addc_co_u32_e32 v175, vcc, 0, v129, vcc
	v_add_co_u32_e32 v176, vcc, s34, v128
	v_mov_b32_e32 v16, v37
	s_nop 0
	v_addc_co_u32_e32 v177, vcc, 0, v129, vcc
	v_add_co_u32_e32 v178, vcc, s35, v128
	v_mov_b32_e32 v36, v18
	s_nop 0
	v_addc_co_u32_e32 v179, vcc, 0, v129, vcc
	v_add_co_u32_e32 v180, vcc, s36, v128
	v_mov_b32_e32 v37, v6
	s_nop 0
	v_addc_co_u32_e32 v181, vcc, 0, v129, vcc
	v_add_co_u32_e32 v182, vcc, s37, v128
	v_mov_b32_e32 v6, v19
	s_nop 0
	v_addc_co_u32_e32 v183, vcc, 0, v129, vcc
	v_add_co_u32_e32 v184, vcc, s38, v128
	v_mov_b32_e32 v18, v20
	s_nop 0
	v_addc_co_u32_e32 v185, vcc, 0, v129, vcc
	v_add_co_u32_e32 v186, vcc, s39, v128
	v_mov_b32_e32 v19, v8
	s_nop 0
	v_addc_co_u32_e32 v187, vcc, 0, v129, vcc
	v_add_co_u32_e32 v188, vcc, s40, v128
	v_mov_b32_e32 v8, v21
	s_nop 0
	v_addc_co_u32_e32 v189, vcc, 0, v129, vcc
	v_add_co_u32_e32 v190, vcc, s41, v128
	v_mov_b32_e32 v20, v26
	s_nop 0
	v_addc_co_u32_e32 v191, vcc, 0, v129, vcc
	v_add_co_u32_e32 v192, vcc, s42, v128
	v_mov_b32_e32 v21, v10
	s_nop 0
	v_addc_co_u32_e32 v193, vcc, 0, v129, vcc
	v_add_co_u32_e32 v194, vcc, s43, v128
	v_mov_b32_e32 v10, v27
	s_nop 0
	v_addc_co_u32_e32 v195, vcc, 0, v129, vcc
	v_add_co_u32_e32 v196, vcc, s44, v128
	v_mov_b32_e32 v26, v28
	s_nop 0
	v_addc_co_u32_e32 v197, vcc, 0, v129, vcc
	v_add_co_u32_e32 v198, vcc, s45, v128
	v_mov_b32_e32 v27, v12
	s_nop 0
	v_addc_co_u32_e32 v199, vcc, 0, v129, vcc
	v_add_co_u32_e32 v200, vcc, s46, v128
	v_mov_b32_e32 v12, v29
	s_nop 0
	v_addc_co_u32_e32 v201, vcc, 0, v129, vcc
	v_add_co_u32_e32 v202, vcc, s47, v128
	v_mov_b32_e32 v28, v54
	s_nop 0
	v_addc_co_u32_e32 v203, vcc, 0, v129, vcc
; __global__ void __launch_bounds__(512, 2) fwd_mega(Args a) {
;     ...
;             const float* w = INF(3) + (size_t)l * 1024 * 6144 + (size_t)(kg * 128) * 6144 + j;
;             float a0 = 0.f, a1 = 0.f, a2 = 0.f, a3 = 0.f;
; #pragma unroll 32
;             for (int k = 0; k < 128; ++k) { const float wv = w[(size_t)k * 6144]; const int kk = kg * 128 + k; a0 += cs[kk] * wv; a1 += cs[1024 + kk] * wv; a2 += cs[2048 + kk] * wv; a3 += cs[3072 + kk] * wv; }
	v_add_co_u32_e32 v204, vcc, s48, v128
	v_mov_b32_e32 v29, v30
	s_nop 0
	v_addc_co_u32_e32 v205, vcc, 0, v129, vcc
	v_add_co_u32_e32 v206, vcc, s49, v128
	v_mov_b32_e32 v30, v55
	s_nop 0
	v_addc_co_u32_e32 v207, vcc, 0, v129, vcc
	v_add_co_u32_e32 v208, vcc, s50, v128
	v_mov_b32_e32 v54, v56
	s_nop 0
	v_addc_co_u32_e32 v209, vcc, 0, v129, vcc
	v_add_co_u32_e32 v210, vcc, s51, v128
	v_mov_b32_e32 v55, v32
	s_nop 0
	v_addc_co_u32_e32 v211, vcc, 0, v129, vcc
	v_add_co_u32_e32 v212, vcc, s52, v128
	v_mov_b32_e32 v32, v57
	s_nop 0
	v_addc_co_u32_e32 v213, vcc, 0, v129, vcc
	global_load_dword v128, v[128:129], off nt
	s_nop 0
	global_load_dword v152, v[152:153], off nt
	s_nop 0
	global_load_dword v154, v[154:155], off nt
	s_nop 0
	global_load_dword v156, v[156:157], off nt
	s_nop 0
	global_load_dword v158, v[158:159], off nt
	s_nop 0
	global_load_dword v160, v[160:161], off nt
	s_nop 0
	global_load_dword v162, v[162:163], off nt
	s_nop 0
	global_load_dword v164, v[164:165], off nt
	s_nop 0
	global_load_dword v166, v[166:167], off nt
	s_nop 0
	global_load_dword v168, v[168:169], off nt
	s_nop 0
	global_load_dword v170, v[170:171], off nt
	s_nop 0
	global_load_dword v172, v[172:173], off nt
	s_nop 0
	global_load_dword v174, v[174:175], off nt
	s_nop 0
	global_load_dword v176, v[176:177], off nt
	s_nop 0
	global_load_dword v178, v[178:179], off nt
	s_nop 0
	global_load_dword v180, v[180:181], off nt
	s_nop 0
	global_load_dword v182, v[182:183], off nt
	s_nop 0
	global_load_dword v184, v[184:185], off nt
	s_nop 0
	global_load_dword v186, v[186:187], off nt
	s_nop 0
	global_load_dword v188, v[188:189], off nt
	s_nop 0
	global_load_dword v190, v[190:191], off nt
	s_nop 0
	global_load_dword v192, v[192:193], off nt
	s_nop 0
	global_load_dword v194, v[194:195], off nt
	s_nop 0
	global_load_dword v196, v[196:197], off nt
	s_nop 0
	global_load_dword v198, v[198:199], off nt
	s_nop 0
	global_load_dword v200, v[200:201], off nt
	s_nop 0
	global_load_dword v202, v[202:203], off nt
	s_nop 0
	global_load_dword v204, v[204:205], off nt
	s_nop 0
	global_load_dword v206, v[206:207], off nt
	s_nop 0
	global_load_dword v208, v[208:209], off nt
	s_nop 0
	global_load_dword v210, v[210:211], off nt
	s_nop 0
	global_load_dword v212, v[212:213], off nt
	v_mov_b32_e32 v56, v62
	v_mov_b32_e32 v57, v50
	v_mov_b32_e32 v50, v63
	v_mov_b32_e32 v62, v64
	v_mov_b32_e32 v63, v52
	v_mov_b32_e32 v52, v65
	v_mov_b32_e32 v64, v42
	v_mov_b32_e32 v65, v38
	v_mov_b32_e32 v38, v43
	v_mov_b32_e32 v42, v44
	v_mov_b32_e32 v43, v40
	v_mov_b32_e32 v40, v45
	v_mov_b32_e32 v44, v58
	v_mov_b32_e32 v45, v46
	v_mov_b32_e32 v46, v59
	v_mov_b32_e32 v58, v60
	v_mov_b32_e32 v59, v48
	v_mov_b32_e32 v48, v61
	v_mov_b32_e32 v60, v82
	s_waitcnt lgkmcnt(13)
	v_mov_b32_e32 v61, v70
	v_mov_b32_e32 v70, v83
	v_mov_b32_e32 v82, v84
	v_mov_b32_e32 v83, v72
	v_mov_b32_e32 v72, v85
	s_waitcnt lgkmcnt(11)
	v_mov_b32_e32 v84, v94
	s_waitcnt lgkmcnt(9)
	v_mov_b32_e32 v85, v78
	v_mov_b32_e32 v78, v95
	v_mov_b32_e32 v94, v96
	v_mov_b32_e32 v95, v80
	v_mov_b32_e32 v80, v97
	v_mov_b32_e32 v96, v86
	v_mov_b32_e32 v97, v66
	v_mov_b32_e32 v66, v87
	v_mov_b32_e32 v86, v88
	v_mov_b32_e32 v87, v68
	v_mov_b32_e32 v68, v89
	v_mov_b32_e32 v88, v90
	s_waitcnt lgkmcnt(8)
	v_mov_b32_e32 v89, v74
	v_mov_b32_e32 v74, v91
	v_mov_b32_e32 v90, v92
	v_mov_b32_e32 v91, v76
	v_mov_b32_e32 v76, v93
	s_waitcnt lgkmcnt(7)
	v_mov_b32_e32 v92, v136
	s_waitcnt lgkmcnt(5)
	v_mov_b32_e32 v93, v102
	v_mov_b32_e32 v102, v137
	v_mov_b32_e32 v136, v138
	v_mov_b32_e32 v137, v104
	v_mov_b32_e32 v104, v139
	s_waitcnt vmcnt(31)
	v_pk_fma_f32 v[124:125], v[128:129], v[214:215], v[124:125] op_sel_hi:[0,1,1]
	v_pk_fma_f32 v[24:25], v[128:129], v[24:25], v[126:127] op_sel_hi:[0,1,1]
	s_waitcnt vmcnt(30)
	v_pk_fma_f32 v[2:3], v[152:153], v[2:3], v[124:125] op_sel_hi:[0,1,1]
	v_pk_fma_f32 v[14:15], v[152:153], v[14:15], v[24:25] op_sel_hi:[0,1,1]
	s_waitcnt vmcnt(29)
	v_pk_fma_f32 v[2:3], v[154:155], v[22:23], v[2:3] op_sel_hi:[0,1,1]
	v_pk_fma_f32 v[14:15], v[154:155], v[34:35], v[14:15] op_sel_hi:[0,1,1]
	s_waitcnt vmcnt(28)
	v_pk_fma_f32 v[2:3], v[156:157], v[4:5], v[2:3] op_sel_hi:[0,1,1]
	v_pk_fma_f32 v[4:5], v[156:157], v[16:17], v[14:15] op_sel_hi:[0,1,1]
	s_waitcnt vmcnt(27)
	v_pk_fma_f32 v[2:3], v[158:159], v[36:37], v[2:3] op_sel_hi:[0,1,1]
	v_pk_fma_f32 v[4:5], v[158:159], v[20:21], v[4:5] op_sel_hi:[0,1,1]
	s_waitcnt vmcnt(26)
	v_pk_fma_f32 v[2:3], v[160:161], v[6:7], v[2:3] op_sel_hi:[0,1,1]
	v_pk_fma_f32 v[4:5], v[160:161], v[10:11], v[4:5] op_sel_hi:[0,1,1]
	s_waitcnt vmcnt(25)
	v_pk_fma_f32 v[2:3], v[162:163], v[18:19], v[2:3] op_sel_hi:[0,1,1]
	v_pk_fma_f32 v[4:5], v[162:163], v[26:27], v[4:5] op_sel_hi:[0,1,1]
	s_waitcnt vmcnt(24)
	v_pk_fma_f32 v[2:3], v[164:165], v[8:9], v[2:3] op_sel_hi:[0,1,1]
	v_pk_fma_f32 v[4:5], v[164:165], v[12:13], v[4:5] op_sel_hi:[0,1,1]
	s_waitcnt vmcnt(23)
	v_pk_fma_f32 v[2:3], v[166:167], v[28:29], v[2:3] op_sel_hi:[0,1,1]
	v_pk_fma_f32 v[4:5], v[166:167], v[56:57], v[4:5] op_sel_hi:[0,1,1]
	s_waitcnt vmcnt(22)
	v_pk_fma_f32 v[2:3], v[168:169], v[30:31], v[2:3] op_sel_hi:[0,1,1]
	v_pk_fma_f32 v[4:5], v[168:169], v[50:51], v[4:5] op_sel_hi:[0,1,1]
	s_waitcnt vmcnt(21)
	v_pk_fma_f32 v[2:3], v[170:171], v[54:55], v[2:3] op_sel_hi:[0,1,1]
	v_pk_fma_f32 v[4:5], v[170:171], v[62:63], v[4:5] op_sel_hi:[0,1,1]
	s_waitcnt vmcnt(20)
; __global__ void __launch_bounds__(512, 2) fwd_mega(Args a) {
;     ...
;             for (int k = 0; k < 128; ++k) { const float wv = w[(size_t)k * 6144]; const int kk = kg * 128 + k; a0 += cs[kk] * wv; a1 += cs[1024 + kk] * wv; a2 += cs[2048 + kk] * wv; a3 += cs[3072 + kk] * wv; }
;             red[(kg * 4 + 0) * 64 + col] = a0; red[(kg * 4 + 1) * 64 + col] = a1; red[(kg * 4 + 2) * 64 + col] = a2; red[(kg * 4 + 3) * 64 + col] = a3;
;             __syncthreads();
;             if (tid < 256) { const int b = tid >> 6, cc = tid & 63; float s = 0.f;
; #pragma unroll
;                 for (int q = 0; q < 8; ++q) s += red[(q * 4 + b) * 64 + cc];
;                 ((float*)(a.ws + WS_MOD))[(size_t)(l * 4 + b) * 6144 + cb * 64 + cc] = s + INF(4)[l * 6144 + cb * 64 + cc]; }
	v_pk_fma_f32 v[2:3], v[172:173], v[32:33], v[2:3] op_sel_hi:[0,1,1]
	v_pk_fma_f32 v[4:5], v[172:173], v[52:53], v[4:5] op_sel_hi:[0,1,1]
	s_waitcnt vmcnt(19)
	v_pk_fma_f32 v[2:3], v[174:175], v[64:65], v[2:3] op_sel_hi:[0,1,1]
	v_pk_fma_f32 v[4:5], v[174:175], v[44:45], v[4:5] op_sel_hi:[0,1,1]
	s_waitcnt vmcnt(18)
	v_pk_fma_f32 v[2:3], v[176:177], v[38:39], v[2:3] op_sel_hi:[0,1,1]
	v_pk_fma_f32 v[4:5], v[176:177], v[46:47], v[4:5] op_sel_hi:[0,1,1]
	s_waitcnt vmcnt(17)
	v_pk_fma_f32 v[2:3], v[178:179], v[42:43], v[2:3] op_sel_hi:[0,1,1]
	v_pk_fma_f32 v[4:5], v[178:179], v[58:59], v[4:5] op_sel_hi:[0,1,1]
	s_waitcnt vmcnt(16)
	v_pk_fma_f32 v[2:3], v[180:181], v[40:41], v[2:3] op_sel_hi:[0,1,1]
	v_pk_fma_f32 v[4:5], v[180:181], v[48:49], v[4:5] op_sel_hi:[0,1,1]
	s_waitcnt vmcnt(15)
	v_pk_fma_f32 v[2:3], v[182:183], v[60:61], v[2:3] op_sel_hi:[0,1,1]
	v_pk_fma_f32 v[4:5], v[182:183], v[84:85], v[4:5] op_sel_hi:[0,1,1]
	s_waitcnt vmcnt(14)
	v_pk_fma_f32 v[2:3], v[184:185], v[70:71], v[2:3] op_sel_hi:[0,1,1]
	v_pk_fma_f32 v[4:5], v[184:185], v[78:79], v[4:5] op_sel_hi:[0,1,1]
	s_waitcnt vmcnt(13)
	v_pk_fma_f32 v[2:3], v[186:187], v[82:83], v[2:3] op_sel_hi:[0,1,1]
	v_pk_fma_f32 v[4:5], v[186:187], v[94:95], v[4:5] op_sel_hi:[0,1,1]
	s_waitcnt vmcnt(12)
	v_pk_fma_f32 v[2:3], v[188:189], v[72:73], v[2:3] op_sel_hi:[0,1,1]
	v_pk_fma_f32 v[4:5], v[188:189], v[80:81], v[4:5] op_sel_hi:[0,1,1]
	s_waitcnt vmcnt(11)
	v_pk_fma_f32 v[2:3], v[190:191], v[96:97], v[2:3] op_sel_hi:[0,1,1]
	v_pk_fma_f32 v[4:5], v[190:191], v[88:89], v[4:5] op_sel_hi:[0,1,1]
	s_waitcnt vmcnt(10)
	v_pk_fma_f32 v[2:3], v[192:193], v[66:67], v[2:3] op_sel_hi:[0,1,1]
	v_pk_fma_f32 v[4:5], v[192:193], v[74:75], v[4:5] op_sel_hi:[0,1,1]
	s_waitcnt vmcnt(9)
	v_pk_fma_f32 v[2:3], v[194:195], v[86:87], v[2:3] op_sel_hi:[0,1,1]
	v_pk_fma_f32 v[4:5], v[194:195], v[90:91], v[4:5] op_sel_hi:[0,1,1]
	s_waitcnt lgkmcnt(3)
	v_mov_b32_e32 v138, v144
	s_waitcnt lgkmcnt(1)
	v_mov_b32_e32 v139, v110
	s_waitcnt vmcnt(8)
	v_pk_fma_f32 v[2:3], v[196:197], v[68:69], v[2:3] op_sel_hi:[0,1,1]
	v_pk_fma_f32 v[4:5], v[196:197], v[76:77], v[4:5] op_sel_hi:[0,1,1]
	v_mov_b32_e32 v110, v145
	s_waitcnt vmcnt(7)
	v_pk_fma_f32 v[2:3], v[198:199], v[92:93], v[2:3] op_sel_hi:[0,1,1]
	v_pk_fma_f32 v[4:5], v[198:199], v[138:139], v[4:5] op_sel_hi:[0,1,1]
	v_mov_b32_e32 v144, v146
	v_mov_b32_e32 v145, v112
	s_waitcnt vmcnt(6)
	v_pk_fma_f32 v[2:3], v[200:201], v[102:103], v[2:3] op_sel_hi:[0,1,1]
	v_pk_fma_f32 v[4:5], v[200:201], v[110:111], v[4:5] op_sel_hi:[0,1,1]
	v_mov_b32_e32 v112, v147
	s_waitcnt vmcnt(5)
	v_pk_fma_f32 v[2:3], v[202:203], v[136:137], v[2:3] op_sel_hi:[0,1,1]
	v_pk_fma_f32 v[4:5], v[202:203], v[144:145], v[4:5] op_sel_hi:[0,1,1]
	v_mov_b32_e32 v146, v140
	v_mov_b32_e32 v147, v98
	v_mov_b32_e32 v98, v141
	v_mov_b32_e32 v140, v142
	v_mov_b32_e32 v141, v100
	v_mov_b32_e32 v100, v143
	v_mov_b32_e32 v142, v148
	s_waitcnt lgkmcnt(0)
	v_mov_b32_e32 v143, v106
	s_waitcnt vmcnt(4)
	v_pk_fma_f32 v[2:3], v[204:205], v[104:105], v[2:3] op_sel_hi:[0,1,1]
	v_pk_fma_f32 v[4:5], v[204:205], v[112:113], v[4:5] op_sel_hi:[0,1,1]
	v_mov_b32_e32 v106, v149
	s_waitcnt vmcnt(3)
	v_pk_fma_f32 v[2:3], v[206:207], v[146:147], v[2:3] op_sel_hi:[0,1,1]
	v_pk_fma_f32 v[4:5], v[206:207], v[142:143], v[4:5] op_sel_hi:[0,1,1]
	s_add_u32 s14, s14, 0xc0000
	v_mov_b32_e32 v148, v150
	v_mov_b32_e32 v149, v108
	s_waitcnt vmcnt(2)
	v_pk_fma_f32 v[2:3], v[208:209], v[98:99], v[2:3] op_sel_hi:[0,1,1]
	v_pk_fma_f32 v[4:5], v[208:209], v[106:107], v[4:5] op_sel_hi:[0,1,1]
	s_addc_u32 s15, s15, 0
	v_mov_b32_e32 v108, v151
	s_waitcnt vmcnt(1)
	v_pk_fma_f32 v[2:3], v[210:211], v[140:141], v[2:3] op_sel_hi:[0,1,1]
	v_pk_fma_f32 v[4:5], v[210:211], v[148:149], v[4:5] op_sel_hi:[0,1,1]
	v_add_u32_e32 v135, 0x80, v135
	s_cmp_eq_u32 s14, 0x300000
	s_waitcnt vmcnt(0)
	v_pk_fma_f32 v[124:125], v[212:213], v[100:101], v[2:3] op_sel_hi:[0,1,1]
	v_pk_fma_f32 v[126:127], v[212:213], v[108:109], v[4:5] op_sel_hi:[0,1,1]
	s_cbranch_scc0 .LBB0_11
	ds_write2st64_b32 v134, v124, v125 offset0:64 offset1:65
	ds_write2st64_b32 v134, v126, v127 offset0:66 offset1:67
	s_waitcnt lgkmcnt(0)
	s_barrier
	s_and_saveexec_b64 s[14:15], s[4:5]
	s_cbranch_execz .LBB0_7
	s_mul_i32 s54, s13, 0x1800
	s_add_i32 s54, s54, s12
	v_or_b32_e32 v2, s54, v114
	v_ashrrev_i32_e32 v3, 31, v2
	v_lshl_add_u64 v[2:3], v[2:3], 2, s[6:7]
	global_load_dword v12, v[2:3], off nt
	ds_read2st64_b32 v[2:3], v130 offset0:64 offset1:68
	ds_read2st64_b32 v[4:5], v130 offset0:72 offset1:76
	ds_read2st64_b32 v[6:7], v130 offset0:80 offset1:84
	ds_read2st64_b32 v[8:9], v130 offset0:88 offset1:92
	v_lshl_or_b32 v13, s13, 2, v1
	s_waitcnt lgkmcnt(3)
	v_add_f32_e32 v2, 0, v2
	v_add_f32_e32 v2, v2, v3
	s_waitcnt lgkmcnt(2)
	v_add_f32_e32 v2, v2, v4
	v_add_f32_e32 v2, v2, v5
	s_waitcnt lgkmcnt(1)
	v_add_f32_e32 v2, v2, v6
	v_mov_b64_e32 v[10:11], s[8:9]
	v_add_f32_e32 v2, v2, v7
	s_ashr_i32 s13, s12, 31
	v_mad_i64_i32 v[10:11], s[54:55], v13, s17, v[10:11]
	s_waitcnt lgkmcnt(0)
	v_add_f32_e32 v2, v2, v8
	v_lshl_add_u64 v[10:11], s[12:13], 2, v[10:11]
	v_add_f32_e32 v2, v2, v9
	s_waitcnt vmcnt(0)
	v_add_f32_e32 v4, v2, v12
	v_lshl_add_u64 v[2:3], v[10:11], 0, v[116:117]
	global_store_dword v[2:3], v4, off
	s_branch .LBB0_7

; __global__ void __launch_bounds__(512, 2) fwd_mega(Args a) {
;     ...
;         for (int row = gtid; row < M; row += NTH) {
;             const float p = (float)((const int*)a.in[2])[row];
; #pragma unroll
;             for (int d = 0; d < 8; ++d) { const float ang = p * a.invf[d]; const double rev = (double)ang * 0.15915494309189535; const float f = (float)(rev - rint(rev));
;                 ((float*)(a.ws + WS_ROPE))[(size_t)row * 16 + d] = __builtin_amdgcn_cosf(f); ((float*)(a.ws + WS_ROPE))[(size_t)row * 16 + 8 + d] = __builtin_amdgcn_sinf(f); }
;         }
.LBB0_16:
	global_load_dword v1, v[4:5], off nt
	v_add_u32_e32 v2, s14, v2
	v_cmp_lt_i32_e32 vcc, s15, v2
	v_lshl_add_u64 v[4:5], v[4:5], 0, s[16:17]
	s_or_b64 s[20:21], vcc, s[20:21]
	s_waitcnt vmcnt(0)
	v_cvt_f32_i32_e32 v1, v1
	v_mul_f32_e32 v3, s4, v1
	v_mul_f32_e32 v10, s5, v1
	v_mul_f32_e32 v12, s6, v1
	v_mul_f32_e32 v14, s7, v1
	v_cvt_f64_f32_e32 v[8:9], v3
	v_cvt_f64_f32_e32 v[10:11], v10
	v_cvt_f64_f32_e32 v[12:13], v12
	v_cvt_f64_f32_e32 v[14:15], v14
	v_mul_f32_e32 v16, s8, v1
	v_mul_f32_e32 v18, s9, v1
	v_mul_f32_e32 v20, s10, v1
	v_mul_f32_e32 v1, s11, v1
	v_mul_f64 v[24:25], v[8:9], s[22:23]
	v_mul_f64 v[26:27], v[10:11], s[22:23]
	v_mul_f64 v[28:29], v[12:13], s[22:23]
	v_mul_f64 v[30:31], v[14:15], s[22:23]
	v_cvt_f64_f32_e32 v[16:17], v16
	v_cvt_f64_f32_e32 v[18:19], v18
	v_cvt_f64_f32_e32 v[20:21], v20
	v_cvt_f64_f32_e32 v[22:23], v1
	v_rndne_f64_e32 v[24:25], v[24:25]
	v_rndne_f64_e32 v[26:27], v[26:27]
	v_rndne_f64_e32 v[28:29], v[28:29]
	v_rndne_f64_e32 v[30:31], v[30:31]
	v_mul_f64 v[32:33], v[16:17], s[22:23]
	v_mul_f64 v[34:35], v[18:19], s[22:23]
	v_mul_f64 v[36:37], v[20:21], s[22:23]
	v_mul_f64 v[38:39], v[22:23], s[22:23]
	v_fma_f64 v[8:9], v[8:9], s[22:23], -v[24:25]
	v_fma_f64 v[10:11], v[10:11], s[22:23], -v[26:27]
	v_fma_f64 v[12:13], v[12:13], s[22:23], -v[28:29]
	v_fma_f64 v[14:15], v[14:15], s[22:23], -v[30:31]
	v_rndne_f64_e32 v[32:33], v[32:33]
	v_rndne_f64_e32 v[34:35], v[34:35]
	v_rndne_f64_e32 v[36:37], v[36:37]
	v_rndne_f64_e32 v[38:39], v[38:39]
	v_cvt_f32_f64_e32 v1, v[8:9]
	v_cvt_f32_f64_e32 v3, v[10:11]
	v_cvt_f32_f64_e32 v11, v[12:13]
	v_cvt_f32_f64_e32 v15, v[14:15]
	v_fma_f64 v[16:17], v[16:17], s[22:23], -v[32:33]
	v_fma_f64 v[18:19], v[18:19], s[22:23], -v[34:35]
	v_fma_f64 v[20:21], v[20:21], s[22:23], -v[36:37]
	v_fma_f64 v[22:23], v[22:23], s[22:23], -v[38:39]
	v_cos_f32_e32 v8, v1
	v_cos_f32_e32 v9, v3
	v_cos_f32_e32 v10, v11
	v_sin_f32_e32 v14, v11
	v_cos_f32_e32 v11, v15
	v_cvt_f32_f64_e32 v17, v[16:17]
	v_cvt_f32_f64_e32 v18, v[18:19]
	v_cvt_f32_f64_e32 v19, v[20:21]
	v_cvt_f32_f64_e32 v23, v[22:23]
	v_sin_f32_e32 v12, v1
	v_sin_f32_e32 v13, v3
	v_sin_f32_e32 v15, v15
	v_cos_f32_e32 v16, v17
	v_sin_f32_e32 v20, v17
	v_cos_f32_e32 v17, v18
	v_sin_f32_e32 v21, v18
	v_cos_f32_e32 v18, v19
	v_sin_f32_e32 v22, v19
	v_cos_f32_e32 v19, v23
	v_sin_f32_e32 v23, v23
	global_store_dwordx4 v[6:7], v[8:11], off
	global_store_dwordx4 v[6:7], v[12:15], off offset:32
	global_store_dwordx4 v[6:7], v[16:19], off offset:16
	global_store_dwordx4 v[6:7], v[20:23], off offset:48
	v_lshl_add_u64 v[6:7], v[6:7], 0, s[18:19]
	s_andn2_b64 exec, exec, s[20:21]
	s_cbranch_execnz .LBB0_16

; #define LAS __attribute__((address_space(3)))
; __device__ __forceinline__ void tr_item(const float* W, int N, bf16* WT, int dpitch, int koff, int drow0, int k0, int n0, LAS float* scr, int lane) {
;     float tv[32];
; #pragma unroll
;     for (int i = 0; i < 32; ++i) tv[i] = W[(size_t)(k0 + 2 * i + (lane >> 5)) * N + n0 + (lane & 31)];
; #pragma unroll
;     for (int i = 0; i < 32; ++i) scr[(2 * i + (lane >> 5)) * 33 + (lane & 31)] = tv[i];
; __global__ void __launch_bounds__(512, 2) fwd_mega(Args a) {
;     ...
;             { const int kb = it / 32, nb = it % 32; tr_item(INF(20) + (size_t)LL * FF * D, D, WSP(wd_off), 2816, 0, 32 * nb, 64 * kb, 32 * nb, scr, lane); }
.LBB0_20:
	s_cmpk_gt_i32 s53, 0xa7f
	s_mov_b64 s[6:7], -1
	s_cbranch_scc0 .LBB0_42
	s_cmpk_gt_u32 s53, 0xc7f
	s_cbranch_scc0 .LBB0_39
	s_cmpk_gt_u32 s53, 0xe7f
	s_cbranch_scc0 .LBB0_36
	s_cmpk_gt_u32 s53, 0x107f
	s_cbranch_scc0 .LBB0_33
	s_cmpk_gt_u32 s53, 0x15ff
	s_cbranch_scc0 .LBB0_30
	s_cmpk_gt_u32 s53, 0x1b7f
	s_cbranch_scc0 .LBB0_27
	s_and_b32 s4, s12, 0x7fffffc0
	s_add_i32 s6, s4, 0xffffc900
	s_and_b32 s8, s10, 0x3e0
	v_or_b32_e32 v2, s6, v200
	s_lshl_b32 s4, s8, 2
	v_or_b32_e32 v44, 2, v2
	v_mov_b32_e32 v45, v3
	v_or_b32_e32 v46, 4, v2
	v_mov_b32_e32 v47, v3
	v_or_b32_e32 v48, 6, v2
	v_mov_b32_e32 v49, v3
	v_or_b32_e32 v50, 8, v2
	v_mov_b32_e32 v51, v3
	v_or_b32_e32 v52, 10, v2
	v_mov_b32_e32 v53, v3
	v_or_b32_e32 v54, 12, v2
	v_mov_b32_e32 v55, v3
	v_lshl_add_u64 v[40:41], v[4:5], 0, s[4:5]
	v_lshlrev_b64 v[42:43], 12, v[2:3]
	v_lshlrev_b64 v[44:45], 12, v[44:45]
	v_lshlrev_b64 v[46:47], 12, v[46:47]
	v_lshlrev_b64 v[48:49], 12, v[48:49]
	v_lshlrev_b64 v[50:51], 12, v[50:51]
	v_lshlrev_b64 v[52:53], 12, v[52:53]
	v_lshlrev_b64 v[54:55], 12, v[54:55]
	v_or_b32_e32 v56, 14, v2
	v_mov_b32_e32 v57, v3
	v_lshl_add_u64 v[42:43], v[40:41], 0, v[42:43]
	v_lshl_add_u64 v[44:45], v[40:41], 0, v[44:45]
	v_lshl_add_u64 v[46:47], v[40:41], 0, v[46:47]
	v_lshl_add_u64 v[48:49], v[40:41], 0, v[48:49]
	v_lshl_add_u64 v[50:51], v[40:41], 0, v[50:51]
	v_lshl_add_u64 v[52:53], v[40:41], 0, v[52:53]
	v_lshl_add_u64 v[54:55], v[40:41], 0, v[54:55]
	v_lshlrev_b64 v[56:57], 12, v[56:57]
	v_lshl_add_u64 v[56:57], v[40:41], 0, v[56:57]
	global_load_dword v39, v[42:43], off nt
	global_load_dword v58, v[44:45], off nt
	global_load_dword v59, v[46:47], off nt
	global_load_dword v60, v[48:49], off nt
	global_load_dword v61, v[50:51], off nt
	global_load_dword v62, v[52:53], off nt
	global_load_dword v63, v[54:55], off nt
	global_load_dword v64, v[56:57], off nt
	v_or_b32_e32 v42, 16, v2
	v_mov_b32_e32 v43, v3
	v_or_b32_e32 v44, 18, v2
	v_mov_b32_e32 v45, v3
	v_or_b32_e32 v46, 20, v2
	v_mov_b32_e32 v47, v3
	v_or_b32_e32 v48, 22, v2
	v_mov_b32_e32 v49, v3
	v_or_b32_e32 v50, 24, v2
	v_mov_b32_e32 v51, v3
	v_or_b32_e32 v52, 26, v2
	v_mov_b32_e32 v53, v3
	v_or_b32_e32 v54, 28, v2
	v_mov_b32_e32 v55, v3
	v_lshlrev_b64 v[42:43], 12, v[42:43]
	v_lshlrev_b64 v[44:45], 12, v[44:45]
	v_lshlrev_b64 v[46:47], 12, v[46:47]
	v_lshlrev_b64 v[48:49], 12, v[48:49]
	v_lshlrev_b64 v[50:51], 12, v[50:51]
	v_lshlrev_b64 v[52:53], 12, v[52:53]
	v_lshlrev_b64 v[54:55], 12, v[54:55]
	v_or_b32_e32 v56, 30, v2
	v_mov_b32_e32 v57, v3
	v_lshl_add_u64 v[42:43], v[40:41], 0, v[42:43]
	v_lshl_add_u64 v[44:45], v[40:41], 0, v[44:45]
	v_lshl_add_u64 v[46:47], v[40:41], 0, v[46:47]
	v_lshl_add_u64 v[48:49], v[40:41], 0, v[48:49]
	v_lshl_add_u64 v[50:51], v[40:41], 0, v[50:51]
	v_lshl_add_u64 v[52:53], v[40:41], 0, v[52:53]
	v_lshl_add_u64 v[54:55], v[40:41], 0, v[54:55]
	v_lshlrev_b64 v[56:57], 12, v[56:57]
	v_lshl_add_u64 v[56:57], v[40:41], 0, v[56:57]
	global_load_dword v65, v[42:43], off nt
	global_load_dword v66, v[44:45], off nt
	global_load_dword v67, v[46:47], off nt
	global_load_dword v68, v[48:49], off nt
	global_load_dword v69, v[50:51], off nt
	global_load_dword v70, v[52:53], off nt
	global_load_dword v71, v[54:55], off nt
	global_load_dword v72, v[56:57], off nt
	v_or_b32_e32 v42, 32, v2
	v_mov_b32_e32 v43, v3
	v_or_b32_e32 v44, 34, v2
	v_mov_b32_e32 v45, v3
	v_or_b32_e32 v46, 36, v2
	v_mov_b32_e32 v47, v3
	v_or_b32_e32 v48, 38, v2
	v_mov_b32_e32 v49, v3
	v_or_b32_e32 v50, 40, v2
	v_mov_b32_e32 v51, v3
	v_or_b32_e32 v52, 42, v2
	v_mov_b32_e32 v53, v3
	v_or_b32_e32 v54, 44, v2
	v_mov_b32_e32 v55, v3
	v_lshlrev_b64 v[42:43], 12, v[42:43]
	v_lshlrev_b64 v[44:45], 12, v[44:45]
	v_lshlrev_b64 v[46:47], 12, v[46:47]
	v_lshlrev_b64 v[48:49], 12, v[48:49]
	v_lshlrev_b64 v[50:51], 12, v[50:51]
	v_lshlrev_b64 v[52:53], 12, v[52:53]
	v_lshlrev_b64 v[54:55], 12, v[54:55]
	v_or_b32_e32 v56, 46, v2
	v_mov_b32_e32 v57, v3
	v_lshl_add_u64 v[42:43], v[40:41], 0, v[42:43]
	v_lshl_add_u64 v[44:45], v[40:41], 0, v[44:45]
	v_lshl_add_u64 v[46:47], v[40:41], 0, v[46:47]
	v_lshl_add_u64 v[48:49], v[40:41], 0, v[48:49]
	v_lshl_add_u64 v[50:51], v[40:41], 0, v[50:51]
	v_lshl_add_u64 v[52:53], v[40:41], 0, v[52:53]
	v_lshl_add_u64 v[54:55], v[40:41], 0, v[54:55]
	v_lshlrev_b64 v[56:57], 12, v[56:57]
	v_lshl_add_u64 v[56:57], v[40:41], 0, v[56:57]
	global_load_dword v73, v[42:43], off nt
	global_load_dword v74, v[44:45], off nt
	global_load_dword v75, v[46:47], off nt
	global_load_dword v76, v[48:49], off nt
	global_load_dword v77, v[50:51], off nt
	global_load_dword v78, v[52:53], off nt
	global_load_dword v79, v[54:55], off nt
	global_load_dword v80, v[56:57], off nt
	v_or_b32_e32 v42, 48, v2
	v_mov_b32_e32 v43, v3
	v_or_b32_e32 v44, 50, v2
	v_mov_b32_e32 v45, v3
	v_or_b32_e32 v46, 52, v2
	v_mov_b32_e32 v47, v3
	v_or_b32_e32 v48, 54, v2
	v_mov_b32_e32 v49, v3
	v_or_b32_e32 v50, 56, v2
	v_mov_b32_e32 v51, v3
	v_or_b32_e32 v52, 58, v2
	v_mov_b32_e32 v53, v3
	v_or_b32_e32 v54, 60, v2
	v_mov_b32_e32 v55, v3
	v_or_b32_e32 v2, 62, v2
	v_lshlrev_b64 v[42:43], 12, v[42:43]
	v_lshlrev_b64 v[44:45], 12, v[44:45]
	v_lshlrev_b64 v[46:47], 12, v[46:47]
	v_lshlrev_b64 v[48:49], 12, v[48:49]
	v_lshlrev_b64 v[50:51], 12, v[50:51]
	v_lshlrev_b64 v[52:53], 12, v[52:53]
	v_lshlrev_b64 v[54:55], 12, v[54:55]
	v_lshlrev_b64 v[56:57], 12, v[2:3]
	v_lshl_add_u64 v[42:43], v[40:41], 0, v[42:43]
	v_lshl_add_u64 v[44:45], v[40:41], 0, v[44:45]
	v_lshl_add_u64 v[46:47], v[40:41], 0, v[46:47]
	v_lshl_add_u64 v[48:49], v[40:41], 0, v[48:49]
	v_lshl_add_u64 v[50:51], v[40:41], 0, v[50:51]
	v_lshl_add_u64 v[52:53], v[40:41], 0, v[52:53]
	v_lshl_add_u64 v[54:55], v[40:41], 0, v[54:55]
	v_lshl_add_u64 v[40:41], v[40:41], 0, v[56:57]
	global_load_dword v2, v[42:43], off nt
	s_nop 0
	global_load_dword v42, v[44:45], off nt
	global_load_dword v43, v[46:47], off nt
	s_nop 0
	global_load_dword v44, v[48:49], off nt
	global_load_dword v45, v[50:51], off nt
	global_load_dword v46, v[52:53], off nt
	global_load_dword v47, v[54:55], off nt
	s_nop 0
	global_load_dword v40, v[40:41], off nt
	s_waitcnt vmcnt(30)
; #define LAS __attribute__((address_space(3)))
; #define LDS_WAIT() asm volatile("s_waitcnt lgkmcnt(0)" ::: "memory")
; __device__ __forceinline__ unsigned pk2(float lo, float hi) { return f2bf(lo) | (f2bf(hi) << 16); }
; __device__ __forceinline__ void tr_item(const float* W, int N, bf16* WT, int dpitch, int koff, int drow0, int k0, int n0, LAS float* scr, int lane) {
;     ...
;     for (int i = 0; i < 32; ++i) tv[i] = W[(size_t)(k0 + 2 * i + (lane >> 5)) * N + n0 + (lane & 31)];
; #pragma unroll
;     for (int i = 0; i < 32; ++i) scr[(2 * i + (lane >> 5)) * 33 + (lane & 31)] = tv[i];
;     LDS_WAIT(); asm volatile("" ::: "memory");
;     const int c = lane & 7;
; #pragma unroll
;     for (int j = 0; j < 4; ++j) { const int n = (lane >> 3) + 8 * j; const LAS float* s = scr + (8 * c) * 33 + n;
;         v4u o; o.x = pk2(s[0 * 33], s[1 * 33]); o.y = pk2(s[2 * 33], s[3 * 33]); o.z = pk2(s[4 * 33], s[5 * 33]); o.w = pk2(s[6 * 33], s[7 * 33]);
;         *(v4u*)(WT + (size_t)(drow0 + n) * dpitch + koff + k0 + 8 * c) = o; }
	ds_write2_b32 v1, v39, v58 offset1:66
	s_waitcnt vmcnt(28)
	ds_write2_b32 v1, v59, v60 offset0:132 offset1:198
	s_waitcnt vmcnt(26)
	ds_write2_b32 v32, v61, v62 offset0:8 offset1:74
	s_waitcnt vmcnt(24)
	ds_write2_b32 v32, v63, v64 offset0:140 offset1:206
	s_waitcnt vmcnt(22)
	ds_write2_b32 v33, v65, v66 offset0:16 offset1:82
	s_waitcnt vmcnt(20)
	ds_write2_b32 v33, v67, v68 offset0:148 offset1:214
	s_waitcnt vmcnt(18)
	ds_write2_b32 v34, v69, v70 offset0:24 offset1:90
	s_waitcnt vmcnt(16)
	ds_write2_b32 v34, v71, v72 offset0:156 offset1:222
	s_waitcnt vmcnt(14)
	ds_write2_b32 v35, v73, v74 offset0:32 offset1:98
	s_waitcnt vmcnt(12)
	ds_write2_b32 v35, v75, v76 offset0:164 offset1:230
	s_waitcnt vmcnt(10)
	ds_write2_b32 v36, v77, v78 offset0:40 offset1:106
	s_waitcnt vmcnt(8)
	ds_write2_b32 v36, v79, v80 offset0:172 offset1:238
	s_waitcnt vmcnt(6)
	ds_write2_b32 v37, v2, v42 offset0:48 offset1:114
	s_waitcnt vmcnt(4)
	ds_write2_b32 v37, v43, v44 offset0:180 offset1:246
	s_waitcnt vmcnt(2)
	ds_write2_b32 v38, v45, v46 offset0:56 offset1:122
	s_waitcnt vmcnt(0)
	ds_write2_b32 v38, v47, v40 offset0:188 offset1:254
	s_waitcnt lgkmcnt(0)
	ds_read2_b32 v[44:45], v28 offset1:8
	ds_read2_b32 v[48:49], v28 offset0:33 offset1:41
	ds_read2_b32 v[50:51], v28 offset0:66 offset1:74
	ds_read2_b32 v[52:53], v28 offset0:99 offset1:107
	ds_read2_b32 v[54:55], v28 offset0:132 offset1:140
	s_waitcnt lgkmcnt(4)
	v_bfe_u32 v2, v44, 16, 1
	v_add3_u32 v2, v44, v2, s14
	s_waitcnt lgkmcnt(3)
	v_bfe_u32 v39, v48, 16, 1
	v_lshrrev_b32_e32 v2, 16, v2
	v_add3_u32 v39, v48, v39, s14
	ds_read2_b32 v[56:57], v28 offset0:165 offset1:173
	v_and_or_b32 v40, v39, s15, v2
	s_waitcnt lgkmcnt(3)
	v_bfe_u32 v2, v50, 16, 1
	v_add3_u32 v2, v50, v2, s14
	s_waitcnt lgkmcnt(2)
	v_bfe_u32 v39, v52, 16, 1
	ds_read2_b32 v[58:59], v28 offset0:198 offset1:206
	v_lshrrev_b32_e32 v2, 16, v2
	v_add3_u32 v39, v52, v39, s14
	ds_read2_b32 v[60:61], v28 offset0:231 offset1:239
	v_and_or_b32 v41, v39, s15, v2
	s_waitcnt lgkmcnt(3)
	v_bfe_u32 v2, v54, 16, 1
	v_add3_u32 v2, v54, v2, s14
	s_waitcnt lgkmcnt(2)
	v_bfe_u32 v39, v56, 16, 1
	v_lshrrev_b32_e32 v2, 16, v2
	v_add3_u32 v39, v56, v39, s14
	v_and_or_b32 v42, v39, s15, v2
	s_waitcnt lgkmcnt(1)
	v_bfe_u32 v2, v58, 16, 1
	v_add3_u32 v2, v58, v2, s14
	s_waitcnt lgkmcnt(0)
	v_bfe_u32 v39, v60, 16, 1
	v_lshrrev_b32_e32 v2, 16, v2
	v_add3_u32 v39, v60, v39, s14
	s_mov_b32 s7, s5
	v_and_or_b32 v43, v39, s15, v2
	v_or_b32_e32 v2, s8, v201
	v_lshl_add_u64 v[46:47], s[6:7], 1, v[6:7]
	v_mul_u32_u24_e32 v2, 0x1600, v2
	v_lshl_add_u64 v[62:63], v[46:47], 0, v[2:3]
	v_bfe_u32 v2, v45, 16, 1
	v_add3_u32 v2, v45, v2, s14
	v_bfe_u32 v39, v49, 16, 1
	v_lshrrev_b32_e32 v2, 16, v2
	v_add3_u32 v39, v49, v39, s14
	global_store_dwordx4 v[62:63], v[40:43], off
	ds_read2_b32 v[44:45], v28 offset0:16 offset1:24
	s_mov_b64 s[6:7], 0
	v_and_or_b32 v40, v39, s15, v2
	v_bfe_u32 v2, v51, 16, 1
	v_add3_u32 v2, v51, v2, s14
	v_bfe_u32 v39, v53, 16, 1
	v_lshrrev_b32_e32 v2, 16, v2
	v_add3_u32 v39, v53, v39, s14
	v_and_or_b32 v41, v39, s15, v2
	v_bfe_u32 v2, v55, 16, 1
	v_add3_u32 v2, v55, v2, s14
	v_bfe_u32 v39, v57, 16, 1
	v_lshrrev_b32_e32 v2, 16, v2
	v_add3_u32 v39, v57, v39, s14
	v_and_or_b32 v42, v39, s15, v2
	v_bfe_u32 v2, v59, 16, 1
	v_add3_u32 v2, v59, v2, s14
	v_bfe_u32 v39, v61, 16, 1
	v_lshrrev_b32_e32 v2, 16, v2
	v_add3_u32 v39, v61, v39, s14
	v_and_or_b32 v43, v39, s15, v2
	v_or_b32_e32 v2, s8, v29
	v_mul_u32_u24_e32 v2, 0x1600, v2
	v_lshl_add_u64 v[48:49], v[46:47], 0, v[2:3]
	global_store_dwordx4 v[48:49], v[40:43], off
	ds_read2_b32 v[48:49], v28 offset0:49 offset1:57
	ds_read2_b32 v[50:51], v28 offset0:82 offset1:90
	ds_read2_b32 v[52:53], v28 offset0:115 offset1:123
	s_waitcnt lgkmcnt(3)
	v_bfe_u32 v2, v44, 16, 1
	v_add3_u32 v2, v44, v2, s14
	s_waitcnt lgkmcnt(2)
	v_bfe_u32 v39, v48, 16, 1
	ds_read2_b32 v[54:55], v28 offset0:148 offset1:156
	v_lshrrev_b32_e32 v2, 16, v2
	v_add3_u32 v39, v48, v39, s14
	ds_read2_b32 v[56:57], v28 offset0:181 offset1:189
	v_and_or_b32 v40, v39, s15, v2
	s_waitcnt lgkmcnt(3)
	v_bfe_u32 v2, v50, 16, 1
	v_add3_u32 v2, v50, v2, s14
	s_waitcnt lgkmcnt(2)
	v_bfe_u32 v39, v52, 16, 1
	ds_read2_b32 v[58:59], v28 offset0:214 offset1:222
	v_lshrrev_b32_e32 v2, 16, v2
	v_add3_u32 v39, v52, v39, s14
	ds_read2_b32 v[60:61], v28 offset0:247 offset1:255
	v_and_or_b32 v41, v39, s15, v2
	s_waitcnt lgkmcnt(3)
	v_bfe_u32 v2, v54, 16, 1
	v_add3_u32 v2, v54, v2, s14
	s_waitcnt lgkmcnt(2)
	v_bfe_u32 v39, v56, 16, 1
	v_lshrrev_b32_e32 v2, 16, v2
	v_add3_u32 v39, v56, v39, s14
	v_and_or_b32 v42, v39, s15, v2
	s_waitcnt lgkmcnt(1)
	v_bfe_u32 v2, v58, 16, 1
	v_add3_u32 v2, v58, v2, s14
	s_waitcnt lgkmcnt(0)
	v_bfe_u32 v39, v60, 16, 1
	v_lshrrev_b32_e32 v2, 16, v2
	v_add3_u32 v39, v60, v39, s14
	v_and_or_b32 v43, v39, s15, v2
	v_or_b32_e32 v2, s8, v30
	v_mul_u32_u24_e32 v2, 0x1600, v2
	v_lshl_add_u64 v[62:63], v[46:47], 0, v[2:3]
	v_bfe_u32 v2, v45, 16, 1
	v_add3_u32 v2, v45, v2, s14
	v_bfe_u32 v39, v49, 16, 1
	v_lshrrev_b32_e32 v2, 16, v2
	v_add3_u32 v39, v49, v39, s14
	global_store_dwordx4 v[62:63], v[40:43], off
	s_nop 1
	v_and_or_b32 v40, v39, s15, v2
	v_bfe_u32 v2, v51, 16, 1
	v_add3_u32 v2, v51, v2, s14
	v_bfe_u32 v39, v53, 16, 1
	v_lshrrev_b32_e32 v2, 16, v2
	v_add3_u32 v39, v53, v39, s14
	v_and_or_b32 v41, v39, s15, v2
	v_bfe_u32 v2, v55, 16, 1
	v_add3_u32 v2, v55, v2, s14
	v_bfe_u32 v39, v57, 16, 1
	v_lshrrev_b32_e32 v2, 16, v2
	v_add3_u32 v39, v57, v39, s14
	v_and_or_b32 v42, v39, s15, v2
	v_bfe_u32 v2, v59, 16, 1
	v_add3_u32 v2, v59, v2, s14
	v_bfe_u32 v39, v61, 16, 1
	v_lshrrev_b32_e32 v2, 16, v2
	v_add3_u32 v39, v61, v39, s14
	v_and_or_b32 v43, v39, s15, v2
	v_or_b32_e32 v2, s8, v31
	v_mul_u32_u24_e32 v2, 0x1600, v2
	v_lshl_add_u64 v[44:45], v[46:47], 0, v[2:3]
	global_store_dwordx4 v[44:45], v[40:43], off
	s_waitcnt lgkmcnt(0)
; #define LAS __attribute__((address_space(3)))
; __device__ __forceinline__ void tr_item(const float* W, int N, bf16* WT, int dpitch, int koff, int drow0, int k0, int n0, LAS float* scr, int lane) {
;     float tv[32];
; #pragma unroll
;     for (int i = 0; i < 32; ++i) tv[i] = W[(size_t)(k0 + 2 * i + (lane >> 5)) * N + n0 + (lane & 31)];
; #pragma unroll
;     for (int i = 0; i < 32; ++i) scr[(2 * i + (lane >> 5)) * 33 + (lane & 31)] = tv[i];
; __global__ void __launch_bounds__(512, 2) fwd_mega(Args a) {
;     ...
;             if (it < 1408) { const int kb = it / 88, nb = it % 88, n0 = 32 * nb; tr_item(INF(17) + (size_t)LL * D * FF, FF, WSP(WS_WGU), 1024, 0, (n0 >> 7) * 256 + 128 + (n0 & 127), 64 * kb, n0, scr, lane); continue; } it -= 1408;
.LBB0_27:
	s_andn2_b64 vcc, exec, s[6:7]
	s_cbranch_vccnz .LBB0_29
	s_add_i32 s4, s53, 0xea00
	s_and_b32 s6, s4, 0xffff
	s_mul_i32 s6, s6, 0xba2f
	s_lshr_b32 s8, s6, 16
	s_lshr_b32 s6, s6, 22
	s_mulk_i32 s6, 0x58
	s_sub_i32 s4, s4, s6
	s_and_b32 s7, s4, 0xffff
	s_and_b32 s6, s8, 0xffc0
	v_or_b32_e32 v2, s6, v200
	s_lshl_b32 s4, s7, 7
	v_lshl_add_u64 v[40:41], v[8:9], 0, s[4:5]
	v_mul_u32_u24_e32 v2, 0x2c00, v2
	v_lshl_add_u64 v[40:41], v[40:41], 0, v[2:3]
	v_add_co_u32_e32 v42, vcc, s16, v40
	s_lshl_b32 s4, s7, 5
	s_nop 0
	v_addc_co_u32_e32 v43, vcc, 0, v41, vcc
	v_add_co_u32_e32 v44, vcc, s17, v40
	s_lshl_b32 s7, s7, 6
	s_nop 0
	v_addc_co_u32_e32 v45, vcc, 0, v41, vcc
	v_add_co_u32_e32 v46, vcc, s18, v40
	s_and_b32 s7, s7, 0x1f00
	s_nop 0
	v_addc_co_u32_e32 v47, vcc, 0, v41, vcc
	v_add_co_u32_e32 v48, vcc, s19, v40
	s_and_b32 s4, s4, 0x60
	s_nop 0
	v_addc_co_u32_e32 v49, vcc, 0, v41, vcc
	v_add_co_u32_e32 v50, vcc, s20, v40
	s_or_b32 s4, s4, s7
	s_nop 0
	v_addc_co_u32_e32 v51, vcc, 0, v41, vcc
	v_add_co_u32_e32 v52, vcc, s21, v40
	s_or_b32 s7, s4, 0x80
	s_nop 0
	v_addc_co_u32_e32 v53, vcc, 0, v41, vcc
	v_add_co_u32_e32 v54, vcc, s23, v40
	s_lshl_b32 s4, s6, 1
	s_nop 0
	v_addc_co_u32_e32 v55, vcc, 0, v41, vcc
	global_load_dword v2, v[40:41], off nt
	global_load_dword v39, v[42:43], off offset:2048 nt
	global_load_dword v58, v[44:45], off nt
	global_load_dword v59, v[46:47], off offset:2048 nt
	global_load_dword v60, v[48:49], off nt
	global_load_dword v61, v[50:51], off offset:2048 nt
	global_load_dword v62, v[52:53], off nt
	global_load_dword v63, v[54:55], off offset:2048 nt
	v_add_co_u32_e32 v42, vcc, s24, v40
	s_nop 1
	v_addc_co_u32_e32 v43, vcc, 0, v41, vcc
	v_add_co_u32_e32 v44, vcc, s25, v40
	s_nop 1
	v_addc_co_u32_e32 v45, vcc, 0, v41, vcc
	v_add_co_u32_e32 v46, vcc, s28, v40
	s_nop 1
	v_addc_co_u32_e32 v47, vcc, 0, v41, vcc
	v_add_co_u32_e32 v48, vcc, s29, v40
	s_nop 1
	v_addc_co_u32_e32 v49, vcc, 0, v41, vcc
	v_add_co_u32_e32 v50, vcc, s30, v40
	s_nop 1
	v_addc_co_u32_e32 v51, vcc, 0, v41, vcc
	v_add_co_u32_e32 v52, vcc, s31, v40
	s_nop 1
	v_addc_co_u32_e32 v53, vcc, 0, v41, vcc
	v_add_co_u32_e32 v54, vcc, s34, v40
	s_nop 1
	v_addc_co_u32_e32 v55, vcc, 0, v41, vcc
	v_add_co_u32_e32 v56, vcc, s35, v40
	s_nop 1
	v_addc_co_u32_e32 v57, vcc, 0, v41, vcc
	global_load_dword v64, v[42:43], off nt
	global_load_dword v65, v[44:45], off offset:2048 nt
	global_load_dword v66, v[46:47], off nt
	global_load_dword v67, v[48:49], off offset:2048 nt
	global_load_dword v68, v[50:51], off nt
	global_load_dword v69, v[52:53], off offset:2048 nt
	global_load_dword v70, v[54:55], off nt
	global_load_dword v71, v[56:57], off offset:2048 nt
	v_add_co_u32_e32 v42, vcc, s36, v40
	s_nop 1
	v_addc_co_u32_e32 v43, vcc, 0, v41, vcc
	v_add_co_u32_e32 v44, vcc, s37, v40
	s_nop 1
	v_addc_co_u32_e32 v45, vcc, 0, v41, vcc
	v_add_co_u32_e32 v46, vcc, s38, v40
	s_nop 1
	v_addc_co_u32_e32 v47, vcc, 0, v41, vcc
	v_add_co_u32_e32 v48, vcc, s39, v40
	s_nop 1
	v_addc_co_u32_e32 v49, vcc, 0, v41, vcc
	v_add_co_u32_e32 v50, vcc, s40, v40
	s_nop 1
	v_addc_co_u32_e32 v51, vcc, 0, v41, vcc
	v_add_co_u32_e32 v52, vcc, s41, v40
	s_nop 1
	v_addc_co_u32_e32 v53, vcc, 0, v41, vcc
	v_add_co_u32_e32 v54, vcc, s42, v40
	s_nop 1
	v_addc_co_u32_e32 v55, vcc, 0, v41, vcc
	v_add_co_u32_e32 v56, vcc, s43, v40
	s_nop 1
	v_addc_co_u32_e32 v57, vcc, 0, v41, vcc
	global_load_dword v72, v[42:43], off nt
	global_load_dword v73, v[44:45], off offset:2048 nt
	global_load_dword v74, v[46:47], off nt
	global_load_dword v75, v[48:49], off offset:2048 nt
	global_load_dword v76, v[50:51], off nt
	global_load_dword v77, v[52:53], off offset:2048 nt
	global_load_dword v78, v[54:55], off nt
	s_nop 0
	global_load_dword v56, v[56:57], off offset:2048 nt
	v_add_co_u32_e32 v42, vcc, s44, v40
	s_nop 1
	v_addc_co_u32_e32 v43, vcc, 0, v41, vcc
	v_add_co_u32_e32 v44, vcc, s45, v40
	s_nop 1
	v_addc_co_u32_e32 v45, vcc, 0, v41, vcc
	v_add_co_u32_e32 v46, vcc, s46, v40
	s_nop 1
	v_addc_co_u32_e32 v47, vcc, 0, v41, vcc
	v_add_co_u32_e32 v48, vcc, s47, v40
	s_nop 1
	v_addc_co_u32_e32 v49, vcc, 0, v41, vcc
	v_add_co_u32_e32 v50, vcc, s48, v40
	s_nop 1
	v_addc_co_u32_e32 v51, vcc, 0, v41, vcc
	v_add_co_u32_e32 v52, vcc, s49, v40
	s_nop 1
	v_addc_co_u32_e32 v53, vcc, 0, v41, vcc
	v_add_co_u32_e32 v54, vcc, s50, v40
	s_nop 1
	v_addc_co_u32_e32 v55, vcc, 0, v41, vcc
	v_add_co_u32_e32 v40, vcc, s51, v40
	s_nop 1
	v_addc_co_u32_e32 v41, vcc, 0, v41, vcc
	global_load_dword v42, v[42:43], off nt
	s_nop 0
	global_load_dword v43, v[44:45], off offset:2048 nt
	s_nop 0
	global_load_dword v44, v[46:47], off nt
	global_load_dword v45, v[48:49], off offset:2048 nt
	s_nop 0
	global_load_dword v46, v[50:51], off nt
	global_load_dword v47, v[52:53], off offset:2048 nt
	global_load_dword v48, v[54:55], off nt
	s_nop 0
	global_load_dword v40, v[40:41], off offset:2048 nt
	s_waitcnt vmcnt(30)
	ds_write2_b32 v1, v2, v39 offset1:66
	s_waitcnt vmcnt(28)
	ds_write2_b32 v1, v58, v59 offset0:132 offset1:198
	s_waitcnt vmcnt(26)
	ds_write2_b32 v32, v60, v61 offset0:8 offset1:74
	s_waitcnt vmcnt(24)
	ds_write2_b32 v32, v62, v63 offset0:140 offset1:206
	s_waitcnt vmcnt(22)
	ds_write2_b32 v33, v64, v65 offset0:16 offset1:82
	s_waitcnt vmcnt(20)
	ds_write2_b32 v33, v66, v67 offset0:148 offset1:214
	s_waitcnt vmcnt(18)
; #define LAS __attribute__((address_space(3)))
; #define LDS_WAIT() asm volatile("s_waitcnt lgkmcnt(0)" ::: "memory")
; __device__ __forceinline__ unsigned pk2(float lo, float hi) { return f2bf(lo) | (f2bf(hi) << 16); }
; __device__ __forceinline__ void tr_item(const float* W, int N, bf16* WT, int dpitch, int koff, int drow0, int k0, int n0, LAS float* scr, int lane) {
;     ...
;     for (int i = 0; i < 32; ++i) tv[i] = W[(size_t)(k0 + 2 * i + (lane >> 5)) * N + n0 + (lane & 31)];
; #pragma unroll
;     for (int i = 0; i < 32; ++i) scr[(2 * i + (lane >> 5)) * 33 + (lane & 31)] = tv[i];
;     LDS_WAIT(); asm volatile("" ::: "memory");
;     const int c = lane & 7;
; #pragma unroll
;     for (int j = 0; j < 4; ++j) { const int n = (lane >> 3) + 8 * j; const LAS float* s = scr + (8 * c) * 33 + n;
;         v4u o; o.x = pk2(s[0 * 33], s[1 * 33]); o.y = pk2(s[2 * 33], s[3 * 33]); o.z = pk2(s[4 * 33], s[5 * 33]); o.w = pk2(s[6 * 33], s[7 * 33]);
;         *(v4u*)(WT + (size_t)(drow0 + n) * dpitch + koff + k0 + 8 * c) = o; }
;     LDS_WAIT(); asm volatile("" ::: "memory");
	ds_write2_b32 v34, v68, v69 offset0:24 offset1:90
	s_waitcnt vmcnt(16)
	ds_write2_b32 v34, v70, v71 offset0:156 offset1:222
	s_waitcnt vmcnt(14)
	ds_write2_b32 v35, v72, v73 offset0:32 offset1:98
	s_waitcnt vmcnt(12)
	ds_write2_b32 v35, v74, v75 offset0:164 offset1:230
	s_waitcnt vmcnt(10)
	ds_write2_b32 v36, v76, v77 offset0:40 offset1:106
	s_waitcnt vmcnt(8)
	ds_write2_b32 v36, v78, v56 offset0:172 offset1:238
	s_waitcnt vmcnt(6)
	ds_write2_b32 v37, v42, v43 offset0:48 offset1:114
	s_waitcnt vmcnt(4)
	ds_write2_b32 v37, v44, v45 offset0:180 offset1:246
	s_waitcnt vmcnt(2)
	ds_write2_b32 v38, v46, v47 offset0:56 offset1:122
	s_waitcnt vmcnt(0)
	ds_write2_b32 v38, v48, v40 offset0:188 offset1:254
	s_waitcnt lgkmcnt(0)
	ds_read2_b32 v[44:45], v28 offset1:8
	ds_read2_b32 v[48:49], v28 offset0:33 offset1:41
	ds_read2_b32 v[50:51], v28 offset0:66 offset1:74
	ds_read2_b32 v[52:53], v28 offset0:99 offset1:107
	ds_read2_b32 v[54:55], v28 offset0:132 offset1:140
	s_waitcnt lgkmcnt(4)
	v_bfe_u32 v2, v44, 16, 1
	v_add3_u32 v2, v44, v2, s14
	s_waitcnt lgkmcnt(3)
	v_bfe_u32 v39, v48, 16, 1
	v_lshrrev_b32_e32 v2, 16, v2
	v_add3_u32 v39, v48, v39, s14
	ds_read2_b32 v[56:57], v28 offset0:165 offset1:173
	v_and_or_b32 v40, v39, s15, v2
	s_waitcnt lgkmcnt(3)
	v_bfe_u32 v2, v50, 16, 1
	v_add3_u32 v2, v50, v2, s14
	s_waitcnt lgkmcnt(2)
	v_bfe_u32 v39, v52, 16, 1
	ds_read2_b32 v[58:59], v28 offset0:198 offset1:206
	v_lshrrev_b32_e32 v2, 16, v2
	v_add3_u32 v39, v52, v39, s14
	ds_read2_b32 v[60:61], v28 offset0:231 offset1:239
	v_and_or_b32 v41, v39, s15, v2
	s_waitcnt lgkmcnt(3)
	v_bfe_u32 v2, v54, 16, 1
	v_add3_u32 v2, v54, v2, s14
	s_waitcnt lgkmcnt(2)
	v_bfe_u32 v39, v56, 16, 1
	v_lshrrev_b32_e32 v2, 16, v2
	v_add3_u32 v39, v56, v39, s14
	v_and_or_b32 v42, v39, s15, v2
	s_waitcnt lgkmcnt(1)
	v_bfe_u32 v2, v58, 16, 1
	v_add3_u32 v2, v58, v2, s14
	s_waitcnt lgkmcnt(0)
	v_bfe_u32 v39, v60, 16, 1
	v_lshrrev_b32_e32 v2, 16, v2
	v_add3_u32 v39, v60, v39, s14
	v_and_or_b32 v43, v39, s15, v2
	v_or_b32_e32 v2, s7, v201
	v_lshl_add_u64 v[46:47], v[10:11], 0, s[4:5]
	v_lshlrev_b32_e32 v2, 11, v2
	v_lshl_add_u64 v[62:63], v[46:47], 0, v[2:3]
	v_bfe_u32 v2, v45, 16, 1
	v_add3_u32 v2, v45, v2, s14
	v_bfe_u32 v39, v49, 16, 1
	v_lshrrev_b32_e32 v2, 16, v2
	v_add3_u32 v39, v49, v39, s14
	global_store_dwordx4 v[62:63], v[40:43], off
	ds_read2_b32 v[44:45], v28 offset0:16 offset1:24
	s_nop 0
	v_and_or_b32 v40, v39, s15, v2
	v_bfe_u32 v2, v51, 16, 1
	v_add3_u32 v2, v51, v2, s14
	v_bfe_u32 v39, v53, 16, 1
	v_lshrrev_b32_e32 v2, 16, v2
	v_add3_u32 v39, v53, v39, s14
	v_and_or_b32 v41, v39, s15, v2
	v_bfe_u32 v2, v55, 16, 1
	v_add3_u32 v2, v55, v2, s14
	v_bfe_u32 v39, v57, 16, 1
	v_lshrrev_b32_e32 v2, 16, v2
	v_add3_u32 v39, v57, v39, s14
	v_and_or_b32 v42, v39, s15, v2
	v_bfe_u32 v2, v59, 16, 1
	v_add3_u32 v2, v59, v2, s14
	v_bfe_u32 v39, v61, 16, 1
	v_lshrrev_b32_e32 v2, 16, v2
	v_add3_u32 v39, v61, v39, s14
	v_and_or_b32 v43, v39, s15, v2
	v_or_b32_e32 v2, s7, v29
	v_lshlrev_b32_e32 v2, 11, v2
	v_lshl_add_u64 v[48:49], v[46:47], 0, v[2:3]
	global_store_dwordx4 v[48:49], v[40:43], off
	ds_read2_b32 v[48:49], v28 offset0:49 offset1:57
	ds_read2_b32 v[50:51], v28 offset0:82 offset1:90
	ds_read2_b32 v[52:53], v28 offset0:115 offset1:123
	s_waitcnt lgkmcnt(3)
	v_bfe_u32 v2, v44, 16, 1
	v_add3_u32 v2, v44, v2, s14
	s_waitcnt lgkmcnt(2)
	v_bfe_u32 v39, v48, 16, 1
	ds_read2_b32 v[54:55], v28 offset0:148 offset1:156
	v_lshrrev_b32_e32 v2, 16, v2
	v_add3_u32 v39, v48, v39, s14
	ds_read2_b32 v[56:57], v28 offset0:181 offset1:189
	v_and_or_b32 v40, v39, s15, v2
	s_waitcnt lgkmcnt(3)
	v_bfe_u32 v2, v50, 16, 1
	v_add3_u32 v2, v50, v2, s14
	s_waitcnt lgkmcnt(2)
	v_bfe_u32 v39, v52, 16, 1
	ds_read2_b32 v[58:59], v28 offset0:214 offset1:222
	v_lshrrev_b32_e32 v2, 16, v2
	v_add3_u32 v39, v52, v39, s14
	ds_read2_b32 v[60:61], v28 offset0:247 offset1:255
	v_and_or_b32 v41, v39, s15, v2
	s_waitcnt lgkmcnt(3)
	v_bfe_u32 v2, v54, 16, 1
	v_add3_u32 v2, v54, v2, s14
	s_waitcnt lgkmcnt(2)
	v_bfe_u32 v39, v56, 16, 1
	v_lshrrev_b32_e32 v2, 16, v2
	v_add3_u32 v39, v56, v39, s14
	v_and_or_b32 v42, v39, s15, v2
	s_waitcnt lgkmcnt(1)
	v_bfe_u32 v2, v58, 16, 1
	v_add3_u32 v2, v58, v2, s14
	s_waitcnt lgkmcnt(0)
	v_bfe_u32 v39, v60, 16, 1
	v_lshrrev_b32_e32 v2, 16, v2
	v_add3_u32 v39, v60, v39, s14
	v_and_or_b32 v43, v39, s15, v2
	v_or_b32_e32 v2, s7, v30
	v_lshlrev_b32_e32 v2, 11, v2
	v_lshl_add_u64 v[62:63], v[46:47], 0, v[2:3]
	v_bfe_u32 v2, v45, 16, 1
	v_add3_u32 v2, v45, v2, s14
	v_bfe_u32 v39, v49, 16, 1
	v_lshrrev_b32_e32 v2, 16, v2
	v_add3_u32 v39, v49, v39, s14
	global_store_dwordx4 v[62:63], v[40:43], off
	s_nop 1
	v_and_or_b32 v40, v39, s15, v2
	v_bfe_u32 v2, v51, 16, 1
	v_add3_u32 v2, v51, v2, s14
	v_bfe_u32 v39, v53, 16, 1
	v_lshrrev_b32_e32 v2, 16, v2
	v_add3_u32 v39, v53, v39, s14
	v_and_or_b32 v41, v39, s15, v2
	v_bfe_u32 v2, v55, 16, 1
	v_add3_u32 v2, v55, v2, s14
	v_bfe_u32 v39, v57, 16, 1
	v_lshrrev_b32_e32 v2, 16, v2
	v_add3_u32 v39, v57, v39, s14
	v_and_or_b32 v42, v39, s15, v2
	v_bfe_u32 v2, v59, 16, 1
	v_add3_u32 v2, v59, v2, s14
	v_bfe_u32 v39, v61, 16, 1
	v_lshrrev_b32_e32 v2, 16, v2
	v_add3_u32 v39, v61, v39, s14
	v_and_or_b32 v43, v39, s15, v2
	v_or_b32_e32 v2, s7, v31
	v_lshlrev_b32_e32 v2, 11, v2
	v_lshl_add_u64 v[44:45], v[46:47], 0, v[2:3]
	global_store_dwordx4 v[44:45], v[40:43], off
	s_waitcnt lgkmcnt(0)

; #define LAS __attribute__((address_space(3)))
; __device__ __forceinline__ void tr_item(const float* W, int N, bf16* WT, int dpitch, int koff, int drow0, int k0, int n0, LAS float* scr, int lane) {
;     float tv[32];
; #pragma unroll
;     for (int i = 0; i < 32; ++i) tv[i] = W[(size_t)(k0 + 2 * i + (lane >> 5)) * N + n0 + (lane & 31)];
; #pragma unroll
;     for (int i = 0; i < 32; ++i) scr[(2 * i + (lane >> 5)) * 33 + (lane & 31)] = tv[i];
; __global__ void __launch_bounds__(512, 2) fwd_mega(Args a) {
;     ...
;             if (it < 1408) { const int kb = it / 88, nb = it % 88, n0 = 32 * nb; tr_item(INF(16) + (size_t)LL * D * FF, FF, WSP(WS_WGU), 1024, 0, (n0 >> 7) * 256 + (n0 & 127), 64 * kb, n0, scr, lane); continue; } it -= 1408;
.LBB0_30:
	s_andn2_b64 vcc, exec, s[6:7]
	s_cbranch_vccnz .LBB0_32
	s_add_i32 s4, s53, 0xef80
	s_and_b32 s6, s4, 0xffff
	s_mul_i32 s6, s6, 0xba2f
	s_lshr_b32 s8, s6, 16
	s_lshr_b32 s6, s6, 22
	s_mulk_i32 s6, 0x58
	s_sub_i32 s4, s4, s6
	s_and_b32 s7, s4, 0xffff
	s_and_b32 s6, s8, 0xffc0
	v_or_b32_e32 v2, s6, v200
	s_lshl_b32 s4, s7, 7
	v_lshl_add_u64 v[40:41], v[12:13], 0, s[4:5]
	v_mul_u32_u24_e32 v2, 0x2c00, v2
	v_lshl_add_u64 v[40:41], v[40:41], 0, v[2:3]
	v_add_co_u32_e32 v42, vcc, s16, v40
	s_lshl_b32 s4, s7, 5
	s_nop 0
	v_addc_co_u32_e32 v43, vcc, 0, v41, vcc
	v_add_co_u32_e32 v44, vcc, s17, v40
	s_lshl_b32 s7, s7, 6
	s_nop 0
	v_addc_co_u32_e32 v45, vcc, 0, v41, vcc
	v_add_co_u32_e32 v46, vcc, s18, v40
	s_and_b32 s7, s7, 0x1f00
	s_nop 0
	v_addc_co_u32_e32 v47, vcc, 0, v41, vcc
	v_add_co_u32_e32 v48, vcc, s19, v40
	s_and_b32 s4, s4, 0x60
	s_nop 0
	v_addc_co_u32_e32 v49, vcc, 0, v41, vcc
	v_add_co_u32_e32 v50, vcc, s20, v40
	s_or_b32 s7, s7, s4
	s_nop 0
	v_addc_co_u32_e32 v51, vcc, 0, v41, vcc
	v_add_co_u32_e32 v52, vcc, s21, v40
	s_lshl_b32 s4, s6, 1
	s_nop 0
	v_addc_co_u32_e32 v53, vcc, 0, v41, vcc
	v_add_co_u32_e32 v54, vcc, s23, v40
	s_nop 1
	v_addc_co_u32_e32 v55, vcc, 0, v41, vcc
	global_load_dword v2, v[40:41], off nt
	global_load_dword v39, v[42:43], off offset:2048 nt
	global_load_dword v58, v[44:45], off nt
	global_load_dword v59, v[46:47], off offset:2048 nt
	global_load_dword v60, v[48:49], off nt
	global_load_dword v61, v[50:51], off offset:2048 nt
	global_load_dword v62, v[52:53], off nt
	global_load_dword v63, v[54:55], off offset:2048 nt
	v_add_co_u32_e32 v42, vcc, s24, v40
	s_nop 1
	v_addc_co_u32_e32 v43, vcc, 0, v41, vcc
	v_add_co_u32_e32 v44, vcc, s25, v40
	s_nop 1
	v_addc_co_u32_e32 v45, vcc, 0, v41, vcc
	v_add_co_u32_e32 v46, vcc, s28, v40
	s_nop 1
	v_addc_co_u32_e32 v47, vcc, 0, v41, vcc
	v_add_co_u32_e32 v48, vcc, s29, v40
	s_nop 1
	v_addc_co_u32_e32 v49, vcc, 0, v41, vcc
	v_add_co_u32_e32 v50, vcc, s30, v40
	s_nop 1
	v_addc_co_u32_e32 v51, vcc, 0, v41, vcc
	v_add_co_u32_e32 v52, vcc, s31, v40
	s_nop 1
	v_addc_co_u32_e32 v53, vcc, 0, v41, vcc
	v_add_co_u32_e32 v54, vcc, s34, v40
	s_nop 1
	v_addc_co_u32_e32 v55, vcc, 0, v41, vcc
	v_add_co_u32_e32 v56, vcc, s35, v40
	s_nop 1
	v_addc_co_u32_e32 v57, vcc, 0, v41, vcc
	global_load_dword v64, v[42:43], off nt
	global_load_dword v65, v[44:45], off offset:2048 nt
	global_load_dword v66, v[46:47], off nt
	global_load_dword v67, v[48:49], off offset:2048 nt
	global_load_dword v68, v[50:51], off nt
	global_load_dword v69, v[52:53], off offset:2048 nt
	global_load_dword v70, v[54:55], off nt
	global_load_dword v71, v[56:57], off offset:2048 nt
	v_add_co_u32_e32 v42, vcc, s36, v40
	s_nop 1
	v_addc_co_u32_e32 v43, vcc, 0, v41, vcc
	v_add_co_u32_e32 v44, vcc, s37, v40
	s_nop 1
	v_addc_co_u32_e32 v45, vcc, 0, v41, vcc
	v_add_co_u32_e32 v46, vcc, s38, v40
	s_nop 1
	v_addc_co_u32_e32 v47, vcc, 0, v41, vcc
	v_add_co_u32_e32 v48, vcc, s39, v40
	s_nop 1
	v_addc_co_u32_e32 v49, vcc, 0, v41, vcc
	v_add_co_u32_e32 v50, vcc, s40, v40
	s_nop 1
	v_addc_co_u32_e32 v51, vcc, 0, v41, vcc
	v_add_co_u32_e32 v52, vcc, s41, v40
	s_nop 1
	v_addc_co_u32_e32 v53, vcc, 0, v41, vcc
	v_add_co_u32_e32 v54, vcc, s42, v40
	s_nop 1
	v_addc_co_u32_e32 v55, vcc, 0, v41, vcc
	v_add_co_u32_e32 v56, vcc, s43, v40
	s_nop 1
	v_addc_co_u32_e32 v57, vcc, 0, v41, vcc
	global_load_dword v72, v[42:43], off nt
	global_load_dword v73, v[44:45], off offset:2048 nt
	global_load_dword v74, v[46:47], off nt
	global_load_dword v75, v[48:49], off offset:2048 nt
	global_load_dword v76, v[50:51], off nt
	global_load_dword v77, v[52:53], off offset:2048 nt
	global_load_dword v78, v[54:55], off nt
	s_nop 0
	global_load_dword v56, v[56:57], off offset:2048 nt
	v_add_co_u32_e32 v42, vcc, s44, v40
	s_nop 1
	v_addc_co_u32_e32 v43, vcc, 0, v41, vcc
	v_add_co_u32_e32 v44, vcc, s45, v40
	s_nop 1
	v_addc_co_u32_e32 v45, vcc, 0, v41, vcc
	v_add_co_u32_e32 v46, vcc, s46, v40
	s_nop 1
	v_addc_co_u32_e32 v47, vcc, 0, v41, vcc
	v_add_co_u32_e32 v48, vcc, s47, v40
	s_nop 1
	v_addc_co_u32_e32 v49, vcc, 0, v41, vcc
	v_add_co_u32_e32 v50, vcc, s48, v40
	s_nop 1
	v_addc_co_u32_e32 v51, vcc, 0, v41, vcc
	v_add_co_u32_e32 v52, vcc, s49, v40
	s_nop 1
	v_addc_co_u32_e32 v53, vcc, 0, v41, vcc
	v_add_co_u32_e32 v54, vcc, s50, v40
	s_nop 1
	v_addc_co_u32_e32 v55, vcc, 0, v41, vcc
	v_add_co_u32_e32 v40, vcc, s51, v40
	s_nop 1
	v_addc_co_u32_e32 v41, vcc, 0, v41, vcc
	global_load_dword v42, v[42:43], off nt
	s_nop 0
	global_load_dword v43, v[44:45], off offset:2048 nt
	s_nop 0
	global_load_dword v44, v[46:47], off nt
	global_load_dword v45, v[48:49], off offset:2048 nt
	s_nop 0
	global_load_dword v46, v[50:51], off nt
	global_load_dword v47, v[52:53], off offset:2048 nt
	global_load_dword v48, v[54:55], off nt
	s_nop 0
	global_load_dword v40, v[40:41], off offset:2048 nt
	s_waitcnt vmcnt(30)
	ds_write2_b32 v1, v2, v39 offset1:66
	s_waitcnt vmcnt(28)
	ds_write2_b32 v1, v58, v59 offset0:132 offset1:198
	s_waitcnt vmcnt(26)
	ds_write2_b32 v32, v60, v61 offset0:8 offset1:74
	s_waitcnt vmcnt(24)
	ds_write2_b32 v32, v62, v63 offset0:140 offset1:206
	s_waitcnt vmcnt(22)
	ds_write2_b32 v33, v64, v65 offset0:16 offset1:82
	s_waitcnt vmcnt(20)
	ds_write2_b32 v33, v66, v67 offset0:148 offset1:214
	s_waitcnt vmcnt(18)
	ds_write2_b32 v34, v68, v69 offset0:24 offset1:90
	s_waitcnt vmcnt(16)
; #define LAS __attribute__((address_space(3)))
; #define LDS_WAIT() asm volatile("s_waitcnt lgkmcnt(0)" ::: "memory")
; __device__ __forceinline__ unsigned pk2(float lo, float hi) { return f2bf(lo) | (f2bf(hi) << 16); }
; __device__ __forceinline__ void tr_item(const float* W, int N, bf16* WT, int dpitch, int koff, int drow0, int k0, int n0, LAS float* scr, int lane) {
;     ...
;     for (int i = 0; i < 32; ++i) tv[i] = W[(size_t)(k0 + 2 * i + (lane >> 5)) * N + n0 + (lane & 31)];
; #pragma unroll
;     for (int i = 0; i < 32; ++i) scr[(2 * i + (lane >> 5)) * 33 + (lane & 31)] = tv[i];
;     LDS_WAIT(); asm volatile("" ::: "memory");
;     const int c = lane & 7;
; #pragma unroll
;     for (int j = 0; j < 4; ++j) { const int n = (lane >> 3) + 8 * j; const LAS float* s = scr + (8 * c) * 33 + n;
;         v4u o; o.x = pk2(s[0 * 33], s[1 * 33]); o.y = pk2(s[2 * 33], s[3 * 33]); o.z = pk2(s[4 * 33], s[5 * 33]); o.w = pk2(s[6 * 33], s[7 * 33]);
;         *(v4u*)(WT + (size_t)(drow0 + n) * dpitch + koff + k0 + 8 * c) = o; }
;     LDS_WAIT(); asm volatile("" ::: "memory");
	ds_write2_b32 v34, v70, v71 offset0:156 offset1:222
	s_waitcnt vmcnt(14)
	ds_write2_b32 v35, v72, v73 offset0:32 offset1:98
	s_waitcnt vmcnt(12)
	ds_write2_b32 v35, v74, v75 offset0:164 offset1:230
	s_waitcnt vmcnt(10)
	ds_write2_b32 v36, v76, v77 offset0:40 offset1:106
	s_waitcnt vmcnt(8)
	ds_write2_b32 v36, v78, v56 offset0:172 offset1:238
	s_waitcnt vmcnt(6)
	ds_write2_b32 v37, v42, v43 offset0:48 offset1:114
	s_waitcnt vmcnt(4)
	ds_write2_b32 v37, v44, v45 offset0:180 offset1:246
	s_waitcnt vmcnt(2)
	ds_write2_b32 v38, v46, v47 offset0:56 offset1:122
	s_waitcnt vmcnt(0)
	ds_write2_b32 v38, v48, v40 offset0:188 offset1:254
	s_waitcnt lgkmcnt(0)
	ds_read2_b32 v[44:45], v28 offset1:8
	ds_read2_b32 v[48:49], v28 offset0:33 offset1:41
	ds_read2_b32 v[50:51], v28 offset0:66 offset1:74
	ds_read2_b32 v[52:53], v28 offset0:99 offset1:107
	ds_read2_b32 v[54:55], v28 offset0:132 offset1:140
	s_waitcnt lgkmcnt(4)
	v_bfe_u32 v2, v44, 16, 1
	v_add3_u32 v2, v44, v2, s14
	s_waitcnt lgkmcnt(3)
	v_bfe_u32 v39, v48, 16, 1
	v_lshrrev_b32_e32 v2, 16, v2
	v_add3_u32 v39, v48, v39, s14
	ds_read2_b32 v[56:57], v28 offset0:165 offset1:173
	v_and_or_b32 v40, v39, s15, v2
	s_waitcnt lgkmcnt(3)
	v_bfe_u32 v2, v50, 16, 1
	v_add3_u32 v2, v50, v2, s14
	s_waitcnt lgkmcnt(2)
	v_bfe_u32 v39, v52, 16, 1
	ds_read2_b32 v[58:59], v28 offset0:198 offset1:206
	v_lshrrev_b32_e32 v2, 16, v2
	v_add3_u32 v39, v52, v39, s14
	ds_read2_b32 v[60:61], v28 offset0:231 offset1:239
	v_and_or_b32 v41, v39, s15, v2
	s_waitcnt lgkmcnt(3)
	v_bfe_u32 v2, v54, 16, 1
	v_add3_u32 v2, v54, v2, s14
	s_waitcnt lgkmcnt(2)
	v_bfe_u32 v39, v56, 16, 1
	v_lshrrev_b32_e32 v2, 16, v2
	v_add3_u32 v39, v56, v39, s14
	v_and_or_b32 v42, v39, s15, v2
	s_waitcnt lgkmcnt(1)
	v_bfe_u32 v2, v58, 16, 1
	v_add3_u32 v2, v58, v2, s14
	s_waitcnt lgkmcnt(0)
	v_bfe_u32 v39, v60, 16, 1
	v_lshrrev_b32_e32 v2, 16, v2
	v_add3_u32 v39, v60, v39, s14
	v_and_or_b32 v43, v39, s15, v2
	v_or_b32_e32 v2, s7, v201
	v_lshl_add_u64 v[46:47], v[10:11], 0, s[4:5]
	v_lshlrev_b32_e32 v2, 11, v2
	v_lshl_add_u64 v[62:63], v[46:47], 0, v[2:3]
	v_bfe_u32 v2, v45, 16, 1
	v_add3_u32 v2, v45, v2, s14
	v_bfe_u32 v39, v49, 16, 1
	v_lshrrev_b32_e32 v2, 16, v2
	v_add3_u32 v39, v49, v39, s14
	global_store_dwordx4 v[62:63], v[40:43], off
	ds_read2_b32 v[44:45], v28 offset0:16 offset1:24
	s_nop 0
	v_and_or_b32 v40, v39, s15, v2
	v_bfe_u32 v2, v51, 16, 1
	v_add3_u32 v2, v51, v2, s14
	v_bfe_u32 v39, v53, 16, 1
	v_lshrrev_b32_e32 v2, 16, v2
	v_add3_u32 v39, v53, v39, s14
	v_and_or_b32 v41, v39, s15, v2
	v_bfe_u32 v2, v55, 16, 1
	v_add3_u32 v2, v55, v2, s14
	v_bfe_u32 v39, v57, 16, 1
	v_lshrrev_b32_e32 v2, 16, v2
	v_add3_u32 v39, v57, v39, s14
	v_and_or_b32 v42, v39, s15, v2
	v_bfe_u32 v2, v59, 16, 1
	v_add3_u32 v2, v59, v2, s14
	v_bfe_u32 v39, v61, 16, 1
	v_lshrrev_b32_e32 v2, 16, v2
	v_add3_u32 v39, v61, v39, s14
	v_and_or_b32 v43, v39, s15, v2
	v_or_b32_e32 v2, s7, v29
	v_lshlrev_b32_e32 v2, 11, v2
	v_lshl_add_u64 v[48:49], v[46:47], 0, v[2:3]
	global_store_dwordx4 v[48:49], v[40:43], off
	ds_read2_b32 v[48:49], v28 offset0:49 offset1:57
	ds_read2_b32 v[50:51], v28 offset0:82 offset1:90
	ds_read2_b32 v[52:53], v28 offset0:115 offset1:123
	s_waitcnt lgkmcnt(3)
	v_bfe_u32 v2, v44, 16, 1
	v_add3_u32 v2, v44, v2, s14
	s_waitcnt lgkmcnt(2)
	v_bfe_u32 v39, v48, 16, 1
	ds_read2_b32 v[54:55], v28 offset0:148 offset1:156
	v_lshrrev_b32_e32 v2, 16, v2
	v_add3_u32 v39, v48, v39, s14
	ds_read2_b32 v[56:57], v28 offset0:181 offset1:189
	v_and_or_b32 v40, v39, s15, v2
	s_waitcnt lgkmcnt(3)
	v_bfe_u32 v2, v50, 16, 1
	v_add3_u32 v2, v50, v2, s14
	s_waitcnt lgkmcnt(2)
	v_bfe_u32 v39, v52, 16, 1
	ds_read2_b32 v[58:59], v28 offset0:214 offset1:222
	v_lshrrev_b32_e32 v2, 16, v2
	v_add3_u32 v39, v52, v39, s14
	ds_read2_b32 v[60:61], v28 offset0:247 offset1:255
	v_and_or_b32 v41, v39, s15, v2
	s_waitcnt lgkmcnt(3)
	v_bfe_u32 v2, v54, 16, 1
	v_add3_u32 v2, v54, v2, s14
	s_waitcnt lgkmcnt(2)
	v_bfe_u32 v39, v56, 16, 1
	v_lshrrev_b32_e32 v2, 16, v2
	v_add3_u32 v39, v56, v39, s14
	v_and_or_b32 v42, v39, s15, v2
	s_waitcnt lgkmcnt(1)
	v_bfe_u32 v2, v58, 16, 1
	v_add3_u32 v2, v58, v2, s14
	s_waitcnt lgkmcnt(0)
	v_bfe_u32 v39, v60, 16, 1
	v_lshrrev_b32_e32 v2, 16, v2
	v_add3_u32 v39, v60, v39, s14
	v_and_or_b32 v43, v39, s15, v2
	v_or_b32_e32 v2, s7, v30
	v_lshlrev_b32_e32 v2, 11, v2
	v_lshl_add_u64 v[62:63], v[46:47], 0, v[2:3]
	v_bfe_u32 v2, v45, 16, 1
	v_add3_u32 v2, v45, v2, s14
	v_bfe_u32 v39, v49, 16, 1
	v_lshrrev_b32_e32 v2, 16, v2
	v_add3_u32 v39, v49, v39, s14
	global_store_dwordx4 v[62:63], v[40:43], off
	s_nop 1
	v_and_or_b32 v40, v39, s15, v2
	v_bfe_u32 v2, v51, 16, 1
	v_add3_u32 v2, v51, v2, s14
	v_bfe_u32 v39, v53, 16, 1
	v_lshrrev_b32_e32 v2, 16, v2
	v_add3_u32 v39, v53, v39, s14
	v_and_or_b32 v41, v39, s15, v2
	v_bfe_u32 v2, v55, 16, 1
	v_add3_u32 v2, v55, v2, s14
	v_bfe_u32 v39, v57, 16, 1
	v_lshrrev_b32_e32 v2, 16, v2
	v_add3_u32 v39, v57, v39, s14
	v_and_or_b32 v42, v39, s15, v2
	v_bfe_u32 v2, v59, 16, 1
	v_add3_u32 v2, v59, v2, s14
	v_bfe_u32 v39, v61, 16, 1
	v_lshrrev_b32_e32 v2, 16, v2
	v_add3_u32 v39, v61, v39, s14
	v_and_or_b32 v43, v39, s15, v2
	v_or_b32_e32 v2, s7, v31
	v_lshlrev_b32_e32 v2, 11, v2
	v_lshl_add_u64 v[44:45], v[46:47], 0, v[2:3]
	global_store_dwordx4 v[44:45], v[40:43], off
	s_waitcnt lgkmcnt(0)

; #define LAS __attribute__((address_space(3)))
; __device__ __forceinline__ void tr_item(const float* W, int N, bf16* WT, int dpitch, int koff, int drow0, int k0, int n0, LAS float* scr, int lane) {
;     float tv[32];
; #pragma unroll
;     for (int i = 0; i < 32; ++i) tv[i] = W[(size_t)(k0 + 2 * i + (lane >> 5)) * N + n0 + (lane & 31)];
; #pragma unroll
;     for (int i = 0; i < 32; ++i) scr[(2 * i + (lane >> 5)) * 33 + (lane & 31)] = tv[i];
; __global__ void __launch_bounds__(512, 2) fwd_mega(Args a) {
;     ...
;             if (it < 512) { const int kb = it / 32, nb = it % 32; tr_item(INF(14) + (size_t)LL * D * D, D, WSP(WS_WO2), 1024, 0, 32 * nb, 64 * kb, 32 * nb, scr, lane); continue; } it -= 512;
.LBB0_33:
	s_andn2_b64 vcc, exec, s[6:7]
	s_cbranch_vccnz .LBB0_35
	s_and_b32 s4, s12, 0x3fc0
	s_add_i32 s6, s4, 0xffffe300
	s_and_b32 s8, s10, 0x3e0
	v_or_b32_e32 v2, s6, v200
	s_lshl_b32 s4, s8, 2
	v_or_b32_e32 v44, 2, v2
	v_mov_b32_e32 v45, v3
	v_or_b32_e32 v46, 4, v2
	v_mov_b32_e32 v47, v3
	v_or_b32_e32 v48, 6, v2
	v_mov_b32_e32 v49, v3
	v_or_b32_e32 v50, 8, v2
	v_mov_b32_e32 v51, v3
	v_or_b32_e32 v52, 10, v2
	v_mov_b32_e32 v53, v3
	v_or_b32_e32 v54, 12, v2
	v_mov_b32_e32 v55, v3
	v_lshl_add_u64 v[40:41], v[14:15], 0, s[4:5]
	v_lshlrev_b64 v[42:43], 12, v[2:3]
	v_lshlrev_b64 v[44:45], 12, v[44:45]
	v_lshlrev_b64 v[46:47], 12, v[46:47]
	v_lshlrev_b64 v[48:49], 12, v[48:49]
	v_lshlrev_b64 v[50:51], 12, v[50:51]
	v_lshlrev_b64 v[52:53], 12, v[52:53]
	v_lshlrev_b64 v[54:55], 12, v[54:55]
	v_or_b32_e32 v56, 14, v2
	v_mov_b32_e32 v57, v3
	v_lshl_add_u64 v[42:43], v[40:41], 0, v[42:43]
	v_lshl_add_u64 v[44:45], v[40:41], 0, v[44:45]
	v_lshl_add_u64 v[46:47], v[40:41], 0, v[46:47]
	v_lshl_add_u64 v[48:49], v[40:41], 0, v[48:49]
	v_lshl_add_u64 v[50:51], v[40:41], 0, v[50:51]
	v_lshl_add_u64 v[52:53], v[40:41], 0, v[52:53]
	v_lshl_add_u64 v[54:55], v[40:41], 0, v[54:55]
	v_lshlrev_b64 v[56:57], 12, v[56:57]
	v_lshl_add_u64 v[56:57], v[40:41], 0, v[56:57]
	global_load_dword v39, v[42:43], off nt
	global_load_dword v58, v[44:45], off nt
	global_load_dword v59, v[46:47], off nt
	global_load_dword v60, v[48:49], off nt
	global_load_dword v61, v[50:51], off nt
	global_load_dword v62, v[52:53], off nt
	global_load_dword v63, v[54:55], off nt
	global_load_dword v64, v[56:57], off nt
	v_or_b32_e32 v42, 16, v2
	v_mov_b32_e32 v43, v3
	v_or_b32_e32 v44, 18, v2
	v_mov_b32_e32 v45, v3
	v_or_b32_e32 v46, 20, v2
	v_mov_b32_e32 v47, v3
	v_or_b32_e32 v48, 22, v2
	v_mov_b32_e32 v49, v3
	v_or_b32_e32 v50, 24, v2
	v_mov_b32_e32 v51, v3
	v_or_b32_e32 v52, 26, v2
	v_mov_b32_e32 v53, v3
	v_or_b32_e32 v54, 28, v2
	v_mov_b32_e32 v55, v3
	v_lshlrev_b64 v[42:43], 12, v[42:43]
	v_lshlrev_b64 v[44:45], 12, v[44:45]
	v_lshlrev_b64 v[46:47], 12, v[46:47]
	v_lshlrev_b64 v[48:49], 12, v[48:49]
	v_lshlrev_b64 v[50:51], 12, v[50:51]
	v_lshlrev_b64 v[52:53], 12, v[52:53]
	v_lshlrev_b64 v[54:55], 12, v[54:55]
	v_or_b32_e32 v56, 30, v2
	v_mov_b32_e32 v57, v3
	v_lshl_add_u64 v[42:43], v[40:41], 0, v[42:43]
	v_lshl_add_u64 v[44:45], v[40:41], 0, v[44:45]
	v_lshl_add_u64 v[46:47], v[40:41], 0, v[46:47]
	v_lshl_add_u64 v[48:49], v[40:41], 0, v[48:49]
	v_lshl_add_u64 v[50:51], v[40:41], 0, v[50:51]
	v_lshl_add_u64 v[52:53], v[40:41], 0, v[52:53]
	v_lshl_add_u64 v[54:55], v[40:41], 0, v[54:55]
	v_lshlrev_b64 v[56:57], 12, v[56:57]
	v_lshl_add_u64 v[56:57], v[40:41], 0, v[56:57]
	global_load_dword v65, v[42:43], off nt
	global_load_dword v66, v[44:45], off nt
	global_load_dword v67, v[46:47], off nt
	global_load_dword v68, v[48:49], off nt
	global_load_dword v69, v[50:51], off nt
	global_load_dword v70, v[52:53], off nt
	global_load_dword v71, v[54:55], off nt
	global_load_dword v72, v[56:57], off nt
	v_or_b32_e32 v42, 32, v2
	v_mov_b32_e32 v43, v3
	v_or_b32_e32 v44, 34, v2
	v_mov_b32_e32 v45, v3
	v_or_b32_e32 v46, 36, v2
	v_mov_b32_e32 v47, v3
	v_or_b32_e32 v48, 38, v2
	v_mov_b32_e32 v49, v3
	v_or_b32_e32 v50, 40, v2
	v_mov_b32_e32 v51, v3
	v_or_b32_e32 v52, 42, v2
	v_mov_b32_e32 v53, v3
	v_or_b32_e32 v54, 44, v2
	v_mov_b32_e32 v55, v3
	v_lshlrev_b64 v[42:43], 12, v[42:43]
	v_lshlrev_b64 v[44:45], 12, v[44:45]
	v_lshlrev_b64 v[46:47], 12, v[46:47]
	v_lshlrev_b64 v[48:49], 12, v[48:49]
	v_lshlrev_b64 v[50:51], 12, v[50:51]
	v_lshlrev_b64 v[52:53], 12, v[52:53]
	v_lshlrev_b64 v[54:55], 12, v[54:55]
	v_or_b32_e32 v56, 46, v2
	v_mov_b32_e32 v57, v3
	v_lshl_add_u64 v[42:43], v[40:41], 0, v[42:43]
	v_lshl_add_u64 v[44:45], v[40:41], 0, v[44:45]
	v_lshl_add_u64 v[46:47], v[40:41], 0, v[46:47]
	v_lshl_add_u64 v[48:49], v[40:41], 0, v[48:49]
	v_lshl_add_u64 v[50:51], v[40:41], 0, v[50:51]
	v_lshl_add_u64 v[52:53], v[40:41], 0, v[52:53]
	v_lshl_add_u64 v[54:55], v[40:41], 0, v[54:55]
	v_lshlrev_b64 v[56:57], 12, v[56:57]
	v_lshl_add_u64 v[56:57], v[40:41], 0, v[56:57]
	global_load_dword v73, v[42:43], off nt
	global_load_dword v74, v[44:45], off nt
	global_load_dword v75, v[46:47], off nt
	global_load_dword v76, v[48:49], off nt
	global_load_dword v77, v[50:51], off nt
	global_load_dword v78, v[52:53], off nt
	global_load_dword v79, v[54:55], off nt
	global_load_dword v80, v[56:57], off nt
	v_or_b32_e32 v42, 48, v2
	v_mov_b32_e32 v43, v3
	v_or_b32_e32 v44, 50, v2
	v_mov_b32_e32 v45, v3
	v_or_b32_e32 v46, 52, v2
	v_mov_b32_e32 v47, v3
	v_or_b32_e32 v48, 54, v2
	v_mov_b32_e32 v49, v3
	v_or_b32_e32 v50, 56, v2
	v_mov_b32_e32 v51, v3
	v_or_b32_e32 v52, 58, v2
	v_mov_b32_e32 v53, v3
	v_or_b32_e32 v54, 60, v2
	v_mov_b32_e32 v55, v3
	v_or_b32_e32 v2, 62, v2
	v_lshlrev_b64 v[42:43], 12, v[42:43]
	v_lshlrev_b64 v[44:45], 12, v[44:45]
	v_lshlrev_b64 v[46:47], 12, v[46:47]
	v_lshlrev_b64 v[48:49], 12, v[48:49]
	v_lshlrev_b64 v[50:51], 12, v[50:51]
	v_lshlrev_b64 v[52:53], 12, v[52:53]
	v_lshlrev_b64 v[54:55], 12, v[54:55]
	v_lshlrev_b64 v[56:57], 12, v[2:3]
	v_lshl_add_u64 v[42:43], v[40:41], 0, v[42:43]
	v_lshl_add_u64 v[44:45], v[40:41], 0, v[44:45]
	v_lshl_add_u64 v[46:47], v[40:41], 0, v[46:47]
	v_lshl_add_u64 v[48:49], v[40:41], 0, v[48:49]
	v_lshl_add_u64 v[50:51], v[40:41], 0, v[50:51]
	v_lshl_add_u64 v[52:53], v[40:41], 0, v[52:53]
	v_lshl_add_u64 v[54:55], v[40:41], 0, v[54:55]
	v_lshl_add_u64 v[40:41], v[40:41], 0, v[56:57]
	global_load_dword v2, v[42:43], off nt
	s_nop 0
	global_load_dword v42, v[44:45], off nt
	global_load_dword v43, v[46:47], off nt
	s_nop 0
	global_load_dword v44, v[48:49], off nt
	global_load_dword v45, v[50:51], off nt
	global_load_dword v46, v[52:53], off nt
	global_load_dword v47, v[54:55], off nt
	s_nop 0
	global_load_dword v40, v[40:41], off nt
	s_waitcnt vmcnt(30)
; #define LAS __attribute__((address_space(3)))
; #define LDS_WAIT() asm volatile("s_waitcnt lgkmcnt(0)" ::: "memory")
; __device__ __forceinline__ unsigned pk2(float lo, float hi) { return f2bf(lo) | (f2bf(hi) << 16); }
; __device__ __forceinline__ void tr_item(const float* W, int N, bf16* WT, int dpitch, int koff, int drow0, int k0, int n0, LAS float* scr, int lane) {
;     ...
;     for (int i = 0; i < 32; ++i) tv[i] = W[(size_t)(k0 + 2 * i + (lane >> 5)) * N + n0 + (lane & 31)];
; #pragma unroll
;     for (int i = 0; i < 32; ++i) scr[(2 * i + (lane >> 5)) * 33 + (lane & 31)] = tv[i];
;     LDS_WAIT(); asm volatile("" ::: "memory");
;     const int c = lane & 7;
; #pragma unroll
;     for (int j = 0; j < 4; ++j) { const int n = (lane >> 3) + 8 * j; const LAS float* s = scr + (8 * c) * 33 + n;
;         v4u o; o.x = pk2(s[0 * 33], s[1 * 33]); o.y = pk2(s[2 * 33], s[3 * 33]); o.z = pk2(s[4 * 33], s[5 * 33]); o.w = pk2(s[6 * 33], s[7 * 33]);
;         *(v4u*)(WT + (size_t)(drow0 + n) * dpitch + koff + k0 + 8 * c) = o; }
;     LDS_WAIT(); asm volatile("" ::: "memory");
	ds_write2_b32 v1, v39, v58 offset1:66
	s_waitcnt vmcnt(28)
	ds_write2_b32 v1, v59, v60 offset0:132 offset1:198
	s_waitcnt vmcnt(26)
	ds_write2_b32 v32, v61, v62 offset0:8 offset1:74
	s_waitcnt vmcnt(24)
	ds_write2_b32 v32, v63, v64 offset0:140 offset1:206
	s_waitcnt vmcnt(22)
	ds_write2_b32 v33, v65, v66 offset0:16 offset1:82
	s_waitcnt vmcnt(20)
	ds_write2_b32 v33, v67, v68 offset0:148 offset1:214
	s_waitcnt vmcnt(18)
	ds_write2_b32 v34, v69, v70 offset0:24 offset1:90
	s_waitcnt vmcnt(16)
	ds_write2_b32 v34, v71, v72 offset0:156 offset1:222
	s_waitcnt vmcnt(14)
	ds_write2_b32 v35, v73, v74 offset0:32 offset1:98
	s_waitcnt vmcnt(12)
	ds_write2_b32 v35, v75, v76 offset0:164 offset1:230
	s_waitcnt vmcnt(10)
	ds_write2_b32 v36, v77, v78 offset0:40 offset1:106
	s_waitcnt vmcnt(8)
	ds_write2_b32 v36, v79, v80 offset0:172 offset1:238
	s_waitcnt vmcnt(6)
	ds_write2_b32 v37, v2, v42 offset0:48 offset1:114
	s_waitcnt vmcnt(4)
	ds_write2_b32 v37, v43, v44 offset0:180 offset1:246
	s_waitcnt vmcnt(2)
	ds_write2_b32 v38, v45, v46 offset0:56 offset1:122
	s_waitcnt vmcnt(0)
	ds_write2_b32 v38, v47, v40 offset0:188 offset1:254
	s_waitcnt lgkmcnt(0)
	ds_read2_b32 v[44:45], v28 offset1:8
	ds_read2_b32 v[48:49], v28 offset0:33 offset1:41
	ds_read2_b32 v[50:51], v28 offset0:66 offset1:74
	ds_read2_b32 v[52:53], v28 offset0:99 offset1:107
	ds_read2_b32 v[54:55], v28 offset0:132 offset1:140
	s_waitcnt lgkmcnt(4)
	v_bfe_u32 v2, v44, 16, 1
	v_add3_u32 v2, v44, v2, s14
	s_waitcnt lgkmcnt(3)
	v_bfe_u32 v39, v48, 16, 1
	v_lshrrev_b32_e32 v2, 16, v2
	v_add3_u32 v39, v48, v39, s14
	ds_read2_b32 v[56:57], v28 offset0:165 offset1:173
	v_and_or_b32 v40, v39, s15, v2
	s_waitcnt lgkmcnt(3)
	v_bfe_u32 v2, v50, 16, 1
	v_add3_u32 v2, v50, v2, s14
	s_waitcnt lgkmcnt(2)
	v_bfe_u32 v39, v52, 16, 1
	ds_read2_b32 v[58:59], v28 offset0:198 offset1:206
	v_lshrrev_b32_e32 v2, 16, v2
	v_add3_u32 v39, v52, v39, s14
	ds_read2_b32 v[60:61], v28 offset0:231 offset1:239
	v_and_or_b32 v41, v39, s15, v2
	s_waitcnt lgkmcnt(3)
	v_bfe_u32 v2, v54, 16, 1
	v_add3_u32 v2, v54, v2, s14
	s_waitcnt lgkmcnt(2)
	v_bfe_u32 v39, v56, 16, 1
	v_lshrrev_b32_e32 v2, 16, v2
	v_add3_u32 v39, v56, v39, s14
	v_and_or_b32 v42, v39, s15, v2
	s_waitcnt lgkmcnt(1)
	v_bfe_u32 v2, v58, 16, 1
	v_add3_u32 v2, v58, v2, s14
	s_waitcnt lgkmcnt(0)
	v_bfe_u32 v39, v60, 16, 1
	v_lshrrev_b32_e32 v2, 16, v2
	v_add3_u32 v39, v60, v39, s14
	s_mov_b32 s7, s5
	v_and_or_b32 v43, v39, s15, v2
	v_or_b32_e32 v2, s8, v201
	v_lshl_add_u64 v[46:47], s[6:7], 1, v[16:17]
	v_lshlrev_b32_e32 v2, 11, v2
	v_lshl_add_u64 v[62:63], v[46:47], 0, v[2:3]
	v_bfe_u32 v2, v45, 16, 1
	v_add3_u32 v2, v45, v2, s14
	v_bfe_u32 v39, v49, 16, 1
	v_lshrrev_b32_e32 v2, 16, v2
	v_add3_u32 v39, v49, v39, s14
	global_store_dwordx4 v[62:63], v[40:43], off
	ds_read2_b32 v[44:45], v28 offset0:16 offset1:24
	s_nop 0
	v_and_or_b32 v40, v39, s15, v2
	v_bfe_u32 v2, v51, 16, 1
	v_add3_u32 v2, v51, v2, s14
	v_bfe_u32 v39, v53, 16, 1
	v_lshrrev_b32_e32 v2, 16, v2
	v_add3_u32 v39, v53, v39, s14
	v_and_or_b32 v41, v39, s15, v2
	v_bfe_u32 v2, v55, 16, 1
	v_add3_u32 v2, v55, v2, s14
	v_bfe_u32 v39, v57, 16, 1
	v_lshrrev_b32_e32 v2, 16, v2
	v_add3_u32 v39, v57, v39, s14
	v_and_or_b32 v42, v39, s15, v2
	v_bfe_u32 v2, v59, 16, 1
	v_add3_u32 v2, v59, v2, s14
	v_bfe_u32 v39, v61, 16, 1
	v_lshrrev_b32_e32 v2, 16, v2
	v_add3_u32 v39, v61, v39, s14
	v_and_or_b32 v43, v39, s15, v2
	v_or_b32_e32 v2, s8, v29
	v_lshlrev_b32_e32 v2, 11, v2
	v_lshl_add_u64 v[48:49], v[46:47], 0, v[2:3]
	global_store_dwordx4 v[48:49], v[40:43], off
	ds_read2_b32 v[48:49], v28 offset0:49 offset1:57
	ds_read2_b32 v[50:51], v28 offset0:82 offset1:90
	ds_read2_b32 v[52:53], v28 offset0:115 offset1:123
	s_waitcnt lgkmcnt(3)
	v_bfe_u32 v2, v44, 16, 1
	v_add3_u32 v2, v44, v2, s14
	s_waitcnt lgkmcnt(2)
	v_bfe_u32 v39, v48, 16, 1
	ds_read2_b32 v[54:55], v28 offset0:148 offset1:156
	v_lshrrev_b32_e32 v2, 16, v2
	v_add3_u32 v39, v48, v39, s14
	ds_read2_b32 v[56:57], v28 offset0:181 offset1:189
	v_and_or_b32 v40, v39, s15, v2
	s_waitcnt lgkmcnt(3)
	v_bfe_u32 v2, v50, 16, 1
	v_add3_u32 v2, v50, v2, s14
	s_waitcnt lgkmcnt(2)
	v_bfe_u32 v39, v52, 16, 1
	ds_read2_b32 v[58:59], v28 offset0:214 offset1:222
	v_lshrrev_b32_e32 v2, 16, v2
	v_add3_u32 v39, v52, v39, s14
	ds_read2_b32 v[60:61], v28 offset0:247 offset1:255
	v_and_or_b32 v41, v39, s15, v2
	s_waitcnt lgkmcnt(3)
	v_bfe_u32 v2, v54, 16, 1
	v_add3_u32 v2, v54, v2, s14
	s_waitcnt lgkmcnt(2)
	v_bfe_u32 v39, v56, 16, 1
	v_lshrrev_b32_e32 v2, 16, v2
	v_add3_u32 v39, v56, v39, s14
	v_and_or_b32 v42, v39, s15, v2
	s_waitcnt lgkmcnt(1)
	v_bfe_u32 v2, v58, 16, 1
	v_add3_u32 v2, v58, v2, s14
	s_waitcnt lgkmcnt(0)
	v_bfe_u32 v39, v60, 16, 1
	v_lshrrev_b32_e32 v2, 16, v2
	v_add3_u32 v39, v60, v39, s14
	v_and_or_b32 v43, v39, s15, v2
	v_or_b32_e32 v2, s8, v30
	v_lshlrev_b32_e32 v2, 11, v2
	v_lshl_add_u64 v[62:63], v[46:47], 0, v[2:3]
	v_bfe_u32 v2, v45, 16, 1
	v_add3_u32 v2, v45, v2, s14
	v_bfe_u32 v39, v49, 16, 1
	v_lshrrev_b32_e32 v2, 16, v2
	v_add3_u32 v39, v49, v39, s14
	global_store_dwordx4 v[62:63], v[40:43], off
	s_nop 1
	v_and_or_b32 v40, v39, s15, v2
	v_bfe_u32 v2, v51, 16, 1
	v_add3_u32 v2, v51, v2, s14
	v_bfe_u32 v39, v53, 16, 1
	v_lshrrev_b32_e32 v2, 16, v2
	v_add3_u32 v39, v53, v39, s14
	v_and_or_b32 v41, v39, s15, v2
	v_bfe_u32 v2, v55, 16, 1
	v_add3_u32 v2, v55, v2, s14
	v_bfe_u32 v39, v57, 16, 1
	v_lshrrev_b32_e32 v2, 16, v2
	v_add3_u32 v39, v57, v39, s14
	v_and_or_b32 v42, v39, s15, v2
	v_bfe_u32 v2, v59, 16, 1
	v_add3_u32 v2, v59, v2, s14
	v_bfe_u32 v39, v61, 16, 1
	v_lshrrev_b32_e32 v2, 16, v2
	v_add3_u32 v39, v61, v39, s14
	v_and_or_b32 v43, v39, s15, v2
	v_or_b32_e32 v2, s8, v31
	v_lshlrev_b32_e32 v2, 11, v2
	v_lshl_add_u64 v[44:45], v[46:47], 0, v[2:3]
	global_store_dwordx4 v[44:45], v[40:43], off
	s_waitcnt lgkmcnt(0)

; #define LAS __attribute__((address_space(3)))
; __device__ __forceinline__ void tr_item(const float* W, int N, bf16* WT, int dpitch, int koff, int drow0, int k0, int n0, LAS float* scr, int lane) {
;     float tv[32];
; #pragma unroll
;     for (int i = 0; i < 32; ++i) tv[i] = W[(size_t)(k0 + 2 * i + (lane >> 5)) * N + n0 + (lane & 31)];
; #pragma unroll
;     for (int i = 0; i < 32; ++i) scr[(2 * i + (lane >> 5)) * 33 + (lane & 31)] = tv[i];
; __global__ void __launch_bounds__(512, 2) fwd_mega(Args a) {
;     ...
;             if (it < 512) { const int kb = it / 32, nb = it % 32; tr_item(INF(12) + (size_t)LL * D * D, D, WSP(WS_PAB), 1024, 0, 1024 + 32 * nb, 64 * kb, 32 * nb, scr, lane); continue; } it -= 512;
.LBB0_36:
	s_andn2_b64 vcc, exec, s[6:7]
	s_cbranch_vccnz .LBB0_38
	s_and_b32 s4, s12, 0x1fc0
	s_add_i32 s6, s4, 0xffffe700
	s_and_b32 s7, s10, 0x3e0
	v_or_b32_e32 v2, s6, v200
	s_lshl_b32 s4, s7, 2
	v_or_b32_e32 v44, 2, v2
	v_mov_b32_e32 v45, v3
	v_or_b32_e32 v46, 4, v2
	v_mov_b32_e32 v47, v3
	v_or_b32_e32 v48, 6, v2
	v_mov_b32_e32 v49, v3
	v_or_b32_e32 v50, 8, v2
	v_mov_b32_e32 v51, v3
	v_or_b32_e32 v52, 10, v2
	v_mov_b32_e32 v53, v3
	v_or_b32_e32 v54, 12, v2
	v_mov_b32_e32 v55, v3
	v_lshl_add_u64 v[40:41], v[18:19], 0, s[4:5]
	v_lshlrev_b64 v[42:43], 12, v[2:3]
	v_lshlrev_b64 v[44:45], 12, v[44:45]
	v_lshlrev_b64 v[46:47], 12, v[46:47]
	v_lshlrev_b64 v[48:49], 12, v[48:49]
	v_lshlrev_b64 v[50:51], 12, v[50:51]
	v_lshlrev_b64 v[52:53], 12, v[52:53]
	v_lshlrev_b64 v[54:55], 12, v[54:55]
	v_or_b32_e32 v56, 14, v2
	v_mov_b32_e32 v57, v3
	v_lshl_add_u64 v[42:43], v[40:41], 0, v[42:43]
	v_lshl_add_u64 v[44:45], v[40:41], 0, v[44:45]
	v_lshl_add_u64 v[46:47], v[40:41], 0, v[46:47]
	v_lshl_add_u64 v[48:49], v[40:41], 0, v[48:49]
	v_lshl_add_u64 v[50:51], v[40:41], 0, v[50:51]
	v_lshl_add_u64 v[52:53], v[40:41], 0, v[52:53]
	v_lshl_add_u64 v[54:55], v[40:41], 0, v[54:55]
	v_lshlrev_b64 v[56:57], 12, v[56:57]
	v_lshl_add_u64 v[56:57], v[40:41], 0, v[56:57]
	global_load_dword v39, v[42:43], off nt
	global_load_dword v58, v[44:45], off nt
	global_load_dword v59, v[46:47], off nt
	global_load_dword v60, v[48:49], off nt
	global_load_dword v61, v[50:51], off nt
	global_load_dword v62, v[52:53], off nt
	global_load_dword v63, v[54:55], off nt
	global_load_dword v64, v[56:57], off nt
	v_or_b32_e32 v42, 16, v2
	v_mov_b32_e32 v43, v3
	v_or_b32_e32 v44, 18, v2
	v_mov_b32_e32 v45, v3
	v_or_b32_e32 v46, 20, v2
	v_mov_b32_e32 v47, v3
	v_or_b32_e32 v48, 22, v2
	v_mov_b32_e32 v49, v3
	v_or_b32_e32 v50, 24, v2
	v_mov_b32_e32 v51, v3
	v_or_b32_e32 v52, 26, v2
	v_mov_b32_e32 v53, v3
	v_or_b32_e32 v54, 28, v2
	v_mov_b32_e32 v55, v3
	v_lshlrev_b64 v[42:43], 12, v[42:43]
	v_lshlrev_b64 v[44:45], 12, v[44:45]
	v_lshlrev_b64 v[46:47], 12, v[46:47]
	v_lshlrev_b64 v[48:49], 12, v[48:49]
	v_lshlrev_b64 v[50:51], 12, v[50:51]
	v_lshlrev_b64 v[52:53], 12, v[52:53]
	v_lshlrev_b64 v[54:55], 12, v[54:55]
	v_or_b32_e32 v56, 30, v2
	v_mov_b32_e32 v57, v3
	v_lshl_add_u64 v[42:43], v[40:41], 0, v[42:43]
	v_lshl_add_u64 v[44:45], v[40:41], 0, v[44:45]
	v_lshl_add_u64 v[46:47], v[40:41], 0, v[46:47]
	v_lshl_add_u64 v[48:49], v[40:41], 0, v[48:49]
	v_lshl_add_u64 v[50:51], v[40:41], 0, v[50:51]
	v_lshl_add_u64 v[52:53], v[40:41], 0, v[52:53]
	v_lshl_add_u64 v[54:55], v[40:41], 0, v[54:55]
	v_lshlrev_b64 v[56:57], 12, v[56:57]
	v_lshl_add_u64 v[56:57], v[40:41], 0, v[56:57]
	global_load_dword v65, v[42:43], off nt
	global_load_dword v66, v[44:45], off nt
	global_load_dword v67, v[46:47], off nt
	global_load_dword v68, v[48:49], off nt
	global_load_dword v69, v[50:51], off nt
	global_load_dword v70, v[52:53], off nt
	global_load_dword v71, v[54:55], off nt
	global_load_dword v72, v[56:57], off nt
	v_or_b32_e32 v42, 32, v2
	v_mov_b32_e32 v43, v3
	v_or_b32_e32 v44, 34, v2
	v_mov_b32_e32 v45, v3
	v_or_b32_e32 v46, 36, v2
	v_mov_b32_e32 v47, v3
	v_or_b32_e32 v48, 38, v2
	v_mov_b32_e32 v49, v3
	v_or_b32_e32 v50, 40, v2
	v_mov_b32_e32 v51, v3
	v_or_b32_e32 v52, 42, v2
	v_mov_b32_e32 v53, v3
	v_or_b32_e32 v54, 44, v2
	v_mov_b32_e32 v55, v3
	v_lshlrev_b64 v[42:43], 12, v[42:43]
	v_lshlrev_b64 v[44:45], 12, v[44:45]
	v_lshlrev_b64 v[46:47], 12, v[46:47]
	v_lshlrev_b64 v[48:49], 12, v[48:49]
	v_lshlrev_b64 v[50:51], 12, v[50:51]
	v_lshlrev_b64 v[52:53], 12, v[52:53]
	v_lshlrev_b64 v[54:55], 12, v[54:55]
	v_or_b32_e32 v56, 46, v2
	v_mov_b32_e32 v57, v3
	v_lshl_add_u64 v[42:43], v[40:41], 0, v[42:43]
	v_lshl_add_u64 v[44:45], v[40:41], 0, v[44:45]
	v_lshl_add_u64 v[46:47], v[40:41], 0, v[46:47]
	v_lshl_add_u64 v[48:49], v[40:41], 0, v[48:49]
	v_lshl_add_u64 v[50:51], v[40:41], 0, v[50:51]
	v_lshl_add_u64 v[52:53], v[40:41], 0, v[52:53]
	v_lshl_add_u64 v[54:55], v[40:41], 0, v[54:55]
	v_lshlrev_b64 v[56:57], 12, v[56:57]
	v_lshl_add_u64 v[56:57], v[40:41], 0, v[56:57]
	global_load_dword v73, v[42:43], off nt
	global_load_dword v74, v[44:45], off nt
	global_load_dword v75, v[46:47], off nt
	global_load_dword v76, v[48:49], off nt
	global_load_dword v77, v[50:51], off nt
	global_load_dword v78, v[52:53], off nt
	global_load_dword v79, v[54:55], off nt
	global_load_dword v80, v[56:57], off nt
	v_or_b32_e32 v42, 48, v2
	v_mov_b32_e32 v43, v3
	v_or_b32_e32 v44, 50, v2
	v_mov_b32_e32 v45, v3
	v_or_b32_e32 v46, 52, v2
	v_mov_b32_e32 v47, v3
	v_or_b32_e32 v48, 54, v2
	v_mov_b32_e32 v49, v3
	v_or_b32_e32 v50, 56, v2
	v_mov_b32_e32 v51, v3
	v_or_b32_e32 v52, 58, v2
	v_mov_b32_e32 v53, v3
	v_or_b32_e32 v54, 60, v2
	v_mov_b32_e32 v55, v3
	v_or_b32_e32 v2, 62, v2
	v_lshlrev_b64 v[42:43], 12, v[42:43]
	v_lshlrev_b64 v[44:45], 12, v[44:45]
	v_lshlrev_b64 v[46:47], 12, v[46:47]
	v_lshlrev_b64 v[48:49], 12, v[48:49]
	v_lshlrev_b64 v[50:51], 12, v[50:51]
	v_lshlrev_b64 v[52:53], 12, v[52:53]
	v_lshlrev_b64 v[54:55], 12, v[54:55]
	v_lshlrev_b64 v[56:57], 12, v[2:3]
	v_lshl_add_u64 v[42:43], v[40:41], 0, v[42:43]
	v_lshl_add_u64 v[44:45], v[40:41], 0, v[44:45]
	v_lshl_add_u64 v[46:47], v[40:41], 0, v[46:47]
	v_lshl_add_u64 v[48:49], v[40:41], 0, v[48:49]
	v_lshl_add_u64 v[50:51], v[40:41], 0, v[50:51]
	v_lshl_add_u64 v[52:53], v[40:41], 0, v[52:53]
	v_lshl_add_u64 v[54:55], v[40:41], 0, v[54:55]
	v_lshl_add_u64 v[40:41], v[40:41], 0, v[56:57]
	global_load_dword v2, v[42:43], off nt
	s_nop 0
	global_load_dword v42, v[44:45], off nt
	global_load_dword v43, v[46:47], off nt
	s_nop 0
	global_load_dword v44, v[48:49], off nt
	global_load_dword v45, v[50:51], off nt
	global_load_dword v46, v[52:53], off nt
	global_load_dword v47, v[54:55], off nt
	s_nop 0
	global_load_dword v40, v[40:41], off nt
	s_waitcnt vmcnt(30)
; #define LAS __attribute__((address_space(3)))
; #define LDS_WAIT() asm volatile("s_waitcnt lgkmcnt(0)" ::: "memory")
; __device__ __forceinline__ unsigned pk2(float lo, float hi) { return f2bf(lo) | (f2bf(hi) << 16); }
; __device__ __forceinline__ void tr_item(const float* W, int N, bf16* WT, int dpitch, int koff, int drow0, int k0, int n0, LAS float* scr, int lane) {
;     ...
;     for (int i = 0; i < 32; ++i) scr[(2 * i + (lane >> 5)) * 33 + (lane & 31)] = tv[i];
;     LDS_WAIT(); asm volatile("" ::: "memory");
;     const int c = lane & 7;
; #pragma unroll
;     for (int j = 0; j < 4; ++j) { const int n = (lane >> 3) + 8 * j; const LAS float* s = scr + (8 * c) * 33 + n;
;         v4u o; o.x = pk2(s[0 * 33], s[1 * 33]); o.y = pk2(s[2 * 33], s[3 * 33]); o.z = pk2(s[4 * 33], s[5 * 33]); o.w = pk2(s[6 * 33], s[7 * 33]);
;         *(v4u*)(WT + (size_t)(drow0 + n) * dpitch + koff + k0 + 8 * c) = o; }
;     LDS_WAIT(); asm volatile("" ::: "memory");
; }
	ds_write2_b32 v1, v39, v58 offset1:66
	s_waitcnt vmcnt(28)
	ds_write2_b32 v1, v59, v60 offset0:132 offset1:198
	s_waitcnt vmcnt(26)
	ds_write2_b32 v32, v61, v62 offset0:8 offset1:74
	s_waitcnt vmcnt(24)
	ds_write2_b32 v32, v63, v64 offset0:140 offset1:206
	s_waitcnt vmcnt(22)
	ds_write2_b32 v33, v65, v66 offset0:16 offset1:82
	s_waitcnt vmcnt(20)
	ds_write2_b32 v33, v67, v68 offset0:148 offset1:214
	s_waitcnt vmcnt(18)
	ds_write2_b32 v34, v69, v70 offset0:24 offset1:90
	s_waitcnt vmcnt(16)
	ds_write2_b32 v34, v71, v72 offset0:156 offset1:222
	s_waitcnt vmcnt(14)
	ds_write2_b32 v35, v73, v74 offset0:32 offset1:98
	s_waitcnt vmcnt(12)
	ds_write2_b32 v35, v75, v76 offset0:164 offset1:230
	s_waitcnt vmcnt(10)
	ds_write2_b32 v36, v77, v78 offset0:40 offset1:106
	s_waitcnt vmcnt(8)
	ds_write2_b32 v36, v79, v80 offset0:172 offset1:238
	s_waitcnt vmcnt(6)
	ds_write2_b32 v37, v2, v42 offset0:48 offset1:114
	s_waitcnt vmcnt(4)
	ds_write2_b32 v37, v43, v44 offset0:180 offset1:246
	s_waitcnt vmcnt(2)
	ds_write2_b32 v38, v45, v46 offset0:56 offset1:122
	s_waitcnt vmcnt(0)
	ds_write2_b32 v38, v47, v40 offset0:188 offset1:254
	s_waitcnt lgkmcnt(0)
	ds_read2_b32 v[44:45], v28 offset1:8
	ds_read2_b32 v[48:49], v28 offset0:33 offset1:41
	ds_read2_b32 v[50:51], v28 offset0:66 offset1:74
	ds_read2_b32 v[52:53], v28 offset0:99 offset1:107
	ds_read2_b32 v[54:55], v28 offset0:132 offset1:140
	s_waitcnt lgkmcnt(4)
	v_bfe_u32 v2, v44, 16, 1
	v_add3_u32 v2, v44, v2, s14
	s_waitcnt lgkmcnt(3)
	v_bfe_u32 v39, v48, 16, 1
	v_lshrrev_b32_e32 v2, 16, v2
	v_add3_u32 v39, v48, v39, s14
	ds_read2_b32 v[56:57], v28 offset0:165 offset1:173
	v_and_or_b32 v40, v39, s15, v2
	s_waitcnt lgkmcnt(3)
	v_bfe_u32 v2, v50, 16, 1
	v_add3_u32 v2, v50, v2, s14
	s_waitcnt lgkmcnt(2)
	v_bfe_u32 v39, v52, 16, 1
	ds_read2_b32 v[58:59], v28 offset0:198 offset1:206
	v_lshrrev_b32_e32 v2, 16, v2
	v_add3_u32 v39, v52, v39, s14
	ds_read2_b32 v[60:61], v28 offset0:231 offset1:239
	v_and_or_b32 v41, v39, s15, v2
	s_waitcnt lgkmcnt(3)
	v_bfe_u32 v2, v54, 16, 1
	v_add3_u32 v2, v54, v2, s14
	s_waitcnt lgkmcnt(2)
	v_bfe_u32 v39, v56, 16, 1
	v_lshrrev_b32_e32 v2, 16, v2
	v_add3_u32 v39, v56, v39, s14
	v_and_or_b32 v42, v39, s15, v2
	s_waitcnt lgkmcnt(1)
	v_bfe_u32 v2, v58, 16, 1
	v_add3_u32 v2, v58, v2, s14
	s_waitcnt lgkmcnt(0)
	v_bfe_u32 v39, v60, 16, 1
	s_or_b32 s4, s7, 0x400
	v_lshrrev_b32_e32 v2, 16, v2
	v_add3_u32 v39, v60, v39, s14
	s_mov_b32 s7, s5
	v_and_or_b32 v43, v39, s15, v2
	v_or_b32_e32 v2, s4, v201
	v_lshl_add_u64 v[46:47], s[6:7], 1, v[20:21]
	v_lshlrev_b32_e32 v2, 11, v2
	v_lshl_add_u64 v[62:63], v[46:47], 0, v[2:3]
	v_bfe_u32 v2, v45, 16, 1
	v_add3_u32 v2, v45, v2, s14
	v_bfe_u32 v39, v49, 16, 1
	v_lshrrev_b32_e32 v2, 16, v2
	v_add3_u32 v39, v49, v39, s14
	global_store_dwordx4 v[62:63], v[40:43], off
	ds_read2_b32 v[44:45], v28 offset0:16 offset1:24
	s_nop 0
	v_and_or_b32 v40, v39, s15, v2
	v_bfe_u32 v2, v51, 16, 1
	v_add3_u32 v2, v51, v2, s14
	v_bfe_u32 v39, v53, 16, 1
	v_lshrrev_b32_e32 v2, 16, v2
	v_add3_u32 v39, v53, v39, s14
	v_and_or_b32 v41, v39, s15, v2
	v_bfe_u32 v2, v55, 16, 1
	v_add3_u32 v2, v55, v2, s14
	v_bfe_u32 v39, v57, 16, 1
	v_lshrrev_b32_e32 v2, 16, v2
	v_add3_u32 v39, v57, v39, s14
	v_and_or_b32 v42, v39, s15, v2
	v_bfe_u32 v2, v59, 16, 1
	v_add3_u32 v2, v59, v2, s14
	v_bfe_u32 v39, v61, 16, 1
	v_lshrrev_b32_e32 v2, 16, v2
	v_add3_u32 v39, v61, v39, s14
	v_and_or_b32 v43, v39, s15, v2
	v_or_b32_e32 v2, s4, v29
	v_lshlrev_b32_e32 v2, 11, v2
	v_lshl_add_u64 v[48:49], v[46:47], 0, v[2:3]
	global_store_dwordx4 v[48:49], v[40:43], off
	ds_read2_b32 v[48:49], v28 offset0:49 offset1:57
	ds_read2_b32 v[50:51], v28 offset0:82 offset1:90
	ds_read2_b32 v[52:53], v28 offset0:115 offset1:123
	s_waitcnt lgkmcnt(3)
	v_bfe_u32 v2, v44, 16, 1
	v_add3_u32 v2, v44, v2, s14
	s_waitcnt lgkmcnt(2)
	v_bfe_u32 v39, v48, 16, 1
	ds_read2_b32 v[54:55], v28 offset0:148 offset1:156
	v_lshrrev_b32_e32 v2, 16, v2
	v_add3_u32 v39, v48, v39, s14
	ds_read2_b32 v[56:57], v28 offset0:181 offset1:189
	v_and_or_b32 v40, v39, s15, v2
	s_waitcnt lgkmcnt(3)
	v_bfe_u32 v2, v50, 16, 1
	v_add3_u32 v2, v50, v2, s14
	s_waitcnt lgkmcnt(2)
	v_bfe_u32 v39, v52, 16, 1
	ds_read2_b32 v[58:59], v28 offset0:214 offset1:222
	v_lshrrev_b32_e32 v2, 16, v2
	v_add3_u32 v39, v52, v39, s14
	ds_read2_b32 v[60:61], v28 offset0:247 offset1:255
	v_and_or_b32 v41, v39, s15, v2
	s_waitcnt lgkmcnt(3)
	v_bfe_u32 v2, v54, 16, 1
	v_add3_u32 v2, v54, v2, s14
	s_waitcnt lgkmcnt(2)
	v_bfe_u32 v39, v56, 16, 1
	v_lshrrev_b32_e32 v2, 16, v2
	v_add3_u32 v39, v56, v39, s14
	v_and_or_b32 v42, v39, s15, v2
	s_waitcnt lgkmcnt(1)
	v_bfe_u32 v2, v58, 16, 1
	v_add3_u32 v2, v58, v2, s14
	s_waitcnt lgkmcnt(0)
	v_bfe_u32 v39, v60, 16, 1
	v_lshrrev_b32_e32 v2, 16, v2
	v_add3_u32 v39, v60, v39, s14
	v_and_or_b32 v43, v39, s15, v2
	v_or_b32_e32 v2, s4, v30
	v_lshlrev_b32_e32 v2, 11, v2
	v_lshl_add_u64 v[62:63], v[46:47], 0, v[2:3]
	v_bfe_u32 v2, v45, 16, 1
	v_add3_u32 v2, v45, v2, s14
	v_bfe_u32 v39, v49, 16, 1
	v_lshrrev_b32_e32 v2, 16, v2
	v_add3_u32 v39, v49, v39, s14
	global_store_dwordx4 v[62:63], v[40:43], off
	s_nop 1
	v_and_or_b32 v40, v39, s15, v2
	v_bfe_u32 v2, v51, 16, 1
	v_add3_u32 v2, v51, v2, s14
	v_bfe_u32 v39, v53, 16, 1
	v_lshrrev_b32_e32 v2, 16, v2
	v_add3_u32 v39, v53, v39, s14
	v_and_or_b32 v41, v39, s15, v2
	v_bfe_u32 v2, v55, 16, 1
	v_add3_u32 v2, v55, v2, s14
	v_bfe_u32 v39, v57, 16, 1
	v_lshrrev_b32_e32 v2, 16, v2
	v_add3_u32 v39, v57, v39, s14
	v_and_or_b32 v42, v39, s15, v2
	v_bfe_u32 v2, v59, 16, 1
	v_add3_u32 v2, v59, v2, s14
	v_bfe_u32 v39, v61, 16, 1
	v_lshrrev_b32_e32 v2, 16, v2
	v_add3_u32 v39, v61, v39, s14
	v_and_or_b32 v43, v39, s15, v2
	v_or_b32_e32 v2, s4, v31
	v_lshlrev_b32_e32 v2, 11, v2
	v_lshl_add_u64 v[44:45], v[46:47], 0, v[2:3]
	global_store_dwordx4 v[44:45], v[40:43], off
	s_waitcnt lgkmcnt(0)

; #define LAS __attribute__((address_space(3)))
; __device__ __forceinline__ void tr_item(const float* W, int N, bf16* WT, int dpitch, int koff, int drow0, int k0, int n0, LAS float* scr, int lane) {
;     float tv[32];
; #pragma unroll
;     for (int i = 0; i < 32; ++i) tv[i] = W[(size_t)(k0 + 2 * i + (lane >> 5)) * N + n0 + (lane & 31)];
; #pragma unroll
;     for (int i = 0; i < 32; ++i) scr[(2 * i + (lane >> 5)) * 33 + (lane & 31)] = tv[i];
; __global__ void __launch_bounds__(512, 2) fwd_mega(Args a) {
;     ...
;             if (it < 512) { const int kb = it / 32, nb = it % 32; tr_item(INF(13) + (size_t)LL * D * D, D, WSP(WS_PAB), 1024, 0, 32 * nb, 64 * kb, 32 * nb, scr, lane); continue; } it -= 512;
;             if (it < 512) { const int kb = it / 32, nb = it % 32; tr_item(INF(12) + (size_t)LL * D * D, D, WSP(WS_PAB), 1024, 0, 1024 + 32 * nb, 64 * kb, 32 * nb, scr, lane); continue; } it -= 512;
;             if (it < 512) { const int kb = it / 32, nb = it % 32; tr_item(INF(14) + (size_t)LL * D * D, D, WSP(WS_WO2), 1024, 0, 32 * nb, 64 * kb, 32 * nb, scr, lane); continue; } it -= 512;
.LBB0_39:
	s_andn2_b64 vcc, exec, s[6:7]
	s_cbranch_vccnz .LBB0_41
	s_and_b32 s4, s12, 0x1fc0
	s_add_i32 s6, s4, 0xffffeb00
	s_and_b32 s8, s10, 0x3e0
	v_or_b32_e32 v2, s6, v200
	s_lshl_b32 s4, s8, 2
	v_or_b32_e32 v44, 2, v2
	v_mov_b32_e32 v45, v3
	v_or_b32_e32 v46, 4, v2
	v_mov_b32_e32 v47, v3
	v_or_b32_e32 v48, 6, v2
	v_mov_b32_e32 v49, v3
	v_or_b32_e32 v50, 8, v2
	v_mov_b32_e32 v51, v3
	v_or_b32_e32 v52, 10, v2
	v_mov_b32_e32 v53, v3
	v_or_b32_e32 v54, 12, v2
	v_mov_b32_e32 v55, v3
	v_lshl_add_u64 v[40:41], v[22:23], 0, s[4:5]
	v_lshlrev_b64 v[42:43], 12, v[2:3]
	v_lshlrev_b64 v[44:45], 12, v[44:45]
	v_lshlrev_b64 v[46:47], 12, v[46:47]
	v_lshlrev_b64 v[48:49], 12, v[48:49]
	v_lshlrev_b64 v[50:51], 12, v[50:51]
	v_lshlrev_b64 v[52:53], 12, v[52:53]
	v_lshlrev_b64 v[54:55], 12, v[54:55]
	v_or_b32_e32 v56, 14, v2
	v_mov_b32_e32 v57, v3
	v_lshl_add_u64 v[42:43], v[40:41], 0, v[42:43]
	v_lshl_add_u64 v[44:45], v[40:41], 0, v[44:45]
	v_lshl_add_u64 v[46:47], v[40:41], 0, v[46:47]
	v_lshl_add_u64 v[48:49], v[40:41], 0, v[48:49]
	v_lshl_add_u64 v[50:51], v[40:41], 0, v[50:51]
	v_lshl_add_u64 v[52:53], v[40:41], 0, v[52:53]
	v_lshl_add_u64 v[54:55], v[40:41], 0, v[54:55]
	v_lshlrev_b64 v[56:57], 12, v[56:57]
	v_lshl_add_u64 v[56:57], v[40:41], 0, v[56:57]
	global_load_dword v39, v[42:43], off nt
	global_load_dword v58, v[44:45], off nt
	global_load_dword v59, v[46:47], off nt
	global_load_dword v60, v[48:49], off nt
	global_load_dword v61, v[50:51], off nt
	global_load_dword v62, v[52:53], off nt
	global_load_dword v63, v[54:55], off nt
	global_load_dword v64, v[56:57], off nt
	v_or_b32_e32 v42, 16, v2
	v_mov_b32_e32 v43, v3
	v_or_b32_e32 v44, 18, v2
	v_mov_b32_e32 v45, v3
	v_or_b32_e32 v46, 20, v2
	v_mov_b32_e32 v47, v3
	v_or_b32_e32 v48, 22, v2
	v_mov_b32_e32 v49, v3
	v_or_b32_e32 v50, 24, v2
	v_mov_b32_e32 v51, v3
	v_or_b32_e32 v52, 26, v2
	v_mov_b32_e32 v53, v3
	v_or_b32_e32 v54, 28, v2
	v_mov_b32_e32 v55, v3
	v_lshlrev_b64 v[42:43], 12, v[42:43]
	v_lshlrev_b64 v[44:45], 12, v[44:45]
	v_lshlrev_b64 v[46:47], 12, v[46:47]
	v_lshlrev_b64 v[48:49], 12, v[48:49]
	v_lshlrev_b64 v[50:51], 12, v[50:51]
	v_lshlrev_b64 v[52:53], 12, v[52:53]
	v_lshlrev_b64 v[54:55], 12, v[54:55]
	v_or_b32_e32 v56, 30, v2
	v_mov_b32_e32 v57, v3
	v_lshl_add_u64 v[42:43], v[40:41], 0, v[42:43]
	v_lshl_add_u64 v[44:45], v[40:41], 0, v[44:45]
	v_lshl_add_u64 v[46:47], v[40:41], 0, v[46:47]
	v_lshl_add_u64 v[48:49], v[40:41], 0, v[48:49]
	v_lshl_add_u64 v[50:51], v[40:41], 0, v[50:51]
	v_lshl_add_u64 v[52:53], v[40:41], 0, v[52:53]
	v_lshl_add_u64 v[54:55], v[40:41], 0, v[54:55]
	v_lshlrev_b64 v[56:57], 12, v[56:57]
	v_lshl_add_u64 v[56:57], v[40:41], 0, v[56:57]
	global_load_dword v65, v[42:43], off nt
	global_load_dword v66, v[44:45], off nt
	global_load_dword v67, v[46:47], off nt
	global_load_dword v68, v[48:49], off nt
	global_load_dword v69, v[50:51], off nt
	global_load_dword v70, v[52:53], off nt
	global_load_dword v71, v[54:55], off nt
	global_load_dword v72, v[56:57], off nt
	v_or_b32_e32 v42, 32, v2
	v_mov_b32_e32 v43, v3
	v_or_b32_e32 v44, 34, v2
	v_mov_b32_e32 v45, v3
	v_or_b32_e32 v46, 36, v2
	v_mov_b32_e32 v47, v3
	v_or_b32_e32 v48, 38, v2
	v_mov_b32_e32 v49, v3
	v_or_b32_e32 v50, 40, v2
	v_mov_b32_e32 v51, v3
	v_or_b32_e32 v52, 42, v2
	v_mov_b32_e32 v53, v3
	v_or_b32_e32 v54, 44, v2
	v_mov_b32_e32 v55, v3
	v_lshlrev_b64 v[42:43], 12, v[42:43]
	v_lshlrev_b64 v[44:45], 12, v[44:45]
	v_lshlrev_b64 v[46:47], 12, v[46:47]
	v_lshlrev_b64 v[48:49], 12, v[48:49]
	v_lshlrev_b64 v[50:51], 12, v[50:51]
	v_lshlrev_b64 v[52:53], 12, v[52:53]
	v_lshlrev_b64 v[54:55], 12, v[54:55]
	v_or_b32_e32 v56, 46, v2
	v_mov_b32_e32 v57, v3
	v_lshl_add_u64 v[42:43], v[40:41], 0, v[42:43]
	v_lshl_add_u64 v[44:45], v[40:41], 0, v[44:45]
	v_lshl_add_u64 v[46:47], v[40:41], 0, v[46:47]
	v_lshl_add_u64 v[48:49], v[40:41], 0, v[48:49]
	v_lshl_add_u64 v[50:51], v[40:41], 0, v[50:51]
	v_lshl_add_u64 v[52:53], v[40:41], 0, v[52:53]
	v_lshl_add_u64 v[54:55], v[40:41], 0, v[54:55]
	v_lshlrev_b64 v[56:57], 12, v[56:57]
	v_lshl_add_u64 v[56:57], v[40:41], 0, v[56:57]
	global_load_dword v73, v[42:43], off nt
	global_load_dword v74, v[44:45], off nt
	global_load_dword v75, v[46:47], off nt
	global_load_dword v76, v[48:49], off nt
	global_load_dword v77, v[50:51], off nt
	global_load_dword v78, v[52:53], off nt
	global_load_dword v79, v[54:55], off nt
	global_load_dword v80, v[56:57], off nt
	v_or_b32_e32 v42, 48, v2
	v_mov_b32_e32 v43, v3
	v_or_b32_e32 v44, 50, v2
	v_mov_b32_e32 v45, v3
	v_or_b32_e32 v46, 52, v2
	v_mov_b32_e32 v47, v3
	v_or_b32_e32 v48, 54, v2
	v_mov_b32_e32 v49, v3
	v_or_b32_e32 v50, 56, v2
	v_mov_b32_e32 v51, v3
	v_or_b32_e32 v52, 58, v2
	v_mov_b32_e32 v53, v3
	v_or_b32_e32 v54, 60, v2
	v_mov_b32_e32 v55, v3
	v_or_b32_e32 v2, 62, v2
	v_lshlrev_b64 v[42:43], 12, v[42:43]
	v_lshlrev_b64 v[44:45], 12, v[44:45]
	v_lshlrev_b64 v[46:47], 12, v[46:47]
	v_lshlrev_b64 v[48:49], 12, v[48:49]
	v_lshlrev_b64 v[50:51], 12, v[50:51]
	v_lshlrev_b64 v[52:53], 12, v[52:53]
	v_lshlrev_b64 v[54:55], 12, v[54:55]
	v_lshlrev_b64 v[56:57], 12, v[2:3]
	v_lshl_add_u64 v[42:43], v[40:41], 0, v[42:43]
	v_lshl_add_u64 v[44:45], v[40:41], 0, v[44:45]
	v_lshl_add_u64 v[46:47], v[40:41], 0, v[46:47]
	v_lshl_add_u64 v[48:49], v[40:41], 0, v[48:49]
	v_lshl_add_u64 v[50:51], v[40:41], 0, v[50:51]
	v_lshl_add_u64 v[52:53], v[40:41], 0, v[52:53]
	v_lshl_add_u64 v[54:55], v[40:41], 0, v[54:55]
	v_lshl_add_u64 v[40:41], v[40:41], 0, v[56:57]
	global_load_dword v2, v[42:43], off nt
	s_nop 0
	global_load_dword v42, v[44:45], off nt
	global_load_dword v43, v[46:47], off nt
	s_nop 0
	global_load_dword v44, v[48:49], off nt
	global_load_dword v45, v[50:51], off nt
	global_load_dword v46, v[52:53], off nt
	global_load_dword v47, v[54:55], off nt
	s_nop 0
	global_load_dword v40, v[40:41], off nt
	s_waitcnt vmcnt(30)
; #define LAS __attribute__((address_space(3)))
; #define LDS_WAIT() asm volatile("s_waitcnt lgkmcnt(0)" ::: "memory")
; __device__ __forceinline__ unsigned pk2(float lo, float hi) { return f2bf(lo) | (f2bf(hi) << 16); }
; __device__ __forceinline__ void tr_item(const float* W, int N, bf16* WT, int dpitch, int koff, int drow0, int k0, int n0, LAS float* scr, int lane) {
;     ...
;     for (int i = 0; i < 32; ++i) scr[(2 * i + (lane >> 5)) * 33 + (lane & 31)] = tv[i];
;     LDS_WAIT(); asm volatile("" ::: "memory");
;     const int c = lane & 7;
; #pragma unroll
;     for (int j = 0; j < 4; ++j) { const int n = (lane >> 3) + 8 * j; const LAS float* s = scr + (8 * c) * 33 + n;
;         v4u o; o.x = pk2(s[0 * 33], s[1 * 33]); o.y = pk2(s[2 * 33], s[3 * 33]); o.z = pk2(s[4 * 33], s[5 * 33]); o.w = pk2(s[6 * 33], s[7 * 33]);
;         *(v4u*)(WT + (size_t)(drow0 + n) * dpitch + koff + k0 + 8 * c) = o; }
;     LDS_WAIT(); asm volatile("" ::: "memory");
; }
	ds_write2_b32 v1, v39, v58 offset1:66
	s_waitcnt vmcnt(28)
	ds_write2_b32 v1, v59, v60 offset0:132 offset1:198
	s_waitcnt vmcnt(26)
	ds_write2_b32 v32, v61, v62 offset0:8 offset1:74
	s_waitcnt vmcnt(24)
	ds_write2_b32 v32, v63, v64 offset0:140 offset1:206
	s_waitcnt vmcnt(22)
	ds_write2_b32 v33, v65, v66 offset0:16 offset1:82
	s_waitcnt vmcnt(20)
	ds_write2_b32 v33, v67, v68 offset0:148 offset1:214
	s_waitcnt vmcnt(18)
	ds_write2_b32 v34, v69, v70 offset0:24 offset1:90
	s_waitcnt vmcnt(16)
	ds_write2_b32 v34, v71, v72 offset0:156 offset1:222
	s_waitcnt vmcnt(14)
	ds_write2_b32 v35, v73, v74 offset0:32 offset1:98
	s_waitcnt vmcnt(12)
	ds_write2_b32 v35, v75, v76 offset0:164 offset1:230
	s_waitcnt vmcnt(10)
	ds_write2_b32 v36, v77, v78 offset0:40 offset1:106
	s_waitcnt vmcnt(8)
	ds_write2_b32 v36, v79, v80 offset0:172 offset1:238
	s_waitcnt vmcnt(6)
	ds_write2_b32 v37, v2, v42 offset0:48 offset1:114
	s_waitcnt vmcnt(4)
	ds_write2_b32 v37, v43, v44 offset0:180 offset1:246
	s_waitcnt vmcnt(2)
	ds_write2_b32 v38, v45, v46 offset0:56 offset1:122
	s_waitcnt vmcnt(0)
	ds_write2_b32 v38, v47, v40 offset0:188 offset1:254
	s_waitcnt lgkmcnt(0)
	ds_read2_b32 v[44:45], v28 offset1:8
	ds_read2_b32 v[48:49], v28 offset0:33 offset1:41
	ds_read2_b32 v[50:51], v28 offset0:66 offset1:74
	ds_read2_b32 v[52:53], v28 offset0:99 offset1:107
	ds_read2_b32 v[54:55], v28 offset0:132 offset1:140
	s_waitcnt lgkmcnt(4)
	v_bfe_u32 v2, v44, 16, 1
	v_add3_u32 v2, v44, v2, s14
	s_waitcnt lgkmcnt(3)
	v_bfe_u32 v39, v48, 16, 1
	v_lshrrev_b32_e32 v2, 16, v2
	v_add3_u32 v39, v48, v39, s14
	ds_read2_b32 v[56:57], v28 offset0:165 offset1:173
	v_and_or_b32 v40, v39, s15, v2
	s_waitcnt lgkmcnt(3)
	v_bfe_u32 v2, v50, 16, 1
	v_add3_u32 v2, v50, v2, s14
	s_waitcnt lgkmcnt(2)
	v_bfe_u32 v39, v52, 16, 1
	ds_read2_b32 v[58:59], v28 offset0:198 offset1:206
	v_lshrrev_b32_e32 v2, 16, v2
	v_add3_u32 v39, v52, v39, s14
	ds_read2_b32 v[60:61], v28 offset0:231 offset1:239
	v_and_or_b32 v41, v39, s15, v2
	s_waitcnt lgkmcnt(3)
	v_bfe_u32 v2, v54, 16, 1
	v_add3_u32 v2, v54, v2, s14
	s_waitcnt lgkmcnt(2)
	v_bfe_u32 v39, v56, 16, 1
	v_lshrrev_b32_e32 v2, 16, v2
	v_add3_u32 v39, v56, v39, s14
	v_and_or_b32 v42, v39, s15, v2
	s_waitcnt lgkmcnt(1)
	v_bfe_u32 v2, v58, 16, 1
	v_add3_u32 v2, v58, v2, s14
	s_waitcnt lgkmcnt(0)
	v_bfe_u32 v39, v60, 16, 1
	v_lshrrev_b32_e32 v2, 16, v2
	v_add3_u32 v39, v60, v39, s14
	s_mov_b32 s7, s5
	v_and_or_b32 v43, v39, s15, v2
	v_or_b32_e32 v2, s8, v201
	v_lshl_add_u64 v[46:47], s[6:7], 1, v[20:21]
	v_lshlrev_b32_e32 v2, 11, v2
	v_lshl_add_u64 v[62:63], v[46:47], 0, v[2:3]
	v_bfe_u32 v2, v45, 16, 1
	v_add3_u32 v2, v45, v2, s14
	v_bfe_u32 v39, v49, 16, 1
	v_lshrrev_b32_e32 v2, 16, v2
	v_add3_u32 v39, v49, v39, s14
	global_store_dwordx4 v[62:63], v[40:43], off
	ds_read2_b32 v[44:45], v28 offset0:16 offset1:24
	s_nop 0
	v_and_or_b32 v40, v39, s15, v2
	v_bfe_u32 v2, v51, 16, 1
	v_add3_u32 v2, v51, v2, s14
	v_bfe_u32 v39, v53, 16, 1
	v_lshrrev_b32_e32 v2, 16, v2
	v_add3_u32 v39, v53, v39, s14
	v_and_or_b32 v41, v39, s15, v2
	v_bfe_u32 v2, v55, 16, 1
	v_add3_u32 v2, v55, v2, s14
	v_bfe_u32 v39, v57, 16, 1
	v_lshrrev_b32_e32 v2, 16, v2
	v_add3_u32 v39, v57, v39, s14
	v_and_or_b32 v42, v39, s15, v2
	v_bfe_u32 v2, v59, 16, 1
	v_add3_u32 v2, v59, v2, s14
	v_bfe_u32 v39, v61, 16, 1
	v_lshrrev_b32_e32 v2, 16, v2
	v_add3_u32 v39, v61, v39, s14
	v_and_or_b32 v43, v39, s15, v2
	v_or_b32_e32 v2, s8, v29
	v_lshlrev_b32_e32 v2, 11, v2
	v_lshl_add_u64 v[48:49], v[46:47], 0, v[2:3]
	global_store_dwordx4 v[48:49], v[40:43], off
	ds_read2_b32 v[48:49], v28 offset0:49 offset1:57
	ds_read2_b32 v[50:51], v28 offset0:82 offset1:90
	ds_read2_b32 v[52:53], v28 offset0:115 offset1:123
	s_waitcnt lgkmcnt(3)
	v_bfe_u32 v2, v44, 16, 1
	v_add3_u32 v2, v44, v2, s14
	s_waitcnt lgkmcnt(2)
	v_bfe_u32 v39, v48, 16, 1
	ds_read2_b32 v[54:55], v28 offset0:148 offset1:156
	v_lshrrev_b32_e32 v2, 16, v2
	v_add3_u32 v39, v48, v39, s14
	ds_read2_b32 v[56:57], v28 offset0:181 offset1:189
	v_and_or_b32 v40, v39, s15, v2
	s_waitcnt lgkmcnt(3)
	v_bfe_u32 v2, v50, 16, 1
	v_add3_u32 v2, v50, v2, s14
	s_waitcnt lgkmcnt(2)
	v_bfe_u32 v39, v52, 16, 1
	ds_read2_b32 v[58:59], v28 offset0:214 offset1:222
	v_lshrrev_b32_e32 v2, 16, v2
	v_add3_u32 v39, v52, v39, s14
	ds_read2_b32 v[60:61], v28 offset0:247 offset1:255
	v_and_or_b32 v41, v39, s15, v2
	s_waitcnt lgkmcnt(3)
	v_bfe_u32 v2, v54, 16, 1
	v_add3_u32 v2, v54, v2, s14
	s_waitcnt lgkmcnt(2)
	v_bfe_u32 v39, v56, 16, 1
	v_lshrrev_b32_e32 v2, 16, v2
	v_add3_u32 v39, v56, v39, s14
	v_and_or_b32 v42, v39, s15, v2
	s_waitcnt lgkmcnt(1)
	v_bfe_u32 v2, v58, 16, 1
	v_add3_u32 v2, v58, v2, s14
	s_waitcnt lgkmcnt(0)
	v_bfe_u32 v39, v60, 16, 1
	v_lshrrev_b32_e32 v2, 16, v2
	v_add3_u32 v39, v60, v39, s14
	v_and_or_b32 v43, v39, s15, v2
	v_or_b32_e32 v2, s8, v30
	v_lshlrev_b32_e32 v2, 11, v2
	v_lshl_add_u64 v[62:63], v[46:47], 0, v[2:3]
	v_bfe_u32 v2, v45, 16, 1
	v_add3_u32 v2, v45, v2, s14
	v_bfe_u32 v39, v49, 16, 1
	v_lshrrev_b32_e32 v2, 16, v2
	v_add3_u32 v39, v49, v39, s14
	global_store_dwordx4 v[62:63], v[40:43], off
	s_nop 1
	v_and_or_b32 v40, v39, s15, v2
	v_bfe_u32 v2, v51, 16, 1
	v_add3_u32 v2, v51, v2, s14
	v_bfe_u32 v39, v53, 16, 1
	v_lshrrev_b32_e32 v2, 16, v2
	v_add3_u32 v39, v53, v39, s14
	v_and_or_b32 v41, v39, s15, v2
	v_bfe_u32 v2, v55, 16, 1
	v_add3_u32 v2, v55, v2, s14
	v_bfe_u32 v39, v57, 16, 1
	v_lshrrev_b32_e32 v2, 16, v2
	v_add3_u32 v39, v57, v39, s14
	v_and_or_b32 v42, v39, s15, v2
	v_bfe_u32 v2, v59, 16, 1
	v_add3_u32 v2, v59, v2, s14
	v_bfe_u32 v39, v61, 16, 1
	v_lshrrev_b32_e32 v2, 16, v2
	v_add3_u32 v39, v61, v39, s14
	v_and_or_b32 v43, v39, s15, v2
	v_or_b32_e32 v2, s8, v31
	v_lshlrev_b32_e32 v2, 11, v2
	v_lshl_add_u64 v[44:45], v[46:47], 0, v[2:3]
	global_store_dwordx4 v[44:45], v[40:43], off
	s_waitcnt lgkmcnt(0)

; #define LAS __attribute__((address_space(3)))
; __device__ __forceinline__ void tr_item(const float* W, int N, bf16* WT, int dpitch, int koff, int drow0, int k0, int n0, LAS float* scr, int lane) {
;     float tv[32];
; #pragma unroll
;     for (int i = 0; i < 32; ++i) tv[i] = W[(size_t)(k0 + 2 * i + (lane >> 5)) * N + n0 + (lane & 31)];
; #pragma unroll
;     for (int i = 0; i < 32; ++i) scr[(2 * i + (lane >> 5)) * 33 + (lane & 31)] = tv[i];
; __global__ void __launch_bounds__(512, 2) fwd_mega(Args a) {
;     ...
;             if (it < 2688) { const int kb = it / 168, nb = it % 168; tr_item(INF(6) + (size_t)LL * D * INC, INC, WSP(WS_WIN), 1024, 0, 32 * nb, 64 * kb, 32 * nb, scr, lane); continue; } it -= 2688;
.LBB0_42:
	s_andn2_b64 vcc, exec, s[6:7]
	s_cbranch_vccnz .LBB0_19
	s_mul_hi_i32 s4, s53, 0x30c30c31
	s_lshr_b32 s6, s4, 31
	s_ashr_i32 s4, s4, 5
	s_add_i32 s4, s4, s6
	s_mul_i32 s6, s4, 0xffffeb00
	s_add_i32 s6, s10, s6
	s_lshl_b32 s8, s4, 6
	v_or_b32_e32 v2, s8, v200
	s_ashr_i32 s7, s6, 31
	v_lshl_add_u64 v[40:41], s[6:7], 2, v[24:25]
	v_or_b32_e32 v39, 2, v2
	v_mad_i64_i32 v[44:45], s[54:55], v39, s52, v[40:41]
	v_or_b32_e32 v39, 4, v2
	v_mad_i64_i32 v[46:47], s[54:55], v39, s52, v[40:41]
	v_or_b32_e32 v39, 6, v2
	v_mad_i64_i32 v[48:49], s[54:55], v39, s52, v[40:41]
	v_or_b32_e32 v39, 8, v2
	v_mad_i64_i32 v[50:51], s[54:55], v39, s52, v[40:41]
	v_or_b32_e32 v39, 10, v2
	v_mad_i64_i32 v[52:53], s[54:55], v39, s52, v[40:41]
	v_or_b32_e32 v39, 12, v2
	v_mad_i64_i32 v[54:55], s[54:55], v39, s52, v[40:41]
	v_or_b32_e32 v39, 14, v2
	v_mad_i64_i32 v[42:43], s[54:55], v2, s52, v[40:41]
	v_mad_i64_i32 v[56:57], s[54:55], v39, s52, v[40:41]
	global_load_dword v39, v[42:43], off nt
	global_load_dword v58, v[44:45], off nt
	global_load_dword v59, v[46:47], off nt
	global_load_dword v60, v[48:49], off nt
	global_load_dword v61, v[50:51], off nt
	global_load_dword v62, v[52:53], off nt
	global_load_dword v63, v[54:55], off nt
	global_load_dword v64, v[56:57], off nt
	v_or_b32_e32 v42, 16, v2
	v_or_b32_e32 v44, 18, v2
	v_or_b32_e32 v46, 20, v2
	v_or_b32_e32 v48, 22, v2
	v_or_b32_e32 v50, 24, v2
	v_or_b32_e32 v52, 26, v2
	v_or_b32_e32 v54, 28, v2
	v_or_b32_e32 v56, 30, v2
	v_mad_i64_i32 v[42:43], s[54:55], v42, s52, v[40:41]
	v_mad_i64_i32 v[44:45], s[54:55], v44, s52, v[40:41]
	v_mad_i64_i32 v[46:47], s[54:55], v46, s52, v[40:41]
	v_mad_i64_i32 v[48:49], s[54:55], v48, s52, v[40:41]
	v_mad_i64_i32 v[50:51], s[54:55], v50, s52, v[40:41]
	v_mad_i64_i32 v[52:53], s[54:55], v52, s52, v[40:41]
	v_mad_i64_i32 v[54:55], s[54:55], v54, s52, v[40:41]
	v_mad_i64_i32 v[56:57], s[54:55], v56, s52, v[40:41]
	global_load_dword v65, v[42:43], off nt
	global_load_dword v66, v[44:45], off nt
	global_load_dword v67, v[46:47], off nt
	global_load_dword v68, v[48:49], off nt
	global_load_dword v69, v[50:51], off nt
	global_load_dword v70, v[52:53], off nt
	global_load_dword v71, v[54:55], off nt
	global_load_dword v72, v[56:57], off nt
	v_or_b32_e32 v42, 32, v2
	v_or_b32_e32 v44, 34, v2
	v_or_b32_e32 v46, 36, v2
	v_or_b32_e32 v48, 38, v2
	v_or_b32_e32 v50, 40, v2
	v_or_b32_e32 v52, 42, v2
	v_or_b32_e32 v54, 44, v2
	v_or_b32_e32 v56, 46, v2
	v_mad_i64_i32 v[42:43], s[54:55], v42, s52, v[40:41]
	v_mad_i64_i32 v[44:45], s[54:55], v44, s52, v[40:41]
	v_mad_i64_i32 v[46:47], s[54:55], v46, s52, v[40:41]
	v_mad_i64_i32 v[48:49], s[54:55], v48, s52, v[40:41]
	v_mad_i64_i32 v[50:51], s[54:55], v50, s52, v[40:41]
	v_mad_i64_i32 v[52:53], s[54:55], v52, s52, v[40:41]
	v_mad_i64_i32 v[54:55], s[54:55], v54, s52, v[40:41]
	v_mad_i64_i32 v[56:57], s[54:55], v56, s52, v[40:41]
	global_load_dword v73, v[42:43], off nt
	global_load_dword v74, v[44:45], off nt
	global_load_dword v75, v[46:47], off nt
	global_load_dword v76, v[48:49], off nt
	global_load_dword v77, v[50:51], off nt
	global_load_dword v78, v[52:53], off nt
	global_load_dword v79, v[54:55], off nt
	s_nop 0
	global_load_dword v56, v[56:57], off nt
	v_or_b32_e32 v42, 48, v2
	v_or_b32_e32 v44, 50, v2
	v_or_b32_e32 v46, 52, v2
	v_or_b32_e32 v48, 54, v2
	v_or_b32_e32 v50, 56, v2
	v_or_b32_e32 v52, 58, v2
	v_or_b32_e32 v54, 60, v2
	v_or_b32_e32 v2, 62, v2
	v_mad_i64_i32 v[42:43], s[54:55], v42, s52, v[40:41]
	v_mad_i64_i32 v[44:45], s[54:55], v44, s52, v[40:41]
	v_mad_i64_i32 v[46:47], s[54:55], v46, s52, v[40:41]
	v_mad_i64_i32 v[48:49], s[54:55], v48, s52, v[40:41]
	v_mad_i64_i32 v[50:51], s[54:55], v50, s52, v[40:41]
	v_mad_i64_i32 v[52:53], s[54:55], v52, s52, v[40:41]
	v_mad_i64_i32 v[54:55], s[54:55], v54, s52, v[40:41]
	v_mad_i64_i32 v[40:41], s[54:55], v2, s52, v[40:41]
	global_load_dword v2, v[42:43], off nt
	s_nop 0
	global_load_dword v42, v[44:45], off nt
	global_load_dword v43, v[46:47], off nt
	s_nop 0
	global_load_dword v44, v[48:49], off nt
	global_load_dword v45, v[50:51], off nt
	global_load_dword v46, v[52:53], off nt
	global_load_dword v47, v[54:55], off nt
	s_nop 0
	global_load_dword v40, v[40:41], off nt
	s_waitcnt vmcnt(30)
	ds_write2_b32 v1, v39, v58 offset1:66
	s_waitcnt vmcnt(28)
	ds_write2_b32 v1, v59, v60 offset0:132 offset1:198
	s_waitcnt vmcnt(26)
	ds_write2_b32 v32, v61, v62 offset0:8 offset1:74
	s_waitcnt vmcnt(24)
	ds_write2_b32 v32, v63, v64 offset0:140 offset1:206
	s_waitcnt vmcnt(22)
	ds_write2_b32 v33, v65, v66 offset0:16 offset1:82
	s_waitcnt vmcnt(20)
	ds_write2_b32 v33, v67, v68 offset0:148 offset1:214
	s_waitcnt vmcnt(18)
	ds_write2_b32 v34, v69, v70 offset0:24 offset1:90
	s_waitcnt vmcnt(16)
	ds_write2_b32 v34, v71, v72 offset0:156 offset1:222
	s_waitcnt vmcnt(14)
	ds_write2_b32 v35, v73, v74 offset0:32 offset1:98
	s_waitcnt vmcnt(12)
	ds_write2_b32 v35, v75, v76 offset0:164 offset1:230
	s_waitcnt vmcnt(10)
	ds_write2_b32 v36, v77, v78 offset0:40 offset1:106
	s_waitcnt vmcnt(8)
	ds_write2_b32 v36, v79, v56 offset0:172 offset1:238
	s_waitcnt vmcnt(6)
; #define LAS __attribute__((address_space(3)))
; #define LDS_WAIT() asm volatile("s_waitcnt lgkmcnt(0)" ::: "memory")
; __device__ __forceinline__ unsigned pk2(float lo, float hi) { return f2bf(lo) | (f2bf(hi) << 16); }
; __device__ __forceinline__ void tr_item(const float* W, int N, bf16* WT, int dpitch, int koff, int drow0, int k0, int n0, LAS float* scr, int lane) {
;     ...
;     for (int i = 0; i < 32; ++i) scr[(2 * i + (lane >> 5)) * 33 + (lane & 31)] = tv[i];
;     LDS_WAIT(); asm volatile("" ::: "memory");
;     const int c = lane & 7;
; #pragma unroll
;     for (int j = 0; j < 4; ++j) { const int n = (lane >> 3) + 8 * j; const LAS float* s = scr + (8 * c) * 33 + n;
;         v4u o; o.x = pk2(s[0 * 33], s[1 * 33]); o.y = pk2(s[2 * 33], s[3 * 33]); o.z = pk2(s[4 * 33], s[5 * 33]); o.w = pk2(s[6 * 33], s[7 * 33]);
;         *(v4u*)(WT + (size_t)(drow0 + n) * dpitch + koff + k0 + 8 * c) = o; }
;     LDS_WAIT(); asm volatile("" ::: "memory");
; }
	ds_write2_b32 v37, v2, v42 offset0:48 offset1:114
	s_waitcnt vmcnt(4)
	ds_write2_b32 v37, v43, v44 offset0:180 offset1:246
	s_waitcnt vmcnt(2)
	ds_write2_b32 v38, v45, v46 offset0:56 offset1:122
	s_waitcnt vmcnt(0)
	ds_write2_b32 v38, v47, v40 offset0:188 offset1:254
	s_waitcnt lgkmcnt(0)
	ds_read2_b32 v[44:45], v28 offset1:8
	ds_read2_b32 v[48:49], v28 offset0:33 offset1:41
	ds_read2_b32 v[50:51], v28 offset0:66 offset1:74
	ds_read2_b32 v[52:53], v28 offset0:99 offset1:107
	ds_read2_b32 v[54:55], v28 offset0:132 offset1:140
	s_waitcnt lgkmcnt(4)
	v_bfe_u32 v2, v44, 16, 1
	v_add3_u32 v2, v44, v2, s14
	s_waitcnt lgkmcnt(3)
	v_bfe_u32 v39, v48, 16, 1
	v_lshrrev_b32_e32 v2, 16, v2
	v_add3_u32 v39, v48, v39, s14
	ds_read2_b32 v[56:57], v28 offset0:165 offset1:173
	v_and_or_b32 v40, v39, s15, v2
	s_waitcnt lgkmcnt(3)
	v_bfe_u32 v2, v50, 16, 1
	v_add3_u32 v2, v50, v2, s14
	s_waitcnt lgkmcnt(2)
	v_bfe_u32 v39, v52, 16, 1
	ds_read2_b32 v[58:59], v28 offset0:198 offset1:206
	v_lshrrev_b32_e32 v2, 16, v2
	v_add3_u32 v39, v52, v39, s14
	ds_read2_b32 v[60:61], v28 offset0:231 offset1:239
	v_and_or_b32 v41, v39, s15, v2
	s_waitcnt lgkmcnt(3)
	v_bfe_u32 v2, v54, 16, 1
	v_add3_u32 v2, v54, v2, s14
	s_waitcnt lgkmcnt(2)
	v_bfe_u32 v39, v56, 16, 1
	v_lshrrev_b32_e32 v2, 16, v2
	v_add3_u32 v39, v56, v39, s14
	v_and_or_b32 v42, v39, s15, v2
	s_waitcnt lgkmcnt(1)
	v_bfe_u32 v2, v58, 16, 1
	v_add3_u32 v2, v58, v2, s14
	s_waitcnt lgkmcnt(0)
	v_bfe_u32 v39, v60, 16, 1
	v_lshrrev_b32_e32 v2, 16, v2
	v_add3_u32 v39, v60, v39, s14
	v_add_u32_e32 v62, s6, v201
	s_ashr_i32 s9, s8, 31
	v_and_or_b32 v43, v39, s15, v2
	v_ashrrev_i32_e32 v63, 31, v62
	v_bfe_u32 v2, v45, 16, 1
	v_lshl_add_u64 v[46:47], s[8:9], 1, v[26:27]
	v_lshlrev_b64 v[64:65], 11, v[62:63]
	v_add3_u32 v2, v45, v2, s14
	v_bfe_u32 v39, v49, 16, 1
	v_lshl_add_u64 v[64:65], v[46:47], 0, v[64:65]
	v_lshrrev_b32_e32 v2, 16, v2
	v_add3_u32 v39, v49, v39, s14
	global_store_dwordx4 v[64:65], v[40:43], off
	v_add_u32_e32 v44, 8, v62
	v_ashrrev_i32_e32 v45, 31, v44
	v_and_or_b32 v40, v39, s15, v2
	v_bfe_u32 v2, v51, 16, 1
	v_add3_u32 v2, v51, v2, s14
	v_bfe_u32 v39, v53, 16, 1
	v_lshrrev_b32_e32 v2, 16, v2
	v_add3_u32 v39, v53, v39, s14
	v_and_or_b32 v41, v39, s15, v2
	v_bfe_u32 v2, v55, 16, 1
	v_add3_u32 v2, v55, v2, s14
	v_bfe_u32 v39, v57, 16, 1
	v_lshrrev_b32_e32 v2, 16, v2
	v_add3_u32 v39, v57, v39, s14
	v_and_or_b32 v42, v39, s15, v2
	v_bfe_u32 v2, v59, 16, 1
	v_add3_u32 v2, v59, v2, s14
	v_bfe_u32 v39, v61, 16, 1
	v_lshrrev_b32_e32 v2, 16, v2
	v_add3_u32 v39, v61, v39, s14
	v_lshlrev_b64 v[44:45], 11, v[44:45]
	v_and_or_b32 v43, v39, s15, v2
	ds_read2_b32 v[48:49], v28 offset0:16 offset1:24
	v_lshl_add_u64 v[44:45], v[46:47], 0, v[44:45]
	global_store_dwordx4 v[44:45], v[40:43], off
	ds_read2_b32 v[44:45], v28 offset0:49 offset1:57
	ds_read2_b32 v[50:51], v28 offset0:82 offset1:90
	ds_read2_b32 v[52:53], v28 offset0:115 offset1:123
	s_waitcnt lgkmcnt(3)
	v_bfe_u32 v2, v48, 16, 1
	v_add3_u32 v2, v48, v2, s14
	s_waitcnt lgkmcnt(2)
	v_bfe_u32 v39, v44, 16, 1
	ds_read2_b32 v[54:55], v28 offset0:148 offset1:156
	v_lshrrev_b32_e32 v2, 16, v2
	v_add3_u32 v39, v44, v39, s14
	ds_read2_b32 v[56:57], v28 offset0:181 offset1:189
	v_and_or_b32 v40, v39, s15, v2
	s_waitcnt lgkmcnt(3)
	v_bfe_u32 v2, v50, 16, 1
	v_add3_u32 v2, v50, v2, s14
	s_waitcnt lgkmcnt(2)
	v_bfe_u32 v39, v52, 16, 1
	ds_read2_b32 v[58:59], v28 offset0:214 offset1:222
	v_lshrrev_b32_e32 v2, 16, v2
	v_add3_u32 v39, v52, v39, s14
	ds_read2_b32 v[60:61], v28 offset0:247 offset1:255
	v_and_or_b32 v41, v39, s15, v2
	s_waitcnt lgkmcnt(3)
	v_bfe_u32 v2, v54, 16, 1
	v_add3_u32 v2, v54, v2, s14
	s_waitcnt lgkmcnt(2)
	v_bfe_u32 v39, v56, 16, 1
	v_lshrrev_b32_e32 v2, 16, v2
	v_add3_u32 v39, v56, v39, s14
	v_and_or_b32 v42, v39, s15, v2
	s_waitcnt lgkmcnt(1)
	v_bfe_u32 v2, v58, 16, 1
	v_add3_u32 v2, v58, v2, s14
	s_waitcnt lgkmcnt(0)
	v_bfe_u32 v39, v60, 16, 1
	v_lshrrev_b32_e32 v2, 16, v2
	v_add3_u32 v39, v60, v39, s14
	v_add_u32_e32 v64, 16, v62
	v_and_or_b32 v43, v39, s15, v2
	v_ashrrev_i32_e32 v65, 31, v64
	v_bfe_u32 v2, v49, 16, 1
	v_lshlrev_b64 v[64:65], 11, v[64:65]
	v_add3_u32 v2, v49, v2, s14
	v_bfe_u32 v39, v45, 16, 1
	v_lshl_add_u64 v[64:65], v[46:47], 0, v[64:65]
	v_lshrrev_b32_e32 v2, 16, v2
	v_add3_u32 v39, v45, v39, s14
	global_store_dwordx4 v[64:65], v[40:43], off
	v_add_u32_e32 v44, 24, v62
	v_ashrrev_i32_e32 v45, 31, v44
	v_and_or_b32 v40, v39, s15, v2
	v_bfe_u32 v2, v51, 16, 1
	v_add3_u32 v2, v51, v2, s14
	v_bfe_u32 v39, v53, 16, 1
	v_lshrrev_b32_e32 v2, 16, v2
	v_add3_u32 v39, v53, v39, s14
	v_and_or_b32 v41, v39, s15, v2
	v_bfe_u32 v2, v55, 16, 1
	v_add3_u32 v2, v55, v2, s14
	v_bfe_u32 v39, v57, 16, 1
	v_lshrrev_b32_e32 v2, 16, v2
	v_add3_u32 v39, v57, v39, s14
	v_and_or_b32 v42, v39, s15, v2
	v_bfe_u32 v2, v59, 16, 1
	v_add3_u32 v2, v59, v2, s14
	v_bfe_u32 v39, v61, 16, 1
	v_lshrrev_b32_e32 v2, 16, v2
	v_add3_u32 v39, v61, v39, s14
	v_lshlrev_b64 v[44:45], 11, v[44:45]
	v_and_or_b32 v43, v39, s15, v2
	v_lshl_add_u64 v[44:45], v[46:47], 0, v[44:45]
	global_store_dwordx4 v[44:45], v[40:43], off
	s_waitcnt lgkmcnt(0)
	s_branch .LBB0_19

; __device__ __forceinline__ unsigned cvt_pk_bf16(float lo, float hi) { unsigned r; asm volatile("v_cvt_pk_bf16_f32 %0, %1, %2" : "=v"(r) : "v"(lo), "v"(hi)); return r; }
; __global__ void __launch_bounds__(512, 2) fwd_mega(Args a) {
;     ...
;             for (int m0 = gw; m0 < M; m0 += 2 * NGW) {
;                 const int m1 = m0 + NGW; const bool has1 = m1 < M; const int m1c = has1 ? m1 : m0;
;                 const f32x4* xr0 = (const f32x4*)(xin + (size_t)m0 * D) + lane; const f32x4* xr1 = (const f32x4*)(xin + (size_t)m1c * D) + lane;
;                 f32x4 v0[4], v1[4]; float ss0 = 0.f, ss1 = 0.f;
; #pragma unroll
;                 for (int j = 0; j < 4; ++j) { v0[j] = xr0[64 * j]; v1[j] = xr1[64 * j]; }
; #pragma unroll
;                 for (int j = 0; j < 4; ++j) { ss0 += (v0[j].x * v0[j].x + v0[j].y * v0[j].y) + (v0[j].z * v0[j].z + v0[j].w * v0[j].w); ss1 += (v1[j].x * v1[j].x + v1[j].y * v1[j].y) + (v1[j].z * v1[j].z + v1[j].w * v1[j].w); }
;                 const float rstd0 = rsqrtf(wave_sum(ss0) * (1.f / D) + 1e-6f), rstd1 = rsqrtf(wave_sum(ss1) * (1.f / D) + 1e-6f);
;                 const int b0 = m0 >> 12, b1 = m1c >> 12;
;                 v2u* o0 = (v2u*)(WSP(WS_H) + (size_t)m0 * D) + lane; v2u* o1 = (v2u*)(WSP(WS_H) + (size_t)m1c * D) + lane;
; #pragma unroll
;                 for (int j = 0; j < 4; ++j) { const int col = 4 * lane + 256 * j; const f32x4 wv = *(const f32x4*)(nw + col);
;                     const f32x4 sh0 = *(const f32x4*)(ml + (size_t)b0 * 6144 + col), sc0 = *(const f32x4*)(ml + (size_t)b0 * 6144 + 1024 + col);
;                     const f32x4 sh1 = *(const f32x4*)(ml + (size_t)b1 * 6144 + col), sc1 = *(const f32x4*)(ml + (size_t)b1 * 6144 + 1024 + col);
;                     const f32x4 y0 = (v0[j] * rstd0) * wv * (sc0 + 1.0f) + sh0, y1 = (v1[j] * rstd1) * wv * (sc1 + 1.0f) + sh1;
;                     v2u w0; w0.x = cvt_pk_bf16(y0.x, y0.y); w0.y = cvt_pk_bf16(y0.z, y0.w); o0[64 * j] = w0;
;                     if (has1) { v2u w1; w1.x = cvt_pk_bf16(y1.x, y1.y); w1.y = cvt_pk_bf16(y1.z, y1.w); o1[64 * j] = w1; } }
.LBB0_102:
	s_add_i32 s23, s77, s15
	global_load_dwordx4 v[30:33], v[52:53], off nt
	global_load_dwordx4 v[22:25], v[52:53], off offset:1024 nt
	global_load_dwordx4 v[6:9], v[52:53], off offset:3072 nt
	global_load_dwordx4 v[14:17], v[52:53], off offset:2048 nt
	s_cmpk_lt_i32 s23, 0x4000
	s_cselect_b64 s[16:17], -1, 0
	s_and_b64 s[4:5], s[16:17], exec
	s_cselect_b32 s4, s23, s15
	s_ashr_i32 s5, s4, 31
	s_lshl_b64 s[18:19], s[4:5], 12
	v_lshl_add_u64 v[38:39], v[46:47], 0, s[18:19]
	global_load_dwordx4 v[26:29], v[38:39], off nt
	global_load_dwordx4 v[18:21], v[38:39], off offset:1024 nt
	global_load_dwordx4 v[2:5], v[38:39], off offset:3072 nt
	global_load_dwordx4 v[10:13], v[38:39], off offset:2048 nt
	global_load_dwordx4 v[34:37], v[50:51], off
	s_ashr_i32 s18, s15, 12
	s_ashr_i32 s19, s4, 12
	s_mul_hi_i32 s20, s18, 0x6000
	s_mulk_i32 s18, 0x6000
	s_lshl_b64 s[4:5], s[4:5], 11
	s_add_u32 s28, s6, s18
	s_addc_u32 s29, s7, s20
	s_add_u32 s18, s28, 0x1000
	s_mul_hi_i32 s21, s19, 0x6000
	s_mul_i32 s24, s19, 0x6000
	s_addc_u32 s19, s29, 0
	s_add_u32 s30, s6, s24
	s_addc_u32 s31, s7, s21
	s_add_u32 s20, s30, 0x1000
	global_load_dwordx4 v[74:77], v58, s[28:29]
	global_load_dwordx4 v[38:41], v58, s[30:31]
	s_addc_u32 s21, s31, 0
	global_load_dwordx4 v[62:65], v58, s[18:19]
	global_load_dwordx4 v[42:45], v58, s[20:21]
	s_cmpk_gt_i32 s23, 0x3fff
	s_waitcnt vmcnt(12)
	v_pk_mul_f32 v[60:61], v[32:33], v[32:33]
	v_pk_mul_f32 v[78:79], v[30:31], v[30:31]
	s_waitcnt vmcnt(11)
	v_pk_mul_f32 v[80:81], v[24:25], v[24:25]
	v_pk_mul_f32 v[82:83], v[22:23], v[22:23]
	v_pk_mov_b32 v[88:89], v[78:79], v[60:61] op_sel:[1,0]
	v_mov_b32_e32 v79, v61
	v_pk_mov_b32 v[60:61], v[82:83], v[80:81] op_sel:[1,0]
	v_mov_b32_e32 v83, v81
	s_waitcnt vmcnt(10)
	v_mul_f32_e32 v87, v6, v6
	s_waitcnt vmcnt(9)
	v_mul_f32_e32 v84, v15, v15
	v_mul_f32_e32 v86, v17, v17
	v_pk_add_f32 v[78:79], v[88:89], v[78:79]
	v_pk_add_f32 v[60:61], v[60:61], v[82:83]
	v_mul_f32_e32 v90, v7, v7
	v_mul_f32_e32 v91, v8, v8
	v_mul_f32_e32 v92, v9, v9
	v_pk_fma_f32 v[80:81], v[14:15], v[14:15], v[84:85] op_sel_hi:[1,1,0]
	v_pk_fma_f32 v[84:85], v[16:17], v[16:17], v[86:87] op_sel_hi:[1,1,0]
	v_pk_add_f32 v[78:79], v[78:79], v[78:79] op_sel:[0,1] op_sel_hi:[1,0]
	v_pk_add_f32 v[60:61], v[60:61], v[60:61] op_sel:[0,1] op_sel_hi:[1,0]
	v_mov_b32_e32 v81, v91
	v_mov_b32_e32 v85, v92
	v_mov_b32_e32 v79, v87
	v_mov_b32_e32 v61, v90
	v_pk_add_f32 v[80:81], v[80:81], v[84:85]
	v_pk_add_f32 v[60:61], v[78:79], v[60:61]
	s_waitcnt vmcnt(8)
	v_pk_mul_f32 v[82:83], v[26:27], v[26:27]
	v_pk_add_f32 v[60:61], v[60:61], v[80:81]
	v_pk_mul_f32 v[80:81], v[28:29], v[28:29]
	s_waitcnt vmcnt(7)
	v_pk_mul_f32 v[84:85], v[20:21], v[20:21]
	v_pk_mul_f32 v[86:87], v[18:19], v[18:19]
	v_pk_mov_b32 v[88:89], v[82:83], v[80:81] op_sel:[1,0]
	v_mov_b32_e32 v83, v81
	v_pk_mov_b32 v[80:81], v[86:87], v[84:85] op_sel:[1,0]
	v_mov_b32_e32 v87, v85
	v_mov_b32_e32 v79, v60
	s_waitcnt vmcnt(5)
	v_mul_f32_e32 v60, v11, v11
	v_mul_f32_e32 v78, v13, v13
	v_pk_add_f32 v[82:83], v[88:89], v[82:83]
	v_pk_add_f32 v[80:81], v[80:81], v[86:87]
	v_mul_f32_e32 v92, v2, v2
	v_mul_f32_e32 v93, v3, v3
	v_mul_f32_e32 v94, v4, v4
	v_mul_f32_e32 v95, v5, v5
	v_pk_fma_f32 v[84:85], v[10:11], v[10:11], v[60:61] op_sel_hi:[1,1,0]
	v_pk_fma_f32 v[90:91], v[12:13], v[12:13], v[78:79] op_sel_hi:[1,1,0]
	v_pk_add_f32 v[82:83], v[82:83], v[82:83] op_sel:[0,1] op_sel_hi:[1,0]
	v_pk_add_f32 v[80:81], v[80:81], v[80:81] op_sel:[0,1] op_sel_hi:[1,0]
	v_mov_b32_e32 v85, v94
	v_mov_b32_e32 v91, v95
	v_mov_b32_e32 v83, v92
	v_mov_b32_e32 v81, v93
	v_pk_add_f32 v[84:85], v[84:85], v[90:91]
	v_pk_add_f32 v[80:81], v[82:83], v[80:81]
	s_nop 0
	v_pk_add_f32 v[80:81], v[80:81], v[84:85]
	s_nop 0
	v_mov_b32_e32 v78, v80
	v_mov_b32_e32 v60, v81
	v_pk_add_f32 v[60:61], v[78:79], v[60:61]
	ds_bpermute_b32 v79, v57, v61
	ds_bpermute_b32 v78, v57, v60
	s_waitcnt lgkmcnt(0)
	v_pk_add_f32 v[60:61], v[60:61], v[78:79]
	ds_bpermute_b32 v79, v66, v61
	ds_bpermute_b32 v78, v66, v60
	s_waitcnt lgkmcnt(0)
	v_pk_add_f32 v[60:61], v[60:61], v[78:79]
	ds_bpermute_b32 v79, v67, v61
	ds_bpermute_b32 v78, v67, v60
	s_waitcnt lgkmcnt(0)
	v_pk_add_f32 v[60:61], v[60:61], v[78:79]
	ds_bpermute_b32 v79, v68, v61
	ds_bpermute_b32 v78, v68, v60
	s_waitcnt lgkmcnt(0)
	v_pk_add_f32 v[60:61], v[60:61], v[78:79]
	ds_bpermute_b32 v79, v69, v61
	ds_bpermute_b32 v78, v69, v60
	s_waitcnt lgkmcnt(0)
	v_pk_add_f32 v[78:79], v[60:61], v[78:79]
	ds_bpermute_b32 v81, v70, v79
	ds_bpermute_b32 v80, v70, v78
	v_lshl_add_u64 v[60:61], v[48:49], 0, s[4:5]
	s_waitcnt lgkmcnt(0)
	v_pk_add_f32 v[78:79], v[78:79], v[80:81]
	s_nop 0
	v_pk_fma_f32 v[78:79], v[78:79], s[14:15], v[56:57] op_sel_hi:[1,0,0]
	s_nop 0
	v_mul_f32_e32 v80, 0x4b800000, v79
	v_cmp_gt_f32_e32 vcc, s9, v79
	v_mul_f32_e32 v81, 0x4b800000, v78
	v_cmp_gt_f32_e64 s[4:5], s9, v78
	v_cndmask_b32_e32 v79, v79, v80, vcc
	v_rsq_f32_e32 v82, v79
	v_cndmask_b32_e64 v78, v78, v81, s[4:5]
	v_rsq_f32_e32 v83, v78
	s_waitcnt vmcnt(1)
	v_pk_add_f32 v[80:81], v[62:63], 1.0 op_sel_hi:[1,0]
	v_mul_f32_e32 v62, 0x45800000, v82
	v_pk_add_f32 v[78:79], v[64:65], 1.0 op_sel_hi:[1,0]
	v_cndmask_b32_e32 v64, v82, v62, vcc
	v_mul_f32_e32 v63, 0x45800000, v83
	v_pk_mul_f32 v[30:31], v[30:31], v[64:65] op_sel_hi:[1,0]
	v_cndmask_b32_e64 v62, v83, v63, s[4:5]
	v_pk_mul_f32 v[32:33], v[32:33], v[64:65] op_sel_hi:[1,0]
	v_pk_mul_f32 v[30:31], v[34:35], v[30:31]
	v_mov_b32_e32 v63, v62
	v_pk_mul_f32 v[32:33], v[36:37], v[32:33]
	v_pk_fma_f32 v[30:31], v[80:81], v[30:31], v[74:75]
	v_pk_fma_f32 v[32:33], v[78:79], v[32:33], v[76:77]
	v_cvt_pk_bf16_f32 v30, v30, v31
	s_nop 0
	v_cvt_pk_bf16_f32 v31, v32, v33
	global_store_dwordx2 v[54:55], v[30:31], off
	s_cbranch_scc1 .LBB0_104
	v_mov_b32_e32 v30, v62
	v_mov_b32_e32 v31, v62
	v_pk_mul_f32 v[26:27], v[26:27], v[62:63]
	v_pk_mul_f32 v[28:29], v[28:29], v[30:31]
	v_pk_mul_f32 v[26:27], v[34:35], v[26:27]
	s_waitcnt vmcnt(1)
	v_pk_add_f32 v[32:33], v[42:43], 1.0 op_sel_hi:[1,0]
	v_pk_mul_f32 v[28:29], v[36:37], v[28:29]
	v_pk_add_f32 v[30:31], v[44:45], 1.0 op_sel_hi:[1,0]
	v_pk_fma_f32 v[26:27], v[32:33], v[26:27], v[38:39]
	v_pk_fma_f32 v[28:29], v[30:31], v[28:29], v[40:41]
	v_cvt_pk_bf16_f32 v26, v26, v27
	s_nop 0
	v_cvt_pk_bf16_f32 v27, v28, v29
	global_store_dwordx2 v[60:61], v[26:27], off
; __device__ __forceinline__ unsigned cvt_pk_bf16(float lo, float hi) { unsigned r; asm volatile("v_cvt_pk_bf16_f32 %0, %1, %2" : "=v"(r) : "v"(lo), "v"(hi)); return r; }
; __global__ void __launch_bounds__(512, 2) fwd_mega(Args a) {
;     ...
;                 v2u* o0 = (v2u*)(WSP(WS_H) + (size_t)m0 * D) + lane; v2u* o1 = (v2u*)(WSP(WS_H) + (size_t)m1c * D) + lane;
; #pragma unroll
;                 for (int j = 0; j < 4; ++j) { const int col = 4 * lane + 256 * j; const f32x4 wv = *(const f32x4*)(nw + col);
;                     const f32x4 sh0 = *(const f32x4*)(ml + (size_t)b0 * 6144 + col), sc0 = *(const f32x4*)(ml + (size_t)b0 * 6144 + 1024 + col);
;                     const f32x4 sh1 = *(const f32x4*)(ml + (size_t)b1 * 6144 + col), sc1 = *(const f32x4*)(ml + (size_t)b1 * 6144 + 1024 + col);
;                     const f32x4 y0 = (v0[j] * rstd0) * wv * (sc0 + 1.0f) + sh0, y1 = (v1[j] * rstd1) * wv * (sc1 + 1.0f) + sh1;
;                     v2u w0; w0.x = cvt_pk_bf16(y0.x, y0.y); w0.y = cvt_pk_bf16(y0.z, y0.w); o0[64 * j] = w0;
;                     if (has1) { v2u w1; w1.x = cvt_pk_bf16(y1.x, y1.y); w1.y = cvt_pk_bf16(y1.z, y1.w); o1[64 * j] = w1; } }
.LBB0_104:
	global_load_dwordx4 v[26:29], v[50:51], off offset:1024
	s_nop 0
	global_load_dwordx4 v[74:77], v71, s[18:19]
	v_lshl_add_u64 v[38:39], s[28:29], 0, v[58:59]
	global_load_dwordx4 v[78:81], v[38:39], off offset:1024 nt
	v_lshl_add_u64 v[40:41], s[30:31], 0, v[58:59]
	global_load_dwordx4 v[34:37], v71, s[20:21]
	global_load_dwordx4 v[30:33], v[40:41], off offset:1024
	v_mov_b32_e32 v65, v64
	s_waitcnt vmcnt(6)
	v_mov_b32_e32 v42, v64
	v_mov_b32_e32 v43, v64
	v_pk_mul_f32 v[22:23], v[22:23], v[64:65]
	v_cndmask_b32_e64 v44, 0, 1, s[16:17]
	v_pk_mul_f32 v[24:25], v[24:25], v[42:43]
	v_cmp_ne_u32_e64 s[4:5], 1, v44
	s_andn2_b64 vcc, exec, s[16:17]
	s_waitcnt vmcnt(4)
	v_pk_mul_f32 v[22:23], v[22:23], v[26:27]
	s_waitcnt vmcnt(3)
	v_pk_add_f32 v[74:75], v[74:75], 1.0 op_sel_hi:[1,0]
	v_pk_mul_f32 v[24:25], v[24:25], v[28:29]
	v_pk_add_f32 v[44:45], v[76:77], 1.0 op_sel_hi:[1,0]
	s_waitcnt vmcnt(2)
	v_pk_fma_f32 v[22:23], v[22:23], v[74:75], v[78:79]
	v_pk_fma_f32 v[24:25], v[24:25], v[44:45], v[80:81]
	v_cvt_pk_bf16_f32 v22, v22, v23
	s_nop 0
	v_cvt_pk_bf16_f32 v23, v24, v25
	global_store_dwordx2 v[54:55], v[22:23], off offset:512
	s_cbranch_vccnz .LBB0_106
	v_mov_b32_e32 v22, v62
	v_mov_b32_e32 v23, v62
	v_pk_mul_f32 v[18:19], v[18:19], v[62:63]
	v_pk_mul_f32 v[20:21], v[20:21], v[22:23]
	v_pk_mul_f32 v[18:19], v[18:19], v[26:27]
	s_waitcnt vmcnt(2)
	v_pk_add_f32 v[24:25], v[34:35], 1.0 op_sel_hi:[1,0]
	v_pk_mul_f32 v[20:21], v[20:21], v[28:29]
	v_pk_add_f32 v[22:23], v[36:37], 1.0 op_sel_hi:[1,0]
	s_waitcnt vmcnt(1)
	v_pk_fma_f32 v[18:19], v[18:19], v[24:25], v[30:31]
	v_pk_fma_f32 v[20:21], v[20:21], v[22:23], v[32:33]
	v_cvt_pk_bf16_f32 v18, v18, v19
	s_nop 0
	v_cvt_pk_bf16_f32 v19, v20, v21
	global_store_dwordx2 v[60:61], v[18:19], off offset:512
.LBB0_106:
	global_load_dwordx4 v[22:25], v[50:51], off offset:2048
	global_load_dwordx4 v[30:33], v72, s[18:19]
	global_load_dwordx4 v[34:37], v[38:39], off offset:2048 nt
	s_nop 0
	global_load_dwordx4 v[18:21], v[40:41], off offset:2048
	global_load_dwordx4 v[26:29], v72, s[20:21]
	v_pk_mul_f32 v[14:15], v[14:15], v[64:65]
	v_pk_mul_f32 v[16:17], v[16:17], v[42:43]
	s_and_b64 vcc, exec, s[4:5]
	s_waitcnt vmcnt(4)
	v_pk_mul_f32 v[14:15], v[14:15], v[22:23]
	s_waitcnt vmcnt(3)
	v_pk_add_f32 v[30:31], v[30:31], 1.0 op_sel_hi:[1,0]
	v_pk_mul_f32 v[16:17], v[16:17], v[24:25]
	v_pk_add_f32 v[32:33], v[32:33], 1.0 op_sel_hi:[1,0]
	s_waitcnt vmcnt(2)
	v_pk_fma_f32 v[14:15], v[14:15], v[30:31], v[34:35]
	v_pk_fma_f32 v[16:17], v[16:17], v[32:33], v[36:37]
	v_cvt_pk_bf16_f32 v14, v14, v15
	s_nop 0
	v_cvt_pk_bf16_f32 v15, v16, v17
	global_store_dwordx2 v[54:55], v[14:15], off offset:1024
	s_cbranch_vccnz .LBB0_108
	v_mov_b32_e32 v14, v62
	v_mov_b32_e32 v15, v62
	v_pk_mul_f32 v[10:11], v[10:11], v[62:63]
	v_pk_mul_f32 v[12:13], v[12:13], v[14:15]
	v_pk_mul_f32 v[10:11], v[10:11], v[22:23]
	s_waitcnt vmcnt(1)
	v_pk_add_f32 v[16:17], v[26:27], 1.0 op_sel_hi:[1,0]
	v_pk_mul_f32 v[12:13], v[12:13], v[24:25]
	v_pk_add_f32 v[14:15], v[28:29], 1.0 op_sel_hi:[1,0]
	v_pk_fma_f32 v[10:11], v[10:11], v[16:17], v[18:19]
	v_pk_fma_f32 v[12:13], v[12:13], v[14:15], v[20:21]
	v_cvt_pk_bf16_f32 v10, v10, v11
	s_nop 0
	v_cvt_pk_bf16_f32 v11, v12, v13
	global_store_dwordx2 v[60:61], v[10:11], off offset:1024
.LBB0_108:
	global_load_dwordx4 v[14:17], v[50:51], off offset:3072
	global_load_dwordx4 v[22:25], v73, s[18:19]
	global_load_dwordx4 v[26:29], v[38:39], off offset:3072 nt
	s_nop 0
	global_load_dwordx4 v[10:13], v[40:41], off offset:3072
	global_load_dwordx4 v[18:21], v73, s[20:21]
	v_mov_b32_e32 v30, v64
	v_mov_b32_e32 v31, v64
	v_pk_mul_f32 v[6:7], v[6:7], v[64:65]
	v_pk_mul_f32 v[8:9], v[8:9], v[30:31]
	s_and_b64 vcc, exec, s[4:5]
	s_waitcnt vmcnt(4)
	v_pk_mul_f32 v[6:7], v[6:7], v[14:15]
	s_waitcnt vmcnt(3)
	v_pk_add_f32 v[22:23], v[22:23], 1.0 op_sel_hi:[1,0]
	v_pk_mul_f32 v[8:9], v[8:9], v[16:17]
	v_pk_add_f32 v[24:25], v[24:25], 1.0 op_sel_hi:[1,0]
	s_waitcnt vmcnt(2)
	v_pk_fma_f32 v[6:7], v[6:7], v[22:23], v[26:27]
	v_pk_fma_f32 v[8:9], v[8:9], v[24:25], v[28:29]
	v_cvt_pk_bf16_f32 v6, v6, v7
	s_nop 0
	v_cvt_pk_bf16_f32 v7, v8, v9
	global_store_dwordx2 v[54:55], v[6:7], off offset:1536
	s_cbranch_vccnz .LBB0_101
	v_mov_b32_e32 v6, v62
	v_mov_b32_e32 v7, v62
	v_pk_mul_f32 v[2:3], v[2:3], v[62:63]
	v_pk_mul_f32 v[4:5], v[4:5], v[6:7]
	v_pk_mul_f32 v[2:3], v[2:3], v[14:15]
	s_waitcnt vmcnt(1)
	v_pk_add_f32 v[8:9], v[18:19], 1.0 op_sel_hi:[1,0]
	v_pk_mul_f32 v[4:5], v[4:5], v[16:17]
	v_pk_add_f32 v[6:7], v[20:21], 1.0 op_sel_hi:[1,0]
	v_pk_fma_f32 v[2:3], v[2:3], v[8:9], v[10:11]
	v_pk_fma_f32 v[4:5], v[4:5], v[6:7], v[12:13]
	v_cvt_pk_bf16_f32 v2, v2, v3
	s_nop 0
	v_cvt_pk_bf16_f32 v3, v4, v5
	global_store_dwordx2 v[60:61], v[2:3], off offset:1536
	s_branch .LBB0_101

; __device__ __forceinline__ unsigned cvt_pk_bf16(float lo, float hi) { unsigned r; asm volatile("v_cvt_pk_bf16_f32 %0, %1, %2" : "=v"(r) : "v"(lo), "v"(hi)); return r; }
; __device__ __forceinline__ float bf_lo(unsigned w) { return __uint_as_float(w << 16); }
; __device__ __forceinline__ float bf_hi(unsigned w) { return __uint_as_float(w & 0xffff0000u); }
; #define LAS __attribute__((address_space(3)))
; __device__ __forceinline__ void sgu_unit(LAS unsigned char* lds, bf16* U, const bf16* VS, const float* SGS, const float* lnw, const float* lnb, const v4u* WF, const float* bsl, int unit, int tid) {
;     ...
;         const int c8 = lane & 7, rp = lane >> 3, col = colbase + 8 * c8;
;         v4u sl[8][2];
; #pragma unroll
;         for (int i = 0; i < 8; ++i) { const int s0 = 2 * (rp + 8 * i); sl[i][0] = *(const v4u*)(VS + (size_t)(r0 + s0) * 1024 + col); sl[i][1] = *(const v4u*)(VS + (size_t)(r0 + s0 + 1) * 1024 + col); }
;         const f32x4 lw0 = *(const f32x4*)(lnw + col), lw1 = *(const f32x4*)(lnw + col + 4), lb0 = *(const f32x4*)(lnb + col), lb1 = *(const f32x4*)(lnb + col + 4);
;         const float lw[8] = {lw0.x, lw0.y, lw0.z, lw0.w, lw1.x, lw1.y, lw1.z, lw1.w}, lb[8] = {lb0.x, lb0.y, lb0.z, lb0.w, lb1.x, lb1.y, lb1.z, lb1.w};
;         __syncthreads();
;         LAS unsigned char* wbase = vt + c8 * SGU_VP + rp * 4;
; #pragma unroll
;         for (int i = 0; i < 8; ++i) {
;             const f32x4 st4 = *(const LAS f32x4*)(stat + 4 * (rp + 8 * i));
;             const v4u w0 = sl[i][0], w1 = sl[i][1];
;             const unsigned A0[4] = {w0.x, w0.y, w0.z, w0.w}, A1[4] = {w1.x, w1.y, w1.z, w1.w};
; #pragma unroll
;             for (int e = 0; e < 8; ++e) { typedef float f32x2p __attribute__((ext_vector_type(2)));
;                 f32x2p v; v.x = (e & 1) ? bf_hi(A0[e >> 1]) : bf_lo(A0[e >> 1]); v.y = (e & 1) ? bf_hi(A1[e >> 1]) : bf_lo(A1[e >> 1]);
;                 const f32x2p mn = {st4.x, st4.z}, rs = {st4.y, st4.w};
;                 const f32x2p o = ((v - mn) * rs) * lw[e] + lb[e];
;                 *(LAS unsigned*)(wbase + e * 8 * SGU_VP + i * 32) = cvt_pk_bf16(o.x, o.y); }
.LBB0_498:
	s_or_b64 exec, exec, s[14:15]
	v_mov_b32_e32 v122, v222
	v_mov_b32_e32 v123, v223
	v_mov_b32_e32 v124, v224
	v_mov_b32_e32 v125, v225
	v_mov_b32_e32 v126, v226
	v_mov_b32_e32 v127, v227
	v_mov_b32_e32 v128, v228
	v_mov_b32_e32 v129, v229
	v_mov_b32_e32 v114, v230
	v_mov_b32_e32 v115, v231
	v_mov_b32_e32 v116, v232
	v_mov_b32_e32 v117, v233
	v_mov_b32_e32 v118, v234
	v_mov_b32_e32 v119, v235
	v_mov_b32_e32 v120, v236
	v_mov_b32_e32 v121, v237
	v_mov_b32_e32 v106, v238
	v_mov_b32_e32 v107, v239
	v_mov_b32_e32 v108, v240
	v_mov_b32_e32 v109, v241
	v_mov_b32_e32 v110, v242
	v_mov_b32_e32 v111, v243
	v_mov_b32_e32 v112, v244
	v_mov_b32_e32 v113, v245
	v_or_b32_e32 v158, v82, v168
	v_or_b32_e32 v82, v158, v170
	v_lshl_or_b32 v84, s16, 11, v181
	v_mov_b32_e32 v85, v147
	v_ashrrev_i32_e32 v83, 31, v82
	v_lshl_add_u64 v[84:85], s[48:49], 0, v[84:85]
	v_lshl_add_u64 v[90:91], v[82:83], 1, v[84:85]
	v_lshlrev_b64 v[82:83], 2, v[82:83]
	s_waitcnt lgkmcnt(0)
	v_lshl_add_u64 v[84:85], s[30:31], 0, v[82:83]
	v_lshl_add_u64 v[86:87], s[50:51], 0, v[82:83]
	global_load_dwordx4 v[98:101], v[86:87], off
	global_load_dwordx4 v[102:105], v[84:85], off
	s_nop 0
	global_load_dwordx4 v[82:85], v[84:85], off offset:16
	s_nop 0
	global_load_dwordx4 v[86:89], v[86:87], off offset:16
	v_add_co_u32_e32 v92, vcc, 0x8000, v90
	s_mov_b64 s[14:15], 0
	s_nop 0
	v_addc_co_u32_e32 v93, vcc, 0, v91, vcc
	v_add_co_u32_e32 v94, vcc, 0x10000, v90
	s_waitcnt vmcnt(7)
	v_and_b32_e32 v228, 0xffff0000, v206
	v_addc_co_u32_e32 v95, vcc, 0, v91, vcc
	v_add_co_u32_e32 v92, vcc, 0x18000, v90
	s_waitcnt vmcnt(8)
	v_and_b32_e32 v229, 0xffff0000, v210
	v_addc_co_u32_e32 v93, vcc, 0, v91, vcc
	v_add_co_u32_e32 v94, vcc, 0x20000, v90
	v_addc_co_u32_e32 v95, vcc, 0, v91, vcc
	v_add_co_u32_e32 v92, vcc, 0x28000, v90
	v_addc_co_u32_e32 v93, vcc, 0, v91, vcc
	v_add_co_u32_e32 v94, vcc, 0x30000, v90
	v_addc_co_u32_e32 v95, vcc, 0, v91, vcc
	v_add_co_u32_e32 v96, vcc, 0x38000, v90
	v_addc_co_u32_e32 v97, vcc, 0, v91, vcc
	v_mov_b32_e32 v90, v248
	v_mov_b32_e32 v91, v249
	v_mov_b32_e32 v92, v250
	v_mov_b32_e32 v93, v251
	s_nop 0
	v_mov_b32_e32 v94, v252
	v_mov_b32_e32 v95, v253
	v_mov_b32_e32 v96, v254
	v_mov_b32_e32 v97, v255
	s_barrier
	ds_read_b128 v[222:225], v182
	v_lshlrev_b32_e32 v230, 16, v207
	v_lshlrev_b32_e32 v231, 16, v211
	s_waitcnt vmcnt(2)
	v_mov_b32_e32 v160, v105
	v_mov_b32_e32 v162, v101
	s_waitcnt lgkmcnt(0)
	v_mov_b32_e32 v226, v222
	v_mov_b32_e32 v227, v224
	v_mov_b32_e32 v224, v223
	v_lshlrev_b32_e32 v222, 16, v206
	v_lshlrev_b32_e32 v223, 16, v210
	v_pk_add_f32 v[222:223], v[222:223], v[226:227] neg_lo:[0,1] neg_hi:[0,1]
	v_and_b32_e32 v206, 0xffff0000, v207
	v_and_b32_e32 v207, 0xffff0000, v211
	v_pk_add_f32 v[228:229], v[228:229], v[226:227] neg_lo:[0,1] neg_hi:[0,1]
	v_pk_mul_f32 v[222:223], v[224:225], v[222:223]
	v_pk_add_f32 v[206:207], v[206:207], v[226:227] neg_lo:[0,1] neg_hi:[0,1]
	v_pk_add_f32 v[230:231], v[230:231], v[226:227] neg_lo:[0,1] neg_hi:[0,1]
	v_pk_mul_f32 v[228:229], v[224:225], v[228:229]
	v_pk_fma_f32 v[222:223], v[102:103], v[222:223], v[98:99] op_sel_hi:[0,1,0]
	v_cvt_pk_bf16_f32 v159, v222, v223
	v_pk_mul_f32 v[206:207], v[224:225], v[206:207]
	v_pk_mul_f32 v[230:231], v[224:225], v[230:231]
	v_pk_fma_f32 v[228:229], v[102:103], v[228:229], v[98:99] op_sel:[1,0,1]
	ds_write_b32 v178, v159 offset:1024
	v_cvt_pk_bf16_f32 v159, v228, v229
	v_pk_fma_f32 v[206:207], v[160:161], v[206:207], v[162:163] op_sel_hi:[0,1,0]
	v_pk_fma_f32 v[230:231], v[104:105], v[230:231], v[100:101] op_sel_hi:[0,1,0]
	ds_write_b32 v178, v159 offset:3200
	v_cvt_pk_bf16_f32 v159, v230, v231
	ds_write_b32 v178, v159 offset:5376
	v_cvt_pk_bf16_f32 v101, v206, v207
	v_lshlrev_b32_e32 v206, 16, v208
	v_lshlrev_b32_e32 v207, 16, v212
	v_pk_add_f32 v[206:207], v[206:207], v[226:227] neg_lo:[0,1] neg_hi:[0,1]
	ds_write_b32 v178, v101 offset:7552
	v_pk_mul_f32 v[206:207], v[224:225], v[206:207]
	s_waitcnt vmcnt(1)
	v_mov_b32_e32 v164, v85
	s_waitcnt vmcnt(0)
	v_pk_fma_f32 v[206:207], v[82:83], v[206:207], v[86:87] op_sel_hi:[0,1,0]
	v_cvt_pk_bf16_f32 v101, v206, v207
	v_and_b32_e32 v206, 0xffff0000, v208
	v_and_b32_e32 v207, 0xffff0000, v212
	v_pk_add_f32 v[206:207], v[206:207], v[226:227] neg_lo:[0,1] neg_hi:[0,1]
	ds_write_b32 v178, v101 offset:9728
	v_pk_mul_f32 v[206:207], v[224:225], v[206:207]
	v_mov_b32_e32 v166, v89
	v_pk_fma_f32 v[206:207], v[82:83], v[206:207], v[86:87] op_sel:[1,0,1]
	v_ashrrev_i32_e32 v159, 31, v158
	v_cvt_pk_bf16_f32 v101, v206, v207
	v_lshlrev_b32_e32 v206, 16, v209
	v_lshlrev_b32_e32 v207, 16, v213
	v_pk_add_f32 v[206:207], v[206:207], v[226:227] neg_lo:[0,1] neg_hi:[0,1]
	ds_write_b32 v178, v101 offset:11904
	v_pk_mul_f32 v[206:207], v[224:225], v[206:207]
	s_nop 0
	v_pk_fma_f32 v[206:207], v[84:85], v[206:207], v[88:89] op_sel_hi:[0,1,0]
	v_cvt_pk_bf16_f32 v101, v206, v207
	v_and_b32_e32 v206, 0xffff0000, v209
	v_and_b32_e32 v207, 0xffff0000, v213
	v_pk_add_f32 v[206:207], v[206:207], v[226:227] neg_lo:[0,1] neg_hi:[0,1]
	ds_write_b32 v178, v101 offset:14080
	v_pk_mul_f32 v[206:207], v[224:225], v[206:207]
	s_nop 0
	v_pk_fma_f32 v[206:207], v[164:165], v[206:207], v[166:167] op_sel_hi:[0,1,0]
	v_cvt_pk_bf16_f32 v85, v206, v207
	ds_write_b32 v178, v85 offset:16256
	ds_read_b128 v[206:209], v182 offset:128
	s_waitcnt lgkmcnt(0)
	v_mov_b32_e32 v210, v206
	v_mov_b32_e32 v211, v208
	v_mov_b32_e32 v208, v207
	s_waitcnt vmcnt(13)
	v_lshlrev_b32_e32 v206, 16, v214
	s_waitcnt vmcnt(12)
; __device__ __forceinline__ unsigned cvt_pk_bf16(float lo, float hi) { unsigned r; asm volatile("v_cvt_pk_bf16_f32 %0, %1, %2" : "=v"(r) : "v"(lo), "v"(hi)); return r; }
; __device__ __forceinline__ float bf_lo(unsigned w) { return __uint_as_float(w << 16); }
; __device__ __forceinline__ float bf_hi(unsigned w) { return __uint_as_float(w & 0xffff0000u); }
; #define LAS __attribute__((address_space(3)))
; __device__ __forceinline__ void sgu_unit(LAS unsigned char* lds, bf16* U, const bf16* VS, const float* SGS, const float* lnw, const float* lnb, const v4u* WF, const float* bsl, int unit, int tid) {
;     ...
;         LAS unsigned char* wbase = vt + c8 * SGU_VP + rp * 4;
; #pragma unroll
;         for (int i = 0; i < 8; ++i) {
;             const f32x4 st4 = *(const LAS f32x4*)(stat + 4 * (rp + 8 * i));
;             const v4u w0 = sl[i][0], w1 = sl[i][1];
;             const unsigned A0[4] = {w0.x, w0.y, w0.z, w0.w}, A1[4] = {w1.x, w1.y, w1.z, w1.w};
; #pragma unroll
;             for (int e = 0; e < 8; ++e) { typedef float f32x2p __attribute__((ext_vector_type(2)));
;                 f32x2p v; v.x = (e & 1) ? bf_hi(A0[e >> 1]) : bf_lo(A0[e >> 1]); v.y = (e & 1) ? bf_hi(A1[e >> 1]) : bf_lo(A1[e >> 1]);
;                 const f32x2p mn = {st4.x, st4.z}, rs = {st4.y, st4.w};
;                 const f32x2p o = ((v - mn) * rs) * lw[e] + lb[e];
;                 *(LAS unsigned*)(wbase + e * 8 * SGU_VP + i * 32) = cvt_pk_bf16(o.x, o.y); }
	v_lshlrev_b32_e32 v207, 16, v218
	v_pk_add_f32 v[206:207], v[206:207], v[210:211] neg_lo:[0,1] neg_hi:[0,1]
	s_nop 0
	v_pk_mul_f32 v[206:207], v[208:209], v[206:207]
	s_nop 0
	v_pk_fma_f32 v[206:207], v[102:103], v[206:207], v[98:99] op_sel_hi:[0,1,0]
	v_cvt_pk_bf16_f32 v85, v206, v207
	v_and_b32_e32 v206, 0xffff0000, v214
	v_and_b32_e32 v207, 0xffff0000, v218
	v_pk_add_f32 v[206:207], v[206:207], v[210:211] neg_lo:[0,1] neg_hi:[0,1]
	ds_write_b32 v178, v85 offset:1056
	v_pk_mul_f32 v[206:207], v[208:209], v[206:207]
	s_nop 0
	v_pk_fma_f32 v[206:207], v[102:103], v[206:207], v[98:99] op_sel:[1,0,1]
	s_nop 0
	v_cvt_pk_bf16_f32 v85, v206, v207
	v_lshlrev_b32_e32 v206, 16, v215
	v_lshlrev_b32_e32 v207, 16, v219
	v_pk_add_f32 v[206:207], v[206:207], v[210:211] neg_lo:[0,1] neg_hi:[0,1]
	ds_write_b32 v178, v85 offset:3232
	v_pk_mul_f32 v[206:207], v[208:209], v[206:207]
	s_nop 0
	v_pk_fma_f32 v[206:207], v[104:105], v[206:207], v[100:101] op_sel_hi:[0,1,0]
	v_cvt_pk_bf16_f32 v85, v206, v207
	v_and_b32_e32 v206, 0xffff0000, v215
	v_and_b32_e32 v207, 0xffff0000, v219
	v_pk_add_f32 v[206:207], v[206:207], v[210:211] neg_lo:[0,1] neg_hi:[0,1]
	ds_write_b32 v178, v85 offset:5408
	v_pk_mul_f32 v[206:207], v[208:209], v[206:207]
	s_nop 0
	v_pk_fma_f32 v[206:207], v[160:161], v[206:207], v[162:163] op_sel_hi:[0,1,0]
	v_cvt_pk_bf16_f32 v85, v206, v207
	v_lshlrev_b32_e32 v206, 16, v216
	v_lshlrev_b32_e32 v207, 16, v220
	v_pk_add_f32 v[206:207], v[206:207], v[210:211] neg_lo:[0,1] neg_hi:[0,1]
	ds_write_b32 v178, v85 offset:7584
	v_pk_mul_f32 v[206:207], v[208:209], v[206:207]
	s_nop 0
	v_pk_fma_f32 v[206:207], v[82:83], v[206:207], v[86:87] op_sel_hi:[0,1,0]
	v_cvt_pk_bf16_f32 v85, v206, v207
	v_and_b32_e32 v206, 0xffff0000, v216
	v_and_b32_e32 v207, 0xffff0000, v220
	v_pk_add_f32 v[206:207], v[206:207], v[210:211] neg_lo:[0,1] neg_hi:[0,1]
	ds_write_b32 v178, v85 offset:9760
	v_pk_mul_f32 v[206:207], v[208:209], v[206:207]
	s_nop 0
	v_pk_fma_f32 v[206:207], v[82:83], v[206:207], v[86:87] op_sel:[1,0,1]
	s_nop 0
	v_cvt_pk_bf16_f32 v85, v206, v207
	v_lshlrev_b32_e32 v206, 16, v217
	v_lshlrev_b32_e32 v207, 16, v221
	v_pk_add_f32 v[206:207], v[206:207], v[210:211] neg_lo:[0,1] neg_hi:[0,1]
	ds_write_b32 v178, v85 offset:11936
	v_pk_mul_f32 v[206:207], v[208:209], v[206:207]
	s_nop 0
	v_pk_fma_f32 v[206:207], v[84:85], v[206:207], v[88:89] op_sel_hi:[0,1,0]
	v_cvt_pk_bf16_f32 v85, v206, v207
	v_and_b32_e32 v206, 0xffff0000, v217
	v_and_b32_e32 v207, 0xffff0000, v221
	v_pk_add_f32 v[206:207], v[206:207], v[210:211] neg_lo:[0,1] neg_hi:[0,1]
	ds_write_b32 v178, v85 offset:14112
	v_pk_mul_f32 v[206:207], v[208:209], v[206:207]
	s_nop 0
	v_pk_fma_f32 v[206:207], v[164:165], v[206:207], v[166:167] op_sel_hi:[0,1,0]
	v_cvt_pk_bf16_f32 v85, v206, v207
	ds_write_b32 v178, v85 offset:16288
	ds_read_b128 v[206:209], v182 offset:256
	s_waitcnt lgkmcnt(0)
	v_mov_b32_e32 v210, v206
	v_mov_b32_e32 v211, v208
	v_mov_b32_e32 v208, v207
	s_waitcnt vmcnt(11)
	v_lshlrev_b32_e32 v206, 16, v138
	s_waitcnt vmcnt(10)
	v_lshlrev_b32_e32 v207, 16, v142
	v_pk_add_f32 v[206:207], v[206:207], v[210:211] neg_lo:[0,1] neg_hi:[0,1]
	s_nop 0
	v_pk_mul_f32 v[206:207], v[208:209], v[206:207]
	s_nop 0
	v_pk_fma_f32 v[206:207], v[102:103], v[206:207], v[98:99] op_sel_hi:[0,1,0]
	v_cvt_pk_bf16_f32 v85, v206, v207
	v_and_b32_e32 v206, 0xffff0000, v138
	v_and_b32_e32 v207, 0xffff0000, v142
	v_pk_add_f32 v[206:207], v[206:207], v[210:211] neg_lo:[0,1] neg_hi:[0,1]
	ds_write_b32 v178, v85 offset:1088
	v_pk_mul_f32 v[206:207], v[208:209], v[206:207]
	v_and_b32_e32 v138, 0xffff0000, v139
	v_pk_fma_f32 v[206:207], v[102:103], v[206:207], v[98:99] op_sel:[1,0,1]
	s_nop 0
	v_cvt_pk_bf16_f32 v85, v206, v207
	v_lshlrev_b32_e32 v206, 16, v139
	v_lshlrev_b32_e32 v207, 16, v143
	v_and_b32_e32 v139, 0xffff0000, v143
	v_pk_add_f32 v[206:207], v[206:207], v[210:211] neg_lo:[0,1] neg_hi:[0,1]
	v_pk_add_f32 v[138:139], v[138:139], v[210:211] neg_lo:[0,1] neg_hi:[0,1]
	v_pk_mul_f32 v[206:207], v[208:209], v[206:207]
	v_pk_mul_f32 v[138:139], v[208:209], v[138:139]
	ds_write_b32 v178, v85 offset:3264
	v_pk_fma_f32 v[206:207], v[104:105], v[206:207], v[100:101] op_sel_hi:[0,1,0]
	v_cvt_pk_bf16_f32 v85, v206, v207
	v_pk_fma_f32 v[138:139], v[160:161], v[138:139], v[162:163] op_sel_hi:[0,1,0]
	ds_write_b32 v178, v85 offset:5440
	v_cvt_pk_bf16_f32 v85, v138, v139
	v_lshlrev_b32_e32 v138, 16, v140
	v_lshlrev_b32_e32 v139, 16, v144
	v_pk_add_f32 v[138:139], v[138:139], v[210:211] neg_lo:[0,1] neg_hi:[0,1]
	ds_write_b32 v178, v85 offset:7616
	v_pk_mul_f32 v[138:139], v[208:209], v[138:139]
	s_nop 0
	v_pk_fma_f32 v[138:139], v[82:83], v[138:139], v[86:87] op_sel_hi:[0,1,0]
	v_cvt_pk_bf16_f32 v85, v138, v139
	v_and_b32_e32 v138, 0xffff0000, v140
	v_and_b32_e32 v139, 0xffff0000, v144
	v_pk_add_f32 v[138:139], v[138:139], v[210:211] neg_lo:[0,1] neg_hi:[0,1]
	ds_write_b32 v178, v85 offset:9792
	v_pk_mul_f32 v[138:139], v[208:209], v[138:139]
	s_nop 0
	v_pk_fma_f32 v[138:139], v[82:83], v[138:139], v[86:87] op_sel:[1,0,1]
	s_nop 0
	v_cvt_pk_bf16_f32 v85, v138, v139
	v_lshlrev_b32_e32 v138, 16, v141
	v_lshlrev_b32_e32 v139, 16, v145
	v_pk_add_f32 v[138:139], v[138:139], v[210:211] neg_lo:[0,1] neg_hi:[0,1]
	ds_write_b32 v178, v85 offset:11968
	v_pk_mul_f32 v[138:139], v[208:209], v[138:139]
	s_nop 0
	v_pk_fma_f32 v[138:139], v[84:85], v[138:139], v[88:89] op_sel_hi:[0,1,0]
	v_cvt_pk_bf16_f32 v85, v138, v139
	v_and_b32_e32 v138, 0xffff0000, v141
	v_and_b32_e32 v139, 0xffff0000, v145
	v_pk_add_f32 v[138:139], v[138:139], v[210:211] neg_lo:[0,1] neg_hi:[0,1]
	ds_write_b32 v178, v85 offset:14144
	v_pk_mul_f32 v[138:139], v[208:209], v[138:139]
	s_nop 0
	v_pk_fma_f32 v[138:139], v[164:165], v[138:139], v[166:167] op_sel_hi:[0,1,0]
	v_cvt_pk_bf16_f32 v85, v138, v139
	ds_write_b32 v178, v85 offset:16320
	ds_read_b128 v[138:141], v182 offset:384
	s_waitcnt lgkmcnt(0)
; __device__ __forceinline__ unsigned cvt_pk_bf16(float lo, float hi) { unsigned r; asm volatile("v_cvt_pk_bf16_f32 %0, %1, %2" : "=v"(r) : "v"(lo), "v"(hi)); return r; }
; __device__ __forceinline__ float bf_lo(unsigned w) { return __uint_as_float(w << 16); }
; __device__ __forceinline__ float bf_hi(unsigned w) { return __uint_as_float(w & 0xffff0000u); }
; #define LAS __attribute__((address_space(3)))
; __device__ __forceinline__ void sgu_unit(LAS unsigned char* lds, bf16* U, const bf16* VS, const float* SGS, const float* lnw, const float* lnb, const v4u* WF, const float* bsl, int unit, int tid) {
;     ...
;         LAS unsigned char* wbase = vt + c8 * SGU_VP + rp * 4;
; #pragma unroll
;         for (int i = 0; i < 8; ++i) {
;             const f32x4 st4 = *(const LAS f32x4*)(stat + 4 * (rp + 8 * i));
;             const v4u w0 = sl[i][0], w1 = sl[i][1];
;             const unsigned A0[4] = {w0.x, w0.y, w0.z, w0.w}, A1[4] = {w1.x, w1.y, w1.z, w1.w};
; #pragma unroll
;             for (int e = 0; e < 8; ++e) { typedef float f32x2p __attribute__((ext_vector_type(2)));
;                 f32x2p v; v.x = (e & 1) ? bf_hi(A0[e >> 1]) : bf_lo(A0[e >> 1]); v.y = (e & 1) ? bf_hi(A1[e >> 1]) : bf_lo(A1[e >> 1]);
;                 const f32x2p mn = {st4.x, st4.z}, rs = {st4.y, st4.w};
;                 const f32x2p o = ((v - mn) * rs) * lw[e] + lb[e];
;                 *(LAS unsigned*)(wbase + e * 8 * SGU_VP + i * 32) = cvt_pk_bf16(o.x, o.y); }
	v_mov_b32_e32 v142, v138
	v_mov_b32_e32 v143, v140
	v_mov_b32_e32 v140, v139
	s_waitcnt vmcnt(9)
	v_lshlrev_b32_e32 v138, 16, v130
	s_waitcnt vmcnt(8)
	v_lshlrev_b32_e32 v139, 16, v134
	v_pk_add_f32 v[138:139], v[138:139], v[142:143] neg_lo:[0,1] neg_hi:[0,1]
	s_nop 0
	v_pk_mul_f32 v[138:139], v[140:141], v[138:139]
	s_nop 0
	v_pk_fma_f32 v[138:139], v[102:103], v[138:139], v[98:99] op_sel_hi:[0,1,0]
	v_cvt_pk_bf16_f32 v85, v138, v139
	v_and_b32_e32 v138, 0xffff0000, v130
	v_and_b32_e32 v139, 0xffff0000, v134
	v_pk_add_f32 v[138:139], v[138:139], v[142:143] neg_lo:[0,1] neg_hi:[0,1]
	ds_write_b32 v178, v85 offset:1120
	v_pk_mul_f32 v[138:139], v[140:141], v[138:139]
	v_and_b32_e32 v130, 0xffff0000, v131
	v_pk_fma_f32 v[138:139], v[102:103], v[138:139], v[98:99] op_sel:[1,0,1]
	s_nop 0
	v_cvt_pk_bf16_f32 v85, v138, v139
	v_lshlrev_b32_e32 v138, 16, v131
	v_lshlrev_b32_e32 v139, 16, v135
	v_and_b32_e32 v131, 0xffff0000, v135
	v_pk_add_f32 v[138:139], v[138:139], v[142:143] neg_lo:[0,1] neg_hi:[0,1]
	v_pk_add_f32 v[130:131], v[130:131], v[142:143] neg_lo:[0,1] neg_hi:[0,1]
	v_pk_mul_f32 v[138:139], v[140:141], v[138:139]
	v_pk_mul_f32 v[130:131], v[140:141], v[130:131]
	ds_write_b32 v178, v85 offset:3296
	v_pk_fma_f32 v[138:139], v[104:105], v[138:139], v[100:101] op_sel_hi:[0,1,0]
	v_cvt_pk_bf16_f32 v85, v138, v139
	v_pk_fma_f32 v[130:131], v[160:161], v[130:131], v[162:163] op_sel_hi:[0,1,0]
	ds_write_b32 v178, v85 offset:5472
	v_cvt_pk_bf16_f32 v85, v130, v131
	v_lshlrev_b32_e32 v130, 16, v132
	v_lshlrev_b32_e32 v131, 16, v136
	v_pk_add_f32 v[130:131], v[130:131], v[142:143] neg_lo:[0,1] neg_hi:[0,1]
	ds_write_b32 v178, v85 offset:7648
	v_pk_mul_f32 v[130:131], v[140:141], v[130:131]
	s_nop 0
	v_pk_fma_f32 v[130:131], v[82:83], v[130:131], v[86:87] op_sel_hi:[0,1,0]
	v_cvt_pk_bf16_f32 v85, v130, v131
	v_and_b32_e32 v130, 0xffff0000, v132
	v_and_b32_e32 v131, 0xffff0000, v136
	v_pk_add_f32 v[130:131], v[130:131], v[142:143] neg_lo:[0,1] neg_hi:[0,1]
	ds_write_b32 v178, v85 offset:9824
	v_pk_mul_f32 v[130:131], v[140:141], v[130:131]
	s_nop 0
	v_pk_fma_f32 v[130:131], v[82:83], v[130:131], v[86:87] op_sel:[1,0,1]
	s_nop 0
	v_cvt_pk_bf16_f32 v85, v130, v131
	v_lshlrev_b32_e32 v130, 16, v133
	v_lshlrev_b32_e32 v131, 16, v137
	v_pk_add_f32 v[130:131], v[130:131], v[142:143] neg_lo:[0,1] neg_hi:[0,1]
	ds_write_b32 v178, v85 offset:12000
	v_pk_mul_f32 v[130:131], v[140:141], v[130:131]
	s_nop 0
	v_pk_fma_f32 v[130:131], v[84:85], v[130:131], v[88:89] op_sel_hi:[0,1,0]
	v_cvt_pk_bf16_f32 v85, v130, v131
	v_and_b32_e32 v130, 0xffff0000, v133
	v_and_b32_e32 v131, 0xffff0000, v137
	v_pk_add_f32 v[130:131], v[130:131], v[142:143] neg_lo:[0,1] neg_hi:[0,1]
	ds_write_b32 v178, v85 offset:14176
	v_pk_mul_f32 v[130:131], v[140:141], v[130:131]
	s_nop 0
	v_pk_fma_f32 v[130:131], v[164:165], v[130:131], v[166:167] op_sel_hi:[0,1,0]
	v_cvt_pk_bf16_f32 v85, v130, v131
	ds_write_b32 v178, v85 offset:16352
	ds_read_b128 v[130:133], v182 offset:512
	s_waitcnt lgkmcnt(0)
	v_mov_b32_e32 v134, v130
	v_mov_b32_e32 v135, v132
	v_mov_b32_e32 v132, v131
	s_waitcnt vmcnt(7)
	v_lshlrev_b32_e32 v130, 16, v122
	s_waitcnt vmcnt(6)
	v_lshlrev_b32_e32 v131, 16, v126
	v_pk_add_f32 v[130:131], v[130:131], v[134:135] neg_lo:[0,1] neg_hi:[0,1]
	s_nop 0
	v_pk_mul_f32 v[130:131], v[132:133], v[130:131]
	s_nop 0
	v_pk_fma_f32 v[130:131], v[102:103], v[130:131], v[98:99] op_sel_hi:[0,1,0]
	v_cvt_pk_bf16_f32 v85, v130, v131
	v_and_b32_e32 v130, 0xffff0000, v122
	v_and_b32_e32 v131, 0xffff0000, v126
	v_pk_add_f32 v[130:131], v[130:131], v[134:135] neg_lo:[0,1] neg_hi:[0,1]
	ds_write_b32 v178, v85 offset:1152
	v_pk_mul_f32 v[130:131], v[132:133], v[130:131]
	v_and_b32_e32 v122, 0xffff0000, v123
	v_pk_fma_f32 v[130:131], v[102:103], v[130:131], v[98:99] op_sel:[1,0,1]
	s_nop 0
	v_cvt_pk_bf16_f32 v85, v130, v131
	v_lshlrev_b32_e32 v130, 16, v123
	v_lshlrev_b32_e32 v131, 16, v127
	v_and_b32_e32 v123, 0xffff0000, v127
	v_pk_add_f32 v[130:131], v[130:131], v[134:135] neg_lo:[0,1] neg_hi:[0,1]
	v_pk_add_f32 v[122:123], v[122:123], v[134:135] neg_lo:[0,1] neg_hi:[0,1]
	v_pk_mul_f32 v[130:131], v[132:133], v[130:131]
	v_pk_mul_f32 v[122:123], v[132:133], v[122:123]
	ds_write_b32 v178, v85 offset:3328
	v_pk_fma_f32 v[130:131], v[104:105], v[130:131], v[100:101] op_sel_hi:[0,1,0]
	v_cvt_pk_bf16_f32 v85, v130, v131
	v_pk_fma_f32 v[122:123], v[160:161], v[122:123], v[162:163] op_sel_hi:[0,1,0]
	ds_write_b32 v178, v85 offset:5504
	v_cvt_pk_bf16_f32 v85, v122, v123
	v_lshlrev_b32_e32 v122, 16, v124
	v_lshlrev_b32_e32 v123, 16, v128
	v_pk_add_f32 v[122:123], v[122:123], v[134:135] neg_lo:[0,1] neg_hi:[0,1]
	ds_write_b32 v178, v85 offset:7680
	v_pk_mul_f32 v[122:123], v[132:133], v[122:123]
	s_nop 0
	v_pk_fma_f32 v[122:123], v[82:83], v[122:123], v[86:87] op_sel_hi:[0,1,0]
	v_cvt_pk_bf16_f32 v85, v122, v123
	v_and_b32_e32 v122, 0xffff0000, v124
	v_and_b32_e32 v123, 0xffff0000, v128
	v_pk_add_f32 v[122:123], v[122:123], v[134:135] neg_lo:[0,1] neg_hi:[0,1]
	ds_write_b32 v178, v85 offset:9856
	v_pk_mul_f32 v[122:123], v[132:133], v[122:123]
	s_nop 0
	v_pk_fma_f32 v[122:123], v[82:83], v[122:123], v[86:87] op_sel:[1,0,1]
	s_nop 0
	v_cvt_pk_bf16_f32 v85, v122, v123
	v_lshlrev_b32_e32 v122, 16, v125
	v_lshlrev_b32_e32 v123, 16, v129
	v_pk_add_f32 v[122:123], v[122:123], v[134:135] neg_lo:[0,1] neg_hi:[0,1]
	ds_write_b32 v178, v85 offset:12032
	v_pk_mul_f32 v[122:123], v[132:133], v[122:123]
	s_nop 0
	v_pk_fma_f32 v[122:123], v[84:85], v[122:123], v[88:89] op_sel_hi:[0,1,0]
	v_cvt_pk_bf16_f32 v85, v122, v123
	v_and_b32_e32 v122, 0xffff0000, v125
	v_and_b32_e32 v123, 0xffff0000, v129
	v_pk_add_f32 v[122:123], v[122:123], v[134:135] neg_lo:[0,1] neg_hi:[0,1]
	ds_write_b32 v178, v85 offset:14208
	v_pk_mul_f32 v[122:123], v[132:133], v[122:123]
	s_nop 0
	v_pk_fma_f32 v[122:123], v[164:165], v[122:123], v[166:167] op_sel_hi:[0,1,0]
	v_cvt_pk_bf16_f32 v85, v122, v123
	ds_write_b32 v178, v85 offset:16384
	ds_read_b128 v[122:125], v182 offset:640
	s_waitcnt lgkmcnt(0)
; __device__ __forceinline__ unsigned cvt_pk_bf16(float lo, float hi) { unsigned r; asm volatile("v_cvt_pk_bf16_f32 %0, %1, %2" : "=v"(r) : "v"(lo), "v"(hi)); return r; }
; __device__ __forceinline__ float bf_lo(unsigned w) { return __uint_as_float(w << 16); }
; __device__ __forceinline__ float bf_hi(unsigned w) { return __uint_as_float(w & 0xffff0000u); }
; #define LAS __attribute__((address_space(3)))
; __device__ __forceinline__ void sgu_unit(LAS unsigned char* lds, bf16* U, const bf16* VS, const float* SGS, const float* lnw, const float* lnb, const v4u* WF, const float* bsl, int unit, int tid) {
;     ...
;         LAS unsigned char* wbase = vt + c8 * SGU_VP + rp * 4;
; #pragma unroll
;         for (int i = 0; i < 8; ++i) {
;             const f32x4 st4 = *(const LAS f32x4*)(stat + 4 * (rp + 8 * i));
;             const v4u w0 = sl[i][0], w1 = sl[i][1];
;             const unsigned A0[4] = {w0.x, w0.y, w0.z, w0.w}, A1[4] = {w1.x, w1.y, w1.z, w1.w};
; #pragma unroll
;             for (int e = 0; e < 8; ++e) { typedef float f32x2p __attribute__((ext_vector_type(2)));
;                 f32x2p v; v.x = (e & 1) ? bf_hi(A0[e >> 1]) : bf_lo(A0[e >> 1]); v.y = (e & 1) ? bf_hi(A1[e >> 1]) : bf_lo(A1[e >> 1]);
;                 const f32x2p mn = {st4.x, st4.z}, rs = {st4.y, st4.w};
;                 const f32x2p o = ((v - mn) * rs) * lw[e] + lb[e];
;                 *(LAS unsigned*)(wbase + e * 8 * SGU_VP + i * 32) = cvt_pk_bf16(o.x, o.y); }
	v_mov_b32_e32 v126, v122
	v_mov_b32_e32 v127, v124
	v_mov_b32_e32 v124, v123
	s_waitcnt vmcnt(5)
	v_lshlrev_b32_e32 v122, 16, v114
	s_waitcnt vmcnt(4)
	v_lshlrev_b32_e32 v123, 16, v118
	v_pk_add_f32 v[122:123], v[122:123], v[126:127] neg_lo:[0,1] neg_hi:[0,1]
	s_nop 0
	v_pk_mul_f32 v[122:123], v[124:125], v[122:123]
	s_nop 0
	v_pk_fma_f32 v[122:123], v[102:103], v[122:123], v[98:99] op_sel_hi:[0,1,0]
	v_cvt_pk_bf16_f32 v85, v122, v123
	v_and_b32_e32 v122, 0xffff0000, v114
	v_and_b32_e32 v123, 0xffff0000, v118
	v_pk_add_f32 v[122:123], v[122:123], v[126:127] neg_lo:[0,1] neg_hi:[0,1]
	ds_write_b32 v178, v85 offset:1184
	v_pk_mul_f32 v[122:123], v[124:125], v[122:123]
	v_and_b32_e32 v114, 0xffff0000, v115
	v_pk_fma_f32 v[122:123], v[102:103], v[122:123], v[98:99] op_sel:[1,0,1]
	s_nop 0
	v_cvt_pk_bf16_f32 v85, v122, v123
	v_lshlrev_b32_e32 v122, 16, v115
	v_lshlrev_b32_e32 v123, 16, v119
	v_and_b32_e32 v115, 0xffff0000, v119
	v_pk_add_f32 v[122:123], v[122:123], v[126:127] neg_lo:[0,1] neg_hi:[0,1]
	v_pk_add_f32 v[114:115], v[114:115], v[126:127] neg_lo:[0,1] neg_hi:[0,1]
	v_pk_mul_f32 v[122:123], v[124:125], v[122:123]
	v_pk_mul_f32 v[114:115], v[124:125], v[114:115]
	ds_write_b32 v178, v85 offset:3360
	v_pk_fma_f32 v[122:123], v[104:105], v[122:123], v[100:101] op_sel_hi:[0,1,0]
	v_cvt_pk_bf16_f32 v85, v122, v123
	v_pk_fma_f32 v[114:115], v[160:161], v[114:115], v[162:163] op_sel_hi:[0,1,0]
	ds_write_b32 v178, v85 offset:5536
	v_cvt_pk_bf16_f32 v85, v114, v115
	v_lshlrev_b32_e32 v114, 16, v116
	v_lshlrev_b32_e32 v115, 16, v120
	v_pk_add_f32 v[114:115], v[114:115], v[126:127] neg_lo:[0,1] neg_hi:[0,1]
	ds_write_b32 v178, v85 offset:7712
	v_pk_mul_f32 v[114:115], v[124:125], v[114:115]
	s_nop 0
	v_pk_fma_f32 v[114:115], v[82:83], v[114:115], v[86:87] op_sel_hi:[0,1,0]
	v_cvt_pk_bf16_f32 v85, v114, v115
	v_and_b32_e32 v114, 0xffff0000, v116
	v_and_b32_e32 v115, 0xffff0000, v120
	v_pk_add_f32 v[114:115], v[114:115], v[126:127] neg_lo:[0,1] neg_hi:[0,1]
	ds_write_b32 v178, v85 offset:9888
	v_pk_mul_f32 v[114:115], v[124:125], v[114:115]
	s_nop 0
	v_pk_fma_f32 v[114:115], v[82:83], v[114:115], v[86:87] op_sel:[1,0,1]
	s_nop 0
	v_cvt_pk_bf16_f32 v85, v114, v115
	v_lshlrev_b32_e32 v114, 16, v117
	v_lshlrev_b32_e32 v115, 16, v121
	v_pk_add_f32 v[114:115], v[114:115], v[126:127] neg_lo:[0,1] neg_hi:[0,1]
	ds_write_b32 v178, v85 offset:12064
	v_pk_mul_f32 v[114:115], v[124:125], v[114:115]
	s_nop 0
	v_pk_fma_f32 v[114:115], v[84:85], v[114:115], v[88:89] op_sel_hi:[0,1,0]
	v_cvt_pk_bf16_f32 v85, v114, v115
	v_and_b32_e32 v114, 0xffff0000, v117
	v_and_b32_e32 v115, 0xffff0000, v121
	v_pk_add_f32 v[114:115], v[114:115], v[126:127] neg_lo:[0,1] neg_hi:[0,1]
	ds_write_b32 v178, v85 offset:14240
	v_pk_mul_f32 v[114:115], v[124:125], v[114:115]
	s_nop 0
	v_pk_fma_f32 v[114:115], v[164:165], v[114:115], v[166:167] op_sel_hi:[0,1,0]
	v_cvt_pk_bf16_f32 v85, v114, v115
	ds_write_b32 v178, v85 offset:16416
	ds_read_b128 v[114:117], v182 offset:768
	s_waitcnt lgkmcnt(0)
	v_mov_b32_e32 v118, v114
	v_mov_b32_e32 v119, v116
	v_mov_b32_e32 v116, v115
	s_waitcnt vmcnt(3)
	v_lshlrev_b32_e32 v114, 16, v106
	s_waitcnt vmcnt(2)
	v_lshlrev_b32_e32 v115, 16, v110
	v_pk_add_f32 v[114:115], v[114:115], v[118:119] neg_lo:[0,1] neg_hi:[0,1]
	s_nop 0
	v_pk_mul_f32 v[114:115], v[116:117], v[114:115]
	s_nop 0
	v_pk_fma_f32 v[114:115], v[102:103], v[114:115], v[98:99] op_sel_hi:[0,1,0]
	v_cvt_pk_bf16_f32 v85, v114, v115
	v_and_b32_e32 v114, 0xffff0000, v106
	v_and_b32_e32 v115, 0xffff0000, v110
	v_pk_add_f32 v[114:115], v[114:115], v[118:119] neg_lo:[0,1] neg_hi:[0,1]
	ds_write_b32 v178, v85 offset:1216
	v_pk_mul_f32 v[114:115], v[116:117], v[114:115]
	v_and_b32_e32 v106, 0xffff0000, v107
	v_pk_fma_f32 v[114:115], v[102:103], v[114:115], v[98:99] op_sel:[1,0,1]
	s_nop 0
	v_cvt_pk_bf16_f32 v85, v114, v115
	v_lshlrev_b32_e32 v114, 16, v107
	v_lshlrev_b32_e32 v115, 16, v111
	v_and_b32_e32 v107, 0xffff0000, v111
	v_pk_add_f32 v[114:115], v[114:115], v[118:119] neg_lo:[0,1] neg_hi:[0,1]
	v_pk_add_f32 v[106:107], v[106:107], v[118:119] neg_lo:[0,1] neg_hi:[0,1]
	v_pk_mul_f32 v[114:115], v[116:117], v[114:115]
	v_pk_mul_f32 v[106:107], v[116:117], v[106:107]
	ds_write_b32 v178, v85 offset:3392
	v_pk_fma_f32 v[114:115], v[104:105], v[114:115], v[100:101] op_sel_hi:[0,1,0]
	v_cvt_pk_bf16_f32 v85, v114, v115
	v_pk_fma_f32 v[106:107], v[160:161], v[106:107], v[162:163] op_sel_hi:[0,1,0]
	ds_write_b32 v178, v85 offset:5568
	v_cvt_pk_bf16_f32 v85, v106, v107
	v_lshlrev_b32_e32 v106, 16, v108
	v_lshlrev_b32_e32 v107, 16, v112
	v_pk_add_f32 v[106:107], v[106:107], v[118:119] neg_lo:[0,1] neg_hi:[0,1]
	ds_write_b32 v178, v85 offset:7744
	v_pk_mul_f32 v[106:107], v[116:117], v[106:107]
	s_nop 0
	v_pk_fma_f32 v[106:107], v[82:83], v[106:107], v[86:87] op_sel_hi:[0,1,0]
	v_cvt_pk_bf16_f32 v85, v106, v107
	v_and_b32_e32 v106, 0xffff0000, v108
	v_and_b32_e32 v107, 0xffff0000, v112
	v_pk_add_f32 v[106:107], v[106:107], v[118:119] neg_lo:[0,1] neg_hi:[0,1]
	ds_write_b32 v178, v85 offset:9920
	v_pk_mul_f32 v[106:107], v[116:117], v[106:107]
	s_nop 0
	v_pk_fma_f32 v[106:107], v[82:83], v[106:107], v[86:87] op_sel:[1,0,1]
	s_nop 0
	v_cvt_pk_bf16_f32 v85, v106, v107
	v_lshlrev_b32_e32 v106, 16, v109
	v_lshlrev_b32_e32 v107, 16, v113
	v_pk_add_f32 v[106:107], v[106:107], v[118:119] neg_lo:[0,1] neg_hi:[0,1]
	ds_write_b32 v178, v85 offset:12096
	v_pk_mul_f32 v[106:107], v[116:117], v[106:107]
	s_nop 0
	v_pk_fma_f32 v[106:107], v[84:85], v[106:107], v[88:89] op_sel_hi:[0,1,0]
	v_cvt_pk_bf16_f32 v85, v106, v107
	v_and_b32_e32 v106, 0xffff0000, v109
	v_and_b32_e32 v107, 0xffff0000, v113
	v_pk_add_f32 v[106:107], v[106:107], v[118:119] neg_lo:[0,1] neg_hi:[0,1]
	ds_write_b32 v178, v85 offset:14272
	v_pk_mul_f32 v[106:107], v[116:117], v[106:107]
	s_nop 0
	v_pk_fma_f32 v[106:107], v[164:165], v[106:107], v[166:167] op_sel_hi:[0,1,0]
	v_cvt_pk_bf16_f32 v85, v106, v107
	ds_write_b32 v178, v85 offset:16448
	ds_read_b128 v[106:109], v182 offset:896
	s_waitcnt lgkmcnt(0)
; __device__ __forceinline__ unsigned cvt_pk_bf16(float lo, float hi) { unsigned r; asm volatile("v_cvt_pk_bf16_f32 %0, %1, %2" : "=v"(r) : "v"(lo), "v"(hi)); return r; }
; __device__ __forceinline__ float bf_lo(unsigned w) { return __uint_as_float(w << 16); }
; __device__ __forceinline__ float bf_hi(unsigned w) { return __uint_as_float(w & 0xffff0000u); }
; #define LAS __attribute__((address_space(3)))
; __device__ __forceinline__ void sgu_unit(LAS unsigned char* lds, bf16* U, const bf16* VS, const float* SGS, const float* lnw, const float* lnb, const v4u* WF, const float* bsl, int unit, int tid) {
;     ...
;         for (int i = 0; i < 8; ++i) {
;             const f32x4 st4 = *(const LAS f32x4*)(stat + 4 * (rp + 8 * i));
;             const v4u w0 = sl[i][0], w1 = sl[i][1];
;             const unsigned A0[4] = {w0.x, w0.y, w0.z, w0.w}, A1[4] = {w1.x, w1.y, w1.z, w1.w};
; #pragma unroll
;             for (int e = 0; e < 8; ++e) { typedef float f32x2p __attribute__((ext_vector_type(2)));
;                 f32x2p v; v.x = (e & 1) ? bf_hi(A0[e >> 1]) : bf_lo(A0[e >> 1]); v.y = (e & 1) ? bf_hi(A1[e >> 1]) : bf_lo(A1[e >> 1]);
;                 const f32x2p mn = {st4.x, st4.z}, rs = {st4.y, st4.w};
;                 const f32x2p o = ((v - mn) * rs) * lw[e] + lb[e];
;                 *(LAS unsigned*)(wbase + e * 8 * SGU_VP + i * 32) = cvt_pk_bf16(o.x, o.y); }
;         }
;     }
;     v2u uu[8][4];
; #pragma unroll
;     for (int mt = 0; mt < 8; ++mt)
; #pragma unroll
;         for (int nt = 0; nt < 4; ++nt) uu[mt][nt] = *(const v2u*)(U + (size_t)(r0 + 16 * mt + fr) * 1024 + colbase + 16 * nt + 4 * fq);
	v_mov_b32_e32 v110, v106
	v_mov_b32_e32 v111, v108
	v_mov_b32_e32 v108, v107
	s_waitcnt vmcnt(1)
	v_lshlrev_b32_e32 v106, 16, v90
	s_waitcnt vmcnt(0)
	v_lshlrev_b32_e32 v107, 16, v94
	v_pk_add_f32 v[106:107], v[106:107], v[110:111] neg_lo:[0,1] neg_hi:[0,1]
	s_nop 0
	v_pk_mul_f32 v[106:107], v[108:109], v[106:107]
	s_nop 0
	v_pk_fma_f32 v[106:107], v[102:103], v[106:107], v[98:99] op_sel_hi:[0,1,0]
	v_cvt_pk_bf16_f32 v85, v106, v107
	v_and_b32_e32 v106, 0xffff0000, v90
	v_and_b32_e32 v107, 0xffff0000, v94
	v_pk_add_f32 v[106:107], v[106:107], v[110:111] neg_lo:[0,1] neg_hi:[0,1]
	ds_write_b32 v178, v85 offset:1248
	v_pk_mul_f32 v[106:107], v[108:109], v[106:107]
	v_and_b32_e32 v90, 0xffff0000, v91
	v_pk_fma_f32 v[98:99], v[102:103], v[106:107], v[98:99] op_sel:[1,0,1]
	s_nop 0
	v_cvt_pk_bf16_f32 v85, v98, v99
	v_lshlrev_b32_e32 v98, 16, v91
	v_lshlrev_b32_e32 v99, 16, v95
	v_and_b32_e32 v91, 0xffff0000, v95
	v_pk_add_f32 v[98:99], v[98:99], v[110:111] neg_lo:[0,1] neg_hi:[0,1]
	v_pk_add_f32 v[90:91], v[90:91], v[110:111] neg_lo:[0,1] neg_hi:[0,1]
	v_pk_mul_f32 v[98:99], v[108:109], v[98:99]
	v_pk_mul_f32 v[90:91], v[108:109], v[90:91]
	ds_write_b32 v178, v85 offset:3424
	v_pk_fma_f32 v[98:99], v[104:105], v[98:99], v[100:101] op_sel_hi:[0,1,0]
	v_cvt_pk_bf16_f32 v85, v98, v99
	v_pk_fma_f32 v[90:91], v[160:161], v[90:91], v[162:163] op_sel_hi:[0,1,0]
	ds_write_b32 v178, v85 offset:5600
	v_cvt_pk_bf16_f32 v85, v90, v91
	v_lshlrev_b32_e32 v90, 16, v92
	v_lshlrev_b32_e32 v91, 16, v96
	v_pk_add_f32 v[90:91], v[90:91], v[110:111] neg_lo:[0,1] neg_hi:[0,1]
	ds_write_b32 v178, v85 offset:7776
	v_pk_mul_f32 v[90:91], v[108:109], v[90:91]
	s_nop 0
	v_pk_fma_f32 v[90:91], v[82:83], v[90:91], v[86:87] op_sel_hi:[0,1,0]
	v_cvt_pk_bf16_f32 v85, v90, v91
	v_and_b32_e32 v90, 0xffff0000, v92
	v_and_b32_e32 v91, 0xffff0000, v96
	v_pk_add_f32 v[90:91], v[90:91], v[110:111] neg_lo:[0,1] neg_hi:[0,1]
	ds_write_b32 v178, v85 offset:9952
	v_pk_mul_f32 v[90:91], v[108:109], v[90:91]
	s_nop 0
	v_pk_fma_f32 v[82:83], v[82:83], v[90:91], v[86:87] op_sel:[1,0,1]
	s_nop 0
	v_cvt_pk_bf16_f32 v82, v82, v83
	ds_write_b32 v178, v82 offset:12128
	v_lshlrev_b32_e32 v82, 16, v93
	v_lshlrev_b32_e32 v83, 16, v97
	v_pk_add_f32 v[82:83], v[82:83], v[110:111] neg_lo:[0,1] neg_hi:[0,1]
	s_nop 0
	v_pk_mul_f32 v[82:83], v[108:109], v[82:83]
	s_nop 0
	v_pk_fma_f32 v[82:83], v[84:85], v[82:83], v[88:89] op_sel_hi:[0,1,0]
	v_cvt_pk_bf16_f32 v82, v82, v83
	ds_write_b32 v178, v82 offset:14304
	v_and_b32_e32 v82, 0xffff0000, v93
	v_and_b32_e32 v83, 0xffff0000, v97
	v_pk_add_f32 v[82:83], v[82:83], v[110:111] neg_lo:[0,1] neg_hi:[0,1]
	v_or_b32_e32 v84, s16, v163
	v_pk_mul_f32 v[82:83], v[108:109], v[82:83]
	v_lshlrev_b32_e32 v84, 11, v84
	v_pk_fma_f32 v[82:83], v[164:165], v[82:83], v[166:167] op_sel_hi:[0,1,0]
	v_cvt_pk_bf16_f32 v82, v82, v83
	ds_write_b32 v178, v82 offset:16480
	v_lshl_add_u64 v[82:83], v[158:159], 1, v[150:151]
	v_mov_b32_e32 v85, v147
	v_lshl_add_u64 v[144:145], v[82:83], 0, v[84:85]
	global_load_dwordx2 v[158:159], v[144:145], off nt
	global_load_dwordx2 v[218:219], v[144:145], off offset:32 nt
	global_load_dwordx2 v[220:221], v[144:145], off offset:64 nt
	global_load_dwordx2 v[222:223], v[144:145], off offset:96 nt
	v_add_co_u32_e32 v226, vcc, s40, v144
	s_waitcnt vmcnt(3)
	v_lshlrev_b32_e32 v160, 16, v158
	v_addc_co_u32_e32 v227, vcc, 0, v145, vcc
	global_load_dwordx2 v[224:225], v[226:227], off nt
	global_load_dwordx2 v[228:229], v[226:227], off offset:32 nt
	global_load_dwordx2 v[230:231], v[226:227], off offset:64 nt
	global_load_dwordx2 v[232:233], v[226:227], off offset:96 nt
	v_add_co_u32_e32 v130, vcc, s41, v144
	v_and_b32_e32 v158, 0xffff0000, v158
	s_nop 0
	v_addc_co_u32_e32 v131, vcc, 0, v145, vcc
	v_add_co_u32_e32 v120, vcc, s44, v144
	global_load_dwordx2 v[234:235], v[130:131], off nt
	global_load_dwordx2 v[138:139], v[130:131], off offset:32 nt
	global_load_dwordx2 v[136:137], v[130:131], off offset:64 nt
	global_load_dwordx2 v[134:135], v[130:131], off offset:96 nt
	v_addc_co_u32_e32 v121, vcc, 0, v145, vcc
	v_add_co_u32_e32 v110, vcc, s45, v144
	global_load_dwordx2 v[132:133], v[120:121], off nt
	global_load_dwordx2 v[128:129], v[120:121], off offset:32 nt
	global_load_dwordx2 v[126:127], v[120:121], off offset:64 nt
	global_load_dwordx2 v[124:125], v[120:121], off offset:96 nt
	v_addc_co_u32_e32 v111, vcc, 0, v145, vcc
	v_add_co_u32_e32 v100, vcc, s46, v144
	global_load_dwordx2 v[122:123], v[110:111], off nt
	global_load_dwordx2 v[118:119], v[110:111], off offset:32 nt
	global_load_dwordx2 v[116:117], v[110:111], off offset:64 nt
	global_load_dwordx2 v[114:115], v[110:111], off offset:96 nt
	v_addc_co_u32_e32 v101, vcc, 0, v145, vcc
	v_add_co_u32_e32 v90, vcc, s47, v144
	global_load_dwordx2 v[112:113], v[100:101], off nt
	global_load_dwordx2 v[108:109], v[100:101], off offset:32 nt
	global_load_dwordx2 v[106:107], v[100:101], off offset:64 nt
	global_load_dwordx2 v[104:105], v[100:101], off offset:96 nt
	v_addc_co_u32_e32 v91, vcc, 0, v145, vcc
	v_lshrrev_b32_e32 v236, 4, v0
	v_and_b32_e32 v236, 1, v236
	v_mul_u32_u24_e32 v236, 24, v236
	v_mov_b32_e32 v237, 0
	v_add_co_u32_e32 v82, vcc, s59, v144
	global_load_dwordx2 v[102:103], v[90:91], off nt
	global_load_dwordx2 v[98:99], v[90:91], off offset:32 nt
	global_load_dwordx2 v[96:97], v[90:91], off offset:64 nt
	global_load_dwordx2 v[94:95], v[90:91], off offset:96 nt
	v_addc_co_u32_e32 v83, vcc, 0, v145, vcc
	global_load_dwordx2 v[92:93], v[82:83], off nt
	global_load_dwordx2 v[88:89], v[82:83], off offset:32 nt
	global_load_dwordx2 v[86:87], v[82:83], off offset:64 nt
	global_load_dwordx2 v[84:85], v[82:83], off offset:96 nt
	s_waitcnt lgkmcnt(0)
; __device__ __forceinline__ unsigned cvt_pk_bf16(float lo, float hi) { unsigned r; asm volatile("v_cvt_pk_bf16_f32 %0, %1, %2" : "=v"(r) : "v"(lo), "v"(hi)); return r; }
; __device__ __forceinline__ float bf_lo(unsigned w) { return __uint_as_float(w << 16); }
; __device__ __forceinline__ float bf_hi(unsigned w) { return __uint_as_float(w & 0xffff0000u); }
; #define LAS __attribute__((address_space(3)))
; __device__ __forceinline__ void sgu_unit(LAS unsigned char* lds, bf16* U, const bf16* VS, const float* SGS, const float* lnw, const float* lnb, const v4u* WF, const float* bsl, int unit, int tid) {
;     ...
;     {
;         int q = 0;
; #pragma unroll
;         for (int mt = 0; mt < 8; ++mt) {
;             const int t = 16 * mt + fr;
;             f32x4 acc[4];
; #pragma unroll
;             for (int nt = 0; nt < 4; ++nt) acc[nt] = (f32x4){0.f, 0.f, 0.f, 0.f};
; #pragma unroll
;             for (int ks = 0; ks <= (mt >> 1); ++ks) {
;                 const int sb = 32 * ks + 8 * fq; const bf16x8_t wf = __builtin_bit_cast(bf16x8_t, wfr[q++]);
; #pragma unroll
;                 for (int nt = 0; nt < 4; ++nt) { const bf16x8_t vf = *(const LAS bf16x8_t*)(vt + ((fr >> 3) + 8 * (fr & 7) + 2 * nt) * SGU_VP + sb * 2);
;                     acc[nt] = __builtin_amdgcn_mfma_f32_16x16x32_bf16(vf, wf, acc[nt], 0, 0, 0); }
;             }
;             const float bb = bbv[mt];
; #pragma unroll
;             for (int nt = 0; nt < 4; ++nt) { const v2u u2 = uu[mt][nt]; v2u w; w.x = cvt_pk_bf16(bf_lo(u2.x) * (acc[nt][0] + bb), bf_hi(u2.x) * (acc[nt][1] + bb)); w.y = cvt_pk_bf16(bf_lo(u2.y) * (acc[nt][2] + bb), bf_hi(u2.y) * (acc[nt][3] + bb));
;                 *(v2u*)(U + (size_t)(r0 + t) * 1024 + colbase + 16 * nt + 4 * fq) = w; }
;         }
	ds_read_b128 v[140:143], v183 offset:1024
	ds_read_b128 v[206:209], v183 offset:1568
	s_waitcnt lgkmcnt(1)
	v_mfma_f32_16x16x32_bf16 v[140:143], v[140:143], v[78:81], 0
	ds_read_b128 v[210:213], v183 offset:2112
	ds_read_b128 v[214:217], v183 offset:2656
	s_nop 5
	v_add_f32_e32 v140, v198, v140
	v_add_f32_e32 v141, v198, v141
	s_waitcnt lgkmcnt(2)
	v_mfma_f32_16x16x32_bf16 v[206:209], v[206:209], v[78:81], 0
	v_mul_f32_e32 v140, v140, v160
	v_mul_f32_e32 v141, v141, v158
	v_cvt_pk_bf16_f32 v248, v140, v141
	v_lshlrev_b32_e32 v141, 16, v159
	v_add_f32_e32 v142, v198, v142
	v_mul_f32_e32 v141, v142, v141
	v_and_b32_e32 v142, 0xffff0000, v159
	v_add_f32_e32 v143, v198, v143
	v_mul_f32_e32 v142, v143, v142
	v_cvt_pk_bf16_f32 v249, v141, v142
	v_lshl_add_u64 v[238:239], v[144:145], 0, v[236:237]
	s_waitcnt vmcnt(30)
	v_lshlrev_b32_e32 v140, 16, v218
	v_add_f32_e32 v141, v198, v206
	v_mul_f32_e32 v140, v141, v140
	v_and_b32_e32 v141, 0xffff0000, v218
	v_add_f32_e32 v142, v198, v207
	s_waitcnt lgkmcnt(1)
	v_mfma_f32_16x16x32_bf16 v[210:213], v[210:213], v[78:81], 0
	v_mul_f32_e32 v141, v142, v141
	v_cvt_pk_bf16_f32 v250, v140, v141
	v_lshlrev_b32_e32 v141, 16, v219
	v_add_f32_e32 v142, v198, v208
	v_mul_f32_e32 v141, v142, v141
	v_and_b32_e32 v142, 0xffff0000, v219
	v_add_f32_e32 v143, v198, v209
	v_mul_f32_e32 v142, v143, v142
	v_cvt_pk_bf16_f32 v251, v141, v142
	s_nop 1
	v_permlane16_swap_b32_e32 v248, v250
	v_permlane16_swap_b32_e32 v249, v251
	global_store_dwordx4 v[238:239], v[248:251], off
	s_waitcnt vmcnt(30)
	v_lshlrev_b32_e32 v140, 16, v220
	v_add_f32_e32 v141, v198, v210
	s_waitcnt lgkmcnt(0)
	v_mfma_f32_16x16x32_bf16 v[78:81], v[214:217], v[78:81], 0
	v_mul_f32_e32 v140, v141, v140
	v_and_b32_e32 v141, 0xffff0000, v220
	v_add_f32_e32 v142, v198, v211
	v_mul_f32_e32 v141, v142, v141
	v_cvt_pk_bf16_f32 v252, v140, v141
	v_lshlrev_b32_e32 v141, 16, v221
	v_add_f32_e32 v142, v198, v212
	v_mul_f32_e32 v141, v142, v141
	v_and_b32_e32 v142, 0xffff0000, v221
	v_add_f32_e32 v143, v198, v213
	v_mul_f32_e32 v142, v143, v142
	v_cvt_pk_bf16_f32 v253, v141, v142
	s_waitcnt vmcnt(29)
	v_lshlrev_b32_e32 v140, 16, v222
	v_add_f32_e32 v78, v198, v78
	v_mul_f32_e32 v78, v78, v140
	v_and_b32_e32 v140, 0xffff0000, v222
	v_add_f32_e32 v79, v198, v79
	v_mul_f32_e32 v79, v79, v140
	v_cvt_pk_bf16_f32 v254, v78, v79
	v_lshlrev_b32_e32 v78, 16, v223
	v_add_f32_e32 v79, v198, v80
	v_mul_f32_e32 v78, v79, v78
	v_and_b32_e32 v79, 0xffff0000, v223
	v_add_f32_e32 v80, v198, v81
	v_mul_f32_e32 v79, v80, v79
	v_cvt_pk_bf16_f32 v255, v78, v79
	ds_read_b128 v[78:81], v183 offset:1024
	ds_read_b128 v[140:143], v183 offset:1568
	s_waitcnt lgkmcnt(1)
	v_mfma_f32_16x16x32_bf16 v[78:81], v[78:81], v[74:77], 0
	ds_read_b128 v[206:209], v183 offset:2112
	ds_read_b128 v[210:213], v183 offset:2656
	s_nop 1
	v_permlane16_swap_b32_e32 v252, v254
	v_permlane16_swap_b32_e32 v253, v255
	global_store_dwordx4 v[238:239], v[252:255], off offset:64
	s_waitcnt vmcnt(29)
	v_lshlrev_b32_e32 v144, 16, v224
	s_nop 2
	v_add_f32_e32 v78, v197, v78
	v_mul_f32_e32 v78, v78, v144
	v_and_b32_e32 v144, 0xffff0000, v224
	v_add_f32_e32 v79, v197, v79
	s_waitcnt lgkmcnt(2)
	v_mfma_f32_16x16x32_bf16 v[140:143], v[140:143], v[74:77], 0
	v_mul_f32_e32 v79, v79, v144
	v_cvt_pk_bf16_f32 v248, v78, v79
	v_lshlrev_b32_e32 v79, 16, v225
	v_add_f32_e32 v80, v197, v80
	v_mul_f32_e32 v79, v80, v79
	v_and_b32_e32 v80, 0xffff0000, v225
	v_add_f32_e32 v81, v197, v81
	v_mul_f32_e32 v80, v81, v80
	v_cvt_pk_bf16_f32 v249, v79, v80
	v_lshl_add_u64 v[238:239], v[226:227], 0, v[236:237]
	s_waitcnt vmcnt(28)
	v_lshlrev_b32_e32 v78, 16, v228
	v_add_f32_e32 v79, v197, v140
	v_mul_f32_e32 v78, v79, v78
	v_and_b32_e32 v79, 0xffff0000, v228
	v_add_f32_e32 v80, v197, v141
	s_waitcnt lgkmcnt(1)
	v_mfma_f32_16x16x32_bf16 v[206:209], v[206:209], v[74:77], 0
	v_mul_f32_e32 v79, v80, v79
	v_cvt_pk_bf16_f32 v250, v78, v79
	v_lshlrev_b32_e32 v79, 16, v229
	v_add_f32_e32 v80, v197, v142
	v_mul_f32_e32 v79, v80, v79
	v_and_b32_e32 v80, 0xffff0000, v229
	v_add_f32_e32 v81, v197, v143
	v_mul_f32_e32 v80, v81, v80
	v_cvt_pk_bf16_f32 v251, v79, v80
	s_nop 1
	v_permlane16_swap_b32_e32 v248, v250
	v_permlane16_swap_b32_e32 v249, v251
	global_store_dwordx4 v[238:239], v[248:251], off
	s_waitcnt vmcnt(28)
	v_lshlrev_b32_e32 v78, 16, v230
	v_add_f32_e32 v79, v197, v206
	s_waitcnt lgkmcnt(0)
	v_mfma_f32_16x16x32_bf16 v[74:77], v[210:213], v[74:77], 0
	v_mul_f32_e32 v78, v79, v78
	v_and_b32_e32 v79, 0xffff0000, v230
	v_add_f32_e32 v80, v197, v207
	v_mul_f32_e32 v79, v80, v79
	v_cvt_pk_bf16_f32 v252, v78, v79
	v_lshlrev_b32_e32 v79, 16, v231
	v_add_f32_e32 v80, v197, v208
	v_mul_f32_e32 v79, v80, v79
	v_and_b32_e32 v80, 0xffff0000, v231
	v_add_f32_e32 v81, v197, v209
	v_mul_f32_e32 v80, v81, v80
	v_cvt_pk_bf16_f32 v253, v79, v80
	s_waitcnt vmcnt(27)
	v_lshlrev_b32_e32 v78, 16, v232
	v_add_f32_e32 v74, v197, v74
	v_mul_f32_e32 v74, v74, v78
	v_and_b32_e32 v78, 0xffff0000, v232
	v_add_f32_e32 v75, v197, v75
	v_mul_f32_e32 v75, v75, v78
	v_cvt_pk_bf16_f32 v254, v74, v75
	v_lshlrev_b32_e32 v74, 16, v233
	v_add_f32_e32 v75, v197, v76
	v_mul_f32_e32 v74, v75, v74
	v_and_b32_e32 v75, 0xffff0000, v233
	v_add_f32_e32 v76, v197, v77
	v_mul_f32_e32 v75, v76, v75
	v_cvt_pk_bf16_f32 v255, v74, v75
	ds_read_b128 v[74:77], v183 offset:1024
	ds_read_b128 v[78:81], v183 offset:1088
	s_waitcnt lgkmcnt(1)
	v_mfma_f32_16x16x32_bf16 v[74:77], v[74:77], v[70:73], 0
	ds_read_b128 v[140:143], v183 offset:1568
	ds_read_b128 v[206:209], v183 offset:1632
	ds_read_b128 v[210:213], v183 offset:2112
	ds_read_b128 v[214:217], v183 offset:2176
	ds_read_b128 v[218:221], v183 offset:2656
	ds_read_b128 v[222:225], v183 offset:2720
	s_waitcnt lgkmcnt(5)
; __device__ __forceinline__ unsigned cvt_pk_bf16(float lo, float hi) { unsigned r; asm volatile("v_cvt_pk_bf16_f32 %0, %1, %2" : "=v"(r) : "v"(lo), "v"(hi)); return r; }
; __device__ __forceinline__ float bf_lo(unsigned w) { return __uint_as_float(w << 16); }
; __device__ __forceinline__ float bf_hi(unsigned w) { return __uint_as_float(w & 0xffff0000u); }
; #define LAS __attribute__((address_space(3)))
; __device__ __forceinline__ void sgu_unit(LAS unsigned char* lds, bf16* U, const bf16* VS, const float* SGS, const float* lnw, const float* lnb, const v4u* WF, const float* bsl, int unit, int tid) {
;     ...
;     {
;         int q = 0;
; #pragma unroll
;         for (int mt = 0; mt < 8; ++mt) {
;             const int t = 16 * mt + fr;
;             f32x4 acc[4];
; #pragma unroll
;             for (int nt = 0; nt < 4; ++nt) acc[nt] = (f32x4){0.f, 0.f, 0.f, 0.f};
; #pragma unroll
;             for (int ks = 0; ks <= (mt >> 1); ++ks) {
;                 const int sb = 32 * ks + 8 * fq; const bf16x8_t wf = __builtin_bit_cast(bf16x8_t, wfr[q++]);
; #pragma unroll
;                 for (int nt = 0; nt < 4; ++nt) { const bf16x8_t vf = *(const LAS bf16x8_t*)(vt + ((fr >> 3) + 8 * (fr & 7) + 2 * nt) * SGU_VP + sb * 2);
;                     acc[nt] = __builtin_amdgcn_mfma_f32_16x16x32_bf16(vf, wf, acc[nt], 0, 0, 0); }
;             }
;             const float bb = bbv[mt];
; #pragma unroll
;             for (int nt = 0; nt < 4; ++nt) { const v2u u2 = uu[mt][nt]; v2u w; w.x = cvt_pk_bf16(bf_lo(u2.x) * (acc[nt][0] + bb), bf_hi(u2.x) * (acc[nt][1] + bb)); w.y = cvt_pk_bf16(bf_lo(u2.y) * (acc[nt][2] + bb), bf_hi(u2.y) * (acc[nt][3] + bb));
;                 *(v2u*)(U + (size_t)(r0 + t) * 1024 + colbase + 16 * nt + 4 * fq) = w; }
;         }
	v_mfma_f32_16x16x32_bf16 v[140:143], v[140:143], v[70:73], 0
	s_nop 1
	v_permlane16_swap_b32_e32 v252, v254
	v_permlane16_swap_b32_e32 v253, v255
	global_store_dwordx4 v[238:239], v[252:255], off offset:64
	s_waitcnt lgkmcnt(3)
	v_mfma_f32_16x16x32_bf16 v[210:213], v[210:213], v[70:73], 0
	s_waitcnt lgkmcnt(1)
	v_mfma_f32_16x16x32_bf16 v[70:73], v[218:221], v[70:73], 0
	v_mfma_f32_16x16x32_bf16 v[74:77], v[78:81], v[66:69], v[74:77]
	v_mfma_f32_16x16x32_bf16 v[78:81], v[206:209], v[66:69], v[140:143]
	v_mfma_f32_16x16x32_bf16 v[140:143], v[214:217], v[66:69], v[210:213]
	s_waitcnt lgkmcnt(0)
	v_mfma_f32_16x16x32_bf16 v[66:69], v[222:225], v[66:69], v[70:73]
	s_waitcnt vmcnt(27)
	s_nop 1
	v_lshlrev_b32_e32 v70, 16, v234
	v_add_f32_e32 v71, v196, v74
	v_mul_f32_e32 v70, v71, v70
	v_and_b32_e32 v71, 0xffff0000, v234
	v_add_f32_e32 v72, v196, v75
	v_mul_f32_e32 v71, v72, v71
	v_cvt_pk_bf16_f32 v248, v70, v71
	v_lshlrev_b32_e32 v71, 16, v235
	v_add_f32_e32 v72, v196, v76
	v_mul_f32_e32 v71, v72, v71
	v_and_b32_e32 v72, 0xffff0000, v235
	v_add_f32_e32 v73, v196, v77
	v_mul_f32_e32 v72, v73, v72
	v_cvt_pk_bf16_f32 v249, v71, v72
	v_lshl_add_u64 v[238:239], v[130:131], 0, v[236:237]
	s_waitcnt vmcnt(26)
	v_lshlrev_b32_e32 v70, 16, v138
	v_add_f32_e32 v71, v196, v78
	v_mul_f32_e32 v70, v71, v70
	v_and_b32_e32 v71, 0xffff0000, v138
	v_add_f32_e32 v72, v196, v79
	v_mul_f32_e32 v71, v72, v71
	v_cvt_pk_bf16_f32 v250, v70, v71
	v_lshlrev_b32_e32 v71, 16, v139
	v_add_f32_e32 v72, v196, v80
	v_mul_f32_e32 v71, v72, v71
	v_and_b32_e32 v72, 0xffff0000, v139
	v_add_f32_e32 v73, v196, v81
	v_mul_f32_e32 v72, v73, v72
	v_cvt_pk_bf16_f32 v251, v71, v72
	s_nop 1
	v_permlane16_swap_b32_e32 v248, v250
	v_permlane16_swap_b32_e32 v249, v251
	global_store_dwordx4 v[238:239], v[248:251], off
	s_waitcnt vmcnt(26)
	v_lshlrev_b32_e32 v70, 16, v136
	v_add_f32_e32 v71, v196, v140
	v_mul_f32_e32 v70, v71, v70
	v_and_b32_e32 v71, 0xffff0000, v136
	v_add_f32_e32 v72, v196, v141
	v_mul_f32_e32 v71, v72, v71
	v_cvt_pk_bf16_f32 v252, v70, v71
	v_lshlrev_b32_e32 v71, 16, v137
	v_add_f32_e32 v72, v196, v142
	v_mul_f32_e32 v71, v72, v71
	v_and_b32_e32 v72, 0xffff0000, v137
	v_add_f32_e32 v73, v196, v143
	v_mul_f32_e32 v72, v73, v72
	v_cvt_pk_bf16_f32 v253, v71, v72
	s_waitcnt vmcnt(25)
	v_lshlrev_b32_e32 v70, 16, v134
	v_add_f32_e32 v66, v196, v66
	v_mul_f32_e32 v66, v66, v70
	v_and_b32_e32 v70, 0xffff0000, v134
	v_add_f32_e32 v67, v196, v67
	v_mul_f32_e32 v67, v67, v70
	v_cvt_pk_bf16_f32 v254, v66, v67
	v_lshlrev_b32_e32 v66, 16, v135
	v_add_f32_e32 v67, v196, v68
	v_mul_f32_e32 v66, v67, v66
	v_and_b32_e32 v67, 0xffff0000, v135
	v_add_f32_e32 v68, v196, v69
	v_mul_f32_e32 v67, v68, v67
	v_cvt_pk_bf16_f32 v255, v66, v67
	ds_read_b128 v[66:69], v183 offset:1024
	ds_read_b128 v[70:73], v183 offset:1088
	s_waitcnt lgkmcnt(1)
	v_mfma_f32_16x16x32_bf16 v[66:69], v[66:69], v[62:65], 0
	ds_read_b128 v[74:77], v183 offset:1568
	ds_read_b128 v[78:81], v183 offset:1632
	ds_read_b128 v[134:137], v183 offset:2112
	ds_read_b128 v[138:141], v183 offset:2176
	ds_read_b128 v[142:145], v183 offset:2656
	ds_read_b128 v[196:199], v183 offset:2720
	s_waitcnt lgkmcnt(5)
	v_mfma_f32_16x16x32_bf16 v[74:77], v[74:77], v[62:65], 0
	s_nop 1
	v_permlane16_swap_b32_e32 v252, v254
	v_permlane16_swap_b32_e32 v253, v255
	global_store_dwordx4 v[238:239], v[252:255], off offset:64
	s_waitcnt lgkmcnt(3)
	v_mfma_f32_16x16x32_bf16 v[134:137], v[134:137], v[62:65], 0
	s_waitcnt lgkmcnt(1)
	v_mfma_f32_16x16x32_bf16 v[62:65], v[142:145], v[62:65], 0
	v_mfma_f32_16x16x32_bf16 v[66:69], v[70:73], v[58:61], v[66:69]
	v_mfma_f32_16x16x32_bf16 v[70:73], v[78:81], v[58:61], v[74:77]
	v_mfma_f32_16x16x32_bf16 v[74:77], v[138:141], v[58:61], v[134:137]
	s_waitcnt lgkmcnt(0)
	v_mfma_f32_16x16x32_bf16 v[58:61], v[196:199], v[58:61], v[62:65]
	s_waitcnt vmcnt(25)
	s_nop 1
	v_lshlrev_b32_e32 v62, 16, v132
	v_add_f32_e32 v63, v195, v66
	v_mul_f32_e32 v62, v63, v62
	v_and_b32_e32 v63, 0xffff0000, v132
	v_add_f32_e32 v64, v195, v67
	v_mul_f32_e32 v63, v64, v63
	v_cvt_pk_bf16_f32 v248, v62, v63
	v_lshlrev_b32_e32 v63, 16, v133
	v_add_f32_e32 v64, v195, v68
	v_mul_f32_e32 v63, v64, v63
	v_and_b32_e32 v64, 0xffff0000, v133
	v_add_f32_e32 v65, v195, v69
	v_mul_f32_e32 v64, v65, v64
	v_cvt_pk_bf16_f32 v249, v63, v64
	v_lshl_add_u64 v[238:239], v[120:121], 0, v[236:237]
	s_waitcnt vmcnt(24)
	v_lshlrev_b32_e32 v62, 16, v128
	v_add_f32_e32 v63, v195, v70
	v_mul_f32_e32 v62, v63, v62
	v_and_b32_e32 v63, 0xffff0000, v128
	v_add_f32_e32 v64, v195, v71
	v_mul_f32_e32 v63, v64, v63
	v_cvt_pk_bf16_f32 v250, v62, v63
	v_lshlrev_b32_e32 v63, 16, v129
	v_add_f32_e32 v64, v195, v72
	v_mul_f32_e32 v63, v64, v63
	v_and_b32_e32 v64, 0xffff0000, v129
	v_add_f32_e32 v65, v195, v73
	v_mul_f32_e32 v64, v65, v64
	v_cvt_pk_bf16_f32 v251, v63, v64
	s_nop 1
	v_permlane16_swap_b32_e32 v248, v250
	v_permlane16_swap_b32_e32 v249, v251
	global_store_dwordx4 v[238:239], v[248:251], off
	s_waitcnt vmcnt(24)
	v_lshlrev_b32_e32 v62, 16, v126
	v_add_f32_e32 v63, v195, v74
	v_mul_f32_e32 v62, v63, v62
	v_and_b32_e32 v63, 0xffff0000, v126
	v_add_f32_e32 v64, v195, v75
	v_mul_f32_e32 v63, v64, v63
	v_cvt_pk_bf16_f32 v252, v62, v63
	v_lshlrev_b32_e32 v63, 16, v127
	v_add_f32_e32 v64, v195, v76
	v_mul_f32_e32 v63, v64, v63
	v_and_b32_e32 v64, 0xffff0000, v127
	v_add_f32_e32 v65, v195, v77
	v_mul_f32_e32 v64, v65, v64
	v_cvt_pk_bf16_f32 v253, v63, v64
	s_waitcnt vmcnt(23)
; __device__ __forceinline__ unsigned cvt_pk_bf16(float lo, float hi) { unsigned r; asm volatile("v_cvt_pk_bf16_f32 %0, %1, %2" : "=v"(r) : "v"(lo), "v"(hi)); return r; }
; __device__ __forceinline__ float bf_lo(unsigned w) { return __uint_as_float(w << 16); }
; __device__ __forceinline__ float bf_hi(unsigned w) { return __uint_as_float(w & 0xffff0000u); }
; #define LAS __attribute__((address_space(3)))
; __device__ __forceinline__ void sgu_unit(LAS unsigned char* lds, bf16* U, const bf16* VS, const float* SGS, const float* lnw, const float* lnb, const v4u* WF, const float* bsl, int unit, int tid) {
;     ...
;     {
;         int q = 0;
; #pragma unroll
;         for (int mt = 0; mt < 8; ++mt) {
;             const int t = 16 * mt + fr;
;             f32x4 acc[4];
; #pragma unroll
;             for (int nt = 0; nt < 4; ++nt) acc[nt] = (f32x4){0.f, 0.f, 0.f, 0.f};
; #pragma unroll
;             for (int ks = 0; ks <= (mt >> 1); ++ks) {
;                 const int sb = 32 * ks + 8 * fq; const bf16x8_t wf = __builtin_bit_cast(bf16x8_t, wfr[q++]);
; #pragma unroll
;                 for (int nt = 0; nt < 4; ++nt) { const bf16x8_t vf = *(const LAS bf16x8_t*)(vt + ((fr >> 3) + 8 * (fr & 7) + 2 * nt) * SGU_VP + sb * 2);
;                     acc[nt] = __builtin_amdgcn_mfma_f32_16x16x32_bf16(vf, wf, acc[nt], 0, 0, 0); }
;             }
;             const float bb = bbv[mt];
; #pragma unroll
;             for (int nt = 0; nt < 4; ++nt) { const v2u u2 = uu[mt][nt]; v2u w; w.x = cvt_pk_bf16(bf_lo(u2.x) * (acc[nt][0] + bb), bf_hi(u2.x) * (acc[nt][1] + bb)); w.y = cvt_pk_bf16(bf_lo(u2.y) * (acc[nt][2] + bb), bf_hi(u2.y) * (acc[nt][3] + bb));
;                 *(v2u*)(U + (size_t)(r0 + t) * 1024 + colbase + 16 * nt + 4 * fq) = w; }
;         }
	v_lshlrev_b32_e32 v62, 16, v124
	v_add_f32_e32 v58, v195, v58
	v_mul_f32_e32 v58, v58, v62
	v_and_b32_e32 v62, 0xffff0000, v124
	v_add_f32_e32 v59, v195, v59
	v_mul_f32_e32 v59, v59, v62
	v_cvt_pk_bf16_f32 v254, v58, v59
	v_lshlrev_b32_e32 v58, 16, v125
	v_add_f32_e32 v59, v195, v60
	v_mul_f32_e32 v58, v59, v58
	v_and_b32_e32 v59, 0xffff0000, v125
	v_add_f32_e32 v60, v195, v61
	v_mul_f32_e32 v59, v60, v59
	v_cvt_pk_bf16_f32 v255, v58, v59
	ds_read_b128 v[58:61], v183 offset:1024
	ds_read_b128 v[62:65], v183 offset:1088
	s_waitcnt lgkmcnt(1)
	v_mfma_f32_16x16x32_bf16 v[58:61], v[58:61], v[50:53], 0
	ds_read_b128 v[66:69], v183 offset:1568
	ds_read_b128 v[70:73], v183 offset:1152
	ds_read_b128 v[74:77], v183 offset:2112
	ds_read_b128 v[78:81], v183 offset:2176
	ds_read_b128 v[124:127], v183 offset:2656
	ds_read_b128 v[128:131], v183 offset:2240
	s_waitcnt lgkmcnt(5)
	v_mfma_f32_16x16x32_bf16 v[66:69], v[66:69], v[50:53], 0
	s_waitcnt lgkmcnt(3)
	v_mfma_f32_16x16x32_bf16 v[74:77], v[74:77], v[50:53], 0
	s_waitcnt lgkmcnt(1)
	v_mfma_f32_16x16x32_bf16 v[50:53], v[124:127], v[50:53], 0
	v_mfma_f32_16x16x32_bf16 v[58:61], v[62:65], v[54:57], v[58:61]
	ds_read_b128 v[62:65], v183 offset:1632
	ds_read_b128 v[124:127], v183 offset:1696
	s_waitcnt lgkmcnt(1)
	v_mfma_f32_16x16x32_bf16 v[62:65], v[62:65], v[54:57], v[66:69]
	v_mfma_f32_16x16x32_bf16 v[66:69], v[78:81], v[54:57], v[74:77]
	s_nop 2
	ds_read_b128 v[74:77], v183 offset:2720
	ds_read_b128 v[78:81], v183 offset:2784
	s_nop 1
	v_permlane16_swap_b32_e32 v252, v254
	v_permlane16_swap_b32_e32 v253, v255
	global_store_dwordx4 v[238:239], v[252:255], off offset:64
	s_waitcnt lgkmcnt(1)
	v_mfma_f32_16x16x32_bf16 v[50:53], v[74:77], v[54:57], v[50:53]
	v_mfma_f32_16x16x32_bf16 v[54:57], v[70:73], v[46:49], v[58:61]
	v_mfma_f32_16x16x32_bf16 v[58:61], v[124:127], v[46:49], v[62:65]
	v_mfma_f32_16x16x32_bf16 v[62:65], v[128:131], v[46:49], v[66:69]
	s_waitcnt lgkmcnt(0)
	v_mfma_f32_16x16x32_bf16 v[46:49], v[78:81], v[46:49], v[50:53]
	s_waitcnt vmcnt(23)
	s_nop 1
	v_lshlrev_b32_e32 v50, 16, v122
	v_add_f32_e32 v51, v194, v54
	v_mul_f32_e32 v50, v51, v50
	v_and_b32_e32 v51, 0xffff0000, v122
	v_add_f32_e32 v52, v194, v55
	v_mul_f32_e32 v51, v52, v51
	v_cvt_pk_bf16_f32 v248, v50, v51
	v_lshlrev_b32_e32 v51, 16, v123
	v_add_f32_e32 v52, v194, v56
	v_mul_f32_e32 v51, v52, v51
	v_and_b32_e32 v52, 0xffff0000, v123
	v_add_f32_e32 v53, v194, v57
	v_mul_f32_e32 v52, v53, v52
	v_cvt_pk_bf16_f32 v249, v51, v52
	v_lshl_add_u64 v[238:239], v[110:111], 0, v[236:237]
	s_waitcnt vmcnt(22)
	v_lshlrev_b32_e32 v50, 16, v118
	v_add_f32_e32 v51, v194, v58
	v_mul_f32_e32 v50, v51, v50
	v_and_b32_e32 v51, 0xffff0000, v118
	v_add_f32_e32 v52, v194, v59
	v_mul_f32_e32 v51, v52, v51
	v_cvt_pk_bf16_f32 v250, v50, v51
	v_lshlrev_b32_e32 v51, 16, v119
	v_add_f32_e32 v52, v194, v60
	v_mul_f32_e32 v51, v52, v51
	v_and_b32_e32 v52, 0xffff0000, v119
	v_add_f32_e32 v53, v194, v61
	v_mul_f32_e32 v52, v53, v52
	v_cvt_pk_bf16_f32 v251, v51, v52
	s_nop 1
	v_permlane16_swap_b32_e32 v248, v250
	v_permlane16_swap_b32_e32 v249, v251
	global_store_dwordx4 v[238:239], v[248:251], off
	s_waitcnt vmcnt(22)
	v_lshlrev_b32_e32 v50, 16, v116
	v_add_f32_e32 v51, v194, v62
	v_mul_f32_e32 v50, v51, v50
	v_and_b32_e32 v51, 0xffff0000, v116
	v_add_f32_e32 v52, v194, v63
	v_mul_f32_e32 v51, v52, v51
	v_cvt_pk_bf16_f32 v252, v50, v51
	v_lshlrev_b32_e32 v51, 16, v117
	v_add_f32_e32 v52, v194, v64
	v_mul_f32_e32 v51, v52, v51
	v_and_b32_e32 v52, 0xffff0000, v117
	v_add_f32_e32 v53, v194, v65
	v_mul_f32_e32 v52, v53, v52
	v_cvt_pk_bf16_f32 v253, v51, v52
	s_waitcnt vmcnt(21)
	v_lshlrev_b32_e32 v50, 16, v114
	v_add_f32_e32 v46, v194, v46
	v_mul_f32_e32 v46, v46, v50
	v_and_b32_e32 v50, 0xffff0000, v114
	v_add_f32_e32 v47, v194, v47
	v_mul_f32_e32 v47, v47, v50
	v_cvt_pk_bf16_f32 v254, v46, v47
	v_lshlrev_b32_e32 v46, 16, v115
	v_add_f32_e32 v47, v194, v48
	v_mul_f32_e32 v46, v47, v46
	v_and_b32_e32 v47, 0xffff0000, v115
	v_add_f32_e32 v48, v194, v49
	v_mul_f32_e32 v47, v48, v47
	v_cvt_pk_bf16_f32 v255, v46, v47
	ds_read_b128 v[46:49], v183 offset:1024
	ds_read_b128 v[50:53], v183 offset:1088
	s_waitcnt lgkmcnt(1)
	v_mfma_f32_16x16x32_bf16 v[46:49], v[46:49], v[42:45], 0
	ds_read_b128 v[54:57], v183 offset:1568
	ds_read_b128 v[58:61], v183 offset:1152
	ds_read_b128 v[62:65], v183 offset:2112
	ds_read_b128 v[66:69], v183 offset:2176
	ds_read_b128 v[70:73], v183 offset:2656
	ds_read_b128 v[74:77], v183 offset:2240
	s_waitcnt lgkmcnt(5)
	v_mfma_f32_16x16x32_bf16 v[54:57], v[54:57], v[42:45], 0
	s_waitcnt lgkmcnt(3)
	v_mfma_f32_16x16x32_bf16 v[62:65], v[62:65], v[42:45], 0
	s_waitcnt lgkmcnt(1)
	v_mfma_f32_16x16x32_bf16 v[42:45], v[70:73], v[42:45], 0
	v_mfma_f32_16x16x32_bf16 v[46:49], v[50:53], v[34:37], v[46:49]
	ds_read_b128 v[50:53], v183 offset:1632
	ds_read_b128 v[70:73], v183 offset:1696
	s_waitcnt lgkmcnt(1)
	v_mfma_f32_16x16x32_bf16 v[50:53], v[50:53], v[34:37], v[54:57]
	v_mfma_f32_16x16x32_bf16 v[54:57], v[66:69], v[34:37], v[62:65]
	s_nop 2
	ds_read_b128 v[62:65], v183 offset:2720
	ds_read_b128 v[66:69], v183 offset:2784
	s_nop 1
	v_permlane16_swap_b32_e32 v252, v254
	v_permlane16_swap_b32_e32 v253, v255
	global_store_dwordx4 v[238:239], v[252:255], off offset:64
	s_waitcnt lgkmcnt(1)
	v_mfma_f32_16x16x32_bf16 v[34:37], v[62:65], v[34:37], v[42:45]
	v_mfma_f32_16x16x32_bf16 v[42:45], v[58:61], v[38:41], v[46:49]
	v_mfma_f32_16x16x32_bf16 v[46:49], v[70:73], v[38:41], v[50:53]
	v_mfma_f32_16x16x32_bf16 v[50:53], v[74:77], v[38:41], v[54:57]
	s_waitcnt lgkmcnt(0)
	v_mfma_f32_16x16x32_bf16 v[34:37], v[66:69], v[38:41], v[34:37]
	s_waitcnt vmcnt(21)
; __device__ __forceinline__ unsigned cvt_pk_bf16(float lo, float hi) { unsigned r; asm volatile("v_cvt_pk_bf16_f32 %0, %1, %2" : "=v"(r) : "v"(lo), "v"(hi)); return r; }
; __device__ __forceinline__ float bf_lo(unsigned w) { return __uint_as_float(w << 16); }
; __device__ __forceinline__ float bf_hi(unsigned w) { return __uint_as_float(w & 0xffff0000u); }
; #define LAS __attribute__((address_space(3)))
; __device__ __forceinline__ void sgu_unit(LAS unsigned char* lds, bf16* U, const bf16* VS, const float* SGS, const float* lnw, const float* lnb, const v4u* WF, const float* bsl, int unit, int tid) {
;     ...
;     {
;         int q = 0;
; #pragma unroll
;         for (int mt = 0; mt < 8; ++mt) {
;             const int t = 16 * mt + fr;
;             f32x4 acc[4];
; #pragma unroll
;             for (int nt = 0; nt < 4; ++nt) acc[nt] = (f32x4){0.f, 0.f, 0.f, 0.f};
; #pragma unroll
;             for (int ks = 0; ks <= (mt >> 1); ++ks) {
;                 const int sb = 32 * ks + 8 * fq; const bf16x8_t wf = __builtin_bit_cast(bf16x8_t, wfr[q++]);
; #pragma unroll
;                 for (int nt = 0; nt < 4; ++nt) { const bf16x8_t vf = *(const LAS bf16x8_t*)(vt + ((fr >> 3) + 8 * (fr & 7) + 2 * nt) * SGU_VP + sb * 2);
;                     acc[nt] = __builtin_amdgcn_mfma_f32_16x16x32_bf16(vf, wf, acc[nt], 0, 0, 0); }
;             }
;             const float bb = bbv[mt];
; #pragma unroll
;             for (int nt = 0; nt < 4; ++nt) { const v2u u2 = uu[mt][nt]; v2u w; w.x = cvt_pk_bf16(bf_lo(u2.x) * (acc[nt][0] + bb), bf_hi(u2.x) * (acc[nt][1] + bb)); w.y = cvt_pk_bf16(bf_lo(u2.y) * (acc[nt][2] + bb), bf_hi(u2.y) * (acc[nt][3] + bb));
;                 *(v2u*)(U + (size_t)(r0 + t) * 1024 + colbase + 16 * nt + 4 * fq) = w; }
;         }
	v_lshlrev_b32_e32 v38, 16, v112
	s_nop 1
	v_add_f32_e32 v39, v193, v42
	v_mul_f32_e32 v38, v39, v38
	v_and_b32_e32 v39, 0xffff0000, v112
	v_add_f32_e32 v40, v193, v43
	v_mul_f32_e32 v39, v40, v39
	v_cvt_pk_bf16_f32 v248, v38, v39
	v_lshlrev_b32_e32 v39, 16, v113
	v_add_f32_e32 v40, v193, v44
	v_mul_f32_e32 v39, v40, v39
	v_and_b32_e32 v40, 0xffff0000, v113
	v_add_f32_e32 v41, v193, v45
	v_mul_f32_e32 v40, v41, v40
	v_cvt_pk_bf16_f32 v249, v39, v40
	v_lshl_add_u64 v[238:239], v[100:101], 0, v[236:237]
	s_waitcnt vmcnt(20)
	v_lshlrev_b32_e32 v38, 16, v108
	v_add_f32_e32 v39, v193, v46
	v_mul_f32_e32 v38, v39, v38
	v_and_b32_e32 v39, 0xffff0000, v108
	v_add_f32_e32 v40, v193, v47
	v_mul_f32_e32 v39, v40, v39
	v_cvt_pk_bf16_f32 v250, v38, v39
	v_lshlrev_b32_e32 v39, 16, v109
	v_add_f32_e32 v40, v193, v48
	v_mul_f32_e32 v39, v40, v39
	v_and_b32_e32 v40, 0xffff0000, v109
	v_add_f32_e32 v41, v193, v49
	v_mul_f32_e32 v40, v41, v40
	v_cvt_pk_bf16_f32 v251, v39, v40
	s_nop 1
	v_permlane16_swap_b32_e32 v248, v250
	v_permlane16_swap_b32_e32 v249, v251
	global_store_dwordx4 v[238:239], v[248:251], off
	s_waitcnt vmcnt(20)
	v_lshlrev_b32_e32 v38, 16, v106
	v_add_f32_e32 v39, v193, v50
	v_mul_f32_e32 v38, v39, v38
	v_and_b32_e32 v39, 0xffff0000, v106
	v_add_f32_e32 v40, v193, v51
	v_mul_f32_e32 v39, v40, v39
	v_cvt_pk_bf16_f32 v252, v38, v39
	v_lshlrev_b32_e32 v39, 16, v107
	v_add_f32_e32 v40, v193, v52
	v_mul_f32_e32 v39, v40, v39
	v_and_b32_e32 v40, 0xffff0000, v107
	v_add_f32_e32 v41, v193, v53
	v_mul_f32_e32 v40, v41, v40
	v_cvt_pk_bf16_f32 v253, v39, v40
	s_waitcnt vmcnt(19)
	v_lshlrev_b32_e32 v38, 16, v104
	v_add_f32_e32 v34, v193, v34
	v_mul_f32_e32 v34, v34, v38
	v_and_b32_e32 v38, 0xffff0000, v104
	v_add_f32_e32 v35, v193, v35
	v_mul_f32_e32 v35, v35, v38
	v_cvt_pk_bf16_f32 v254, v34, v35
	v_lshlrev_b32_e32 v34, 16, v105
	v_add_f32_e32 v35, v193, v36
	v_mul_f32_e32 v34, v35, v34
	v_and_b32_e32 v35, 0xffff0000, v105
	v_add_f32_e32 v36, v193, v37
	v_mul_f32_e32 v35, v36, v35
	v_cvt_pk_bf16_f32 v255, v34, v35
	ds_read_b128 v[34:37], v183 offset:1024
	ds_read_b128 v[38:41], v183 offset:1088
	ds_read_b128 v[42:45], v183 offset:1568
	ds_read_b128 v[46:49], v183 offset:1632
	ds_read_b128 v[50:53], v183 offset:2112
	ds_read_b128 v[54:57], v183 offset:2176
	ds_read_b128 v[58:61], v183 offset:2656
	ds_read_b128 v[62:65], v183 offset:2720
	s_waitcnt lgkmcnt(7)
	v_mfma_f32_16x16x32_bf16 v[34:37], v[34:37], v[30:33], 0
	s_waitcnt lgkmcnt(5)
	v_mfma_f32_16x16x32_bf16 v[42:45], v[42:45], v[30:33], 0
	s_waitcnt lgkmcnt(3)
	v_mfma_f32_16x16x32_bf16 v[50:53], v[50:53], v[30:33], 0
	s_waitcnt lgkmcnt(1)
	v_mfma_f32_16x16x32_bf16 v[30:33], v[58:61], v[30:33], 0
	v_mfma_f32_16x16x32_bf16 v[34:37], v[38:41], v[26:29], v[34:37]
	v_mfma_f32_16x16x32_bf16 v[38:41], v[46:49], v[26:29], v[42:45]
	v_mfma_f32_16x16x32_bf16 v[42:45], v[54:57], v[26:29], v[50:53]
	s_waitcnt lgkmcnt(0)
	v_mfma_f32_16x16x32_bf16 v[26:29], v[62:65], v[26:29], v[30:33]
	s_nop 2
	ds_read_b128 v[30:33], v183 offset:1152
	ds_read_b128 v[46:49], v183 offset:1216
	s_waitcnt lgkmcnt(1)
	v_mfma_f32_16x16x32_bf16 v[30:33], v[30:33], v[22:25], v[34:37]
	s_nop 2
	ds_read_b128 v[34:37], v183 offset:1696
	ds_read_b128 v[50:53], v183 offset:1760
	s_waitcnt lgkmcnt(1)
	v_mfma_f32_16x16x32_bf16 v[34:37], v[34:37], v[22:25], v[38:41]
	s_nop 2
	ds_read_b128 v[38:41], v183 offset:2240
	ds_read_b128 v[54:57], v183 offset:2304
	s_waitcnt lgkmcnt(1)
	v_mfma_f32_16x16x32_bf16 v[38:41], v[38:41], v[22:25], v[42:45]
	s_nop 2
	ds_read_b128 v[42:45], v183 offset:2784
	ds_read_b128 v[58:61], v183 offset:2848
	s_nop 1
	v_permlane16_swap_b32_e32 v252, v254
	v_permlane16_swap_b32_e32 v253, v255
	global_store_dwordx4 v[238:239], v[252:255], off offset:64
	s_waitcnt lgkmcnt(1)
	v_mfma_f32_16x16x32_bf16 v[22:25], v[42:45], v[22:25], v[26:29]
	v_mfma_f32_16x16x32_bf16 v[26:29], v[46:49], v[18:21], v[30:33]
	v_mfma_f32_16x16x32_bf16 v[30:33], v[50:53], v[18:21], v[34:37]
	v_mfma_f32_16x16x32_bf16 v[34:37], v[54:57], v[18:21], v[38:41]
	s_waitcnt lgkmcnt(0)
	v_mfma_f32_16x16x32_bf16 v[18:21], v[58:61], v[18:21], v[22:25]
	s_waitcnt vmcnt(19)
	s_nop 1
	v_lshlrev_b32_e32 v22, 16, v102
	v_add_f32_e32 v23, v192, v26
	v_mul_f32_e32 v22, v23, v22
	v_and_b32_e32 v23, 0xffff0000, v102
	v_add_f32_e32 v24, v192, v27
	v_mul_f32_e32 v23, v24, v23
	v_cvt_pk_bf16_f32 v248, v22, v23
	v_lshlrev_b32_e32 v23, 16, v103
	v_add_f32_e32 v24, v192, v28
	v_mul_f32_e32 v23, v24, v23
	v_and_b32_e32 v24, 0xffff0000, v103
	v_add_f32_e32 v25, v192, v29
	v_mul_f32_e32 v24, v25, v24
	v_cvt_pk_bf16_f32 v249, v23, v24
	v_lshl_add_u64 v[238:239], v[90:91], 0, v[236:237]
	s_waitcnt vmcnt(18)
	v_lshlrev_b32_e32 v22, 16, v98
	v_add_f32_e32 v23, v192, v30
	v_mul_f32_e32 v22, v23, v22
	v_and_b32_e32 v23, 0xffff0000, v98
	v_add_f32_e32 v24, v192, v31
	v_mul_f32_e32 v23, v24, v23
	v_cvt_pk_bf16_f32 v250, v22, v23
	v_lshlrev_b32_e32 v23, 16, v99
	v_add_f32_e32 v24, v192, v32
	v_mul_f32_e32 v23, v24, v23
	v_and_b32_e32 v24, 0xffff0000, v99
	v_add_f32_e32 v25, v192, v33
	v_mul_f32_e32 v24, v25, v24
	v_cvt_pk_bf16_f32 v251, v23, v24
	s_nop 1
	v_permlane16_swap_b32_e32 v248, v250
	v_permlane16_swap_b32_e32 v249, v251
	global_store_dwordx4 v[238:239], v[248:251], off
	s_waitcnt vmcnt(18)
; __device__ __forceinline__ unsigned cvt_pk_bf16(float lo, float hi) { unsigned r; asm volatile("v_cvt_pk_bf16_f32 %0, %1, %2" : "=v"(r) : "v"(lo), "v"(hi)); return r; }
; __device__ __forceinline__ float bf_lo(unsigned w) { return __uint_as_float(w << 16); }
; __device__ __forceinline__ float bf_hi(unsigned w) { return __uint_as_float(w & 0xffff0000u); }
; #define LAS __attribute__((address_space(3)))
; __device__ __forceinline__ void sgu_unit(LAS unsigned char* lds, bf16* U, const bf16* VS, const float* SGS, const float* lnw, const float* lnb, const v4u* WF, const float* bsl, int unit, int tid) {
;     ...
;     {
;         int q = 0;
; #pragma unroll
;         for (int mt = 0; mt < 8; ++mt) {
;             const int t = 16 * mt + fr;
;             f32x4 acc[4];
; #pragma unroll
;             for (int nt = 0; nt < 4; ++nt) acc[nt] = (f32x4){0.f, 0.f, 0.f, 0.f};
; #pragma unroll
;             for (int ks = 0; ks <= (mt >> 1); ++ks) {
;                 const int sb = 32 * ks + 8 * fq; const bf16x8_t wf = __builtin_bit_cast(bf16x8_t, wfr[q++]);
; #pragma unroll
;                 for (int nt = 0; nt < 4; ++nt) { const bf16x8_t vf = *(const LAS bf16x8_t*)(vt + ((fr >> 3) + 8 * (fr & 7) + 2 * nt) * SGU_VP + sb * 2);
;                     acc[nt] = __builtin_amdgcn_mfma_f32_16x16x32_bf16(vf, wf, acc[nt], 0, 0, 0); }
;             }
;             const float bb = bbv[mt];
; #pragma unroll
;             for (int nt = 0; nt < 4; ++nt) { const v2u u2 = uu[mt][nt]; v2u w; w.x = cvt_pk_bf16(bf_lo(u2.x) * (acc[nt][0] + bb), bf_hi(u2.x) * (acc[nt][1] + bb)); w.y = cvt_pk_bf16(bf_lo(u2.y) * (acc[nt][2] + bb), bf_hi(u2.y) * (acc[nt][3] + bb));
;                 *(v2u*)(U + (size_t)(r0 + t) * 1024 + colbase + 16 * nt + 4 * fq) = w; }
;         }
;     }
;     __syncthreads();
	v_lshlrev_b32_e32 v22, 16, v96
	v_add_f32_e32 v23, v192, v34
	v_mul_f32_e32 v22, v23, v22
	v_and_b32_e32 v23, 0xffff0000, v96
	v_add_f32_e32 v24, v192, v35
	v_mul_f32_e32 v23, v24, v23
	v_cvt_pk_bf16_f32 v252, v22, v23
	v_lshlrev_b32_e32 v23, 16, v97
	v_add_f32_e32 v24, v192, v36
	v_mul_f32_e32 v23, v24, v23
	v_and_b32_e32 v24, 0xffff0000, v97
	v_add_f32_e32 v25, v192, v37
	v_mul_f32_e32 v24, v25, v24
	v_cvt_pk_bf16_f32 v253, v23, v24
	s_waitcnt vmcnt(17)
	v_lshlrev_b32_e32 v22, 16, v94
	v_add_f32_e32 v18, v192, v18
	v_mul_f32_e32 v18, v18, v22
	v_and_b32_e32 v22, 0xffff0000, v94
	v_add_f32_e32 v19, v192, v19
	v_mul_f32_e32 v19, v19, v22
	v_cvt_pk_bf16_f32 v254, v18, v19
	v_lshlrev_b32_e32 v18, 16, v95
	v_add_f32_e32 v19, v192, v20
	v_mul_f32_e32 v18, v19, v18
	v_and_b32_e32 v19, 0xffff0000, v95
	v_add_f32_e32 v20, v192, v21
	v_mul_f32_e32 v19, v20, v19
	v_cvt_pk_bf16_f32 v255, v18, v19
	ds_read_b128 v[18:21], v183 offset:1024
	ds_read_b128 v[22:25], v183 offset:1088
	ds_read_b128 v[26:29], v183 offset:1568
	ds_read_b128 v[30:33], v183 offset:1632
	ds_read_b128 v[34:37], v183 offset:2112
	ds_read_b128 v[38:41], v183 offset:2176
	ds_read_b128 v[42:45], v183 offset:2656
	ds_read_b128 v[46:49], v183 offset:2720
	s_waitcnt lgkmcnt(7)
	v_mfma_f32_16x16x32_bf16 v[18:21], v[18:21], v[14:17], 0
	s_waitcnt lgkmcnt(5)
	v_mfma_f32_16x16x32_bf16 v[26:29], v[26:29], v[14:17], 0
	s_waitcnt lgkmcnt(3)
	v_mfma_f32_16x16x32_bf16 v[34:37], v[34:37], v[14:17], 0
	s_waitcnt lgkmcnt(1)
	v_mfma_f32_16x16x32_bf16 v[14:17], v[42:45], v[14:17], 0
	v_mfma_f32_16x16x32_bf16 v[18:21], v[22:25], v[10:13], v[18:21]
	v_mfma_f32_16x16x32_bf16 v[22:25], v[30:33], v[10:13], v[26:29]
	v_mfma_f32_16x16x32_bf16 v[26:29], v[38:41], v[10:13], v[34:37]
	s_waitcnt lgkmcnt(0)
	v_mfma_f32_16x16x32_bf16 v[10:13], v[46:49], v[10:13], v[14:17]
	s_nop 2
	ds_read_b128 v[14:17], v183 offset:1152
	ds_read_b128 v[30:33], v183 offset:1216
	s_waitcnt lgkmcnt(1)
	v_mfma_f32_16x16x32_bf16 v[14:17], v[14:17], v[6:9], v[18:21]
	s_nop 2
	ds_read_b128 v[18:21], v183 offset:1696
	ds_read_b128 v[34:37], v183 offset:1760
	s_waitcnt lgkmcnt(1)
	v_mfma_f32_16x16x32_bf16 v[18:21], v[18:21], v[6:9], v[22:25]
	s_nop 2
	ds_read_b128 v[22:25], v183 offset:2240
	ds_read_b128 v[38:41], v183 offset:2304
	s_waitcnt lgkmcnt(1)
	v_mfma_f32_16x16x32_bf16 v[22:25], v[22:25], v[6:9], v[26:29]
	s_nop 2
	ds_read_b128 v[26:29], v183 offset:2784
	ds_read_b128 v[42:45], v183 offset:2848
	s_nop 1
	v_permlane16_swap_b32_e32 v252, v254
	v_permlane16_swap_b32_e32 v253, v255
	global_store_dwordx4 v[238:239], v[252:255], off offset:64
	s_waitcnt lgkmcnt(1)
	v_mfma_f32_16x16x32_bf16 v[6:9], v[26:29], v[6:9], v[10:13]
	v_mfma_f32_16x16x32_bf16 v[10:13], v[30:33], v[2:5], v[14:17]
	v_mfma_f32_16x16x32_bf16 v[14:17], v[34:37], v[2:5], v[18:21]
	v_mfma_f32_16x16x32_bf16 v[18:21], v[38:41], v[2:5], v[22:25]
	s_waitcnt lgkmcnt(0)
	v_mfma_f32_16x16x32_bf16 v[2:5], v[42:45], v[2:5], v[6:9]
	s_waitcnt vmcnt(17)
	s_nop 1
	v_lshlrev_b32_e32 v6, 16, v92
	v_add_f32_e32 v7, v157, v10
	v_mul_f32_e32 v6, v7, v6
	v_and_b32_e32 v7, 0xffff0000, v92
	v_add_f32_e32 v8, v157, v11
	v_mul_f32_e32 v7, v8, v7
	v_cvt_pk_bf16_f32 v248, v6, v7
	v_lshlrev_b32_e32 v7, 16, v93
	v_add_f32_e32 v8, v157, v12
	v_mul_f32_e32 v7, v8, v7
	v_and_b32_e32 v8, 0xffff0000, v93
	v_add_f32_e32 v9, v157, v13
	v_mul_f32_e32 v8, v9, v8
	v_cvt_pk_bf16_f32 v249, v7, v8
	v_lshl_add_u64 v[238:239], v[82:83], 0, v[236:237]
	s_waitcnt vmcnt(16)
	v_lshlrev_b32_e32 v6, 16, v88
	v_add_f32_e32 v7, v157, v14
	v_mul_f32_e32 v6, v7, v6
	v_and_b32_e32 v7, 0xffff0000, v88
	v_add_f32_e32 v8, v157, v15
	v_mul_f32_e32 v7, v8, v7
	v_cvt_pk_bf16_f32 v250, v6, v7
	v_lshlrev_b32_e32 v7, 16, v89
	v_add_f32_e32 v8, v157, v16
	v_mul_f32_e32 v7, v8, v7
	v_and_b32_e32 v8, 0xffff0000, v89
	v_add_f32_e32 v9, v157, v17
	v_mul_f32_e32 v8, v9, v8
	v_cvt_pk_bf16_f32 v251, v7, v8
	s_nop 1
	v_permlane16_swap_b32_e32 v248, v250
	v_permlane16_swap_b32_e32 v249, v251
	global_store_dwordx4 v[238:239], v[248:251], off
	s_waitcnt vmcnt(16)
	v_lshlrev_b32_e32 v6, 16, v86
	v_add_f32_e32 v7, v157, v18
	v_mul_f32_e32 v6, v7, v6
	v_and_b32_e32 v7, 0xffff0000, v86
	v_add_f32_e32 v8, v157, v19
	v_mul_f32_e32 v7, v8, v7
	v_cvt_pk_bf16_f32 v252, v6, v7
	v_lshlrev_b32_e32 v7, 16, v87
	v_add_f32_e32 v8, v157, v20
	v_mul_f32_e32 v7, v8, v7
	v_and_b32_e32 v8, 0xffff0000, v87
	v_add_f32_e32 v9, v157, v21
	v_mul_f32_e32 v8, v9, v8
	v_cvt_pk_bf16_f32 v253, v7, v8
	s_waitcnt vmcnt(15)
	v_lshlrev_b32_e32 v6, 16, v84
	v_add_f32_e32 v2, v157, v2
	v_mul_f32_e32 v2, v2, v6
	v_and_b32_e32 v6, 0xffff0000, v84
	v_add_f32_e32 v3, v157, v3
	v_mul_f32_e32 v3, v3, v6
	v_cvt_pk_bf16_f32 v254, v2, v3
	v_lshlrev_b32_e32 v3, 16, v85
	v_add_f32_e32 v4, v157, v4
	v_mul_f32_e32 v3, v4, v3
	v_and_b32_e32 v4, 0xffff0000, v85
	v_add_f32_e32 v5, v157, v5
	v_mul_f32_e32 v4, v5, v4
	v_cvt_pk_bf16_f32 v255, v3, v4
	s_nop 1
	v_permlane16_swap_b32_e32 v252, v254
	v_permlane16_swap_b32_e32 v253, v255
	global_store_dwordx4 v[238:239], v[252:255], off offset:64
	s_barrier

; __device__ __forceinline__ float bf_lo(unsigned w) { return __uint_as_float(w << 16); }
; __device__ __forceinline__ float bf_hi(unsigned w) { return __uint_as_float(w & 0xffff0000u); }
;     __device__ __forceinline__ void fused(f32x4 (&acc)[2][2][4][2], const Unit& u, int wr, int wc, int fr, int fq, PG8_LAS unsigned char* lds, int wid, int lane) const {
;     ...
;         const int col0 = u.pn * BM + wc * 32 + 8 * fq, b = u.pm >> 4;
;         {
;             f32x4 gv[2][2];
; #pragma unroll
;             for (int bj = 0; bj < 2; ++bj)
; #pragma unroll
;                 for (int n = 0; n < 2; ++n) gv[bj][n] = *(const f32x4*)(g + (size_t)b * 6144 + col0 + bj * HALF + 4 * n);
; #pragma unroll
;             for (int ai = 0; ai < 2; ++ai)
; #pragma unroll
;                 for (int m = 0; m < 4; ++m) { const int r = ai * HALF + wr * 64 + m * 16 + fr; const size_t off = (size_t)(u.pm * BM + r) * 1024 + col0;
; #pragma unroll
;                     for (int bj = 0; bj < 2; ++bj) { f32x4 b0, b1;
;                         if (XIN_BF16) { const u32x4 w = *(const u32x4*)((const bf16_t*)xin + off + bj * HALF); b0 = (f32x4){bf_lo(w.x), bf_hi(w.x), bf_lo(w.y), bf_hi(w.y)}; b1 = (f32x4){bf_lo(w.z), bf_hi(w.z), bf_lo(w.w), bf_hi(w.w)}; }
;                         else { b0 = *(const f32x4*)((const float*)xin + off + bj * HALF); b1 = *(const f32x4*)((const float*)xin + off + bj * HALF + 4); }
;                         acc[ai][bj][m][0] = b0 + gv[bj][0] * acc[ai][bj][m][0]; acc[ai][bj][m][1] = b1 + gv[bj][1] * acc[ai][bj][m][1]; }
;                     asm volatile("" : "+v"(acc[ai][0][m][0]), "+v"(acc[ai][0][m][1]), "+v"(acc[ai][1][m][0]), "+v"(acc[ai][1][m][1]));
;                     if (m == 3) asm volatile("" ::: "memory"); }
.LBB0_732:
	s_lshl_b32 s6, s17, 5
	s_lshl_b32 s7, s10, 8
	v_lshrrev_b32_e32 v130, 1, v166
	s_or_b32 s6, s7, s6
	v_and_or_b32 v156, v130, 24, s6
	s_ashr_i32 s6, s16, 4
	s_mul_i32 s25, s6, 0x6000
	s_mul_hi_i32 s24, s6, 0x6000
	s_add_u32 s6, s12, s25
	s_addc_u32 s7, s13, s24
	s_lshl_b32 s30, s16, 8
	v_ashrrev_i32_e32 v157, 31, v156
	v_add_u32_e32 v154, s30, v170
	v_lshlrev_b64 v[158:159], 2, v[156:157]
	v_ashrrev_i32_e32 v155, 31, v154
	v_lshl_add_u64 v[134:135], s[6:7], 0, v[158:159]
	s_movk_i32 s8, 0x2000
	v_lshlrev_b64 v[136:137], 12, v[154:155]
	s_mov_b64 s[6:7], 0x2000
	v_add_co_u32_e32 v130, vcc, s8, v134
	v_lshl_add_u64 v[136:137], s[18:19], 0, v[136:137]
	s_nop 0
	v_addc_co_u32_e32 v131, vcc, 0, v135, vcc
	v_lshl_add_u64 v[142:143], v[136:137], 0, v[158:159]
	v_lshl_add_u64 v[144:145], v[134:135], 0, s[6:7]
	s_barrier
	v_mov_b64_e32 v[244:245], v[142:143]
	s_mov_b64 s[98:99], 0x10000
	v_lshl_add_u64 v[248:249], v[244:245], 0, s[98:99]
	global_load_dwordx4 v[228:231], v[248:249], off nt
	global_load_dwordx4 v[232:235], v[248:249], off offset:16 nt
	global_load_dwordx4 v[236:239], v[248:249], off offset:512 nt
	global_load_dwordx4 v[240:243], v[248:249], off offset:528 nt
	s_mov_b64 s[98:99], 0x20000
	v_lshl_add_u64 v[248:249], v[244:245], 0, s[98:99]
	global_load_dwordx4 v[212:215], v[248:249], off nt
	global_load_dwordx4 v[216:219], v[248:249], off offset:16 nt
	global_load_dwordx4 v[220:223], v[248:249], off offset:512 nt
	global_load_dwordx4 v[224:227], v[248:249], off offset:528 nt
	global_load_dwordx4 v[130:133], v[130:131], off nt
	s_nop 0
	global_load_dwordx4 v[146:149], v[142:143], off offset:16 nt
	global_load_dwordx4 v[150:153], v[142:143], off nt
	global_load_dwordx4 v[138:141], v[144:145], off offset:16 nt
	global_load_dwordx4 v[134:137], v[144:145], off offset:512 nt
	global_load_dwordx4 v[162:165], v[142:143], off offset:512 nt
	global_load_dwordx4 v[174:177], v[142:143], off offset:528 nt
	s_nop 0
	global_load_dwordx4 v[142:145], v[144:145], off offset:528 nt
	v_add_u32_e32 v160, 16, v154
	v_ashrrev_i32_e32 v161, 31, v160
	v_lshlrev_b64 v[168:169], 12, v[160:161]
	v_lshl_add_u64 v[168:169], s[18:19], 0, v[168:169]
	v_lshl_add_u64 v[168:169], v[168:169], 0, v[158:159]
	v_mbcnt_hi_u32_b32 v173, -1, v1
	s_lshl_b32 s6, s17, 3
	s_add_i32 s8, s6, 0
	s_waitcnt vmcnt(0)
	v_pk_fma_f32 v[120:121], v[120:121], v[136:137], v[164:165]
	v_pk_fma_f32 v[124:125], v[124:125], v[132:133], v[152:153]
	v_pk_fma_f32 v[122:123], v[122:123], v[130:131], v[150:151]
	v_pk_fma_f32 v[128:129], v[128:129], v[140:141], v[148:149]
	v_pk_fma_f32 v[126:127], v[126:127], v[138:139], v[146:147]
	v_pk_fma_f32 v[118:119], v[118:119], v[134:135], v[162:163]
	v_pk_fma_f32 v[116:117], v[116:117], v[144:145], v[176:177]
	v_pk_fma_f32 v[114:115], v[114:115], v[142:143], v[174:175]
	v_add_u32_e32 v162, 32, v154
	s_waitcnt vmcnt(4)
	v_mov_b32_e32 v146, v228
	v_mov_b32_e32 v147, v229
	v_mov_b32_e32 v148, v230
	v_mov_b32_e32 v149, v231
	v_mov_b32_e32 v150, v232
	v_mov_b32_e32 v151, v233
	v_mov_b32_e32 v152, v234
	v_mov_b32_e32 v153, v235
	v_mov_b32_e32 v174, v236
	v_mov_b32_e32 v175, v237
	v_mov_b32_e32 v176, v238
	v_mov_b32_e32 v177, v239
	v_mov_b32_e32 v178, v240
	v_mov_b32_e32 v179, v241
	v_mov_b32_e32 v180, v242
	v_mov_b32_e32 v181, v243
	s_mov_b64 s[98:99], 0x30000
	v_lshl_add_u64 v[248:249], v[244:245], 0, s[98:99]
	global_load_dwordx4 v[228:231], v[248:249], off nt
	global_load_dwordx4 v[232:235], v[248:249], off offset:16 nt
	global_load_dwordx4 v[236:239], v[248:249], off offset:512 nt
	global_load_dwordx4 v[240:243], v[248:249], off offset:528 nt
	v_ashrrev_i32_e32 v163, 31, v162
	v_lshlrev_b64 v[164:165], 12, v[162:163]
	v_lshl_add_u64 v[164:165], s[18:19], 0, v[164:165]
	v_lshl_add_u64 v[164:165], v[164:165], 0, v[158:159]
	v_mov_b32_e32 v192, v123
	v_mov_b32_e32 v193, v124
	v_mov_b32_e32 v194, v122
	v_mov_b32_e32 v195, v125
	v_pk_add_f32 v[192:193], v[192:193], v[194:195]
	v_add_f32_e32 v197, v118, v119
	v_add_f32_e32 v192, v192, v193
	v_add_f32_e32 v199, v120, v121
	v_mov_b32_e32 v196, v114
	v_mov_b32_e32 v198, v115
	v_mov_b32_e32 v206, v117
	v_add_f32_e32 v207, 0, v192
	s_nop 0
	v_pk_fma_f32 v[112:113], v[112:113], v[132:133], v[148:149]
	v_pk_fma_f32 v[110:111], v[110:111], v[130:131], v[146:147]
	s_nop 0
	v_pk_fma_f32 v[108:109], v[108:109], v[140:141], v[152:153]
	v_pk_fma_f32 v[106:107], v[106:107], v[138:139], v[150:151]
	s_nop 0
	v_pk_fma_f32 v[72:73], v[72:73], v[136:137], v[176:177]
	v_pk_fma_f32 v[70:71], v[70:71], v[134:135], v[174:175]
	s_nop 0
	v_pk_fma_f32 v[68:69], v[68:69], v[144:145], v[180:181]
	v_pk_fma_f32 v[66:67], v[66:67], v[142:143], v[178:179]
	s_nop 0
	s_waitcnt vmcnt(4)
	v_mov_b32_e32 v146, v212
	v_mov_b32_e32 v147, v213
	v_mov_b32_e32 v148, v214
	v_mov_b32_e32 v149, v215
	v_mov_b32_e32 v150, v216
	v_mov_b32_e32 v151, v217
	v_mov_b32_e32 v152, v218
	v_mov_b32_e32 v153, v219
	v_mov_b32_e32 v174, v220
	v_mov_b32_e32 v175, v221
	v_mov_b32_e32 v176, v222
	v_mov_b32_e32 v177, v223
	v_mov_b32_e32 v178, v224
	v_mov_b32_e32 v179, v225
	v_mov_b32_e32 v180, v226
	v_mov_b32_e32 v181, v227
	s_mov_b64 s[98:99], 0x80000
	v_lshl_add_u64 v[248:249], v[244:245], 0, s[98:99]
	global_load_dwordx4 v[212:215], v[248:249], off nt
	global_load_dwordx4 v[216:219], v[248:249], off offset:16 nt
	global_load_dwordx4 v[220:223], v[248:249], off offset:512 nt
	global_load_dwordx4 v[224:227], v[248:249], off offset:528 nt
	v_add_u32_e32 v164, 48, v154
	v_ashrrev_i32_e32 v165, 31, v164
	v_lshlrev_b64 v[168:169], 12, v[164:165]
	v_lshl_add_u64 v[168:169], s[18:19], 0, v[168:169]
	v_lshl_add_u64 v[168:169], v[168:169], 0, v[158:159]
	s_nop 0
	v_pk_fma_f32 v[104:105], v[104:105], v[132:133], v[148:149]
	v_pk_fma_f32 v[102:103], v[102:103], v[130:131], v[146:147]
	s_nop 0
	v_pk_fma_f32 v[100:101], v[100:101], v[140:141], v[152:153]
	v_pk_fma_f32 v[98:99], v[98:99], v[138:139], v[150:151]
	s_nop 0
	v_pk_fma_f32 v[64:65], v[64:65], v[136:137], v[176:177]
	v_pk_fma_f32 v[62:63], v[62:63], v[134:135], v[174:175]
	s_nop 0
	v_pk_fma_f32 v[60:61], v[60:61], v[144:145], v[180:181]
	v_pk_fma_f32 v[58:59], v[58:59], v[142:143], v[178:179]
	v_add_u32_e32 v150, 0x80, v154
	s_waitcnt vmcnt(4)
; __device__ __forceinline__ float bf_lo(unsigned w) { return __uint_as_float(w << 16); }
; __device__ __forceinline__ float bf_hi(unsigned w) { return __uint_as_float(w & 0xffff0000u); }
;     __device__ __forceinline__ void fused(f32x4 (&acc)[2][2][4][2], const Unit& u, int wr, int wc, int fr, int fq, PG8_LAS unsigned char* lds, int wid, int lane) const {
;     ...
; #pragma unroll
;             for (int ai = 0; ai < 2; ++ai)
; #pragma unroll
;                 for (int m = 0; m < 4; ++m) { const int r = ai * HALF + wr * 64 + m * 16 + fr; const size_t off = (size_t)(u.pm * BM + r) * 1024 + col0;
; #pragma unroll
;                     for (int bj = 0; bj < 2; ++bj) { f32x4 b0, b1;
;                         if (XIN_BF16) { const u32x4 w = *(const u32x4*)((const bf16_t*)xin + off + bj * HALF); b0 = (f32x4){bf_lo(w.x), bf_hi(w.x), bf_lo(w.y), bf_hi(w.y)}; b1 = (f32x4){bf_lo(w.z), bf_hi(w.z), bf_lo(w.w), bf_hi(w.w)}; }
;                         else { b0 = *(const f32x4*)((const float*)xin + off + bj * HALF); b1 = *(const f32x4*)((const float*)xin + off + bj * HALF + 4); }
;                         acc[ai][bj][m][0] = b0 + gv[bj][0] * acc[ai][bj][m][0]; acc[ai][bj][m][1] = b1 + gv[bj][1] * acc[ai][bj][m][1]; }
;                     asm volatile("" : "+v"(acc[ai][0][m][0]), "+v"(acc[ai][0][m][1]), "+v"(acc[ai][1][m][0]), "+v"(acc[ai][1][m][1]));
;                     if (m == 3) asm volatile("" ::: "memory"); }
	v_mov_b32_e32 v146, v228
	v_mov_b32_e32 v147, v229
	v_mov_b32_e32 v148, v230
	v_mov_b32_e32 v149, v231
	v_mov_b32_e32 v174, v232
	v_mov_b32_e32 v175, v233
	v_mov_b32_e32 v176, v234
	v_mov_b32_e32 v177, v235
	v_mov_b32_e32 v178, v236
	v_mov_b32_e32 v179, v237
	v_mov_b32_e32 v180, v238
	v_mov_b32_e32 v181, v239
	v_mov_b32_e32 v182, v240
	v_mov_b32_e32 v183, v241
	v_mov_b32_e32 v184, v242
	v_mov_b32_e32 v185, v243
	s_mov_b64 s[98:99], 0x90000
	v_lshl_add_u64 v[248:249], v[244:245], 0, s[98:99]
	global_load_dwordx4 v[228:231], v[248:249], off nt
	global_load_dwordx4 v[232:235], v[248:249], off offset:16 nt
	global_load_dwordx4 v[236:239], v[248:249], off offset:512 nt
	global_load_dwordx4 v[240:243], v[248:249], off offset:528 nt
	v_ashrrev_i32_e32 v151, 31, v150
	v_lshlrev_b64 v[152:153], 12, v[150:151]
	v_lshl_add_u64 v[152:153], s[18:19], 0, v[152:153]
	v_lshl_add_u64 v[152:153], v[152:153], 0, v[158:159]
	s_nop 0
	v_pk_fma_f32 v[96:97], v[96:97], v[132:133], v[148:149]
	v_pk_fma_f32 v[94:95], v[94:95], v[130:131], v[146:147]
	s_nop 0
	v_pk_fma_f32 v[92:93], v[92:93], v[140:141], v[176:177]
	v_pk_fma_f32 v[90:91], v[90:91], v[138:139], v[174:175]
	s_nop 0
	v_pk_fma_f32 v[56:57], v[56:57], v[136:137], v[180:181]
	v_pk_fma_f32 v[54:55], v[54:55], v[134:135], v[178:179]
	s_nop 0
	v_pk_fma_f32 v[52:53], v[52:53], v[144:145], v[184:185]
	v_pk_fma_f32 v[50:51], v[50:51], v[142:143], v[182:183]
	v_add_u32_e32 v148, 0x90, v154
	s_waitcnt vmcnt(4)
	v_mov_b32_e32 v174, v212
	v_mov_b32_e32 v175, v213
	v_mov_b32_e32 v176, v214
	v_mov_b32_e32 v177, v215
	v_mov_b32_e32 v178, v216
	v_mov_b32_e32 v179, v217
	v_mov_b32_e32 v180, v218
	v_mov_b32_e32 v181, v219
	v_mov_b32_e32 v182, v220
	v_mov_b32_e32 v183, v221
	v_mov_b32_e32 v184, v222
	v_mov_b32_e32 v185, v223
	v_mov_b32_e32 v186, v224
	v_mov_b32_e32 v187, v225
	v_mov_b32_e32 v188, v226
	v_mov_b32_e32 v189, v227
	s_mov_b64 s[98:99], 0xa0000
	v_lshl_add_u64 v[248:249], v[244:245], 0, s[98:99]
	global_load_dwordx4 v[212:215], v[248:249], off nt
	global_load_dwordx4 v[216:219], v[248:249], off offset:16 nt
	global_load_dwordx4 v[220:223], v[248:249], off offset:512 nt
	global_load_dwordx4 v[224:227], v[248:249], off offset:528 nt
	v_ashrrev_i32_e32 v149, 31, v148
	v_lshlrev_b64 v[146:147], 12, v[148:149]
	v_lshl_add_u64 v[146:147], s[18:19], 0, v[146:147]
	v_lshl_add_u64 v[146:147], v[146:147], 0, v[158:159]
	s_nop 0
	v_pk_fma_f32 v[88:89], v[88:89], v[132:133], v[176:177]
	v_pk_fma_f32 v[86:87], v[86:87], v[130:131], v[174:175]
	s_nop 0
	v_pk_fma_f32 v[84:85], v[84:85], v[140:141], v[180:181]
	v_pk_fma_f32 v[82:83], v[82:83], v[138:139], v[178:179]
	s_nop 0
	v_pk_fma_f32 v[48:49], v[48:49], v[136:137], v[184:185]
	v_pk_fma_f32 v[46:47], v[46:47], v[134:135], v[182:183]
	s_nop 0
	v_pk_fma_f32 v[44:45], v[44:45], v[144:145], v[188:189]
	v_pk_fma_f32 v[42:43], v[42:43], v[142:143], v[186:187]
	s_nop 0
	s_waitcnt vmcnt(4)
	v_mov_b32_e32 v174, v228
	v_mov_b32_e32 v175, v229
	v_mov_b32_e32 v176, v230
	v_mov_b32_e32 v177, v231
	v_mov_b32_e32 v178, v232
	v_mov_b32_e32 v179, v233
	v_mov_b32_e32 v180, v234
	v_mov_b32_e32 v181, v235
	v_mov_b32_e32 v182, v236
	v_mov_b32_e32 v183, v237
	v_mov_b32_e32 v184, v238
	v_mov_b32_e32 v185, v239
	v_mov_b32_e32 v186, v240
	v_mov_b32_e32 v187, v241
	v_mov_b32_e32 v188, v242
	v_mov_b32_e32 v189, v243
	s_mov_b64 s[98:99], 0xb0000
	v_lshl_add_u64 v[248:249], v[244:245], 0, s[98:99]
	global_load_dwordx4 v[228:231], v[248:249], off nt
	global_load_dwordx4 v[232:235], v[248:249], off offset:16 nt
	global_load_dwordx4 v[236:239], v[248:249], off offset:512 nt
	global_load_dwordx4 v[240:243], v[248:249], off offset:528 nt
	v_add_u32_e32 v146, 0xa0, v154
	v_ashrrev_i32_e32 v147, 31, v146
	v_lshlrev_b64 v[152:153], 12, v[146:147]
	v_lshl_add_u64 v[152:153], s[18:19], 0, v[152:153]
	v_lshl_add_u64 v[152:153], v[152:153], 0, v[158:159]
	s_nop 0
	v_pk_fma_f32 v[80:81], v[80:81], v[132:133], v[176:177]
	v_pk_fma_f32 v[78:79], v[78:79], v[130:131], v[174:175]
	s_nop 0
	v_pk_fma_f32 v[76:77], v[76:77], v[140:141], v[180:181]
	v_pk_fma_f32 v[74:75], v[74:75], v[138:139], v[178:179]
	s_nop 0
	v_pk_fma_f32 v[40:41], v[40:41], v[136:137], v[184:185]
	v_pk_fma_f32 v[38:39], v[38:39], v[134:135], v[182:183]
	s_nop 0
	v_pk_fma_f32 v[36:37], v[36:37], v[144:145], v[188:189]
	v_pk_fma_f32 v[34:35], v[34:35], v[142:143], v[186:187]
	s_nop 0
	s_waitcnt vmcnt(4)
; __device__ __forceinline__ float bf_lo(unsigned w) { return __uint_as_float(w << 16); }
; __device__ __forceinline__ float bf_hi(unsigned w) { return __uint_as_float(w & 0xffff0000u); }
;     template <class Mid> __device__ __forceinline__ bool run(const f32x4 (&v)[2][2][4][2], const Unit& u, int wr, int wc, int fr, int fq, PG8_LAS unsigned char* lds, int wid, int lane, const Mid& mid) const {
;     ...
; #pragma unroll
;         for (int ai = 0; ai < 2; ++ai)
; #pragma unroll
;             for (int m = 0; m < 4; ++m) {
;                 float s = 0.f;
; #pragma unroll
;                 for (int bj = 0; bj < 2; ++bj)
; #pragma unroll
;                     for (int n = 0; n < 2; ++n) { const f32x4 x = v[ai][bj][m][n]; s += (x[0] + x[1]) + (x[2] + x[3]); }
;                 s += __shfl_xor(s, 16); s += __shfl_xor(s, 32);
;                 const float mw = s * (1.0f / 64.0f); float q = 0.f;
; #pragma unroll
;                 for (int bj = 0; bj < 2; ++bj)
; #pragma unroll
;                     for (int n = 0; n < 2; ++n) { const f32x4 d = v[ai][bj][m][n] - mw; q += (d[0] * d[0] + d[1] * d[1]) + (d[2] * d[2] + d[3] * d[3]); }
;                 q += __shfl_xor(q, 16); q += __shfl_xor(q, 32);
;                 if (fq == 0) P[(ai * HALF + wr * 64 + m * 16 + fr) * 4 + wc] = (f32x2v){mw, q};
;     __device__ __forceinline__ void fused(f32x4 (&acc)[2][2][4][2], const Unit& u, int wr, int wc, int fr, int fq, PG8_LAS unsigned char* lds, int wid, int lane) const {
;     ...
;                 for (int m = 0; m < 4; ++m) { const int r = ai * HALF + wr * 64 + m * 16 + fr; const size_t off = (size_t)(u.pm * BM + r) * 1024 + col0;
; #pragma unroll
;                     for (int bj = 0; bj < 2; ++bj) { f32x4 b0, b1;
;                         if (XIN_BF16) { const u32x4 w = *(const u32x4*)((const bf16_t*)xin + off + bj * HALF); b0 = (f32x4){bf_lo(w.x), bf_hi(w.x), bf_lo(w.y), bf_hi(w.y)}; b1 = (f32x4){bf_lo(w.z), bf_hi(w.z), bf_lo(w.w), bf_hi(w.w)}; }
;                         else { b0 = *(const f32x4*)((const float*)xin + off + bj * HALF); b1 = *(const f32x4*)((const float*)xin + off + bj * HALF + 4); }
;                         acc[ai][bj][m][0] = b0 + gv[bj][0] * acc[ai][bj][m][0]; acc[ai][bj][m][1] = b1 + gv[bj][1] * acc[ai][bj][m][1]; }
	v_mov_b32_e32 v174, v212
	v_mov_b32_e32 v175, v213
	v_mov_b32_e32 v176, v214
	v_mov_b32_e32 v177, v215
	v_mov_b32_e32 v178, v216
	v_mov_b32_e32 v179, v217
	v_mov_b32_e32 v180, v218
	v_mov_b32_e32 v181, v219
	v_mov_b32_e32 v182, v220
	v_mov_b32_e32 v183, v221
	v_mov_b32_e32 v184, v222
	v_mov_b32_e32 v185, v223
	v_mov_b32_e32 v186, v224
	v_mov_b32_e32 v187, v225
	v_mov_b32_e32 v188, v226
	v_mov_b32_e32 v189, v227
	v_and_b32_e32 v153, 64, v173
	v_xor_b32_e32 v152, 16, v173
	v_add_u32_e32 v208, 64, v153
	v_cmp_lt_i32_e32 vcc, v152, v208
	s_nop 0
	v_pk_fma_f32 v[32:33], v[32:33], v[132:133], v[176:177]
	v_cndmask_b32_e32 v152, v173, v152, vcc
	v_lshlrev_b32_e32 v167, 2, v152
	v_add_u32_e32 v152, 0xb0, v154
	v_ashrrev_i32_e32 v153, 31, v152
	v_lshlrev_b64 v[168:169], 12, v[152:153]
	v_lshl_add_u64 v[168:169], s[18:19], 0, v[168:169]
	v_lshl_add_u64 v[168:169], v[168:169], 0, v[158:159]
	v_pk_fma_f32 v[30:31], v[30:31], v[130:131], v[174:175]
	s_nop 0
	v_pk_fma_f32 v[28:29], v[28:29], v[140:141], v[180:181]
	v_pk_fma_f32 v[26:27], v[26:27], v[138:139], v[178:179]
	s_nop 0
	v_pk_fma_f32 v[24:25], v[24:25], v[136:137], v[184:185]
	v_pk_fma_f32 v[22:23], v[22:23], v[134:135], v[182:183]
	s_nop 0
	v_pk_fma_f32 v[20:21], v[20:21], v[144:145], v[188:189]
	v_pk_fma_f32 v[18:19], v[18:19], v[142:143], v[186:187]
	v_mov_b32_e32 v174, v127
	s_waitcnt vmcnt(0)
	v_mov_b32_e32 v176, v232
	v_mov_b32_e32 v177, v233
	v_mov_b32_e32 v178, v234
	v_mov_b32_e32 v179, v235
	v_mov_b32_e32 v180, v228
	v_mov_b32_e32 v181, v229
	v_mov_b32_e32 v182, v230
	v_mov_b32_e32 v183, v231
	v_mov_b32_e32 v184, v240
	v_mov_b32_e32 v185, v241
	v_mov_b32_e32 v186, v242
	v_mov_b32_e32 v187, v243
	v_mov_b32_e32 v188, v236
	v_mov_b32_e32 v189, v237
	v_mov_b32_e32 v190, v238
	v_mov_b32_e32 v191, v239
	v_mov_b32_e32 v175, v128
	v_mov_b32_e32 v168, v126
	v_mov_b32_e32 v169, v129
	v_pk_add_f32 v[168:169], v[174:175], v[168:169]
	v_pk_add_f32 v[174:175], v[196:197], v[198:199]
	v_pk_add_f32 v[168:169], v[168:169], v[168:169] op_sel_hi:[0,1]
	v_mov_b32_e32 v168, v116
	v_pk_add_f32 v[168:169], v[168:169], v[206:207]
	s_nop 0
	v_pk_fma_f32 v[12:13], v[12:13], v[140:141], v[178:179]
	v_pk_add_f32 v[168:169], v[174:175], v[168:169]
	s_nop 0
	v_pk_fma_f32 v[16:17], v[16:17], v[132:133], v[182:183]
	v_add_f32_e32 v168, v168, v169
	ds_bpermute_b32 v174, v167, v168
	v_xor_b32_e32 v169, 32, v173
	v_cmp_lt_i32_e32 vcc, v169, v208
	v_pk_fma_f32 v[14:15], v[14:15], v[130:131], v[180:181]
	v_pk_fma_f32 v[10:11], v[10:11], v[138:139], v[176:177]
	v_cndmask_b32_e32 v169, v173, v169, vcc
	v_lshlrev_b32_e32 v169, 2, v169
	s_waitcnt lgkmcnt(0)
	v_add_f32_e32 v168, v168, v174
	ds_bpermute_b32 v173, v169, v168
	s_nop 0
	v_pk_fma_f32 v[8:9], v[8:9], v[136:137], v[190:191]
	v_pk_fma_f32 v[6:7], v[6:7], v[134:135], v[188:189]
	v_pk_fma_f32 v[4:5], v[4:5], v[144:145], v[186:187]
	v_pk_fma_f32 v[2:3], v[2:3], v[142:143], v[184:185]
	s_waitcnt lgkmcnt(0)
	v_add_f32_e32 v173, v168, v173
	v_fmamk_f32 v174, v173, 0xbc800000, v125
	v_fmamk_f32 v192, v173, 0xbc800000, v123
	v_fmamk_f32 v194, v173, 0xbc800000, v129
	v_fmamk_f32 v196, v173, 0xbc800000, v127
	v_fmamk_f32 v168, v173, 0xbc800000, v124
	v_fmamk_f32 v175, v173, 0xbc800000, v122
	v_fmamk_f32 v193, v173, 0xbc800000, v128
	v_fmamk_f32 v195, v173, 0xbc800000, v126
	v_fmamk_f32 v198, v173, 0xbc800000, v121
	v_fmamk_f32 v206, v173, 0xbc800000, v119
	v_mul_f32_e32 v192, v192, v192
	v_mul_f32_e32 v174, v174, v174
	v_mul_f32_e32 v196, v196, v196
	v_mul_f32_e32 v194, v194, v194
	v_fmamk_f32 v197, v173, 0xbc800000, v120
	v_fmamk_f32 v199, v173, 0xbc800000, v118
	v_fmamk_f32 v208, v173, 0xbc800000, v117
	v_fmamk_f32 v210, v173, 0xbc800000, v115
	v_mul_f32_e32 v206, v206, v206
	v_mul_f32_e32 v198, v198, v198
	v_fmac_f32_e32 v192, v175, v175
	v_fmac_f32_e32 v174, v168, v168
	v_fmac_f32_e32 v196, v195, v195
	v_fmac_f32_e32 v194, v193, v193
	v_fmamk_f32 v207, v173, 0xbc800000, v116
	v_fmamk_f32 v209, v173, 0xbc800000, v114
	v_mul_f32_e32 v210, v210, v210
	v_mul_f32_e32 v208, v208, v208
	v_fmac_f32_e32 v206, v199, v199
	v_fmac_f32_e32 v198, v197, v197
	v_add_f32_e32 v168, v192, v174
	v_add_f32_e32 v174, v196, v194
	v_fmac_f32_e32 v210, v209, v209
	v_fmac_f32_e32 v208, v207, v207
	v_add_f32_e32 v175, v206, v198
	v_add_f32_e32 v168, v168, v174
	v_add_f32_e32 v192, v210, v208
	v_add_f32_e32 v168, v175, v168
	v_add_f32_e32 v174, v192, v168
	ds_bpermute_b32 v175, v167, v174
	v_and_b32_e32 v168, 63, v166
	v_cmp_gt_u32_e32 vcc, 16, v168
	s_waitcnt lgkmcnt(0)
	v_add_f32_e32 v174, v174, v175
	ds_bpermute_b32 v175, v169, v174
	s_and_saveexec_b64 s[6:7], vcc
	s_cbranch_execz .LBB0_734
	s_lshl_b32 s9, s23, 11
	s_add_i32 s9, s8, s9
	v_mul_f32_e32 v130, 0x3c800000, v173
	s_waitcnt lgkmcnt(0)
	v_add_f32_e32 v131, v174, v175
	v_lshl_add_u32 v132, v171, 5, s9
	ds_write_b64 v132, v[130:131]

; __device__ __forceinline__ float sigm(float v) { return __builtin_amdgcn_rcpf(1.0f + __expf(-v)); }
; __device__ __forceinline__ unsigned f2bf(float f) { unsigned u = __builtin_bit_cast(unsigned, f); return (u + 0x7fffu + ((u >> 16) & 1u)) >> 16; }
; __global__ void __launch_bounds__(512, 2) fwd_mega(Args a) {
;     ...
;                     for (int idx = threadIdx.x; idx < 2 * FF; idx += 512) {
;                         const int j = idx / FF, f = idx % FF; const size_t cur = (size_t)fu.pm * 2 * FF, prv = (size_t)(fu.pm - 1) * 2 * FF;
;                         const float a2 = RA[cur + j * FF + f], a1 = (j == 0) ? TA[prv + FF + f] : RA[cur + f], a0 = (j == 0) ? TA[prv + f] : TA[prv + FF + f];
;                         const float cv = cbp[f] + cw[f] * a0 + cw[FF + f] * a1 + cw[2 * FF + f] * a2;
;                         WSP(WS_ACT)[(size_t)(fu.pm * 256 + j) * FF + f] = (bf16)f2bf(cv * pg8::sigm(cv) * RU[cur + j * FF + f]);
.LBB0_914:
	v_subrev_co_u32_e32 v6, vcc, 0xb00, v17
	s_nop 0
	v_mov_b32_e32 v41, v7
	v_cndmask_b32_e32 v40, v6, v17, vcc
	v_cmp_lt_u32_e64 s[6:7], s25, v17
	v_cndmask_b32_e32 v45, v11, v12, vcc
	v_cndmask_b32_e32 v44, v13, v14, vcc
	v_lshlrev_b64 v[46:47], 2, v[40:41]
	v_cndmask_b32_e32 v49, v12, v15, vcc
	v_cndmask_b32_e32 v48, v14, v16, vcc
	v_cndmask_b32_e64 v6, 0, v10, s[6:7]
	v_lshl_add_u64 v[44:45], v[44:45], 0, v[46:47]
	v_lshl_add_u64 v[48:49], v[48:49], 0, v[46:47]
	v_lshl_add_u64 v[50:51], s[10:11], 0, v[46:47]
	v_lshl_add_u64 v[46:47], s[8:9], 0, v[46:47]
	v_lshl_add_u64 v[42:43], v[6:7], 0, s[18:19]
	global_load_dword v44, v[44:45], off nt
	s_nop 0
	global_load_dword v57, v[48:49], off nt
	global_load_dword v53, v[50:51], off nt
	global_load_dword v54, v[46:47], off nt
	v_add_co_u32_e32 v48, vcc, s30, v46
	v_lshl_add_u64 v[42:43], v[42:43], 0, v[40:41]
	s_nop 0
	v_addc_co_u32_e32 v49, vcc, 0, v47, vcc
	v_lshlrev_b64 v[42:43], 2, v[42:43]
	v_add_co_u32_e32 v46, vcc, s31, v46
	v_lshl_add_u64 v[50:51], s[14:15], 0, v[42:43]
	s_nop 0
	v_addc_co_u32_e32 v47, vcc, 0, v47, vcc
	global_load_dword v48, v[48:49], off offset:3072 nt
	s_nop 0
	global_load_dword v49, v[46:47], off offset:2048 nt
	global_load_dword v45, v[50:51], off nt
	v_lshl_add_u64 v[42:43], s[16:17], 0, v[42:43]
	global_load_dword v46, v[42:43], off nt
	v_cndmask_b32_e64 v52, 0, 1, s[6:7]
	v_add_u32_e32 v17, 0x200, v17
	v_subrev_co_u32_e32 v6, vcc, 0xb00, v17
	s_nop 0
	v_mov_b32_e32 v59, v7
	v_cndmask_b32_e32 v58, v6, v17, vcc
	v_cmp_lt_u32_e64 s[6:7], s25, v17
	v_cndmask_b32_e32 v63, v11, v12, vcc
	v_cndmask_b32_e32 v62, v13, v14, vcc
	v_lshlrev_b64 v[64:65], 2, v[58:59]
	v_cndmask_b32_e32 v67, v12, v15, vcc
	v_cndmask_b32_e32 v66, v14, v16, vcc
	v_cndmask_b32_e64 v6, 0, v10, s[6:7]
	v_lshl_add_u64 v[62:63], v[62:63], 0, v[64:65]
	v_lshl_add_u64 v[66:67], v[66:67], 0, v[64:65]
	v_lshl_add_u64 v[68:69], s[10:11], 0, v[64:65]
	v_lshl_add_u64 v[64:65], s[8:9], 0, v[64:65]
	v_lshl_add_u64 v[60:61], v[6:7], 0, s[18:19]
	global_load_dword v62, v[62:63], off nt
	s_nop 0
	global_load_dword v75, v[66:67], off nt
	global_load_dword v71, v[68:69], off nt
	global_load_dword v72, v[64:65], off nt
	v_add_co_u32_e32 v66, vcc, s30, v64
	v_lshl_add_u64 v[60:61], v[60:61], 0, v[58:59]
	s_nop 0
	v_addc_co_u32_e32 v67, vcc, 0, v65, vcc
	v_lshlrev_b64 v[60:61], 2, v[60:61]
	v_add_co_u32_e32 v64, vcc, s31, v64
	v_lshl_add_u64 v[68:69], s[14:15], 0, v[60:61]
	s_nop 0
	v_addc_co_u32_e32 v65, vcc, 0, v65, vcc
	global_load_dword v66, v[66:67], off offset:3072 nt
	s_nop 0
	global_load_dword v67, v[64:65], off offset:2048 nt
	global_load_dword v63, v[68:69], off nt
	v_lshl_add_u64 v[60:61], s[16:17], 0, v[60:61]
	global_load_dword v64, v[60:61], off nt
	v_cndmask_b32_e64 v70, 0, 1, s[6:7]
	v_add_u32_e32 v17, 0x200, v17
	v_subrev_co_u32_e32 v6, vcc, 0xb00, v17
	s_nop 0
	v_mov_b32_e32 v77, v7
	v_cndmask_b32_e32 v76, v6, v17, vcc
	v_cmp_lt_u32_e64 s[6:7], s25, v17
	v_cndmask_b32_e32 v81, v11, v12, vcc
	v_cndmask_b32_e32 v80, v13, v14, vcc
	v_lshlrev_b64 v[82:83], 2, v[76:77]
	v_cndmask_b32_e32 v85, v12, v15, vcc
	v_cndmask_b32_e32 v84, v14, v16, vcc
	v_cndmask_b32_e64 v6, 0, v10, s[6:7]
	v_lshl_add_u64 v[80:81], v[80:81], 0, v[82:83]
	v_lshl_add_u64 v[84:85], v[84:85], 0, v[82:83]
	v_lshl_add_u64 v[86:87], s[10:11], 0, v[82:83]
	v_lshl_add_u64 v[82:83], s[8:9], 0, v[82:83]
	v_lshl_add_u64 v[78:79], v[6:7], 0, s[18:19]
	global_load_dword v80, v[80:81], off nt
	s_nop 0
	global_load_dword v93, v[84:85], off nt
	global_load_dword v89, v[86:87], off nt
	global_load_dword v90, v[82:83], off nt
	v_add_co_u32_e32 v84, vcc, s30, v82
	v_lshl_add_u64 v[78:79], v[78:79], 0, v[76:77]
	s_nop 0
	v_addc_co_u32_e32 v85, vcc, 0, v83, vcc
	v_lshlrev_b64 v[78:79], 2, v[78:79]
	v_add_co_u32_e32 v82, vcc, s31, v82
	v_lshl_add_u64 v[86:87], s[14:15], 0, v[78:79]
	s_nop 0
	v_addc_co_u32_e32 v83, vcc, 0, v83, vcc
	global_load_dword v84, v[84:85], off offset:3072 nt
	s_nop 0
	global_load_dword v85, v[82:83], off offset:2048 nt
	global_load_dword v81, v[86:87], off nt
	v_lshl_add_u64 v[78:79], s[16:17], 0, v[78:79]
	global_load_dword v82, v[78:79], off nt
	v_cndmask_b32_e64 v88, 0, 1, s[6:7]
	v_add_u32_e32 v17, 0x200, v17
	v_subrev_co_u32_e32 v6, vcc, 0xb00, v17
	s_nop 0
	v_mov_b32_e32 v95, v7
	v_cndmask_b32_e32 v94, v6, v17, vcc
	v_cmp_lt_u32_e64 s[6:7], s25, v17
	v_cndmask_b32_e32 v99, v11, v12, vcc
	v_cndmask_b32_e32 v98, v13, v14, vcc
	v_lshlrev_b64 v[100:101], 2, v[94:95]
	v_cndmask_b32_e32 v103, v12, v15, vcc
	v_cndmask_b32_e32 v102, v14, v16, vcc
	v_cndmask_b32_e64 v6, 0, v10, s[6:7]
	v_lshl_add_u64 v[98:99], v[98:99], 0, v[100:101]
	v_lshl_add_u64 v[102:103], v[102:103], 0, v[100:101]
	v_lshl_add_u64 v[104:105], s[10:11], 0, v[100:101]
	v_lshl_add_u64 v[100:101], s[8:9], 0, v[100:101]
	v_lshl_add_u64 v[96:97], v[6:7], 0, s[18:19]
	global_load_dword v98, v[98:99], off nt
	s_nop 0
	global_load_dword v111, v[102:103], off nt
	global_load_dword v107, v[104:105], off nt
	global_load_dword v108, v[100:101], off nt
	v_add_co_u32_e32 v102, vcc, s30, v100
	v_lshl_add_u64 v[96:97], v[96:97], 0, v[94:95]
	s_nop 0
	v_addc_co_u32_e32 v103, vcc, 0, v101, vcc
	v_lshlrev_b64 v[96:97], 2, v[96:97]
	v_add_co_u32_e32 v100, vcc, s31, v100
	v_lshl_add_u64 v[104:105], s[14:15], 0, v[96:97]
	s_nop 0
	v_addc_co_u32_e32 v101, vcc, 0, v101, vcc
	global_load_dword v102, v[102:103], off offset:3072 nt
	s_nop 0
	global_load_dword v103, v[100:101], off offset:2048 nt
	global_load_dword v99, v[104:105], off nt
	v_lshl_add_u64 v[96:97], s[16:17], 0, v[96:97]
	global_load_dword v100, v[96:97], off nt
	v_cndmask_b32_e64 v106, 0, 1, s[6:7]
; __device__ __forceinline__ float sigm(float v) { return __builtin_amdgcn_rcpf(1.0f + __expf(-v)); }
; __device__ __forceinline__ unsigned f2bf(float f) { unsigned u = __builtin_bit_cast(unsigned, f); return (u + 0x7fffu + ((u >> 16) & 1u)) >> 16; }
; __global__ void __launch_bounds__(512, 2) fwd_mega(Args a) {
;     ...
;                     for (int idx = threadIdx.x; idx < 2 * FF; idx += 512) {
;                         const int j = idx / FF, f = idx % FF; const size_t cur = (size_t)fu.pm * 2 * FF, prv = (size_t)(fu.pm - 1) * 2 * FF;
;                         const float a2 = RA[cur + j * FF + f], a1 = (j == 0) ? TA[prv + FF + f] : RA[cur + f], a0 = (j == 0) ? TA[prv + f] : TA[prv + FF + f];
;                         const float cv = cbp[f] + cw[f] * a0 + cw[FF + f] * a1 + cw[2 * FF + f] * a2;
;                         WSP(WS_ACT)[(size_t)(fu.pm * 256 + j) * FF + f] = (bf16)f2bf(cv * pg8::sigm(cv) * RU[cur + j * FF + f]);
	v_add_u32_e32 v17, 0x200, v17
	v_subrev_co_u32_e32 v6, vcc, 0xb00, v17
	s_nop 0
	v_mov_b32_e32 v113, v7
	v_cndmask_b32_e32 v112, v6, v17, vcc
	v_cmp_lt_u32_e64 s[6:7], s25, v17
	v_cndmask_b32_e32 v117, v11, v12, vcc
	v_cndmask_b32_e32 v116, v13, v14, vcc
	v_lshlrev_b64 v[118:119], 2, v[112:113]
	v_cndmask_b32_e32 v121, v12, v15, vcc
	v_cndmask_b32_e32 v120, v14, v16, vcc
	v_cndmask_b32_e64 v6, 0, v10, s[6:7]
	v_lshl_add_u64 v[116:117], v[116:117], 0, v[118:119]
	v_lshl_add_u64 v[120:121], v[120:121], 0, v[118:119]
	v_lshl_add_u64 v[122:123], s[10:11], 0, v[118:119]
	v_lshl_add_u64 v[118:119], s[8:9], 0, v[118:119]
	v_lshl_add_u64 v[114:115], v[6:7], 0, s[18:19]
	global_load_dword v116, v[116:117], off nt
	s_nop 0
	global_load_dword v129, v[120:121], off nt
	global_load_dword v125, v[122:123], off nt
	global_load_dword v126, v[118:119], off nt
	v_add_co_u32_e32 v120, vcc, s30, v118
	v_lshl_add_u64 v[114:115], v[114:115], 0, v[112:113]
	s_nop 0
	v_addc_co_u32_e32 v121, vcc, 0, v119, vcc
	v_lshlrev_b64 v[114:115], 2, v[114:115]
	v_add_co_u32_e32 v118, vcc, s31, v118
	v_lshl_add_u64 v[122:123], s[14:15], 0, v[114:115]
	s_nop 0
	v_addc_co_u32_e32 v119, vcc, 0, v119, vcc
	global_load_dword v120, v[120:121], off offset:3072 nt
	s_nop 0
	global_load_dword v121, v[118:119], off offset:2048 nt
	global_load_dword v117, v[122:123], off nt
	v_lshl_add_u64 v[114:115], s[16:17], 0, v[114:115]
	global_load_dword v118, v[114:115], off nt
	v_cndmask_b32_e64 v124, 0, 1, s[6:7]
	v_add_u32_e32 v17, 0x200, v17
	v_subrev_co_u32_e32 v6, vcc, 0xb00, v17
	s_nop 0
	v_mov_b32_e32 v131, v7
	v_cndmask_b32_e32 v130, v6, v17, vcc
	v_cmp_lt_u32_e64 s[6:7], s25, v17
	v_cndmask_b32_e32 v135, v11, v12, vcc
	v_cndmask_b32_e32 v134, v13, v14, vcc
	v_lshlrev_b64 v[136:137], 2, v[130:131]
	v_cndmask_b32_e32 v139, v12, v15, vcc
	v_cndmask_b32_e32 v138, v14, v16, vcc
	v_cndmask_b32_e64 v6, 0, v10, s[6:7]
	v_lshl_add_u64 v[134:135], v[134:135], 0, v[136:137]
	v_lshl_add_u64 v[138:139], v[138:139], 0, v[136:137]
	v_lshl_add_u64 v[140:141], s[10:11], 0, v[136:137]
	v_lshl_add_u64 v[136:137], s[8:9], 0, v[136:137]
	v_lshl_add_u64 v[132:133], v[6:7], 0, s[18:19]
	global_load_dword v134, v[134:135], off nt
	s_nop 0
	global_load_dword v147, v[138:139], off nt
	global_load_dword v143, v[140:141], off nt
	global_load_dword v144, v[136:137], off nt
	v_add_co_u32_e32 v138, vcc, s30, v136
	v_lshl_add_u64 v[132:133], v[132:133], 0, v[130:131]
	s_nop 0
	v_addc_co_u32_e32 v139, vcc, 0, v137, vcc
	v_lshlrev_b64 v[132:133], 2, v[132:133]
	v_add_co_u32_e32 v136, vcc, s31, v136
	v_lshl_add_u64 v[140:141], s[14:15], 0, v[132:133]
	s_nop 0
	v_addc_co_u32_e32 v137, vcc, 0, v137, vcc
	global_load_dword v138, v[138:139], off offset:3072 nt
	s_nop 0
	global_load_dword v139, v[136:137], off offset:2048 nt
	global_load_dword v135, v[140:141], off nt
	v_lshl_add_u64 v[132:133], s[16:17], 0, v[132:133]
	global_load_dword v136, v[132:133], off nt
	v_cndmask_b32_e64 v142, 0, 1, s[6:7]
	v_add_u32_e32 v17, 0x200, v17
	s_waitcnt vmcnt(40)
	v_fmac_f32_e32 v53, v57, v54
	s_nop 0
	v_pk_mul_f32 v[42:43], v[44:45], v[48:49]
	s_nop 0
	v_add_f32_e32 v57, v53, v42
	v_add_f32_e32 v57, v57, v43
	v_mul_f32_e32 v42, 0xbfb8aa3b, v57
	v_exp_f32_e32 v42, v42
	v_or_b32_e32 v43, s37, v52
	v_add_f32_e32 v42, 1.0, v42
	v_rcp_f32_e32 v44, v42
	v_mad_i64_i32 v[42:43], s[6:7], v43, s24, v[8:9]
	v_lshl_add_u64 v[40:41], v[40:41], 1, v[42:43]
	v_mul_f32_e32 v57, v57, v44
	s_nop 0
	v_mul_f32_e32 v57, v46, v57
	v_bfe_u32 v42, v57, 16, 1
	v_add3_u32 v57, v57, v42, s34
	global_store_short_d16_hi v[40:41], v57, off
	s_waitcnt vmcnt(33)
	v_fmac_f32_e32 v71, v75, v72
	s_nop 0
	v_pk_mul_f32 v[60:61], v[62:63], v[66:67]
	s_nop 0
	v_add_f32_e32 v75, v71, v60
	v_add_f32_e32 v75, v75, v61
	v_mul_f32_e32 v60, 0xbfb8aa3b, v75
	v_exp_f32_e32 v60, v60
	v_or_b32_e32 v61, s37, v70
	v_add_f32_e32 v60, 1.0, v60
	v_rcp_f32_e32 v62, v60
	v_mad_i64_i32 v[60:61], s[6:7], v61, s24, v[8:9]
	v_lshl_add_u64 v[58:59], v[58:59], 1, v[60:61]
	v_mul_f32_e32 v75, v75, v62
	s_nop 0
	v_mul_f32_e32 v75, v64, v75
	v_bfe_u32 v60, v75, 16, 1
	v_add3_u32 v75, v75, v60, s34
	global_store_short_d16_hi v[58:59], v75, off
	s_waitcnt vmcnt(26)
	v_fmac_f32_e32 v89, v93, v90
	s_nop 0
	v_pk_mul_f32 v[78:79], v[80:81], v[84:85]
	s_nop 0
	v_add_f32_e32 v93, v89, v78
	v_add_f32_e32 v93, v93, v79
	v_mul_f32_e32 v78, 0xbfb8aa3b, v93
	v_exp_f32_e32 v78, v78
	v_or_b32_e32 v79, s37, v88
	v_add_f32_e32 v78, 1.0, v78
	v_rcp_f32_e32 v80, v78
	v_mad_i64_i32 v[78:79], s[6:7], v79, s24, v[8:9]
	v_lshl_add_u64 v[76:77], v[76:77], 1, v[78:79]
	v_mul_f32_e32 v93, v93, v80
	s_nop 0
	v_mul_f32_e32 v93, v82, v93
	v_bfe_u32 v78, v93, 16, 1
	v_add3_u32 v93, v93, v78, s34
	global_store_short_d16_hi v[76:77], v93, off
	s_waitcnt vmcnt(19)
	v_fmac_f32_e32 v107, v111, v108
	s_nop 0
	v_pk_mul_f32 v[96:97], v[98:99], v[102:103]
	s_nop 0
	v_add_f32_e32 v111, v107, v96
	v_add_f32_e32 v111, v111, v97
	v_mul_f32_e32 v96, 0xbfb8aa3b, v111
	v_exp_f32_e32 v96, v96
	v_or_b32_e32 v97, s37, v106
	v_add_f32_e32 v96, 1.0, v96
	v_rcp_f32_e32 v98, v96
	v_mad_i64_i32 v[96:97], s[6:7], v97, s24, v[8:9]
	v_lshl_add_u64 v[94:95], v[94:95], 1, v[96:97]
	v_mul_f32_e32 v111, v111, v98
	s_nop 0
	v_mul_f32_e32 v111, v100, v111
	v_bfe_u32 v96, v111, 16, 1
	v_add3_u32 v111, v111, v96, s34
	global_store_short_d16_hi v[94:95], v111, off
	s_waitcnt vmcnt(12)
; __device__ __forceinline__ float sigm(float v) { return __builtin_amdgcn_rcpf(1.0f + __expf(-v)); }
; __device__ __forceinline__ unsigned f2bf(float f) { unsigned u = __builtin_bit_cast(unsigned, f); return (u + 0x7fffu + ((u >> 16) & 1u)) >> 16; }
; __global__ void __launch_bounds__(512, 2) fwd_mega(Args a) {
;     ...
;                     for (int idx = threadIdx.x; idx < 2 * FF; idx += 512) {
;                         const int j = idx / FF, f = idx % FF; const size_t cur = (size_t)fu.pm * 2 * FF, prv = (size_t)(fu.pm - 1) * 2 * FF;
;                         const float a2 = RA[cur + j * FF + f], a1 = (j == 0) ? TA[prv + FF + f] : RA[cur + f], a0 = (j == 0) ? TA[prv + f] : TA[prv + FF + f];
;                         const float cv = cbp[f] + cw[f] * a0 + cw[FF + f] * a1 + cw[2 * FF + f] * a2;
;                         WSP(WS_ACT)[(size_t)(fu.pm * 256 + j) * FF + f] = (bf16)f2bf(cv * pg8::sigm(cv) * RU[cur + j * FF + f]);
	v_fmac_f32_e32 v125, v129, v126
	s_nop 0
	v_pk_mul_f32 v[114:115], v[116:117], v[120:121]
	s_nop 0
	v_add_f32_e32 v129, v125, v114
	v_add_f32_e32 v129, v129, v115
	v_mul_f32_e32 v114, 0xbfb8aa3b, v129
	v_exp_f32_e32 v114, v114
	v_or_b32_e32 v115, s37, v124
	v_add_f32_e32 v114, 1.0, v114
	v_rcp_f32_e32 v116, v114
	v_mad_i64_i32 v[114:115], s[6:7], v115, s24, v[8:9]
	v_lshl_add_u64 v[112:113], v[112:113], 1, v[114:115]
	v_mul_f32_e32 v129, v129, v116
	s_nop 0
	v_mul_f32_e32 v129, v118, v129
	v_bfe_u32 v114, v129, 16, 1
	v_add3_u32 v129, v129, v114, s34
	global_store_short_d16_hi v[112:113], v129, off
	s_waitcnt vmcnt(5)
	v_fmac_f32_e32 v143, v147, v144
	s_nop 0
	v_pk_mul_f32 v[132:133], v[134:135], v[138:139]
	s_nop 0
	v_add_f32_e32 v147, v143, v132
	v_add_f32_e32 v147, v147, v133
	v_mul_f32_e32 v132, 0xbfb8aa3b, v147
	v_exp_f32_e32 v132, v132
	v_or_b32_e32 v133, s37, v142
	v_add_f32_e32 v132, 1.0, v132
	v_rcp_f32_e32 v134, v132
	v_mad_i64_i32 v[132:133], s[6:7], v133, s24, v[8:9]
	v_lshl_add_u64 v[130:131], v[130:131], 1, v[132:133]
	v_mul_f32_e32 v147, v147, v134
	s_nop 0
	v_mul_f32_e32 v147, v136, v147
	v_bfe_u32 v132, v147, 16, 1
	v_add3_u32 v147, v147, v132, s34
	global_store_short_d16_hi v[130:131], v147, off
	v_subrev_co_u32_e32 v6, vcc, 0xb00, v17
	s_nop 0
	v_mov_b32_e32 v41, v7
	v_cndmask_b32_e32 v40, v6, v17, vcc
	v_cmp_lt_u32_e64 s[6:7], s25, v17
	v_cndmask_b32_e32 v45, v11, v12, vcc
	v_cndmask_b32_e32 v44, v13, v14, vcc
	v_lshlrev_b64 v[46:47], 2, v[40:41]
	v_cndmask_b32_e32 v49, v12, v15, vcc
	v_cndmask_b32_e32 v48, v14, v16, vcc
	v_cndmask_b32_e64 v6, 0, v10, s[6:7]
	v_lshl_add_u64 v[44:45], v[44:45], 0, v[46:47]
	v_lshl_add_u64 v[48:49], v[48:49], 0, v[46:47]
	v_lshl_add_u64 v[50:51], s[10:11], 0, v[46:47]
	v_lshl_add_u64 v[46:47], s[8:9], 0, v[46:47]
	v_lshl_add_u64 v[42:43], v[6:7], 0, s[18:19]
	global_load_dword v44, v[44:45], off nt
	s_nop 0
	global_load_dword v57, v[48:49], off nt
	global_load_dword v53, v[50:51], off nt
	global_load_dword v54, v[46:47], off nt
	v_add_co_u32_e32 v48, vcc, s30, v46
	v_lshl_add_u64 v[42:43], v[42:43], 0, v[40:41]
	s_nop 0
	v_addc_co_u32_e32 v49, vcc, 0, v47, vcc
	v_lshlrev_b64 v[42:43], 2, v[42:43]
	v_add_co_u32_e32 v46, vcc, s31, v46
	v_lshl_add_u64 v[50:51], s[14:15], 0, v[42:43]
	s_nop 0
	v_addc_co_u32_e32 v47, vcc, 0, v47, vcc
	global_load_dword v48, v[48:49], off offset:3072 nt
	s_nop 0
	global_load_dword v49, v[46:47], off offset:2048 nt
	global_load_dword v45, v[50:51], off nt
	v_lshl_add_u64 v[42:43], s[16:17], 0, v[42:43]
	global_load_dword v46, v[42:43], off nt
	v_cndmask_b32_e64 v52, 0, 1, s[6:7]
	v_add_u32_e32 v17, 0x200, v17
	v_subrev_co_u32_e32 v6, vcc, 0xb00, v17
	s_nop 0
	v_mov_b32_e32 v59, v7
	v_cndmask_b32_e32 v58, v6, v17, vcc
	v_cmp_lt_u32_e64 s[6:7], s25, v17
	v_cndmask_b32_e32 v63, v11, v12, vcc
	v_cndmask_b32_e32 v62, v13, v14, vcc
	v_lshlrev_b64 v[64:65], 2, v[58:59]
	v_cndmask_b32_e32 v67, v12, v15, vcc
	v_cndmask_b32_e32 v66, v14, v16, vcc
	v_cndmask_b32_e64 v6, 0, v10, s[6:7]
	v_lshl_add_u64 v[62:63], v[62:63], 0, v[64:65]
	v_lshl_add_u64 v[66:67], v[66:67], 0, v[64:65]
	v_lshl_add_u64 v[68:69], s[10:11], 0, v[64:65]
	v_lshl_add_u64 v[64:65], s[8:9], 0, v[64:65]
	v_lshl_add_u64 v[60:61], v[6:7], 0, s[18:19]
	global_load_dword v62, v[62:63], off nt
	s_nop 0
	global_load_dword v75, v[66:67], off nt
	global_load_dword v71, v[68:69], off nt
	global_load_dword v72, v[64:65], off nt
	v_add_co_u32_e32 v66, vcc, s30, v64
	v_lshl_add_u64 v[60:61], v[60:61], 0, v[58:59]
	s_nop 0
	v_addc_co_u32_e32 v67, vcc, 0, v65, vcc
	v_lshlrev_b64 v[60:61], 2, v[60:61]
	v_add_co_u32_e32 v64, vcc, s31, v64
	v_lshl_add_u64 v[68:69], s[14:15], 0, v[60:61]
	s_nop 0
	v_addc_co_u32_e32 v65, vcc, 0, v65, vcc
	global_load_dword v66, v[66:67], off offset:3072 nt
	s_nop 0
	global_load_dword v67, v[64:65], off offset:2048 nt
	global_load_dword v63, v[68:69], off nt
	v_lshl_add_u64 v[60:61], s[16:17], 0, v[60:61]
	global_load_dword v64, v[60:61], off nt
	v_cndmask_b32_e64 v70, 0, 1, s[6:7]
	v_add_u32_e32 v17, 0x200, v17
	v_subrev_co_u32_e32 v6, vcc, 0xb00, v17
	s_nop 0
	v_mov_b32_e32 v77, v7
	v_cndmask_b32_e32 v76, v6, v17, vcc
	v_cmp_lt_u32_e64 s[6:7], s25, v17
	v_cndmask_b32_e32 v81, v11, v12, vcc
	v_cndmask_b32_e32 v80, v13, v14, vcc
	v_lshlrev_b64 v[82:83], 2, v[76:77]
	v_cndmask_b32_e32 v85, v12, v15, vcc
	v_cndmask_b32_e32 v84, v14, v16, vcc
	v_cndmask_b32_e64 v6, 0, v10, s[6:7]
	v_lshl_add_u64 v[80:81], v[80:81], 0, v[82:83]
	v_lshl_add_u64 v[84:85], v[84:85], 0, v[82:83]
	v_lshl_add_u64 v[86:87], s[10:11], 0, v[82:83]
	v_lshl_add_u64 v[82:83], s[8:9], 0, v[82:83]
	v_lshl_add_u64 v[78:79], v[6:7], 0, s[18:19]
	global_load_dword v80, v[80:81], off nt
	s_nop 0
	global_load_dword v93, v[84:85], off nt
	global_load_dword v89, v[86:87], off nt
	global_load_dword v90, v[82:83], off nt
	v_add_co_u32_e32 v84, vcc, s30, v82
	v_lshl_add_u64 v[78:79], v[78:79], 0, v[76:77]
	s_nop 0
	v_addc_co_u32_e32 v85, vcc, 0, v83, vcc
	v_lshlrev_b64 v[78:79], 2, v[78:79]
	v_add_co_u32_e32 v82, vcc, s31, v82
	v_lshl_add_u64 v[86:87], s[14:15], 0, v[78:79]
	s_nop 0
	v_addc_co_u32_e32 v83, vcc, 0, v83, vcc
	global_load_dword v84, v[84:85], off offset:3072 nt
	s_nop 0
	global_load_dword v85, v[82:83], off offset:2048 nt
	global_load_dword v81, v[86:87], off nt
	v_lshl_add_u64 v[78:79], s[16:17], 0, v[78:79]
	global_load_dword v82, v[78:79], off nt
	v_cndmask_b32_e64 v88, 0, 1, s[6:7]
	v_add_u32_e32 v17, 0x200, v17
	v_subrev_co_u32_e32 v6, vcc, 0xb00, v17
	s_nop 0
	v_mov_b32_e32 v95, v7
	v_cndmask_b32_e32 v94, v6, v17, vcc
	v_cmp_lt_u32_e64 s[6:7], s25, v17
	v_cndmask_b32_e32 v99, v11, v12, vcc
	v_cndmask_b32_e32 v98, v13, v14, vcc
; __device__ __forceinline__ float sigm(float v) { return __builtin_amdgcn_rcpf(1.0f + __expf(-v)); }
; __device__ __forceinline__ unsigned f2bf(float f) { unsigned u = __builtin_bit_cast(unsigned, f); return (u + 0x7fffu + ((u >> 16) & 1u)) >> 16; }
; __global__ void __launch_bounds__(512, 2) fwd_mega(Args a) {
;     ...
;                     for (int idx = threadIdx.x; idx < 2 * FF; idx += 512) {
;                         const int j = idx / FF, f = idx % FF; const size_t cur = (size_t)fu.pm * 2 * FF, prv = (size_t)(fu.pm - 1) * 2 * FF;
;                         const float a2 = RA[cur + j * FF + f], a1 = (j == 0) ? TA[prv + FF + f] : RA[cur + f], a0 = (j == 0) ? TA[prv + f] : TA[prv + FF + f];
;                         const float cv = cbp[f] + cw[f] * a0 + cw[FF + f] * a1 + cw[2 * FF + f] * a2;
;                         WSP(WS_ACT)[(size_t)(fu.pm * 256 + j) * FF + f] = (bf16)f2bf(cv * pg8::sigm(cv) * RU[cur + j * FF + f]);
	v_lshlrev_b64 v[100:101], 2, v[94:95]
	v_cndmask_b32_e32 v103, v12, v15, vcc
	v_cndmask_b32_e32 v102, v14, v16, vcc
	v_cndmask_b32_e64 v6, 0, v10, s[6:7]
	v_lshl_add_u64 v[98:99], v[98:99], 0, v[100:101]
	v_lshl_add_u64 v[102:103], v[102:103], 0, v[100:101]
	v_lshl_add_u64 v[104:105], s[10:11], 0, v[100:101]
	v_lshl_add_u64 v[100:101], s[8:9], 0, v[100:101]
	v_lshl_add_u64 v[96:97], v[6:7], 0, s[18:19]
	global_load_dword v98, v[98:99], off nt
	s_nop 0
	global_load_dword v111, v[102:103], off nt
	global_load_dword v107, v[104:105], off nt
	global_load_dword v108, v[100:101], off nt
	v_add_co_u32_e32 v102, vcc, s30, v100
	v_lshl_add_u64 v[96:97], v[96:97], 0, v[94:95]
	s_nop 0
	v_addc_co_u32_e32 v103, vcc, 0, v101, vcc
	v_lshlrev_b64 v[96:97], 2, v[96:97]
	v_add_co_u32_e32 v100, vcc, s31, v100
	v_lshl_add_u64 v[104:105], s[14:15], 0, v[96:97]
	s_nop 0
	v_addc_co_u32_e32 v101, vcc, 0, v101, vcc
	global_load_dword v102, v[102:103], off offset:3072 nt
	s_nop 0
	global_load_dword v103, v[100:101], off offset:2048 nt
	global_load_dword v99, v[104:105], off nt
	v_lshl_add_u64 v[96:97], s[16:17], 0, v[96:97]
	global_load_dword v100, v[96:97], off nt
	v_cndmask_b32_e64 v106, 0, 1, s[6:7]
	v_add_u32_e32 v17, 0x200, v17
	v_subrev_co_u32_e32 v6, vcc, 0xb00, v17
	s_nop 0
	v_mov_b32_e32 v113, v7
	v_cndmask_b32_e32 v112, v6, v17, vcc
	v_cmp_lt_u32_e64 s[6:7], s25, v17
	v_cndmask_b32_e32 v117, v11, v12, vcc
	v_cndmask_b32_e32 v116, v13, v14, vcc
	v_lshlrev_b64 v[118:119], 2, v[112:113]
	v_cndmask_b32_e32 v121, v12, v15, vcc
	v_cndmask_b32_e32 v120, v14, v16, vcc
	v_cndmask_b32_e64 v6, 0, v10, s[6:7]
	v_lshl_add_u64 v[116:117], v[116:117], 0, v[118:119]
	v_lshl_add_u64 v[120:121], v[120:121], 0, v[118:119]
	v_lshl_add_u64 v[122:123], s[10:11], 0, v[118:119]
	v_lshl_add_u64 v[118:119], s[8:9], 0, v[118:119]
	v_lshl_add_u64 v[114:115], v[6:7], 0, s[18:19]
	global_load_dword v116, v[116:117], off nt
	s_nop 0
	global_load_dword v129, v[120:121], off nt
	global_load_dword v125, v[122:123], off nt
	global_load_dword v126, v[118:119], off nt
	v_add_co_u32_e32 v120, vcc, s30, v118
	v_lshl_add_u64 v[114:115], v[114:115], 0, v[112:113]
	s_nop 0
	v_addc_co_u32_e32 v121, vcc, 0, v119, vcc
	v_lshlrev_b64 v[114:115], 2, v[114:115]
	v_add_co_u32_e32 v118, vcc, s31, v118
	v_lshl_add_u64 v[122:123], s[14:15], 0, v[114:115]
	s_nop 0
	v_addc_co_u32_e32 v119, vcc, 0, v119, vcc
	global_load_dword v120, v[120:121], off offset:3072 nt
	s_nop 0
	global_load_dword v121, v[118:119], off offset:2048 nt
	global_load_dword v117, v[122:123], off nt
	v_lshl_add_u64 v[114:115], s[16:17], 0, v[114:115]
	global_load_dword v118, v[114:115], off nt
	v_cndmask_b32_e64 v124, 0, 1, s[6:7]
	v_add_u32_e32 v17, 0x200, v17
	s_waitcnt vmcnt(32)
	v_fmac_f32_e32 v53, v57, v54
	s_nop 0
	v_pk_mul_f32 v[42:43], v[44:45], v[48:49]
	s_nop 0
	v_add_f32_e32 v57, v53, v42
	v_add_f32_e32 v57, v57, v43
	v_mul_f32_e32 v42, 0xbfb8aa3b, v57
	v_exp_f32_e32 v42, v42
	v_or_b32_e32 v43, s37, v52
	v_add_f32_e32 v42, 1.0, v42
	v_rcp_f32_e32 v44, v42
	v_mad_i64_i32 v[42:43], s[6:7], v43, s24, v[8:9]
	v_lshl_add_u64 v[40:41], v[40:41], 1, v[42:43]
	v_mul_f32_e32 v57, v57, v44
	s_nop 0
	v_mul_f32_e32 v57, v46, v57
	v_bfe_u32 v42, v57, 16, 1
	v_add3_u32 v57, v57, v42, s34
	global_store_short_d16_hi v[40:41], v57, off
	s_waitcnt vmcnt(25)
	v_fmac_f32_e32 v71, v75, v72
	s_nop 0
	v_pk_mul_f32 v[60:61], v[62:63], v[66:67]
	s_nop 0
	v_add_f32_e32 v75, v71, v60
	v_add_f32_e32 v75, v75, v61
	v_mul_f32_e32 v60, 0xbfb8aa3b, v75
	v_exp_f32_e32 v60, v60
	v_or_b32_e32 v61, s37, v70
	v_add_f32_e32 v60, 1.0, v60
	v_rcp_f32_e32 v62, v60
	v_mad_i64_i32 v[60:61], s[6:7], v61, s24, v[8:9]
	v_lshl_add_u64 v[58:59], v[58:59], 1, v[60:61]
	v_mul_f32_e32 v75, v75, v62
	s_nop 0
	v_mul_f32_e32 v75, v64, v75
	v_bfe_u32 v60, v75, 16, 1
	v_add3_u32 v75, v75, v60, s34
	global_store_short_d16_hi v[58:59], v75, off
	s_waitcnt vmcnt(18)
	v_fmac_f32_e32 v89, v93, v90
	s_nop 0
	v_pk_mul_f32 v[78:79], v[80:81], v[84:85]
	s_nop 0
	v_add_f32_e32 v93, v89, v78
	v_add_f32_e32 v93, v93, v79
	v_mul_f32_e32 v78, 0xbfb8aa3b, v93
	v_exp_f32_e32 v78, v78
	v_or_b32_e32 v79, s37, v88
	v_add_f32_e32 v78, 1.0, v78
	v_rcp_f32_e32 v80, v78
	v_mad_i64_i32 v[78:79], s[6:7], v79, s24, v[8:9]
	v_lshl_add_u64 v[76:77], v[76:77], 1, v[78:79]
	v_mul_f32_e32 v93, v93, v80
	s_nop 0
	v_mul_f32_e32 v93, v82, v93
	v_bfe_u32 v78, v93, 16, 1
	v_add3_u32 v93, v93, v78, s34
	global_store_short_d16_hi v[76:77], v93, off
	s_waitcnt vmcnt(11)
	v_fmac_f32_e32 v107, v111, v108
	s_nop 0
	v_pk_mul_f32 v[96:97], v[98:99], v[102:103]
	s_nop 0
	v_add_f32_e32 v111, v107, v96
	v_add_f32_e32 v111, v111, v97
	v_mul_f32_e32 v96, 0xbfb8aa3b, v111
	v_exp_f32_e32 v96, v96
	v_or_b32_e32 v97, s37, v106
	v_add_f32_e32 v96, 1.0, v96
	v_rcp_f32_e32 v98, v96
	v_mad_i64_i32 v[96:97], s[6:7], v97, s24, v[8:9]
	v_lshl_add_u64 v[94:95], v[94:95], 1, v[96:97]
	v_mul_f32_e32 v111, v111, v98
	s_nop 0
	v_mul_f32_e32 v111, v100, v111
	v_bfe_u32 v96, v111, 16, 1
	v_add3_u32 v111, v111, v96, s34
	global_store_short_d16_hi v[94:95], v111, off
	s_waitcnt vmcnt(4)
	v_fmac_f32_e32 v125, v129, v126
	s_nop 0
	v_pk_mul_f32 v[114:115], v[116:117], v[120:121]
	s_nop 0
	v_add_f32_e32 v129, v125, v114
	v_add_f32_e32 v129, v129, v115
	v_mul_f32_e32 v114, 0xbfb8aa3b, v129
	v_exp_f32_e32 v114, v114
	v_or_b32_e32 v115, s37, v124
	v_add_f32_e32 v114, 1.0, v114
	v_rcp_f32_e32 v116, v114
	v_mad_i64_i32 v[114:115], s[6:7], v115, s24, v[8:9]
	v_lshl_add_u64 v[112:113], v[112:113], 1, v[114:115]
	v_mul_f32_e32 v129, v129, v116
	s_nop 0
	v_mul_f32_e32 v129, v118, v129
	v_bfe_u32 v114, v129, 16, 1
	v_add3_u32 v129, v129, v114, s34
	global_store_short_d16_hi v[112:113], v129, off
	s_or_b64 exec, exec, s[28:29]
	s_branch .LBB0_903

; __device__ __forceinline__ float bf_lo(unsigned w) { return __uint_as_float(w << 16); }
; __device__ __forceinline__ float bf_hi(unsigned w) { return __uint_as_float(w & 0xffff0000u); }
;     __device__ __forceinline__ void fused(f32x4 (&acc)[2][2][4][2], const Unit& u, int wr, int wc, int fr, int fq, PG8_LAS unsigned char* lds, int wid, int lane) const {
;     ...
;         const int col0 = u.pn * BM + wc * 32 + 8 * fq, b = u.pm >> 4;
;         {
;             f32x4 gv[2][2];
; #pragma unroll
;             for (int bj = 0; bj < 2; ++bj)
; #pragma unroll
;                 for (int n = 0; n < 2; ++n) gv[bj][n] = *(const f32x4*)(g + (size_t)b * 6144 + col0 + bj * HALF + 4 * n);
; #pragma unroll
;             for (int ai = 0; ai < 2; ++ai)
; #pragma unroll
;                 for (int m = 0; m < 4; ++m) { const int r = ai * HALF + wr * 64 + m * 16 + fr; const size_t off = (size_t)(u.pm * BM + r) * 1024 + col0;
; #pragma unroll
;                     for (int bj = 0; bj < 2; ++bj) { f32x4 b0, b1;
;                         if (XIN_BF16) { const u32x4 w = *(const u32x4*)((const bf16_t*)xin + off + bj * HALF); b0 = (f32x4){bf_lo(w.x), bf_hi(w.x), bf_lo(w.y), bf_hi(w.y)}; b1 = (f32x4){bf_lo(w.z), bf_hi(w.z), bf_lo(w.w), bf_hi(w.w)}; }
;                         else { b0 = *(const f32x4*)((const float*)xin + off + bj * HALF); b1 = *(const f32x4*)((const float*)xin + off + bj * HALF + 4); }
;                         acc[ai][bj][m][0] = b0 + gv[bj][0] * acc[ai][bj][m][0]; acc[ai][bj][m][1] = b1 + gv[bj][1] * acc[ai][bj][m][1]; }
.LBB0_942:
	s_add_u32 s6, s12, 0xc800000
	s_addc_u32 s7, s13, 0
	s_lshl_b32 s8, s25, 5
	s_lshl_b32 s9, s18, 8
	v_lshrrev_b32_e32 v130, 1, v168
	s_or_b32 s8, s9, s8
	v_and_or_b32 v156, v130, 24, s8
	s_ashr_i32 s8, s5, 4
	s_mul_i32 s35, s8, 0x6000
	s_mul_hi_i32 s34, s8, 0x6000
	s_add_u32 s8, s12, s35
	s_addc_u32 s9, s13, s34
	s_lshl_b32 s30, s5, 8
	v_add_u32_e32 v164, s30, v166
	v_ashrrev_i32_e32 v165, 31, v164
	v_ashrrev_i32_e32 v157, 31, v156
	v_lshlrev_b64 v[150:151], 11, v[164:165]
	v_lshl_add_u64 v[130:131], s[6:7], 0, v[150:151]
	v_lshlrev_b64 v[146:147], 1, v[156:157]
	v_lshl_add_u64 v[130:131], v[130:131], 0, v[146:147]
	v_lshl_add_u64 v[132:133], v[156:157], 2, s[8:9]
	s_movk_i32 s10, 0x5000
	s_barrier
	s_mov_b64 s[98:99], 0x8000
	v_lshl_add_u64 v[198:199], v[130:131], 0, s[98:99]
	global_load_dwordx4 v[206:209], v[198:199], off nt
	global_load_dwordx4 v[210:213], v[198:199], off offset:256 nt
	s_mov_b64 s[98:99], 0x10000
	v_lshl_add_u64 v[198:199], v[130:131], 0, s[98:99]
	global_load_dwordx4 v[214:217], v[198:199], off nt
	global_load_dwordx4 v[218:221], v[198:199], off offset:256 nt
	s_mov_b64 s[98:99], 0x18000
	v_lshl_add_u64 v[198:199], v[130:131], 0, s[98:99]
	global_load_dwordx4 v[222:225], v[198:199], off nt
	global_load_dwordx4 v[226:229], v[198:199], off offset:256 nt
	s_mov_b64 s[98:99], 0x40000
	v_lshl_add_u64 v[198:199], v[130:131], 0, s[98:99]
	global_load_dwordx4 v[230:233], v[198:199], off nt
	global_load_dwordx4 v[234:237], v[198:199], off offset:256 nt
	s_mov_b64 s[98:99], 0x48000
	v_lshl_add_u64 v[198:199], v[130:131], 0, s[98:99]
	global_load_dwordx4 v[238:241], v[198:199], off nt
	global_load_dwordx4 v[242:245], v[198:199], off offset:256 nt
	s_mov_b64 s[98:99], 0x50000
	v_lshl_add_u64 v[198:199], v[130:131], 0, s[98:99]
	global_load_dwordx4 v[248:251], v[198:199], off nt
	global_load_dwordx4 v[252:255], v[198:199], off offset:256 nt
	global_load_dwordx4 v[152:155], v[130:131], off nt
	global_load_dwordx4 v[158:161], v[130:131], off offset:256 nt
	v_add_co_u32_e32 v130, vcc, s10, v132
	s_mov_b64 s[8:9], 0x5000
	s_nop 0
	v_addc_co_u32_e32 v131, vcc, 0, v133, vcc
	global_load_dwordx4 v[138:141], v[130:131], off nt
	v_lshl_add_u64 v[130:131], v[132:133], 0, s[8:9]
	global_load_dwordx4 v[142:145], v[130:131], off offset:16 nt
	global_load_dwordx4 v[134:137], v[130:131], off offset:512 nt
	s_nop 0
	global_load_dwordx4 v[130:133], v[130:131], off offset:528 nt
	v_add_u32_e32 v148, 16, v164
	v_ashrrev_i32_e32 v149, 31, v148
	v_lshlrev_b64 v[148:149], 11, v[148:149]
	v_lshl_add_u64 v[162:163], s[6:7], 0, v[148:149]
	v_lshl_add_u64 v[162:163], v[162:163], 0, v[146:147]
	v_mbcnt_hi_u32_b32 v173, -1, v1
	v_and_b32_e32 v169, 64, v173
	v_xor_b32_e32 v165, 16, v173
	v_add_u32_e32 v194, 64, v169
	v_cmp_lt_i32_e32 vcc, v165, v194
	s_waitcnt vmcnt(0)
	v_lshlrev_b32_e32 v170, 16, v152
	v_and_b32_e32 v171, 0xffff0000, v152
	v_lshlrev_b32_e32 v152, 16, v153
	v_and_b32_e32 v153, 0xffff0000, v153
	v_lshlrev_b32_e32 v174, 16, v154
	v_and_b32_e32 v175, 0xffff0000, v154
	v_lshlrev_b32_e32 v154, 16, v155
	v_and_b32_e32 v155, 0xffff0000, v155
	v_lshlrev_b32_e32 v176, 16, v158
	v_and_b32_e32 v177, 0xffff0000, v158
	v_lshlrev_b32_e32 v158, 16, v159
	v_and_b32_e32 v159, 0xffff0000, v159
	v_lshlrev_b32_e32 v178, 16, v160
	v_and_b32_e32 v179, 0xffff0000, v160
	v_lshlrev_b32_e32 v160, 16, v161
	v_and_b32_e32 v161, 0xffff0000, v161
	v_pk_fma_f32 v[58:59], v[58:59], v[138:139], v[170:171]
	v_pk_fma_f32 v[60:61], v[60:61], v[140:141], v[152:153]
	v_pk_fma_f32 v[64:65], v[64:65], v[144:145], v[154:155]
	v_pk_fma_f32 v[62:63], v[62:63], v[142:143], v[174:175]
	v_pk_fma_f32 v[56:57], v[56:57], v[136:137], v[158:159]
	v_pk_fma_f32 v[54:55], v[54:55], v[134:135], v[176:177]
	v_pk_fma_f32 v[48:49], v[48:49], v[132:133], v[160:161]
	v_pk_fma_f32 v[46:47], v[46:47], v[130:131], v[178:179]
	v_add_u32_e32 v152, 32, v164
	v_mov_b32_e32 v158, v206
	v_mov_b32_e32 v159, v207
	v_mov_b32_e32 v160, v208
	v_mov_b32_e32 v161, v209
	v_mov_b32_e32 v174, v210
	v_mov_b32_e32 v175, v211
	v_mov_b32_e32 v176, v212
	v_mov_b32_e32 v177, v213
	v_ashrrev_i32_e32 v153, 31, v152
	v_lshlrev_b64 v[152:153], 11, v[152:153]
	v_lshl_add_u64 v[154:155], s[6:7], 0, v[152:153]
	v_lshl_add_u64 v[154:155], v[154:155], 0, v[146:147]
	v_cndmask_b32_e32 v165, v173, v165, vcc
	v_lshlrev_b32_e32 v169, 2, v165
	s_waitcnt vmcnt(1)
	v_lshlrev_b32_e32 v162, 16, v158
	v_and_b32_e32 v163, 0xffff0000, v158
	v_lshlrev_b32_e32 v158, 16, v159
	v_and_b32_e32 v159, 0xffff0000, v159
	v_lshlrev_b32_e32 v170, 16, v160
	v_and_b32_e32 v171, 0xffff0000, v160
	v_lshlrev_b32_e32 v160, 16, v161
	v_and_b32_e32 v161, 0xffff0000, v161
	s_waitcnt vmcnt(0)
	v_lshlrev_b32_e32 v178, 16, v174
	v_and_b32_e32 v179, 0xffff0000, v174
	v_lshlrev_b32_e32 v174, 16, v175
	v_and_b32_e32 v175, 0xffff0000, v175
	v_lshlrev_b32_e32 v180, 16, v176
	v_and_b32_e32 v181, 0xffff0000, v176
	v_lshlrev_b32_e32 v176, 16, v177
	v_and_b32_e32 v177, 0xffff0000, v177
	v_pk_fma_f32 v[84:85], v[84:85], v[140:141], v[158:159]
	v_pk_fma_f32 v[82:83], v[82:83], v[138:139], v[162:163]
	v_pk_fma_f32 v[76:77], v[76:77], v[144:145], v[160:161]
	v_pk_fma_f32 v[74:75], v[74:75], v[142:143], v[170:171]
	v_pk_fma_f32 v[52:53], v[52:53], v[136:137], v[174:175]
	v_pk_fma_f32 v[50:51], v[50:51], v[134:135], v[178:179]
	v_pk_fma_f32 v[44:45], v[44:45], v[132:133], v[176:177]
	v_pk_fma_f32 v[42:43], v[42:43], v[130:131], v[180:181]
	s_nop 0
	v_mov_b32_e32 v158, v214
	v_mov_b32_e32 v159, v215
	v_mov_b32_e32 v160, v216
	v_mov_b32_e32 v161, v217
	v_mov_b32_e32 v174, v218
	v_mov_b32_e32 v175, v219
	v_mov_b32_e32 v176, v220
	v_mov_b32_e32 v177, v221
	v_add_u32_e32 v154, 48, v164
	v_ashrrev_i32_e32 v155, 31, v154
	v_lshlrev_b64 v[154:155], 11, v[154:155]
	v_lshl_add_u64 v[162:163], s[6:7], 0, v[154:155]
	v_lshl_add_u64 v[170:171], v[162:163], 0, v[146:147]
	s_waitcnt vmcnt(1)
; __device__ __forceinline__ float bf_lo(unsigned w) { return __uint_as_float(w << 16); }
; __device__ __forceinline__ float bf_hi(unsigned w) { return __uint_as_float(w & 0xffff0000u); }
;     __device__ __forceinline__ void fused(f32x4 (&acc)[2][2][4][2], const Unit& u, int wr, int wc, int fr, int fq, PG8_LAS unsigned char* lds, int wid, int lane) const {
;     ...
;                 for (int m = 0; m < 4; ++m) { const int r = ai * HALF + wr * 64 + m * 16 + fr; const size_t off = (size_t)(u.pm * BM + r) * 1024 + col0;
; #pragma unroll
;                     for (int bj = 0; bj < 2; ++bj) { f32x4 b0, b1;
;                         if (XIN_BF16) { const u32x4 w = *(const u32x4*)((const bf16_t*)xin + off + bj * HALF); b0 = (f32x4){bf_lo(w.x), bf_hi(w.x), bf_lo(w.y), bf_hi(w.y)}; b1 = (f32x4){bf_lo(w.z), bf_hi(w.z), bf_lo(w.w), bf_hi(w.w)}; }
;                         else { b0 = *(const f32x4*)((const float*)xin + off + bj * HALF); b1 = *(const f32x4*)((const float*)xin + off + bj * HALF + 4); }
;                         acc[ai][bj][m][0] = b0 + gv[bj][0] * acc[ai][bj][m][0]; acc[ai][bj][m][1] = b1 + gv[bj][1] * acc[ai][bj][m][1]; }
	v_lshlrev_b32_e32 v162, 16, v158
	v_and_b32_e32 v163, 0xffff0000, v158
	v_lshlrev_b32_e32 v158, 16, v159
	v_and_b32_e32 v159, 0xffff0000, v159
	v_lshlrev_b32_e32 v178, 16, v160
	v_and_b32_e32 v179, 0xffff0000, v160
	v_lshlrev_b32_e32 v160, 16, v161
	v_and_b32_e32 v161, 0xffff0000, v161
	s_waitcnt vmcnt(0)
	v_lshlrev_b32_e32 v180, 16, v174
	v_and_b32_e32 v181, 0xffff0000, v174
	v_lshlrev_b32_e32 v174, 16, v175
	v_and_b32_e32 v175, 0xffff0000, v175
	v_lshlrev_b32_e32 v182, 16, v176
	v_and_b32_e32 v183, 0xffff0000, v176
	v_lshlrev_b32_e32 v176, 16, v177
	v_and_b32_e32 v177, 0xffff0000, v177
	v_pk_fma_f32 v[100:101], v[100:101], v[140:141], v[158:159]
	v_pk_fma_f32 v[98:99], v[98:99], v[138:139], v[162:163]
	v_pk_fma_f32 v[92:93], v[92:93], v[144:145], v[160:161]
	v_pk_fma_f32 v[90:91], v[90:91], v[142:143], v[178:179]
	v_pk_fma_f32 v[80:81], v[80:81], v[136:137], v[174:175]
	v_pk_fma_f32 v[78:79], v[78:79], v[134:135], v[180:181]
	v_pk_fma_f32 v[72:73], v[72:73], v[132:133], v[176:177]
	v_pk_fma_f32 v[70:71], v[70:71], v[130:131], v[182:183]
	v_add_u32_e32 v158, 0x80, v164
	v_mov_b32_e32 v160, v222
	v_mov_b32_e32 v161, v223
	v_mov_b32_e32 v162, v224
	v_mov_b32_e32 v163, v225
	v_mov_b32_e32 v174, v226
	v_mov_b32_e32 v175, v227
	v_mov_b32_e32 v176, v228
	v_mov_b32_e32 v177, v229
	v_ashrrev_i32_e32 v159, 31, v158
	v_lshlrev_b64 v[158:159], 11, v[158:159]
	v_lshl_add_u64 v[170:171], s[6:7], 0, v[158:159]
	v_lshl_add_u64 v[170:171], v[170:171], 0, v[146:147]
	s_waitcnt vmcnt(1)
	v_lshlrev_b32_e32 v178, 16, v160
	v_and_b32_e32 v179, 0xffff0000, v160
	v_lshlrev_b32_e32 v160, 16, v161
	v_and_b32_e32 v161, 0xffff0000, v161
	v_lshlrev_b32_e32 v180, 16, v162
	v_and_b32_e32 v181, 0xffff0000, v162
	v_lshlrev_b32_e32 v162, 16, v163
	v_and_b32_e32 v163, 0xffff0000, v163
	s_waitcnt vmcnt(0)
	v_lshlrev_b32_e32 v182, 16, v174
	v_and_b32_e32 v183, 0xffff0000, v174
	v_lshlrev_b32_e32 v174, 16, v175
	v_and_b32_e32 v175, 0xffff0000, v175
	v_lshlrev_b32_e32 v184, 16, v176
	v_and_b32_e32 v185, 0xffff0000, v176
	v_lshlrev_b32_e32 v176, 16, v177
	v_and_b32_e32 v177, 0xffff0000, v177
	v_pk_fma_f32 v[116:117], v[116:117], v[140:141], v[160:161]
	v_pk_fma_f32 v[114:115], v[114:115], v[138:139], v[178:179]
	v_pk_fma_f32 v[112:113], v[112:113], v[144:145], v[162:163]
	v_pk_fma_f32 v[110:111], v[110:111], v[142:143], v[180:181]
	v_pk_fma_f32 v[104:105], v[104:105], v[136:137], v[174:175]
	v_pk_fma_f32 v[102:103], v[102:103], v[134:135], v[182:183]
	v_pk_fma_f32 v[96:97], v[96:97], v[132:133], v[176:177]
	v_pk_fma_f32 v[94:95], v[94:95], v[130:131], v[184:185]
	v_add_u32_e32 v160, 0x90, v164
	v_mov_b32_e32 v174, v230
	v_mov_b32_e32 v175, v231
	v_mov_b32_e32 v176, v232
	v_mov_b32_e32 v177, v233
	v_mov_b32_e32 v178, v234
	v_mov_b32_e32 v179, v235
	v_mov_b32_e32 v180, v236
	v_mov_b32_e32 v181, v237
	v_ashrrev_i32_e32 v161, 31, v160
	v_lshlrev_b64 v[160:161], 11, v[160:161]
	v_lshl_add_u64 v[162:163], s[6:7], 0, v[160:161]
	v_lshl_add_u64 v[162:163], v[162:163], 0, v[146:147]
	s_waitcnt vmcnt(1)
	v_lshlrev_b32_e32 v170, 16, v174
	v_and_b32_e32 v171, 0xffff0000, v174
	v_lshlrev_b32_e32 v174, 16, v175
	v_and_b32_e32 v175, 0xffff0000, v175
	v_lshlrev_b32_e32 v182, 16, v176
	v_and_b32_e32 v183, 0xffff0000, v176
	v_lshlrev_b32_e32 v176, 16, v177
	v_and_b32_e32 v177, 0xffff0000, v177
	s_waitcnt vmcnt(0)
	v_lshlrev_b32_e32 v184, 16, v178
	v_and_b32_e32 v185, 0xffff0000, v178
	v_lshlrev_b32_e32 v178, 16, v179
	v_and_b32_e32 v179, 0xffff0000, v179
	v_lshlrev_b32_e32 v186, 16, v180
	v_and_b32_e32 v187, 0xffff0000, v180
	v_lshlrev_b32_e32 v180, 16, v181
	v_and_b32_e32 v181, 0xffff0000, v181
	v_pk_fma_f32 v[128:129], v[128:129], v[140:141], v[174:175]
	v_pk_fma_f32 v[126:127], v[126:127], v[138:139], v[170:171]
	v_pk_fma_f32 v[124:125], v[124:125], v[144:145], v[176:177]
	v_pk_fma_f32 v[122:123], v[122:123], v[142:143], v[182:183]
	v_pk_fma_f32 v[120:121], v[120:121], v[136:137], v[178:179]
	v_pk_fma_f32 v[118:119], v[118:119], v[134:135], v[184:185]
	v_pk_fma_f32 v[108:109], v[108:109], v[132:133], v[180:181]
	v_pk_fma_f32 v[106:107], v[106:107], v[130:131], v[186:187]
	s_nop 0
	v_mov_b32_e32 v174, v238
	v_mov_b32_e32 v175, v239
	v_mov_b32_e32 v176, v240
	v_mov_b32_e32 v177, v241
	v_mov_b32_e32 v178, v242
	v_mov_b32_e32 v179, v243
	v_mov_b32_e32 v180, v244
	v_mov_b32_e32 v181, v245
	v_add_u32_e32 v162, 0xa0, v164
	v_ashrrev_i32_e32 v163, 31, v162
	v_lshlrev_b64 v[162:163], 11, v[162:163]
	v_lshl_add_u64 v[170:171], s[6:7], 0, v[162:163]
	v_lshl_add_u64 v[170:171], v[170:171], 0, v[146:147]
	v_add_u32_e32 v164, 0xb0, v164
	v_ashrrev_i32_e32 v165, 31, v164
	v_lshlrev_b64 v[164:165], 11, v[164:165]
	s_waitcnt vmcnt(1)
	v_lshlrev_b32_e32 v182, 16, v174
	v_and_b32_e32 v183, 0xffff0000, v174
	v_lshlrev_b32_e32 v174, 16, v175
	v_and_b32_e32 v175, 0xffff0000, v175
	v_lshlrev_b32_e32 v184, 16, v176
	v_and_b32_e32 v185, 0xffff0000, v176
	v_lshlrev_b32_e32 v176, 16, v177
	v_and_b32_e32 v177, 0xffff0000, v177
	s_waitcnt vmcnt(0)
	v_lshlrev_b32_e32 v186, 16, v178
	v_and_b32_e32 v187, 0xffff0000, v178
	v_lshlrev_b32_e32 v178, 16, v179
	v_and_b32_e32 v179, 0xffff0000, v179
	v_lshlrev_b32_e32 v188, 16, v180
	v_and_b32_e32 v189, 0xffff0000, v180
	v_lshlrev_b32_e32 v180, 16, v181
	v_and_b32_e32 v181, 0xffff0000, v181
	v_pk_fma_f32 v[88:89], v[88:89], v[140:141], v[174:175]
	v_pk_fma_f32 v[86:87], v[86:87], v[138:139], v[182:183]
	v_pk_fma_f32 v[68:69], v[68:69], v[144:145], v[176:177]
	v_pk_fma_f32 v[66:67], v[66:67], v[142:143], v[184:185]
	v_pk_fma_f32 v[40:41], v[40:41], v[136:137], v[178:179]
	v_pk_fma_f32 v[38:39], v[38:39], v[134:135], v[186:187]
	v_pk_fma_f32 v[36:37], v[36:37], v[132:133], v[180:181]
	v_pk_fma_f32 v[34:35], v[34:35], v[130:131], v[188:189]
	v_mov_b32_e32 v184, v59
	v_mov_b32_e32 v174, v248
	v_mov_b32_e32 v175, v249
	v_mov_b32_e32 v176, v250
	v_mov_b32_e32 v177, v251
	v_mov_b32_e32 v178, v252
	v_mov_b32_e32 v179, v253
	v_mov_b32_e32 v180, v254
	v_mov_b32_e32 v181, v255
	v_lshl_add_u64 v[170:171], s[6:7], 0, v[164:165]
	v_lshl_add_u64 v[170:171], v[170:171], 0, v[146:147]
	v_mov_b32_e32 v185, v60
	v_mov_b32_e32 v186, v58
	v_mov_b32_e32 v187, v61
	v_pk_add_f32 v[184:185], v[184:185], v[186:187]
	s_lshl_b32 s6, s25, 3
	s_add_i32 s8, s6, 0
	s_waitcnt vmcnt(1)
; __device__ __forceinline__ float bf_lo(unsigned w) { return __uint_as_float(w << 16); }
; __device__ __forceinline__ float bf_hi(unsigned w) { return __uint_as_float(w & 0xffff0000u); }
;     template <class Mid> __device__ __forceinline__ bool run(const f32x4 (&v)[2][2][4][2], const Unit& u, int wr, int wc, int fr, int fq, PG8_LAS unsigned char* lds, int wid, int lane, const Mid& mid) const {
;     ...
;                 float s = 0.f;
; #pragma unroll
;                 for (int bj = 0; bj < 2; ++bj)
; #pragma unroll
;                     for (int n = 0; n < 2; ++n) { const f32x4 x = v[ai][bj][m][n]; s += (x[0] + x[1]) + (x[2] + x[3]); }
;                 s += __shfl_xor(s, 16); s += __shfl_xor(s, 32);
;                 const float mw = s * (1.0f / 64.0f); float q = 0.f;
; #pragma unroll
;                 for (int bj = 0; bj < 2; ++bj)
; #pragma unroll
;                     for (int n = 0; n < 2; ++n) { const f32x4 d = v[ai][bj][m][n] - mw; q += (d[0] * d[0] + d[1] * d[1]) + (d[2] * d[2] + d[3] * d[3]); }
;                 q += __shfl_xor(q, 16); q += __shfl_xor(q, 32);
;                 if (fq == 0) P[(ai * HALF + wr * 64 + m * 16 + fr) * 4 + wc] = (f32x2v){mw, q};
;     __device__ __forceinline__ void fused(f32x4 (&acc)[2][2][4][2], const Unit& u, int wr, int wc, int fr, int fq, PG8_LAS unsigned char* lds, int wid, int lane) const {
;     ...
;                 for (int m = 0; m < 4; ++m) { const int r = ai * HALF + wr * 64 + m * 16 + fr; const size_t off = (size_t)(u.pm * BM + r) * 1024 + col0;
; #pragma unroll
;                     for (int bj = 0; bj < 2; ++bj) { f32x4 b0, b1;
;                         if (XIN_BF16) { const u32x4 w = *(const u32x4*)((const bf16_t*)xin + off + bj * HALF); b0 = (f32x4){bf_lo(w.x), bf_hi(w.x), bf_lo(w.y), bf_hi(w.y)}; b1 = (f32x4){bf_lo(w.z), bf_hi(w.z), bf_lo(w.w), bf_hi(w.w)}; }
;                         else { b0 = *(const f32x4*)((const float*)xin + off + bj * HALF); b1 = *(const f32x4*)((const float*)xin + off + bj * HALF + 4); }
;                         acc[ai][bj][m][0] = b0 + gv[bj][0] * acc[ai][bj][m][0]; acc[ai][bj][m][1] = b1 + gv[bj][1] * acc[ai][bj][m][1]; }
	v_lshlrev_b32_e32 v182, 16, v174
	v_and_b32_e32 v183, 0xffff0000, v174
	v_lshlrev_b32_e32 v174, 16, v175
	v_and_b32_e32 v175, 0xffff0000, v175
	v_lshlrev_b32_e32 v188, 16, v176
	v_and_b32_e32 v189, 0xffff0000, v176
	v_lshlrev_b32_e32 v176, 16, v177
	v_and_b32_e32 v177, 0xffff0000, v177
	s_waitcnt vmcnt(0)
	v_lshlrev_b32_e32 v190, 16, v178
	v_and_b32_e32 v191, 0xffff0000, v178
	v_lshlrev_b32_e32 v178, 16, v179
	v_and_b32_e32 v179, 0xffff0000, v179
	v_lshlrev_b32_e32 v192, 16, v180
	v_and_b32_e32 v193, 0xffff0000, v180
	v_lshlrev_b32_e32 v180, 16, v181
	v_and_b32_e32 v181, 0xffff0000, v181
	v_pk_fma_f32 v[32:33], v[32:33], v[140:141], v[174:175]
	v_pk_fma_f32 v[30:31], v[30:31], v[138:139], v[182:183]
	v_pk_fma_f32 v[28:29], v[28:29], v[144:145], v[176:177]
	v_pk_fma_f32 v[26:27], v[26:27], v[142:143], v[188:189]
	v_pk_fma_f32 v[24:25], v[24:25], v[136:137], v[178:179]
	v_pk_fma_f32 v[22:23], v[22:23], v[134:135], v[190:191]
	v_pk_fma_f32 v[20:21], v[20:21], v[132:133], v[180:181]
	v_pk_fma_f32 v[18:19], v[18:19], v[130:131], v[192:193]
	v_mov_b32_e32 v174, v63
	global_load_dwordx4 v[176:179], v[170:171], off nt
	global_load_dwordx4 v[180:183], v[170:171], off offset:256 nt
	v_mov_b32_e32 v175, v64
	v_mov_b32_e32 v188, v62
	v_mov_b32_e32 v189, v65
	v_pk_add_f32 v[174:175], v[174:175], v[188:189]
	v_add_f32_e32 v171, v184, v185
	v_pk_add_f32 v[174:175], v[174:175], v[174:175] op_sel_hi:[0,1]
	v_add_f32_e32 v191, v54, v55
	v_add_f32_e32 v193, v56, v57
	v_mov_b32_e32 v190, v46
	v_mov_b32_e32 v192, v47
	v_mov_b32_e32 v170, v49
	v_add_f32_e32 v171, 0, v171
	v_mov_b32_e32 v174, v48
	v_pk_add_f32 v[186:187], v[190:191], v[192:193]
	v_pk_add_f32 v[170:171], v[174:175], v[170:171]
	s_nop 0
	v_pk_add_f32 v[170:171], v[186:187], v[170:171]
	s_nop 0
	v_add_f32_e32 v170, v170, v171
	ds_bpermute_b32 v174, v169, v170
	v_xor_b32_e32 v171, 32, v173
	v_cmp_lt_i32_e32 vcc, v171, v194
	s_waitcnt lgkmcnt(0)
	v_add_f32_e32 v170, v170, v174
	v_cndmask_b32_e32 v171, v173, v171, vcc
	v_lshlrev_b32_e32 v171, 2, v171
	ds_bpermute_b32 v173, v171, v170
	s_waitcnt lgkmcnt(0)
	v_add_f32_e32 v173, v170, v173
	v_fmamk_f32 v174, v173, 0xbc800000, v61
	v_fmamk_f32 v184, v173, 0xbc800000, v59
	v_fmamk_f32 v186, v173, 0xbc800000, v65
	v_fmamk_f32 v188, v173, 0xbc800000, v63
	v_fmamk_f32 v170, v173, 0xbc800000, v60
	v_fmamk_f32 v175, v173, 0xbc800000, v58
	v_fmamk_f32 v185, v173, 0xbc800000, v64
	v_fmamk_f32 v187, v173, 0xbc800000, v62
	v_fmamk_f32 v190, v173, 0xbc800000, v57
	v_fmamk_f32 v192, v173, 0xbc800000, v55
	v_mul_f32_e32 v184, v184, v184
	v_mul_f32_e32 v174, v174, v174
	v_mul_f32_e32 v188, v188, v188
	v_mul_f32_e32 v186, v186, v186
	v_fmamk_f32 v189, v173, 0xbc800000, v56
	v_fmamk_f32 v191, v173, 0xbc800000, v54
	v_fmamk_f32 v194, v173, 0xbc800000, v49
	v_fmamk_f32 v196, v173, 0xbc800000, v47
	v_mul_f32_e32 v192, v192, v192
	v_mul_f32_e32 v190, v190, v190
	v_fmac_f32_e32 v184, v175, v175
	v_fmac_f32_e32 v174, v170, v170
	v_fmac_f32_e32 v188, v187, v187
	v_fmac_f32_e32 v186, v185, v185
	v_fmamk_f32 v193, v173, 0xbc800000, v48
	v_fmamk_f32 v195, v173, 0xbc800000, v46
	v_mul_f32_e32 v196, v196, v196
	v_mul_f32_e32 v194, v194, v194
	v_fmac_f32_e32 v192, v191, v191
	v_fmac_f32_e32 v190, v189, v189
	v_add_f32_e32 v170, v184, v174
	v_add_f32_e32 v174, v188, v186
	v_fmac_f32_e32 v196, v195, v195
	v_fmac_f32_e32 v194, v193, v193
	v_add_f32_e32 v175, v192, v190
	v_add_f32_e32 v170, v170, v174
	v_add_f32_e32 v184, v196, v194
	v_add_f32_e32 v170, v175, v170
	v_add_f32_e32 v174, v184, v170
	ds_bpermute_b32 v175, v169, v174
	v_and_b32_e32 v170, 63, v168
	v_cmp_gt_u32_e32 vcc, 16, v170
	s_waitcnt lgkmcnt(0)
	v_add_f32_e32 v174, v174, v175
	ds_bpermute_b32 v175, v171, v174
	s_waitcnt vmcnt(1)
	v_lshlrev_b32_e32 v184, 16, v176
	v_and_b32_e32 v185, 0xffff0000, v176
	v_lshlrev_b32_e32 v176, 16, v177
	v_and_b32_e32 v177, 0xffff0000, v177
	v_lshlrev_b32_e32 v186, 16, v178
	v_and_b32_e32 v187, 0xffff0000, v178
	v_lshlrev_b32_e32 v178, 16, v179
	v_and_b32_e32 v179, 0xffff0000, v179
	s_waitcnt vmcnt(0)
	v_lshlrev_b32_e32 v188, 16, v180
	v_and_b32_e32 v189, 0xffff0000, v180
	v_lshlrev_b32_e32 v180, 16, v181
	v_and_b32_e32 v181, 0xffff0000, v181
	v_lshlrev_b32_e32 v190, 16, v182
	v_and_b32_e32 v191, 0xffff0000, v182
	v_lshlrev_b32_e32 v182, 16, v183
	v_and_b32_e32 v183, 0xffff0000, v183
	v_pk_fma_f32 v[16:17], v[16:17], v[140:141], v[176:177]
	v_pk_fma_f32 v[14:15], v[14:15], v[138:139], v[184:185]
	v_pk_fma_f32 v[12:13], v[12:13], v[144:145], v[178:179]
	v_pk_fma_f32 v[10:11], v[10:11], v[142:143], v[186:187]
	v_pk_fma_f32 v[8:9], v[8:9], v[136:137], v[180:181]
	v_pk_fma_f32 v[6:7], v[6:7], v[134:135], v[188:189]
	v_pk_fma_f32 v[4:5], v[4:5], v[132:133], v[182:183]
	v_pk_fma_f32 v[2:3], v[2:3], v[130:131], v[190:191]
	s_nop 0
	s_and_saveexec_b64 s[6:7], vcc
	s_cbranch_execz .LBB0_944
	s_lshl_b32 s9, s24, 11
	s_add_i32 s9, s8, s9
	v_mul_f32_e32 v130, 0x3c800000, v173
	s_waitcnt lgkmcnt(0)
	v_add_f32_e32 v131, v174, v175
	v_lshl_add_u32 v132, v167, 5, s9
	ds_write_b64 v132, v[130:131]

; #define LAS __attribute__((address_space(3)))
; __device__ __forceinline__ void tr_item(const float* W, int N, bf16* WT, int dpitch, int koff, int drow0, int k0, int n0, LAS float* scr, int lane) {
;     float tv[32];
; #pragma unroll
;     for (int i = 0; i < 32; ++i) tv[i] = W[(size_t)(k0 + 2 * i + (lane >> 5)) * N + n0 + (lane & 31)];
; #pragma unroll
;     for (int i = 0; i < 32; ++i) scr[(2 * i + (lane >> 5)) * 33 + (lane & 31)] = tv[i];
; __global__ void __launch_bounds__(512, 2) fwd_mega(Args a) {
;     ...
;             { const int kb = it / 32, nb = it % 32; tr_item(INF(20) + (size_t)LL * FF * D, D, WSP(wd_off), 2816, 0, 32 * nb, 64 * kb, 32 * nb, scr, lane); }
.LBB0_986:
	s_cmpk_gt_i32 s53, 0xa7f
	s_mov_b64 s[8:9], -1
	s_cbranch_scc0 .LBB0_1008
	s_cmpk_gt_u32 s53, 0xc7f
	s_cbranch_scc0 .LBB0_1005
	s_cmpk_gt_u32 s53, 0xe7f
	s_cbranch_scc0 .LBB0_1002
	s_cmpk_gt_u32 s53, 0x107f
	s_cbranch_scc0 .LBB0_999
	s_cmpk_gt_u32 s53, 0x15ff
	s_cbranch_scc0 .LBB0_996
	s_cmpk_gt_u32 s53, 0x1b7f
	s_cbranch_scc0 .LBB0_993
	s_and_b32 s6, s12, 0x7fffffc0
	s_add_i32 s8, s6, 0xffffc900
	s_and_b32 s10, s4, 0x3e0
	v_or_b32_e32 v2, s8, v200
	s_lshl_b32 s6, s10, 2
	v_or_b32_e32 v44, 2, v2
	v_mov_b32_e32 v45, v3
	v_or_b32_e32 v46, 4, v2
	v_mov_b32_e32 v47, v3
	v_or_b32_e32 v48, 6, v2
	v_mov_b32_e32 v49, v3
	v_or_b32_e32 v50, 8, v2
	v_mov_b32_e32 v51, v3
	v_or_b32_e32 v52, 10, v2
	v_mov_b32_e32 v53, v3
	v_or_b32_e32 v54, 12, v2
	v_mov_b32_e32 v55, v3
	v_lshl_add_u64 v[40:41], v[4:5], 0, s[6:7]
	v_lshlrev_b64 v[42:43], 12, v[2:3]
	v_lshlrev_b64 v[44:45], 12, v[44:45]
	v_lshlrev_b64 v[46:47], 12, v[46:47]
	v_lshlrev_b64 v[48:49], 12, v[48:49]
	v_lshlrev_b64 v[50:51], 12, v[50:51]
	v_lshlrev_b64 v[52:53], 12, v[52:53]
	v_lshlrev_b64 v[54:55], 12, v[54:55]
	v_or_b32_e32 v56, 14, v2
	v_mov_b32_e32 v57, v3
	v_lshl_add_u64 v[42:43], v[40:41], 0, v[42:43]
	v_lshl_add_u64 v[44:45], v[40:41], 0, v[44:45]
	v_lshl_add_u64 v[46:47], v[40:41], 0, v[46:47]
	v_lshl_add_u64 v[48:49], v[40:41], 0, v[48:49]
	v_lshl_add_u64 v[50:51], v[40:41], 0, v[50:51]
	v_lshl_add_u64 v[52:53], v[40:41], 0, v[52:53]
	v_lshl_add_u64 v[54:55], v[40:41], 0, v[54:55]
	v_lshlrev_b64 v[56:57], 12, v[56:57]
	v_lshl_add_u64 v[56:57], v[40:41], 0, v[56:57]
	global_load_dword v58, v[42:43], off nt
	global_load_dword v59, v[44:45], off nt
	global_load_dword v60, v[46:47], off nt
	global_load_dword v61, v[48:49], off nt
	global_load_dword v62, v[50:51], off nt
	global_load_dword v63, v[52:53], off nt
	global_load_dword v64, v[54:55], off nt
	global_load_dword v65, v[56:57], off nt
	v_or_b32_e32 v42, 16, v2
	v_mov_b32_e32 v43, v3
	v_or_b32_e32 v44, 18, v2
	v_mov_b32_e32 v45, v3
	v_or_b32_e32 v46, 20, v2
	v_mov_b32_e32 v47, v3
	v_or_b32_e32 v48, 22, v2
	v_mov_b32_e32 v49, v3
	v_or_b32_e32 v50, 24, v2
	v_mov_b32_e32 v51, v3
	v_or_b32_e32 v52, 26, v2
	v_mov_b32_e32 v53, v3
	v_or_b32_e32 v54, 28, v2
	v_mov_b32_e32 v55, v3
	v_lshlrev_b64 v[42:43], 12, v[42:43]
	v_lshlrev_b64 v[44:45], 12, v[44:45]
	v_lshlrev_b64 v[46:47], 12, v[46:47]
	v_lshlrev_b64 v[48:49], 12, v[48:49]
	v_lshlrev_b64 v[50:51], 12, v[50:51]
	v_lshlrev_b64 v[52:53], 12, v[52:53]
	v_lshlrev_b64 v[54:55], 12, v[54:55]
	v_or_b32_e32 v56, 30, v2
	v_mov_b32_e32 v57, v3
	v_lshl_add_u64 v[42:43], v[40:41], 0, v[42:43]
	v_lshl_add_u64 v[44:45], v[40:41], 0, v[44:45]
	v_lshl_add_u64 v[46:47], v[40:41], 0, v[46:47]
	v_lshl_add_u64 v[48:49], v[40:41], 0, v[48:49]
	v_lshl_add_u64 v[50:51], v[40:41], 0, v[50:51]
	v_lshl_add_u64 v[52:53], v[40:41], 0, v[52:53]
	v_lshl_add_u64 v[54:55], v[40:41], 0, v[54:55]
	v_lshlrev_b64 v[56:57], 12, v[56:57]
	v_lshl_add_u64 v[56:57], v[40:41], 0, v[56:57]
	global_load_dword v66, v[42:43], off nt
	global_load_dword v67, v[44:45], off nt
	global_load_dword v68, v[46:47], off nt
	global_load_dword v69, v[48:49], off nt
	global_load_dword v70, v[50:51], off nt
	global_load_dword v71, v[52:53], off nt
	global_load_dword v72, v[54:55], off nt
	global_load_dword v73, v[56:57], off nt
	v_or_b32_e32 v42, 32, v2
	v_mov_b32_e32 v43, v3
	v_or_b32_e32 v44, 34, v2
	v_mov_b32_e32 v45, v3
	v_or_b32_e32 v46, 36, v2
	v_mov_b32_e32 v47, v3
	v_or_b32_e32 v48, 38, v2
	v_mov_b32_e32 v49, v3
	v_or_b32_e32 v50, 40, v2
	v_mov_b32_e32 v51, v3
	v_or_b32_e32 v52, 42, v2
	v_mov_b32_e32 v53, v3
	v_or_b32_e32 v54, 44, v2
	v_mov_b32_e32 v55, v3
	v_lshlrev_b64 v[42:43], 12, v[42:43]
	v_lshlrev_b64 v[44:45], 12, v[44:45]
	v_lshlrev_b64 v[46:47], 12, v[46:47]
	v_lshlrev_b64 v[48:49], 12, v[48:49]
	v_lshlrev_b64 v[50:51], 12, v[50:51]
	v_lshlrev_b64 v[52:53], 12, v[52:53]
	v_lshlrev_b64 v[54:55], 12, v[54:55]
	v_or_b32_e32 v56, 46, v2
	v_mov_b32_e32 v57, v3
	v_lshl_add_u64 v[42:43], v[40:41], 0, v[42:43]
	v_lshl_add_u64 v[44:45], v[40:41], 0, v[44:45]
	v_lshl_add_u64 v[46:47], v[40:41], 0, v[46:47]
	v_lshl_add_u64 v[48:49], v[40:41], 0, v[48:49]
	v_lshl_add_u64 v[50:51], v[40:41], 0, v[50:51]
	v_lshl_add_u64 v[52:53], v[40:41], 0, v[52:53]
	v_lshl_add_u64 v[54:55], v[40:41], 0, v[54:55]
	v_lshlrev_b64 v[56:57], 12, v[56:57]
	v_lshl_add_u64 v[56:57], v[40:41], 0, v[56:57]
	global_load_dword v74, v[42:43], off nt
	global_load_dword v75, v[44:45], off nt
	global_load_dword v76, v[46:47], off nt
	global_load_dword v77, v[48:49], off nt
	global_load_dword v78, v[50:51], off nt
	global_load_dword v79, v[52:53], off nt
	global_load_dword v80, v[54:55], off nt
	global_load_dword v81, v[56:57], off nt
	v_or_b32_e32 v42, 48, v2
	v_mov_b32_e32 v43, v3
	v_or_b32_e32 v44, 50, v2
	v_mov_b32_e32 v45, v3
	v_or_b32_e32 v46, 52, v2
	v_mov_b32_e32 v47, v3
	v_or_b32_e32 v48, 54, v2
	v_mov_b32_e32 v49, v3
	v_or_b32_e32 v50, 56, v2
	v_mov_b32_e32 v51, v3
	v_or_b32_e32 v52, 58, v2
	v_mov_b32_e32 v53, v3
	v_or_b32_e32 v54, 60, v2
	v_mov_b32_e32 v55, v3
	v_or_b32_e32 v2, 62, v2
	v_lshlrev_b64 v[42:43], 12, v[42:43]
	v_lshlrev_b64 v[44:45], 12, v[44:45]
	v_lshlrev_b64 v[46:47], 12, v[46:47]
	v_lshlrev_b64 v[48:49], 12, v[48:49]
	v_lshlrev_b64 v[50:51], 12, v[50:51]
	v_lshlrev_b64 v[52:53], 12, v[52:53]
	v_lshlrev_b64 v[54:55], 12, v[54:55]
	v_lshlrev_b64 v[56:57], 12, v[2:3]
	v_lshl_add_u64 v[42:43], v[40:41], 0, v[42:43]
	v_lshl_add_u64 v[44:45], v[40:41], 0, v[44:45]
	v_lshl_add_u64 v[46:47], v[40:41], 0, v[46:47]
	v_lshl_add_u64 v[48:49], v[40:41], 0, v[48:49]
	v_lshl_add_u64 v[50:51], v[40:41], 0, v[50:51]
	v_lshl_add_u64 v[52:53], v[40:41], 0, v[52:53]
	v_lshl_add_u64 v[54:55], v[40:41], 0, v[54:55]
	v_lshl_add_u64 v[40:41], v[40:41], 0, v[56:57]
	global_load_dword v2, v[42:43], off nt
	s_nop 0
	global_load_dword v42, v[44:45], off nt
	global_load_dword v43, v[46:47], off nt
	s_nop 0
	global_load_dword v44, v[48:49], off nt
	global_load_dword v45, v[50:51], off nt
	global_load_dword v46, v[52:53], off nt
	global_load_dword v47, v[54:55], off nt
	s_nop 0
	global_load_dword v40, v[40:41], off nt
	s_waitcnt vmcnt(30)
; #define LAS __attribute__((address_space(3)))
; #define LDS_WAIT() asm volatile("s_waitcnt lgkmcnt(0)" ::: "memory")
; __device__ __forceinline__ unsigned pk2(float lo, float hi) { return f2bf(lo) | (f2bf(hi) << 16); }
; __device__ __forceinline__ void tr_item(const float* W, int N, bf16* WT, int dpitch, int koff, int drow0, int k0, int n0, LAS float* scr, int lane) {
;     ...
;     for (int i = 0; i < 32; ++i) scr[(2 * i + (lane >> 5)) * 33 + (lane & 31)] = tv[i];
;     LDS_WAIT(); asm volatile("" ::: "memory");
;     const int c = lane & 7;
; #pragma unroll
;     for (int j = 0; j < 4; ++j) { const int n = (lane >> 3) + 8 * j; const LAS float* s = scr + (8 * c) * 33 + n;
;         v4u o; o.x = pk2(s[0 * 33], s[1 * 33]); o.y = pk2(s[2 * 33], s[3 * 33]); o.z = pk2(s[4 * 33], s[5 * 33]); o.w = pk2(s[6 * 33], s[7 * 33]);
;         *(v4u*)(WT + (size_t)(drow0 + n) * dpitch + koff + k0 + 8 * c) = o; }
	ds_write2_b32 v28, v58, v59 offset1:66
	s_waitcnt vmcnt(28)
	ds_write2_b32 v28, v60, v61 offset0:132 offset1:198
	s_waitcnt vmcnt(26)
	ds_write2_b32 v33, v62, v63 offset0:8 offset1:74
	s_waitcnt vmcnt(24)
	ds_write2_b32 v33, v64, v65 offset0:140 offset1:206
	s_waitcnt vmcnt(22)
	ds_write2_b32 v34, v66, v67 offset0:16 offset1:82
	s_waitcnt vmcnt(20)
	ds_write2_b32 v34, v68, v69 offset0:148 offset1:214
	s_waitcnt vmcnt(18)
	ds_write2_b32 v35, v70, v71 offset0:24 offset1:90
	s_waitcnt vmcnt(16)
	ds_write2_b32 v35, v72, v73 offset0:156 offset1:222
	s_waitcnt vmcnt(14)
	ds_write2_b32 v36, v74, v75 offset0:32 offset1:98
	s_waitcnt vmcnt(12)
	ds_write2_b32 v36, v76, v77 offset0:164 offset1:230
	s_waitcnt vmcnt(10)
	ds_write2_b32 v37, v78, v79 offset0:40 offset1:106
	s_waitcnt vmcnt(8)
	ds_write2_b32 v37, v80, v81 offset0:172 offset1:238
	s_waitcnt vmcnt(6)
	ds_write2_b32 v38, v2, v42 offset0:48 offset1:114
	s_waitcnt vmcnt(4)
	ds_write2_b32 v38, v43, v44 offset0:180 offset1:246
	s_waitcnt vmcnt(2)
	ds_write2_b32 v39, v45, v46 offset0:56 offset1:122
	s_waitcnt vmcnt(0)
	ds_write2_b32 v39, v47, v40 offset0:188 offset1:254
	s_waitcnt lgkmcnt(0)
	ds_read2_b32 v[44:45], v29 offset1:8
	ds_read2_b32 v[48:49], v29 offset0:33 offset1:41
	ds_read2_b32 v[50:51], v29 offset0:66 offset1:74
	ds_read2_b32 v[52:53], v29 offset0:99 offset1:107
	ds_read2_b32 v[54:55], v29 offset0:132 offset1:140
	s_waitcnt lgkmcnt(4)
	v_bfe_u32 v2, v44, 16, 1
	v_add3_u32 v2, v44, v2, s14
	s_waitcnt lgkmcnt(3)
	v_bfe_u32 v40, v48, 16, 1
	v_lshrrev_b32_e32 v2, 16, v2
	v_add3_u32 v40, v48, v40, s14
	ds_read2_b32 v[56:57], v29 offset0:165 offset1:173
	v_and_or_b32 v40, v40, s15, v2
	s_waitcnt lgkmcnt(3)
	v_bfe_u32 v2, v50, 16, 1
	v_add3_u32 v2, v50, v2, s14
	s_waitcnt lgkmcnt(2)
	v_bfe_u32 v41, v52, 16, 1
	ds_read2_b32 v[58:59], v29 offset0:198 offset1:206
	v_lshrrev_b32_e32 v2, 16, v2
	v_add3_u32 v41, v52, v41, s14
	ds_read2_b32 v[60:61], v29 offset0:231 offset1:239
	v_and_or_b32 v41, v41, s15, v2
	s_waitcnt lgkmcnt(3)
	v_bfe_u32 v2, v54, 16, 1
	v_add3_u32 v2, v54, v2, s14
	s_waitcnt lgkmcnt(2)
	v_bfe_u32 v42, v56, 16, 1
	v_lshrrev_b32_e32 v2, 16, v2
	v_add3_u32 v42, v56, v42, s14
	v_and_or_b32 v42, v42, s15, v2
	s_waitcnt lgkmcnt(1)
	v_bfe_u32 v2, v58, 16, 1
	v_add3_u32 v2, v58, v2, s14
	s_waitcnt lgkmcnt(0)
	v_bfe_u32 v43, v60, 16, 1
	v_lshrrev_b32_e32 v2, 16, v2
	v_add3_u32 v43, v60, v43, s14
	s_mov_b32 s9, s7
	v_and_or_b32 v43, v43, s15, v2
	v_or_b32_e32 v2, s10, v201
	v_lshl_add_u64 v[46:47], s[8:9], 1, v[6:7]
	v_mul_u32_u24_e32 v2, 0x1600, v2
	v_lshl_add_u64 v[62:63], v[46:47], 0, v[2:3]
	v_bfe_u32 v2, v45, 16, 1
	global_store_dwordx4 v[62:63], v[40:43], off
	v_add3_u32 v2, v45, v2, s14
	v_lshrrev_b32_e32 v2, 16, v2
	v_bfe_u32 v40, v49, 16, 1
	v_add3_u32 v40, v49, v40, s14
	v_and_or_b32 v40, v40, s15, v2
	v_bfe_u32 v2, v51, 16, 1
	v_add3_u32 v2, v51, v2, s14
	v_bfe_u32 v41, v53, 16, 1
	v_lshrrev_b32_e32 v2, 16, v2
	v_add3_u32 v41, v53, v41, s14
	v_and_or_b32 v41, v41, s15, v2
	v_bfe_u32 v2, v55, 16, 1
	v_add3_u32 v2, v55, v2, s14
	v_bfe_u32 v42, v57, 16, 1
	v_lshrrev_b32_e32 v2, 16, v2
	v_add3_u32 v42, v57, v42, s14
	v_and_or_b32 v42, v42, s15, v2
	v_bfe_u32 v2, v59, 16, 1
	v_add3_u32 v2, v59, v2, s14
	v_bfe_u32 v43, v61, 16, 1
	v_lshrrev_b32_e32 v2, 16, v2
	v_add3_u32 v43, v61, v43, s14
	v_and_or_b32 v43, v43, s15, v2
	v_or_b32_e32 v2, s10, v30
	v_mul_u32_u24_e32 v2, 0x1600, v2
	ds_read2_b32 v[44:45], v29 offset0:16 offset1:24
	v_lshl_add_u64 v[48:49], v[46:47], 0, v[2:3]
	global_store_dwordx4 v[48:49], v[40:43], off
	ds_read2_b32 v[48:49], v29 offset0:49 offset1:57
	ds_read2_b32 v[50:51], v29 offset0:82 offset1:90
	ds_read2_b32 v[52:53], v29 offset0:115 offset1:123
	s_waitcnt lgkmcnt(3)
	v_bfe_u32 v2, v44, 16, 1
	v_add3_u32 v2, v44, v2, s14
	s_waitcnt lgkmcnt(2)
	v_bfe_u32 v40, v48, 16, 1
	ds_read2_b32 v[54:55], v29 offset0:148 offset1:156
	v_lshrrev_b32_e32 v2, 16, v2
	v_add3_u32 v40, v48, v40, s14
	ds_read2_b32 v[56:57], v29 offset0:181 offset1:189
	v_and_or_b32 v40, v40, s15, v2
	s_waitcnt lgkmcnt(3)
	v_bfe_u32 v2, v50, 16, 1
	v_add3_u32 v2, v50, v2, s14
	s_waitcnt lgkmcnt(2)
	v_bfe_u32 v41, v52, 16, 1
	ds_read2_b32 v[58:59], v29 offset0:214 offset1:222
	v_lshrrev_b32_e32 v2, 16, v2
	v_add3_u32 v41, v52, v41, s14
	ds_read2_b32 v[60:61], v29 offset0:247 offset1:255
	v_and_or_b32 v41, v41, s15, v2
	s_waitcnt lgkmcnt(3)
	v_bfe_u32 v2, v54, 16, 1
	v_add3_u32 v2, v54, v2, s14
	s_waitcnt lgkmcnt(2)
	v_bfe_u32 v42, v56, 16, 1
	v_lshrrev_b32_e32 v2, 16, v2
	v_add3_u32 v42, v56, v42, s14
	v_and_or_b32 v42, v42, s15, v2
	s_waitcnt lgkmcnt(1)
	v_bfe_u32 v2, v58, 16, 1
	v_add3_u32 v2, v58, v2, s14
	s_waitcnt lgkmcnt(0)
	v_bfe_u32 v43, v60, 16, 1
	v_lshrrev_b32_e32 v2, 16, v2
	v_add3_u32 v43, v60, v43, s14
	v_and_or_b32 v43, v43, s15, v2
	v_or_b32_e32 v2, s10, v31
	v_mul_u32_u24_e32 v2, 0x1600, v2
	v_lshl_add_u64 v[62:63], v[46:47], 0, v[2:3]
	v_bfe_u32 v2, v45, 16, 1
	global_store_dwordx4 v[62:63], v[40:43], off
	v_add3_u32 v2, v45, v2, s14
	v_lshrrev_b32_e32 v2, 16, v2
	v_bfe_u32 v40, v49, 16, 1
	v_add3_u32 v40, v49, v40, s14
	v_and_or_b32 v40, v40, s15, v2
	v_bfe_u32 v2, v51, 16, 1
	v_add3_u32 v2, v51, v2, s14
	v_bfe_u32 v41, v53, 16, 1
	v_lshrrev_b32_e32 v2, 16, v2
	v_add3_u32 v41, v53, v41, s14
	v_and_or_b32 v41, v41, s15, v2
	v_bfe_u32 v2, v55, 16, 1
	v_add3_u32 v2, v55, v2, s14
	v_bfe_u32 v42, v57, 16, 1
	v_lshrrev_b32_e32 v2, 16, v2
	v_add3_u32 v42, v57, v42, s14
	v_and_or_b32 v42, v42, s15, v2
	v_bfe_u32 v2, v59, 16, 1
	v_add3_u32 v2, v59, v2, s14
	v_bfe_u32 v43, v61, 16, 1
	v_lshrrev_b32_e32 v2, 16, v2
	v_add3_u32 v43, v61, v43, s14
	v_and_or_b32 v43, v43, s15, v2
	v_or_b32_e32 v2, s10, v32
	v_mul_u32_u24_e32 v2, 0x1600, v2
	v_lshl_add_u64 v[44:45], v[46:47], 0, v[2:3]
	global_store_dwordx4 v[44:45], v[40:43], off
	s_waitcnt lgkmcnt(0)
	s_mov_b64 s[8:9], 0
; __device__ __forceinline__ void tr_item(const float* W, int N, bf16* WT, int dpitch, int koff, int drow0, int k0, int n0, LAS float* scr, int lane) {
;     ...
;     for (int i = 0; i < 32; ++i) tv[i] = W[(size_t)(k0 + 2 * i + (lane >> 5)) * N + n0 + (lane & 31)];
; #pragma unroll
;     for (int i = 0; i < 32; ++i) scr[(2 * i + (lane >> 5)) * 33 + (lane & 31)] = tv[i];
; __global__ void __launch_bounds__(512, 2) fwd_mega(Args a) {
;     ...
;             if (it < 1408) { const int kb = it / 88, nb = it % 88, n0 = 32 * nb; tr_item(INF(17) + (size_t)LL * D * FF, FF, WSP(WS_WGU), 1024, 0, (n0 >> 7) * 256 + 128 + (n0 & 127), 64 * kb, n0, scr, lane); continue; } it -= 1408;
.LBB0_993:
	s_andn2_b64 vcc, exec, s[8:9]
	s_cbranch_vccnz .LBB0_995
	s_add_i32 s6, s53, 0xea00
	s_and_b32 s8, s6, 0xffff
	s_mul_i32 s8, s8, 0xba2f
	s_lshr_b32 s10, s8, 16
	s_lshr_b32 s8, s8, 22
	s_mulk_i32 s8, 0x58
	s_sub_i32 s6, s6, s8
	s_and_b32 s9, s6, 0xffff
	s_and_b32 s8, s10, 0xffc0
	v_or_b32_e32 v2, s8, v200
	s_lshl_b32 s6, s9, 7
	v_lshl_add_u64 v[40:41], v[8:9], 0, s[6:7]
	v_mul_u32_u24_e32 v2, 0x2c00, v2
	v_lshl_add_u64 v[40:41], v[40:41], 0, v[2:3]
	v_add_co_u32_e32 v42, vcc, s16, v40
	s_lshl_b32 s6, s9, 5
	s_nop 0
	v_addc_co_u32_e32 v43, vcc, 0, v41, vcc
	v_add_co_u32_e32 v44, vcc, s17, v40
	s_lshl_b32 s9, s9, 6
	s_nop 0
	v_addc_co_u32_e32 v45, vcc, 0, v41, vcc
	v_add_co_u32_e32 v46, vcc, s18, v40
	s_and_b32 s9, s9, 0x1f00
	s_nop 0
	v_addc_co_u32_e32 v47, vcc, 0, v41, vcc
	v_add_co_u32_e32 v48, vcc, s19, v40
	s_and_b32 s6, s6, 0x60
	s_nop 0
	v_addc_co_u32_e32 v49, vcc, 0, v41, vcc
	v_add_co_u32_e32 v50, vcc, s20, v40
	s_or_b32 s6, s6, s9
	s_nop 0
	v_addc_co_u32_e32 v51, vcc, 0, v41, vcc
	v_add_co_u32_e32 v52, vcc, s21, v40
	s_or_b32 s9, s6, 0x80
	s_nop 0
	v_addc_co_u32_e32 v53, vcc, 0, v41, vcc
	v_add_co_u32_e32 v54, vcc, s23, v40
	s_lshl_b32 s6, s8, 1
	s_nop 0
	v_addc_co_u32_e32 v55, vcc, 0, v41, vcc
	global_load_dword v2, v[40:41], off nt
	global_load_dword v58, v[42:43], off offset:2048 nt
	global_load_dword v59, v[44:45], off nt
	global_load_dword v60, v[46:47], off offset:2048 nt
	global_load_dword v61, v[48:49], off nt
	global_load_dword v62, v[50:51], off offset:2048 nt
	global_load_dword v63, v[52:53], off nt
	global_load_dword v64, v[54:55], off offset:2048 nt
	v_add_co_u32_e32 v42, vcc, s24, v40
	s_nop 1
	v_addc_co_u32_e32 v43, vcc, 0, v41, vcc
	v_add_co_u32_e32 v44, vcc, s25, v40
	s_nop 1
	v_addc_co_u32_e32 v45, vcc, 0, v41, vcc
	v_add_co_u32_e32 v46, vcc, s28, v40
	s_nop 1
	v_addc_co_u32_e32 v47, vcc, 0, v41, vcc
	v_add_co_u32_e32 v48, vcc, s29, v40
	s_nop 1
	v_addc_co_u32_e32 v49, vcc, 0, v41, vcc
	v_add_co_u32_e32 v50, vcc, s30, v40
	s_nop 1
	v_addc_co_u32_e32 v51, vcc, 0, v41, vcc
	v_add_co_u32_e32 v52, vcc, s31, v40
	s_nop 1
	v_addc_co_u32_e32 v53, vcc, 0, v41, vcc
	v_add_co_u32_e32 v54, vcc, s34, v40
	s_nop 1
	v_addc_co_u32_e32 v55, vcc, 0, v41, vcc
	v_add_co_u32_e32 v56, vcc, s35, v40
	s_nop 1
	v_addc_co_u32_e32 v57, vcc, 0, v41, vcc
	global_load_dword v65, v[42:43], off nt
	global_load_dword v66, v[44:45], off offset:2048 nt
	global_load_dword v67, v[46:47], off nt
	global_load_dword v68, v[48:49], off offset:2048 nt
	global_load_dword v69, v[50:51], off nt
	global_load_dword v70, v[52:53], off offset:2048 nt
	global_load_dword v71, v[54:55], off nt
	global_load_dword v72, v[56:57], off offset:2048 nt
	v_add_co_u32_e32 v42, vcc, s36, v40
	s_nop 1
	v_addc_co_u32_e32 v43, vcc, 0, v41, vcc
	v_add_co_u32_e32 v44, vcc, s37, v40
	s_nop 1
	v_addc_co_u32_e32 v45, vcc, 0, v41, vcc
	v_add_co_u32_e32 v46, vcc, s38, v40
	s_nop 1
	v_addc_co_u32_e32 v47, vcc, 0, v41, vcc
	v_add_co_u32_e32 v48, vcc, s39, v40
	s_nop 1
	v_addc_co_u32_e32 v49, vcc, 0, v41, vcc
	v_add_co_u32_e32 v50, vcc, s40, v40
	s_nop 1
	v_addc_co_u32_e32 v51, vcc, 0, v41, vcc
	v_add_co_u32_e32 v52, vcc, s41, v40
	s_nop 1
	v_addc_co_u32_e32 v53, vcc, 0, v41, vcc
	v_add_co_u32_e32 v54, vcc, s42, v40
	s_nop 1
	v_addc_co_u32_e32 v55, vcc, 0, v41, vcc
	v_add_co_u32_e32 v56, vcc, s43, v40
	s_nop 1
	v_addc_co_u32_e32 v57, vcc, 0, v41, vcc
	global_load_dword v73, v[42:43], off nt
	global_load_dword v74, v[44:45], off offset:2048 nt
	global_load_dword v75, v[46:47], off nt
	global_load_dword v76, v[48:49], off offset:2048 nt
	global_load_dword v77, v[50:51], off nt
	global_load_dword v78, v[52:53], off offset:2048 nt
	global_load_dword v79, v[54:55], off nt
	s_nop 0
	global_load_dword v56, v[56:57], off offset:2048 nt
	v_add_co_u32_e32 v42, vcc, s44, v40
	s_nop 1
	v_addc_co_u32_e32 v43, vcc, 0, v41, vcc
	v_add_co_u32_e32 v44, vcc, s45, v40
	s_nop 1
	v_addc_co_u32_e32 v45, vcc, 0, v41, vcc
	v_add_co_u32_e32 v46, vcc, s46, v40
	s_nop 1
	v_addc_co_u32_e32 v47, vcc, 0, v41, vcc
	v_add_co_u32_e32 v48, vcc, s47, v40
	s_nop 1
	v_addc_co_u32_e32 v49, vcc, 0, v41, vcc
	v_add_co_u32_e32 v50, vcc, s48, v40
	s_nop 1
	v_addc_co_u32_e32 v51, vcc, 0, v41, vcc
	v_add_co_u32_e32 v52, vcc, s49, v40
	s_nop 1
	v_addc_co_u32_e32 v53, vcc, 0, v41, vcc
	v_add_co_u32_e32 v54, vcc, s50, v40
	s_nop 1
	v_addc_co_u32_e32 v55, vcc, 0, v41, vcc
	v_add_co_u32_e32 v40, vcc, s51, v40
	s_nop 1
	v_addc_co_u32_e32 v41, vcc, 0, v41, vcc
	global_load_dword v42, v[42:43], off nt
	s_nop 0
	global_load_dword v43, v[44:45], off offset:2048 nt
	s_nop 0
	global_load_dword v44, v[46:47], off nt
	global_load_dword v45, v[48:49], off offset:2048 nt
	s_nop 0
	global_load_dword v46, v[50:51], off nt
	global_load_dword v47, v[52:53], off offset:2048 nt
	global_load_dword v48, v[54:55], off nt
	s_nop 0
	global_load_dword v40, v[40:41], off offset:2048 nt
	s_waitcnt vmcnt(30)
	ds_write2_b32 v28, v2, v58 offset1:66
	s_waitcnt vmcnt(28)
	ds_write2_b32 v28, v59, v60 offset0:132 offset1:198
	s_waitcnt vmcnt(26)
	ds_write2_b32 v33, v61, v62 offset0:8 offset1:74
	s_waitcnt vmcnt(24)
	ds_write2_b32 v33, v63, v64 offset0:140 offset1:206
	s_waitcnt vmcnt(22)
	ds_write2_b32 v34, v65, v66 offset0:16 offset1:82
	s_waitcnt vmcnt(20)
	ds_write2_b32 v34, v67, v68 offset0:148 offset1:214
	s_waitcnt vmcnt(18)
; #define LAS __attribute__((address_space(3)))
; #define LDS_WAIT() asm volatile("s_waitcnt lgkmcnt(0)" ::: "memory")
; __device__ __forceinline__ unsigned pk2(float lo, float hi) { return f2bf(lo) | (f2bf(hi) << 16); }
; __device__ __forceinline__ void tr_item(const float* W, int N, bf16* WT, int dpitch, int koff, int drow0, int k0, int n0, LAS float* scr, int lane) {
;     ...
;     for (int i = 0; i < 32; ++i) scr[(2 * i + (lane >> 5)) * 33 + (lane & 31)] = tv[i];
;     LDS_WAIT(); asm volatile("" ::: "memory");
;     const int c = lane & 7;
; #pragma unroll
;     for (int j = 0; j < 4; ++j) { const int n = (lane >> 3) + 8 * j; const LAS float* s = scr + (8 * c) * 33 + n;
;         v4u o; o.x = pk2(s[0 * 33], s[1 * 33]); o.y = pk2(s[2 * 33], s[3 * 33]); o.z = pk2(s[4 * 33], s[5 * 33]); o.w = pk2(s[6 * 33], s[7 * 33]);
;         *(v4u*)(WT + (size_t)(drow0 + n) * dpitch + koff + k0 + 8 * c) = o; }
	ds_write2_b32 v35, v69, v70 offset0:24 offset1:90
	s_waitcnt vmcnt(16)
	ds_write2_b32 v35, v71, v72 offset0:156 offset1:222
	s_waitcnt vmcnt(14)
	ds_write2_b32 v36, v73, v74 offset0:32 offset1:98
	s_waitcnt vmcnt(12)
	ds_write2_b32 v36, v75, v76 offset0:164 offset1:230
	s_waitcnt vmcnt(10)
	ds_write2_b32 v37, v77, v78 offset0:40 offset1:106
	s_waitcnt vmcnt(8)
	ds_write2_b32 v37, v79, v56 offset0:172 offset1:238
	s_waitcnt vmcnt(6)
	ds_write2_b32 v38, v42, v43 offset0:48 offset1:114
	s_waitcnt vmcnt(4)
	ds_write2_b32 v38, v44, v45 offset0:180 offset1:246
	s_waitcnt vmcnt(2)
	ds_write2_b32 v39, v46, v47 offset0:56 offset1:122
	s_waitcnt vmcnt(0)
	ds_write2_b32 v39, v48, v40 offset0:188 offset1:254
	s_waitcnt lgkmcnt(0)
	ds_read2_b32 v[44:45], v29 offset1:8
	ds_read2_b32 v[48:49], v29 offset0:33 offset1:41
	ds_read2_b32 v[50:51], v29 offset0:66 offset1:74
	ds_read2_b32 v[52:53], v29 offset0:99 offset1:107
	ds_read2_b32 v[54:55], v29 offset0:132 offset1:140
	s_waitcnt lgkmcnt(4)
	v_bfe_u32 v2, v44, 16, 1
	v_add3_u32 v2, v44, v2, s14
	s_waitcnt lgkmcnt(3)
	v_bfe_u32 v40, v48, 16, 1
	v_lshrrev_b32_e32 v2, 16, v2
	v_add3_u32 v40, v48, v40, s14
	ds_read2_b32 v[56:57], v29 offset0:165 offset1:173
	v_and_or_b32 v40, v40, s15, v2
	s_waitcnt lgkmcnt(3)
	v_bfe_u32 v2, v50, 16, 1
	v_add3_u32 v2, v50, v2, s14
	s_waitcnt lgkmcnt(2)
	v_bfe_u32 v41, v52, 16, 1
	ds_read2_b32 v[58:59], v29 offset0:198 offset1:206
	v_lshrrev_b32_e32 v2, 16, v2
	v_add3_u32 v41, v52, v41, s14
	ds_read2_b32 v[60:61], v29 offset0:231 offset1:239
	v_and_or_b32 v41, v41, s15, v2
	s_waitcnt lgkmcnt(3)
	v_bfe_u32 v2, v54, 16, 1
	v_add3_u32 v2, v54, v2, s14
	s_waitcnt lgkmcnt(2)
	v_bfe_u32 v42, v56, 16, 1
	v_lshrrev_b32_e32 v2, 16, v2
	v_add3_u32 v42, v56, v42, s14
	v_and_or_b32 v42, v42, s15, v2
	s_waitcnt lgkmcnt(1)
	v_bfe_u32 v2, v58, 16, 1
	v_add3_u32 v2, v58, v2, s14
	s_waitcnt lgkmcnt(0)
	v_bfe_u32 v43, v60, 16, 1
	v_lshrrev_b32_e32 v2, 16, v2
	v_add3_u32 v43, v60, v43, s14
	v_and_or_b32 v43, v43, s15, v2
	v_or_b32_e32 v2, s9, v201
	v_lshl_add_u64 v[46:47], v[10:11], 0, s[6:7]
	v_lshlrev_b32_e32 v2, 11, v2
	v_lshl_add_u64 v[62:63], v[46:47], 0, v[2:3]
	v_bfe_u32 v2, v45, 16, 1
	global_store_dwordx4 v[62:63], v[40:43], off
	v_add3_u32 v2, v45, v2, s14
	v_lshrrev_b32_e32 v2, 16, v2
	v_bfe_u32 v40, v49, 16, 1
	v_add3_u32 v40, v49, v40, s14
	v_and_or_b32 v40, v40, s15, v2
	v_bfe_u32 v2, v51, 16, 1
	v_add3_u32 v2, v51, v2, s14
	v_bfe_u32 v41, v53, 16, 1
	v_lshrrev_b32_e32 v2, 16, v2
	v_add3_u32 v41, v53, v41, s14
	v_and_or_b32 v41, v41, s15, v2
	v_bfe_u32 v2, v55, 16, 1
	v_add3_u32 v2, v55, v2, s14
	v_bfe_u32 v42, v57, 16, 1
	v_lshrrev_b32_e32 v2, 16, v2
	v_add3_u32 v42, v57, v42, s14
	v_and_or_b32 v42, v42, s15, v2
	v_bfe_u32 v2, v59, 16, 1
	v_add3_u32 v2, v59, v2, s14
	v_bfe_u32 v43, v61, 16, 1
	v_lshrrev_b32_e32 v2, 16, v2
	v_add3_u32 v43, v61, v43, s14
	v_and_or_b32 v43, v43, s15, v2
	v_or_b32_e32 v2, s9, v30
	v_lshlrev_b32_e32 v2, 11, v2
	ds_read2_b32 v[44:45], v29 offset0:16 offset1:24
	v_lshl_add_u64 v[48:49], v[46:47], 0, v[2:3]
	global_store_dwordx4 v[48:49], v[40:43], off
	ds_read2_b32 v[48:49], v29 offset0:49 offset1:57
	ds_read2_b32 v[50:51], v29 offset0:82 offset1:90
	ds_read2_b32 v[52:53], v29 offset0:115 offset1:123
	s_waitcnt lgkmcnt(3)
	v_bfe_u32 v2, v44, 16, 1
	v_add3_u32 v2, v44, v2, s14
	s_waitcnt lgkmcnt(2)
	v_bfe_u32 v40, v48, 16, 1
	ds_read2_b32 v[54:55], v29 offset0:148 offset1:156
	v_lshrrev_b32_e32 v2, 16, v2
	v_add3_u32 v40, v48, v40, s14
	ds_read2_b32 v[56:57], v29 offset0:181 offset1:189
	v_and_or_b32 v40, v40, s15, v2
	s_waitcnt lgkmcnt(3)
	v_bfe_u32 v2, v50, 16, 1
	v_add3_u32 v2, v50, v2, s14
	s_waitcnt lgkmcnt(2)
	v_bfe_u32 v41, v52, 16, 1
	ds_read2_b32 v[58:59], v29 offset0:214 offset1:222
	v_lshrrev_b32_e32 v2, 16, v2
	v_add3_u32 v41, v52, v41, s14
	ds_read2_b32 v[60:61], v29 offset0:247 offset1:255
	v_and_or_b32 v41, v41, s15, v2
	s_waitcnt lgkmcnt(3)
	v_bfe_u32 v2, v54, 16, 1
	v_add3_u32 v2, v54, v2, s14
	s_waitcnt lgkmcnt(2)
	v_bfe_u32 v42, v56, 16, 1
	v_lshrrev_b32_e32 v2, 16, v2
	v_add3_u32 v42, v56, v42, s14
	v_and_or_b32 v42, v42, s15, v2
	s_waitcnt lgkmcnt(1)
	v_bfe_u32 v2, v58, 16, 1
	v_add3_u32 v2, v58, v2, s14
	s_waitcnt lgkmcnt(0)
	v_bfe_u32 v43, v60, 16, 1
	v_lshrrev_b32_e32 v2, 16, v2
	v_add3_u32 v43, v60, v43, s14
	v_and_or_b32 v43, v43, s15, v2
	v_or_b32_e32 v2, s9, v31
	v_lshlrev_b32_e32 v2, 11, v2
	v_lshl_add_u64 v[62:63], v[46:47], 0, v[2:3]
	v_bfe_u32 v2, v45, 16, 1
	global_store_dwordx4 v[62:63], v[40:43], off
	v_add3_u32 v2, v45, v2, s14
	v_lshrrev_b32_e32 v2, 16, v2
	v_bfe_u32 v40, v49, 16, 1
	v_add3_u32 v40, v49, v40, s14
	v_and_or_b32 v40, v40, s15, v2
	v_bfe_u32 v2, v51, 16, 1
	v_add3_u32 v2, v51, v2, s14
	v_bfe_u32 v41, v53, 16, 1
	v_lshrrev_b32_e32 v2, 16, v2
	v_add3_u32 v41, v53, v41, s14
	v_and_or_b32 v41, v41, s15, v2
	v_bfe_u32 v2, v55, 16, 1
	v_add3_u32 v2, v55, v2, s14
	v_bfe_u32 v42, v57, 16, 1
	v_lshrrev_b32_e32 v2, 16, v2
	v_add3_u32 v42, v57, v42, s14
	v_and_or_b32 v42, v42, s15, v2
	v_bfe_u32 v2, v59, 16, 1
	v_add3_u32 v2, v59, v2, s14
	v_bfe_u32 v43, v61, 16, 1
	v_lshrrev_b32_e32 v2, 16, v2
	v_add3_u32 v43, v61, v43, s14
	v_and_or_b32 v43, v43, s15, v2
	v_or_b32_e32 v2, s9, v32
	v_lshlrev_b32_e32 v2, 11, v2
	v_lshl_add_u64 v[44:45], v[46:47], 0, v[2:3]
	global_store_dwordx4 v[44:45], v[40:43], off
	s_waitcnt lgkmcnt(0)

; __device__ __forceinline__ void tr_item(const float* W, int N, bf16* WT, int dpitch, int koff, int drow0, int k0, int n0, LAS float* scr, int lane) {
;     ...
;     for (int i = 0; i < 32; ++i) tv[i] = W[(size_t)(k0 + 2 * i + (lane >> 5)) * N + n0 + (lane & 31)];
; #pragma unroll
;     for (int i = 0; i < 32; ++i) scr[(2 * i + (lane >> 5)) * 33 + (lane & 31)] = tv[i];
; __global__ void __launch_bounds__(512, 2) fwd_mega(Args a) {
;     ...
;             if (it < 1408) { const int kb = it / 88, nb = it % 88, n0 = 32 * nb; tr_item(INF(16) + (size_t)LL * D * FF, FF, WSP(WS_WGU), 1024, 0, (n0 >> 7) * 256 + (n0 & 127), 64 * kb, n0, scr, lane); continue; } it -= 1408;
.LBB0_996:
	s_andn2_b64 vcc, exec, s[8:9]
	s_cbranch_vccnz .LBB0_998
	s_add_i32 s6, s53, 0xef80
	s_and_b32 s8, s6, 0xffff
	s_mul_i32 s8, s8, 0xba2f
	s_lshr_b32 s10, s8, 16
	s_lshr_b32 s8, s8, 22
	s_mulk_i32 s8, 0x58
	s_sub_i32 s6, s6, s8
	s_and_b32 s9, s6, 0xffff
	s_and_b32 s8, s10, 0xffc0
	v_or_b32_e32 v2, s8, v200
	s_lshl_b32 s6, s9, 7
	v_lshl_add_u64 v[40:41], v[12:13], 0, s[6:7]
	v_mul_u32_u24_e32 v2, 0x2c00, v2
	v_lshl_add_u64 v[40:41], v[40:41], 0, v[2:3]
	v_add_co_u32_e32 v42, vcc, s16, v40
	s_lshl_b32 s6, s9, 5
	s_nop 0
	v_addc_co_u32_e32 v43, vcc, 0, v41, vcc
	v_add_co_u32_e32 v44, vcc, s17, v40
	s_lshl_b32 s9, s9, 6
	s_nop 0
	v_addc_co_u32_e32 v45, vcc, 0, v41, vcc
	v_add_co_u32_e32 v46, vcc, s18, v40
	s_and_b32 s9, s9, 0x1f00
	s_nop 0
	v_addc_co_u32_e32 v47, vcc, 0, v41, vcc
	v_add_co_u32_e32 v48, vcc, s19, v40
	s_and_b32 s6, s6, 0x60
	s_nop 0
	v_addc_co_u32_e32 v49, vcc, 0, v41, vcc
	v_add_co_u32_e32 v50, vcc, s20, v40
	s_or_b32 s9, s9, s6
	s_nop 0
	v_addc_co_u32_e32 v51, vcc, 0, v41, vcc
	v_add_co_u32_e32 v52, vcc, s21, v40
	s_lshl_b32 s6, s8, 1
	s_nop 0
	v_addc_co_u32_e32 v53, vcc, 0, v41, vcc
	v_add_co_u32_e32 v54, vcc, s23, v40
	s_nop 1
	v_addc_co_u32_e32 v55, vcc, 0, v41, vcc
	global_load_dword v2, v[40:41], off nt
	global_load_dword v58, v[42:43], off offset:2048 nt
	global_load_dword v59, v[44:45], off nt
	global_load_dword v60, v[46:47], off offset:2048 nt
	global_load_dword v61, v[48:49], off nt
	global_load_dword v62, v[50:51], off offset:2048 nt
	global_load_dword v63, v[52:53], off nt
	global_load_dword v64, v[54:55], off offset:2048 nt
	v_add_co_u32_e32 v42, vcc, s24, v40
	s_nop 1
	v_addc_co_u32_e32 v43, vcc, 0, v41, vcc
	v_add_co_u32_e32 v44, vcc, s25, v40
	s_nop 1
	v_addc_co_u32_e32 v45, vcc, 0, v41, vcc
	v_add_co_u32_e32 v46, vcc, s28, v40
	s_nop 1
	v_addc_co_u32_e32 v47, vcc, 0, v41, vcc
	v_add_co_u32_e32 v48, vcc, s29, v40
	s_nop 1
	v_addc_co_u32_e32 v49, vcc, 0, v41, vcc
	v_add_co_u32_e32 v50, vcc, s30, v40
	s_nop 1
	v_addc_co_u32_e32 v51, vcc, 0, v41, vcc
	v_add_co_u32_e32 v52, vcc, s31, v40
	s_nop 1
	v_addc_co_u32_e32 v53, vcc, 0, v41, vcc
	v_add_co_u32_e32 v54, vcc, s34, v40
	s_nop 1
	v_addc_co_u32_e32 v55, vcc, 0, v41, vcc
	v_add_co_u32_e32 v56, vcc, s35, v40
	s_nop 1
	v_addc_co_u32_e32 v57, vcc, 0, v41, vcc
	global_load_dword v65, v[42:43], off nt
	global_load_dword v66, v[44:45], off offset:2048 nt
	global_load_dword v67, v[46:47], off nt
	global_load_dword v68, v[48:49], off offset:2048 nt
	global_load_dword v69, v[50:51], off nt
	global_load_dword v70, v[52:53], off offset:2048 nt
	global_load_dword v71, v[54:55], off nt
	global_load_dword v72, v[56:57], off offset:2048 nt
	v_add_co_u32_e32 v42, vcc, s36, v40
	s_nop 1
	v_addc_co_u32_e32 v43, vcc, 0, v41, vcc
	v_add_co_u32_e32 v44, vcc, s37, v40
	s_nop 1
	v_addc_co_u32_e32 v45, vcc, 0, v41, vcc
	v_add_co_u32_e32 v46, vcc, s38, v40
	s_nop 1
	v_addc_co_u32_e32 v47, vcc, 0, v41, vcc
	v_add_co_u32_e32 v48, vcc, s39, v40
	s_nop 1
	v_addc_co_u32_e32 v49, vcc, 0, v41, vcc
	v_add_co_u32_e32 v50, vcc, s40, v40
	s_nop 1
	v_addc_co_u32_e32 v51, vcc, 0, v41, vcc
	v_add_co_u32_e32 v52, vcc, s41, v40
	s_nop 1
	v_addc_co_u32_e32 v53, vcc, 0, v41, vcc
	v_add_co_u32_e32 v54, vcc, s42, v40
	s_nop 1
	v_addc_co_u32_e32 v55, vcc, 0, v41, vcc
	v_add_co_u32_e32 v56, vcc, s43, v40
	s_nop 1
	v_addc_co_u32_e32 v57, vcc, 0, v41, vcc
	global_load_dword v73, v[42:43], off nt
	global_load_dword v74, v[44:45], off offset:2048 nt
	global_load_dword v75, v[46:47], off nt
	global_load_dword v76, v[48:49], off offset:2048 nt
	global_load_dword v77, v[50:51], off nt
	global_load_dword v78, v[52:53], off offset:2048 nt
	global_load_dword v79, v[54:55], off nt
	s_nop 0
	global_load_dword v56, v[56:57], off offset:2048 nt
	v_add_co_u32_e32 v42, vcc, s44, v40
	s_nop 1
	v_addc_co_u32_e32 v43, vcc, 0, v41, vcc
	v_add_co_u32_e32 v44, vcc, s45, v40
	s_nop 1
	v_addc_co_u32_e32 v45, vcc, 0, v41, vcc
	v_add_co_u32_e32 v46, vcc, s46, v40
	s_nop 1
	v_addc_co_u32_e32 v47, vcc, 0, v41, vcc
	v_add_co_u32_e32 v48, vcc, s47, v40
	s_nop 1
	v_addc_co_u32_e32 v49, vcc, 0, v41, vcc
	v_add_co_u32_e32 v50, vcc, s48, v40
	s_nop 1
	v_addc_co_u32_e32 v51, vcc, 0, v41, vcc
	v_add_co_u32_e32 v52, vcc, s49, v40
	s_nop 1
	v_addc_co_u32_e32 v53, vcc, 0, v41, vcc
	v_add_co_u32_e32 v54, vcc, s50, v40
	s_nop 1
	v_addc_co_u32_e32 v55, vcc, 0, v41, vcc
	v_add_co_u32_e32 v40, vcc, s51, v40
	s_nop 1
	v_addc_co_u32_e32 v41, vcc, 0, v41, vcc
	global_load_dword v42, v[42:43], off nt
	s_nop 0
	global_load_dword v43, v[44:45], off offset:2048 nt
	s_nop 0
	global_load_dword v44, v[46:47], off nt
	global_load_dword v45, v[48:49], off offset:2048 nt
	s_nop 0
	global_load_dword v46, v[50:51], off nt
	global_load_dword v47, v[52:53], off offset:2048 nt
	global_load_dword v48, v[54:55], off nt
	s_nop 0
	global_load_dword v40, v[40:41], off offset:2048 nt
	s_waitcnt vmcnt(30)
	ds_write2_b32 v28, v2, v58 offset1:66
	s_waitcnt vmcnt(28)
	ds_write2_b32 v28, v59, v60 offset0:132 offset1:198
	s_waitcnt vmcnt(26)
	ds_write2_b32 v33, v61, v62 offset0:8 offset1:74
	s_waitcnt vmcnt(24)
	ds_write2_b32 v33, v63, v64 offset0:140 offset1:206
	s_waitcnt vmcnt(22)
	ds_write2_b32 v34, v65, v66 offset0:16 offset1:82
	s_waitcnt vmcnt(20)
	ds_write2_b32 v34, v67, v68 offset0:148 offset1:214
	s_waitcnt vmcnt(18)
; #define LAS __attribute__((address_space(3)))
; #define LDS_WAIT() asm volatile("s_waitcnt lgkmcnt(0)" ::: "memory")
; __device__ __forceinline__ unsigned pk2(float lo, float hi) { return f2bf(lo) | (f2bf(hi) << 16); }
; __device__ __forceinline__ void tr_item(const float* W, int N, bf16* WT, int dpitch, int koff, int drow0, int k0, int n0, LAS float* scr, int lane) {
;     ...
;     for (int i = 0; i < 32; ++i) scr[(2 * i + (lane >> 5)) * 33 + (lane & 31)] = tv[i];
;     LDS_WAIT(); asm volatile("" ::: "memory");
;     const int c = lane & 7;
; #pragma unroll
;     for (int j = 0; j < 4; ++j) { const int n = (lane >> 3) + 8 * j; const LAS float* s = scr + (8 * c) * 33 + n;
;         v4u o; o.x = pk2(s[0 * 33], s[1 * 33]); o.y = pk2(s[2 * 33], s[3 * 33]); o.z = pk2(s[4 * 33], s[5 * 33]); o.w = pk2(s[6 * 33], s[7 * 33]);
;         *(v4u*)(WT + (size_t)(drow0 + n) * dpitch + koff + k0 + 8 * c) = o; }
	ds_write2_b32 v35, v69, v70 offset0:24 offset1:90
	s_waitcnt vmcnt(16)
	ds_write2_b32 v35, v71, v72 offset0:156 offset1:222
	s_waitcnt vmcnt(14)
	ds_write2_b32 v36, v73, v74 offset0:32 offset1:98
	s_waitcnt vmcnt(12)
	ds_write2_b32 v36, v75, v76 offset0:164 offset1:230
	s_waitcnt vmcnt(10)
	ds_write2_b32 v37, v77, v78 offset0:40 offset1:106
	s_waitcnt vmcnt(8)
	ds_write2_b32 v37, v79, v56 offset0:172 offset1:238
	s_waitcnt vmcnt(6)
	ds_write2_b32 v38, v42, v43 offset0:48 offset1:114
	s_waitcnt vmcnt(4)
	ds_write2_b32 v38, v44, v45 offset0:180 offset1:246
	s_waitcnt vmcnt(2)
	ds_write2_b32 v39, v46, v47 offset0:56 offset1:122
	s_waitcnt vmcnt(0)
	ds_write2_b32 v39, v48, v40 offset0:188 offset1:254
	s_waitcnt lgkmcnt(0)
	ds_read2_b32 v[44:45], v29 offset1:8
	ds_read2_b32 v[48:49], v29 offset0:33 offset1:41
	ds_read2_b32 v[50:51], v29 offset0:66 offset1:74
	ds_read2_b32 v[52:53], v29 offset0:99 offset1:107
	ds_read2_b32 v[54:55], v29 offset0:132 offset1:140
	s_waitcnt lgkmcnt(4)
	v_bfe_u32 v2, v44, 16, 1
	v_add3_u32 v2, v44, v2, s14
	s_waitcnt lgkmcnt(3)
	v_bfe_u32 v40, v48, 16, 1
	v_lshrrev_b32_e32 v2, 16, v2
	v_add3_u32 v40, v48, v40, s14
	ds_read2_b32 v[56:57], v29 offset0:165 offset1:173
	v_and_or_b32 v40, v40, s15, v2
	s_waitcnt lgkmcnt(3)
	v_bfe_u32 v2, v50, 16, 1
	v_add3_u32 v2, v50, v2, s14
	s_waitcnt lgkmcnt(2)
	v_bfe_u32 v41, v52, 16, 1
	ds_read2_b32 v[58:59], v29 offset0:198 offset1:206
	v_lshrrev_b32_e32 v2, 16, v2
	v_add3_u32 v41, v52, v41, s14
	ds_read2_b32 v[60:61], v29 offset0:231 offset1:239
	v_and_or_b32 v41, v41, s15, v2
	s_waitcnt lgkmcnt(3)
	v_bfe_u32 v2, v54, 16, 1
	v_add3_u32 v2, v54, v2, s14
	s_waitcnt lgkmcnt(2)
	v_bfe_u32 v42, v56, 16, 1
	v_lshrrev_b32_e32 v2, 16, v2
	v_add3_u32 v42, v56, v42, s14
	v_and_or_b32 v42, v42, s15, v2
	s_waitcnt lgkmcnt(1)
	v_bfe_u32 v2, v58, 16, 1
	v_add3_u32 v2, v58, v2, s14
	s_waitcnt lgkmcnt(0)
	v_bfe_u32 v43, v60, 16, 1
	v_lshrrev_b32_e32 v2, 16, v2
	v_add3_u32 v43, v60, v43, s14
	v_and_or_b32 v43, v43, s15, v2
	v_or_b32_e32 v2, s9, v201
	v_lshl_add_u64 v[46:47], v[10:11], 0, s[6:7]
	v_lshlrev_b32_e32 v2, 11, v2
	v_lshl_add_u64 v[62:63], v[46:47], 0, v[2:3]
	v_bfe_u32 v2, v45, 16, 1
	global_store_dwordx4 v[62:63], v[40:43], off
	v_add3_u32 v2, v45, v2, s14
	v_lshrrev_b32_e32 v2, 16, v2
	v_bfe_u32 v40, v49, 16, 1
	v_add3_u32 v40, v49, v40, s14
	v_and_or_b32 v40, v40, s15, v2
	v_bfe_u32 v2, v51, 16, 1
	v_add3_u32 v2, v51, v2, s14
	v_bfe_u32 v41, v53, 16, 1
	v_lshrrev_b32_e32 v2, 16, v2
	v_add3_u32 v41, v53, v41, s14
	v_and_or_b32 v41, v41, s15, v2
	v_bfe_u32 v2, v55, 16, 1
	v_add3_u32 v2, v55, v2, s14
	v_bfe_u32 v42, v57, 16, 1
	v_lshrrev_b32_e32 v2, 16, v2
	v_add3_u32 v42, v57, v42, s14
	v_and_or_b32 v42, v42, s15, v2
	v_bfe_u32 v2, v59, 16, 1
	v_add3_u32 v2, v59, v2, s14
	v_bfe_u32 v43, v61, 16, 1
	v_lshrrev_b32_e32 v2, 16, v2
	v_add3_u32 v43, v61, v43, s14
	v_and_or_b32 v43, v43, s15, v2
	v_or_b32_e32 v2, s9, v30
	v_lshlrev_b32_e32 v2, 11, v2
	ds_read2_b32 v[44:45], v29 offset0:16 offset1:24
	v_lshl_add_u64 v[48:49], v[46:47], 0, v[2:3]
	global_store_dwordx4 v[48:49], v[40:43], off
	ds_read2_b32 v[48:49], v29 offset0:49 offset1:57
	ds_read2_b32 v[50:51], v29 offset0:82 offset1:90
	ds_read2_b32 v[52:53], v29 offset0:115 offset1:123
	s_waitcnt lgkmcnt(3)
	v_bfe_u32 v2, v44, 16, 1
	v_add3_u32 v2, v44, v2, s14
	s_waitcnt lgkmcnt(2)
	v_bfe_u32 v40, v48, 16, 1
	ds_read2_b32 v[54:55], v29 offset0:148 offset1:156
	v_lshrrev_b32_e32 v2, 16, v2
	v_add3_u32 v40, v48, v40, s14
	ds_read2_b32 v[56:57], v29 offset0:181 offset1:189
	v_and_or_b32 v40, v40, s15, v2
	s_waitcnt lgkmcnt(3)
	v_bfe_u32 v2, v50, 16, 1
	v_add3_u32 v2, v50, v2, s14
	s_waitcnt lgkmcnt(2)
	v_bfe_u32 v41, v52, 16, 1
	ds_read2_b32 v[58:59], v29 offset0:214 offset1:222
	v_lshrrev_b32_e32 v2, 16, v2
	v_add3_u32 v41, v52, v41, s14
	ds_read2_b32 v[60:61], v29 offset0:247 offset1:255
	v_and_or_b32 v41, v41, s15, v2
	s_waitcnt lgkmcnt(3)
	v_bfe_u32 v2, v54, 16, 1
	v_add3_u32 v2, v54, v2, s14
	s_waitcnt lgkmcnt(2)
	v_bfe_u32 v42, v56, 16, 1
	v_lshrrev_b32_e32 v2, 16, v2
	v_add3_u32 v42, v56, v42, s14
	v_and_or_b32 v42, v42, s15, v2
	s_waitcnt lgkmcnt(1)
	v_bfe_u32 v2, v58, 16, 1
	v_add3_u32 v2, v58, v2, s14
	s_waitcnt lgkmcnt(0)
	v_bfe_u32 v43, v60, 16, 1
	v_lshrrev_b32_e32 v2, 16, v2
	v_add3_u32 v43, v60, v43, s14
	v_and_or_b32 v43, v43, s15, v2
	v_or_b32_e32 v2, s9, v31
	v_lshlrev_b32_e32 v2, 11, v2
	v_lshl_add_u64 v[62:63], v[46:47], 0, v[2:3]
	v_bfe_u32 v2, v45, 16, 1
	global_store_dwordx4 v[62:63], v[40:43], off
	v_add3_u32 v2, v45, v2, s14
	v_lshrrev_b32_e32 v2, 16, v2
	v_bfe_u32 v40, v49, 16, 1
	v_add3_u32 v40, v49, v40, s14
	v_and_or_b32 v40, v40, s15, v2
	v_bfe_u32 v2, v51, 16, 1
	v_add3_u32 v2, v51, v2, s14
	v_bfe_u32 v41, v53, 16, 1
	v_lshrrev_b32_e32 v2, 16, v2
	v_add3_u32 v41, v53, v41, s14
	v_and_or_b32 v41, v41, s15, v2
	v_bfe_u32 v2, v55, 16, 1
	v_add3_u32 v2, v55, v2, s14
	v_bfe_u32 v42, v57, 16, 1
	v_lshrrev_b32_e32 v2, 16, v2
	v_add3_u32 v42, v57, v42, s14
	v_and_or_b32 v42, v42, s15, v2
	v_bfe_u32 v2, v59, 16, 1
	v_add3_u32 v2, v59, v2, s14
	v_bfe_u32 v43, v61, 16, 1
	v_lshrrev_b32_e32 v2, 16, v2
	v_add3_u32 v43, v61, v43, s14
	v_and_or_b32 v43, v43, s15, v2
	v_or_b32_e32 v2, s9, v32
	v_lshlrev_b32_e32 v2, 11, v2
	v_lshl_add_u64 v[44:45], v[46:47], 0, v[2:3]
	global_store_dwordx4 v[44:45], v[40:43], off
	s_waitcnt lgkmcnt(0)

; __device__ __forceinline__ void tr_item(const float* W, int N, bf16* WT, int dpitch, int koff, int drow0, int k0, int n0, LAS float* scr, int lane) {
;     ...
;     for (int i = 0; i < 32; ++i) tv[i] = W[(size_t)(k0 + 2 * i + (lane >> 5)) * N + n0 + (lane & 31)];
; #pragma unroll
;     for (int i = 0; i < 32; ++i) scr[(2 * i + (lane >> 5)) * 33 + (lane & 31)] = tv[i];
; __global__ void __launch_bounds__(512, 2) fwd_mega(Args a) {
;     ...
;             if (it < 512) { const int kb = it / 32, nb = it % 32; tr_item(INF(14) + (size_t)LL * D * D, D, WSP(WS_WO2), 1024, 0, 32 * nb, 64 * kb, 32 * nb, scr, lane); continue; } it -= 512;
.LBB0_999:
	s_andn2_b64 vcc, exec, s[8:9]
	s_cbranch_vccnz .LBB0_1001
	s_and_b32 s6, s12, 0x3fc0
	s_add_i32 s8, s6, 0xffffe300
	s_and_b32 s10, s4, 0x3e0
	v_or_b32_e32 v2, s8, v200
	s_lshl_b32 s6, s10, 2
	v_or_b32_e32 v44, 2, v2
	v_mov_b32_e32 v45, v3
	v_or_b32_e32 v46, 4, v2
	v_mov_b32_e32 v47, v3
	v_or_b32_e32 v48, 6, v2
	v_mov_b32_e32 v49, v3
	v_or_b32_e32 v50, 8, v2
	v_mov_b32_e32 v51, v3
	v_or_b32_e32 v52, 10, v2
	v_mov_b32_e32 v53, v3
	v_or_b32_e32 v54, 12, v2
	v_mov_b32_e32 v55, v3
	v_lshl_add_u64 v[40:41], v[14:15], 0, s[6:7]
	v_lshlrev_b64 v[42:43], 12, v[2:3]
	v_lshlrev_b64 v[44:45], 12, v[44:45]
	v_lshlrev_b64 v[46:47], 12, v[46:47]
	v_lshlrev_b64 v[48:49], 12, v[48:49]
	v_lshlrev_b64 v[50:51], 12, v[50:51]
	v_lshlrev_b64 v[52:53], 12, v[52:53]
	v_lshlrev_b64 v[54:55], 12, v[54:55]
	v_or_b32_e32 v56, 14, v2
	v_mov_b32_e32 v57, v3
	v_lshl_add_u64 v[42:43], v[40:41], 0, v[42:43]
	v_lshl_add_u64 v[44:45], v[40:41], 0, v[44:45]
	v_lshl_add_u64 v[46:47], v[40:41], 0, v[46:47]
	v_lshl_add_u64 v[48:49], v[40:41], 0, v[48:49]
	v_lshl_add_u64 v[50:51], v[40:41], 0, v[50:51]
	v_lshl_add_u64 v[52:53], v[40:41], 0, v[52:53]
	v_lshl_add_u64 v[54:55], v[40:41], 0, v[54:55]
	v_lshlrev_b64 v[56:57], 12, v[56:57]
	v_lshl_add_u64 v[56:57], v[40:41], 0, v[56:57]
	global_load_dword v58, v[42:43], off nt
	global_load_dword v59, v[44:45], off nt
	global_load_dword v60, v[46:47], off nt
	global_load_dword v61, v[48:49], off nt
	global_load_dword v62, v[50:51], off nt
	global_load_dword v63, v[52:53], off nt
	global_load_dword v64, v[54:55], off nt
	global_load_dword v65, v[56:57], off nt
	v_or_b32_e32 v42, 16, v2
	v_mov_b32_e32 v43, v3
	v_or_b32_e32 v44, 18, v2
	v_mov_b32_e32 v45, v3
	v_or_b32_e32 v46, 20, v2
	v_mov_b32_e32 v47, v3
	v_or_b32_e32 v48, 22, v2
	v_mov_b32_e32 v49, v3
	v_or_b32_e32 v50, 24, v2
	v_mov_b32_e32 v51, v3
	v_or_b32_e32 v52, 26, v2
	v_mov_b32_e32 v53, v3
	v_or_b32_e32 v54, 28, v2
	v_mov_b32_e32 v55, v3
	v_lshlrev_b64 v[42:43], 12, v[42:43]
	v_lshlrev_b64 v[44:45], 12, v[44:45]
	v_lshlrev_b64 v[46:47], 12, v[46:47]
	v_lshlrev_b64 v[48:49], 12, v[48:49]
	v_lshlrev_b64 v[50:51], 12, v[50:51]
	v_lshlrev_b64 v[52:53], 12, v[52:53]
	v_lshlrev_b64 v[54:55], 12, v[54:55]
	v_or_b32_e32 v56, 30, v2
	v_mov_b32_e32 v57, v3
	v_lshl_add_u64 v[42:43], v[40:41], 0, v[42:43]
	v_lshl_add_u64 v[44:45], v[40:41], 0, v[44:45]
	v_lshl_add_u64 v[46:47], v[40:41], 0, v[46:47]
	v_lshl_add_u64 v[48:49], v[40:41], 0, v[48:49]
	v_lshl_add_u64 v[50:51], v[40:41], 0, v[50:51]
	v_lshl_add_u64 v[52:53], v[40:41], 0, v[52:53]
	v_lshl_add_u64 v[54:55], v[40:41], 0, v[54:55]
	v_lshlrev_b64 v[56:57], 12, v[56:57]
	v_lshl_add_u64 v[56:57], v[40:41], 0, v[56:57]
	global_load_dword v66, v[42:43], off nt
	global_load_dword v67, v[44:45], off nt
	global_load_dword v68, v[46:47], off nt
	global_load_dword v69, v[48:49], off nt
	global_load_dword v70, v[50:51], off nt
	global_load_dword v71, v[52:53], off nt
	global_load_dword v72, v[54:55], off nt
	global_load_dword v73, v[56:57], off nt
	v_or_b32_e32 v42, 32, v2
	v_mov_b32_e32 v43, v3
	v_or_b32_e32 v44, 34, v2
	v_mov_b32_e32 v45, v3
	v_or_b32_e32 v46, 36, v2
	v_mov_b32_e32 v47, v3
	v_or_b32_e32 v48, 38, v2
	v_mov_b32_e32 v49, v3
	v_or_b32_e32 v50, 40, v2
	v_mov_b32_e32 v51, v3
	v_or_b32_e32 v52, 42, v2
	v_mov_b32_e32 v53, v3
	v_or_b32_e32 v54, 44, v2
	v_mov_b32_e32 v55, v3
	v_lshlrev_b64 v[42:43], 12, v[42:43]
	v_lshlrev_b64 v[44:45], 12, v[44:45]
	v_lshlrev_b64 v[46:47], 12, v[46:47]
	v_lshlrev_b64 v[48:49], 12, v[48:49]
	v_lshlrev_b64 v[50:51], 12, v[50:51]
	v_lshlrev_b64 v[52:53], 12, v[52:53]
	v_lshlrev_b64 v[54:55], 12, v[54:55]
	v_or_b32_e32 v56, 46, v2
	v_mov_b32_e32 v57, v3
	v_lshl_add_u64 v[42:43], v[40:41], 0, v[42:43]
	v_lshl_add_u64 v[44:45], v[40:41], 0, v[44:45]
	v_lshl_add_u64 v[46:47], v[40:41], 0, v[46:47]
	v_lshl_add_u64 v[48:49], v[40:41], 0, v[48:49]
	v_lshl_add_u64 v[50:51], v[40:41], 0, v[50:51]
	v_lshl_add_u64 v[52:53], v[40:41], 0, v[52:53]
	v_lshl_add_u64 v[54:55], v[40:41], 0, v[54:55]
	v_lshlrev_b64 v[56:57], 12, v[56:57]
	v_lshl_add_u64 v[56:57], v[40:41], 0, v[56:57]
	global_load_dword v74, v[42:43], off nt
	global_load_dword v75, v[44:45], off nt
	global_load_dword v76, v[46:47], off nt
	global_load_dword v77, v[48:49], off nt
	global_load_dword v78, v[50:51], off nt
	global_load_dword v79, v[52:53], off nt
	global_load_dword v80, v[54:55], off nt
	global_load_dword v81, v[56:57], off nt
	v_or_b32_e32 v42, 48, v2
	v_mov_b32_e32 v43, v3
	v_or_b32_e32 v44, 50, v2
	v_mov_b32_e32 v45, v3
	v_or_b32_e32 v46, 52, v2
	v_mov_b32_e32 v47, v3
	v_or_b32_e32 v48, 54, v2
	v_mov_b32_e32 v49, v3
	v_or_b32_e32 v50, 56, v2
	v_mov_b32_e32 v51, v3
	v_or_b32_e32 v52, 58, v2
	v_mov_b32_e32 v53, v3
	v_or_b32_e32 v54, 60, v2
	v_mov_b32_e32 v55, v3
	v_or_b32_e32 v2, 62, v2
	v_lshlrev_b64 v[42:43], 12, v[42:43]
	v_lshlrev_b64 v[44:45], 12, v[44:45]
	v_lshlrev_b64 v[46:47], 12, v[46:47]
	v_lshlrev_b64 v[48:49], 12, v[48:49]
	v_lshlrev_b64 v[50:51], 12, v[50:51]
	v_lshlrev_b64 v[52:53], 12, v[52:53]
	v_lshlrev_b64 v[54:55], 12, v[54:55]
	v_lshlrev_b64 v[56:57], 12, v[2:3]
	v_lshl_add_u64 v[42:43], v[40:41], 0, v[42:43]
	v_lshl_add_u64 v[44:45], v[40:41], 0, v[44:45]
	v_lshl_add_u64 v[46:47], v[40:41], 0, v[46:47]
	v_lshl_add_u64 v[48:49], v[40:41], 0, v[48:49]
	v_lshl_add_u64 v[50:51], v[40:41], 0, v[50:51]
	v_lshl_add_u64 v[52:53], v[40:41], 0, v[52:53]
	v_lshl_add_u64 v[54:55], v[40:41], 0, v[54:55]
	v_lshl_add_u64 v[40:41], v[40:41], 0, v[56:57]
	global_load_dword v2, v[42:43], off nt
	s_nop 0
	global_load_dword v42, v[44:45], off nt
	global_load_dword v43, v[46:47], off nt
	s_nop 0
	global_load_dword v44, v[48:49], off nt
	global_load_dword v45, v[50:51], off nt
	global_load_dword v46, v[52:53], off nt
	global_load_dword v47, v[54:55], off nt
	s_nop 0
	global_load_dword v40, v[40:41], off nt
	s_waitcnt vmcnt(30)
; #define LAS __attribute__((address_space(3)))
; #define LDS_WAIT() asm volatile("s_waitcnt lgkmcnt(0)" ::: "memory")
; __device__ __forceinline__ unsigned pk2(float lo, float hi) { return f2bf(lo) | (f2bf(hi) << 16); }
; __device__ __forceinline__ void tr_item(const float* W, int N, bf16* WT, int dpitch, int koff, int drow0, int k0, int n0, LAS float* scr, int lane) {
;     ...
;     for (int i = 0; i < 32; ++i) scr[(2 * i + (lane >> 5)) * 33 + (lane & 31)] = tv[i];
;     LDS_WAIT(); asm volatile("" ::: "memory");
;     const int c = lane & 7;
; #pragma unroll
;     for (int j = 0; j < 4; ++j) { const int n = (lane >> 3) + 8 * j; const LAS float* s = scr + (8 * c) * 33 + n;
;         v4u o; o.x = pk2(s[0 * 33], s[1 * 33]); o.y = pk2(s[2 * 33], s[3 * 33]); o.z = pk2(s[4 * 33], s[5 * 33]); o.w = pk2(s[6 * 33], s[7 * 33]);
;         *(v4u*)(WT + (size_t)(drow0 + n) * dpitch + koff + k0 + 8 * c) = o; }
	ds_write2_b32 v28, v58, v59 offset1:66
	s_waitcnt vmcnt(28)
	ds_write2_b32 v28, v60, v61 offset0:132 offset1:198
	s_waitcnt vmcnt(26)
	ds_write2_b32 v33, v62, v63 offset0:8 offset1:74
	s_waitcnt vmcnt(24)
	ds_write2_b32 v33, v64, v65 offset0:140 offset1:206
	s_waitcnt vmcnt(22)
	ds_write2_b32 v34, v66, v67 offset0:16 offset1:82
	s_waitcnt vmcnt(20)
	ds_write2_b32 v34, v68, v69 offset0:148 offset1:214
	s_waitcnt vmcnt(18)
	ds_write2_b32 v35, v70, v71 offset0:24 offset1:90
	s_waitcnt vmcnt(16)
	ds_write2_b32 v35, v72, v73 offset0:156 offset1:222
	s_waitcnt vmcnt(14)
	ds_write2_b32 v36, v74, v75 offset0:32 offset1:98
	s_waitcnt vmcnt(12)
	ds_write2_b32 v36, v76, v77 offset0:164 offset1:230
	s_waitcnt vmcnt(10)
	ds_write2_b32 v37, v78, v79 offset0:40 offset1:106
	s_waitcnt vmcnt(8)
	ds_write2_b32 v37, v80, v81 offset0:172 offset1:238
	s_waitcnt vmcnt(6)
	ds_write2_b32 v38, v2, v42 offset0:48 offset1:114
	s_waitcnt vmcnt(4)
	ds_write2_b32 v38, v43, v44 offset0:180 offset1:246
	s_waitcnt vmcnt(2)
	ds_write2_b32 v39, v45, v46 offset0:56 offset1:122
	s_waitcnt vmcnt(0)
	ds_write2_b32 v39, v47, v40 offset0:188 offset1:254
	s_waitcnt lgkmcnt(0)
	ds_read2_b32 v[44:45], v29 offset1:8
	ds_read2_b32 v[48:49], v29 offset0:33 offset1:41
	ds_read2_b32 v[50:51], v29 offset0:66 offset1:74
	ds_read2_b32 v[52:53], v29 offset0:99 offset1:107
	ds_read2_b32 v[54:55], v29 offset0:132 offset1:140
	s_waitcnt lgkmcnt(4)
	v_bfe_u32 v2, v44, 16, 1
	v_add3_u32 v2, v44, v2, s14
	s_waitcnt lgkmcnt(3)
	v_bfe_u32 v40, v48, 16, 1
	v_lshrrev_b32_e32 v2, 16, v2
	v_add3_u32 v40, v48, v40, s14
	ds_read2_b32 v[56:57], v29 offset0:165 offset1:173
	v_and_or_b32 v40, v40, s15, v2
	s_waitcnt lgkmcnt(3)
	v_bfe_u32 v2, v50, 16, 1
	v_add3_u32 v2, v50, v2, s14
	s_waitcnt lgkmcnt(2)
	v_bfe_u32 v41, v52, 16, 1
	ds_read2_b32 v[58:59], v29 offset0:198 offset1:206
	v_lshrrev_b32_e32 v2, 16, v2
	v_add3_u32 v41, v52, v41, s14
	ds_read2_b32 v[60:61], v29 offset0:231 offset1:239
	v_and_or_b32 v41, v41, s15, v2
	s_waitcnt lgkmcnt(3)
	v_bfe_u32 v2, v54, 16, 1
	v_add3_u32 v2, v54, v2, s14
	s_waitcnt lgkmcnt(2)
	v_bfe_u32 v42, v56, 16, 1
	v_lshrrev_b32_e32 v2, 16, v2
	v_add3_u32 v42, v56, v42, s14
	v_and_or_b32 v42, v42, s15, v2
	s_waitcnt lgkmcnt(1)
	v_bfe_u32 v2, v58, 16, 1
	v_add3_u32 v2, v58, v2, s14
	s_waitcnt lgkmcnt(0)
	v_bfe_u32 v43, v60, 16, 1
	v_lshrrev_b32_e32 v2, 16, v2
	v_add3_u32 v43, v60, v43, s14
	s_mov_b32 s9, s7
	v_and_or_b32 v43, v43, s15, v2
	v_or_b32_e32 v2, s10, v201
	v_lshl_add_u64 v[46:47], s[8:9], 1, v[16:17]
	v_lshlrev_b32_e32 v2, 11, v2
	v_lshl_add_u64 v[62:63], v[46:47], 0, v[2:3]
	v_bfe_u32 v2, v45, 16, 1
	global_store_dwordx4 v[62:63], v[40:43], off
	v_add3_u32 v2, v45, v2, s14
	v_lshrrev_b32_e32 v2, 16, v2
	v_bfe_u32 v40, v49, 16, 1
	v_add3_u32 v40, v49, v40, s14
	v_and_or_b32 v40, v40, s15, v2
	v_bfe_u32 v2, v51, 16, 1
	v_add3_u32 v2, v51, v2, s14
	v_bfe_u32 v41, v53, 16, 1
	v_lshrrev_b32_e32 v2, 16, v2
	v_add3_u32 v41, v53, v41, s14
	v_and_or_b32 v41, v41, s15, v2
	v_bfe_u32 v2, v55, 16, 1
	v_add3_u32 v2, v55, v2, s14
	v_bfe_u32 v42, v57, 16, 1
	v_lshrrev_b32_e32 v2, 16, v2
	v_add3_u32 v42, v57, v42, s14
	v_and_or_b32 v42, v42, s15, v2
	v_bfe_u32 v2, v59, 16, 1
	v_add3_u32 v2, v59, v2, s14
	v_bfe_u32 v43, v61, 16, 1
	v_lshrrev_b32_e32 v2, 16, v2
	v_add3_u32 v43, v61, v43, s14
	v_and_or_b32 v43, v43, s15, v2
	v_or_b32_e32 v2, s10, v30
	v_lshlrev_b32_e32 v2, 11, v2
	ds_read2_b32 v[44:45], v29 offset0:16 offset1:24
	v_lshl_add_u64 v[48:49], v[46:47], 0, v[2:3]
	global_store_dwordx4 v[48:49], v[40:43], off
	ds_read2_b32 v[48:49], v29 offset0:49 offset1:57
	ds_read2_b32 v[50:51], v29 offset0:82 offset1:90
	ds_read2_b32 v[52:53], v29 offset0:115 offset1:123
	s_waitcnt lgkmcnt(3)
	v_bfe_u32 v2, v44, 16, 1
	v_add3_u32 v2, v44, v2, s14
	s_waitcnt lgkmcnt(2)
	v_bfe_u32 v40, v48, 16, 1
	ds_read2_b32 v[54:55], v29 offset0:148 offset1:156
	v_lshrrev_b32_e32 v2, 16, v2
	v_add3_u32 v40, v48, v40, s14
	ds_read2_b32 v[56:57], v29 offset0:181 offset1:189
	v_and_or_b32 v40, v40, s15, v2
	s_waitcnt lgkmcnt(3)
	v_bfe_u32 v2, v50, 16, 1
	v_add3_u32 v2, v50, v2, s14
	s_waitcnt lgkmcnt(2)
	v_bfe_u32 v41, v52, 16, 1
	ds_read2_b32 v[58:59], v29 offset0:214 offset1:222
	v_lshrrev_b32_e32 v2, 16, v2
	v_add3_u32 v41, v52, v41, s14
	ds_read2_b32 v[60:61], v29 offset0:247 offset1:255
	v_and_or_b32 v41, v41, s15, v2
	s_waitcnt lgkmcnt(3)
	v_bfe_u32 v2, v54, 16, 1
	v_add3_u32 v2, v54, v2, s14
	s_waitcnt lgkmcnt(2)
	v_bfe_u32 v42, v56, 16, 1
	v_lshrrev_b32_e32 v2, 16, v2
	v_add3_u32 v42, v56, v42, s14
	v_and_or_b32 v42, v42, s15, v2
	s_waitcnt lgkmcnt(1)
	v_bfe_u32 v2, v58, 16, 1
	v_add3_u32 v2, v58, v2, s14
	s_waitcnt lgkmcnt(0)
	v_bfe_u32 v43, v60, 16, 1
	v_lshrrev_b32_e32 v2, 16, v2
	v_add3_u32 v43, v60, v43, s14
	v_and_or_b32 v43, v43, s15, v2
	v_or_b32_e32 v2, s10, v31
	v_lshlrev_b32_e32 v2, 11, v2
	v_lshl_add_u64 v[62:63], v[46:47], 0, v[2:3]
	v_bfe_u32 v2, v45, 16, 1
	global_store_dwordx4 v[62:63], v[40:43], off
	v_add3_u32 v2, v45, v2, s14
	v_lshrrev_b32_e32 v2, 16, v2
	v_bfe_u32 v40, v49, 16, 1
	v_add3_u32 v40, v49, v40, s14
	v_and_or_b32 v40, v40, s15, v2
	v_bfe_u32 v2, v51, 16, 1
	v_add3_u32 v2, v51, v2, s14
	v_bfe_u32 v41, v53, 16, 1
	v_lshrrev_b32_e32 v2, 16, v2
	v_add3_u32 v41, v53, v41, s14
	v_and_or_b32 v41, v41, s15, v2
	v_bfe_u32 v2, v55, 16, 1
	v_add3_u32 v2, v55, v2, s14
	v_bfe_u32 v42, v57, 16, 1
	v_lshrrev_b32_e32 v2, 16, v2
	v_add3_u32 v42, v57, v42, s14
	v_and_or_b32 v42, v42, s15, v2
	v_bfe_u32 v2, v59, 16, 1
	v_add3_u32 v2, v59, v2, s14
	v_bfe_u32 v43, v61, 16, 1
	v_lshrrev_b32_e32 v2, 16, v2
	v_add3_u32 v43, v61, v43, s14
	v_and_or_b32 v43, v43, s15, v2
	v_or_b32_e32 v2, s10, v32
	v_lshlrev_b32_e32 v2, 11, v2
	v_lshl_add_u64 v[44:45], v[46:47], 0, v[2:3]
	global_store_dwordx4 v[44:45], v[40:43], off
	s_waitcnt lgkmcnt(0)

; __device__ __forceinline__ void tr_item(const float* W, int N, bf16* WT, int dpitch, int koff, int drow0, int k0, int n0, LAS float* scr, int lane) {
;     ...
;     for (int i = 0; i < 32; ++i) tv[i] = W[(size_t)(k0 + 2 * i + (lane >> 5)) * N + n0 + (lane & 31)];
; #pragma unroll
;     for (int i = 0; i < 32; ++i) scr[(2 * i + (lane >> 5)) * 33 + (lane & 31)] = tv[i];
; __global__ void __launch_bounds__(512, 2) fwd_mega(Args a) {
;     ...
;             if (it < 512) { const int kb = it / 32, nb = it % 32; tr_item(INF(12) + (size_t)LL * D * D, D, WSP(WS_PAB), 1024, 0, 1024 + 32 * nb, 64 * kb, 32 * nb, scr, lane); continue; } it -= 512;
.LBB0_1002:
	s_andn2_b64 vcc, exec, s[8:9]
	s_cbranch_vccnz .LBB0_1004
	s_and_b32 s6, s12, 0x1fc0
	s_add_i32 s8, s6, 0xffffe700
	s_and_b32 s9, s4, 0x3e0
	v_or_b32_e32 v2, s8, v200
	s_lshl_b32 s6, s9, 2
	v_or_b32_e32 v44, 2, v2
	v_mov_b32_e32 v45, v3
	v_or_b32_e32 v46, 4, v2
	v_mov_b32_e32 v47, v3
	v_or_b32_e32 v48, 6, v2
	v_mov_b32_e32 v49, v3
	v_or_b32_e32 v50, 8, v2
	v_mov_b32_e32 v51, v3
	v_or_b32_e32 v52, 10, v2
	v_mov_b32_e32 v53, v3
	v_or_b32_e32 v54, 12, v2
	v_mov_b32_e32 v55, v3
	v_lshl_add_u64 v[40:41], v[18:19], 0, s[6:7]
	v_lshlrev_b64 v[42:43], 12, v[2:3]
	v_lshlrev_b64 v[44:45], 12, v[44:45]
	v_lshlrev_b64 v[46:47], 12, v[46:47]
	v_lshlrev_b64 v[48:49], 12, v[48:49]
	v_lshlrev_b64 v[50:51], 12, v[50:51]
	v_lshlrev_b64 v[52:53], 12, v[52:53]
	v_lshlrev_b64 v[54:55], 12, v[54:55]
	v_or_b32_e32 v56, 14, v2
	v_mov_b32_e32 v57, v3
	v_lshl_add_u64 v[42:43], v[40:41], 0, v[42:43]
	v_lshl_add_u64 v[44:45], v[40:41], 0, v[44:45]
	v_lshl_add_u64 v[46:47], v[40:41], 0, v[46:47]
	v_lshl_add_u64 v[48:49], v[40:41], 0, v[48:49]
	v_lshl_add_u64 v[50:51], v[40:41], 0, v[50:51]
	v_lshl_add_u64 v[52:53], v[40:41], 0, v[52:53]
	v_lshl_add_u64 v[54:55], v[40:41], 0, v[54:55]
	v_lshlrev_b64 v[56:57], 12, v[56:57]
	v_lshl_add_u64 v[56:57], v[40:41], 0, v[56:57]
	global_load_dword v58, v[42:43], off nt
	global_load_dword v59, v[44:45], off nt
	global_load_dword v60, v[46:47], off nt
	global_load_dword v61, v[48:49], off nt
	global_load_dword v62, v[50:51], off nt
	global_load_dword v63, v[52:53], off nt
	global_load_dword v64, v[54:55], off nt
	global_load_dword v65, v[56:57], off nt
	v_or_b32_e32 v42, 16, v2
	v_mov_b32_e32 v43, v3
	v_or_b32_e32 v44, 18, v2
	v_mov_b32_e32 v45, v3
	v_or_b32_e32 v46, 20, v2
	v_mov_b32_e32 v47, v3
	v_or_b32_e32 v48, 22, v2
	v_mov_b32_e32 v49, v3
	v_or_b32_e32 v50, 24, v2
	v_mov_b32_e32 v51, v3
	v_or_b32_e32 v52, 26, v2
	v_mov_b32_e32 v53, v3
	v_or_b32_e32 v54, 28, v2
	v_mov_b32_e32 v55, v3
	v_lshlrev_b64 v[42:43], 12, v[42:43]
	v_lshlrev_b64 v[44:45], 12, v[44:45]
	v_lshlrev_b64 v[46:47], 12, v[46:47]
	v_lshlrev_b64 v[48:49], 12, v[48:49]
	v_lshlrev_b64 v[50:51], 12, v[50:51]
	v_lshlrev_b64 v[52:53], 12, v[52:53]
	v_lshlrev_b64 v[54:55], 12, v[54:55]
	v_or_b32_e32 v56, 30, v2
	v_mov_b32_e32 v57, v3
	v_lshl_add_u64 v[42:43], v[40:41], 0, v[42:43]
	v_lshl_add_u64 v[44:45], v[40:41], 0, v[44:45]
	v_lshl_add_u64 v[46:47], v[40:41], 0, v[46:47]
	v_lshl_add_u64 v[48:49], v[40:41], 0, v[48:49]
	v_lshl_add_u64 v[50:51], v[40:41], 0, v[50:51]
	v_lshl_add_u64 v[52:53], v[40:41], 0, v[52:53]
	v_lshl_add_u64 v[54:55], v[40:41], 0, v[54:55]
	v_lshlrev_b64 v[56:57], 12, v[56:57]
	v_lshl_add_u64 v[56:57], v[40:41], 0, v[56:57]
	global_load_dword v66, v[42:43], off nt
	global_load_dword v67, v[44:45], off nt
	global_load_dword v68, v[46:47], off nt
	global_load_dword v69, v[48:49], off nt
	global_load_dword v70, v[50:51], off nt
	global_load_dword v71, v[52:53], off nt
	global_load_dword v72, v[54:55], off nt
	global_load_dword v73, v[56:57], off nt
	v_or_b32_e32 v42, 32, v2
	v_mov_b32_e32 v43, v3
	v_or_b32_e32 v44, 34, v2
	v_mov_b32_e32 v45, v3
	v_or_b32_e32 v46, 36, v2
	v_mov_b32_e32 v47, v3
	v_or_b32_e32 v48, 38, v2
	v_mov_b32_e32 v49, v3
	v_or_b32_e32 v50, 40, v2
	v_mov_b32_e32 v51, v3
	v_or_b32_e32 v52, 42, v2
	v_mov_b32_e32 v53, v3
	v_or_b32_e32 v54, 44, v2
	v_mov_b32_e32 v55, v3
	v_lshlrev_b64 v[42:43], 12, v[42:43]
	v_lshlrev_b64 v[44:45], 12, v[44:45]
	v_lshlrev_b64 v[46:47], 12, v[46:47]
	v_lshlrev_b64 v[48:49], 12, v[48:49]
	v_lshlrev_b64 v[50:51], 12, v[50:51]
	v_lshlrev_b64 v[52:53], 12, v[52:53]
	v_lshlrev_b64 v[54:55], 12, v[54:55]
	v_or_b32_e32 v56, 46, v2
	v_mov_b32_e32 v57, v3
	v_lshl_add_u64 v[42:43], v[40:41], 0, v[42:43]
	v_lshl_add_u64 v[44:45], v[40:41], 0, v[44:45]
	v_lshl_add_u64 v[46:47], v[40:41], 0, v[46:47]
	v_lshl_add_u64 v[48:49], v[40:41], 0, v[48:49]
	v_lshl_add_u64 v[50:51], v[40:41], 0, v[50:51]
	v_lshl_add_u64 v[52:53], v[40:41], 0, v[52:53]
	v_lshl_add_u64 v[54:55], v[40:41], 0, v[54:55]
	v_lshlrev_b64 v[56:57], 12, v[56:57]
	v_lshl_add_u64 v[56:57], v[40:41], 0, v[56:57]
	global_load_dword v74, v[42:43], off nt
	global_load_dword v75, v[44:45], off nt
	global_load_dword v76, v[46:47], off nt
	global_load_dword v77, v[48:49], off nt
	global_load_dword v78, v[50:51], off nt
	global_load_dword v79, v[52:53], off nt
	global_load_dword v80, v[54:55], off nt
	global_load_dword v81, v[56:57], off nt
	v_or_b32_e32 v42, 48, v2
	v_mov_b32_e32 v43, v3
	v_or_b32_e32 v44, 50, v2
	v_mov_b32_e32 v45, v3
	v_or_b32_e32 v46, 52, v2
	v_mov_b32_e32 v47, v3
	v_or_b32_e32 v48, 54, v2
	v_mov_b32_e32 v49, v3
	v_or_b32_e32 v50, 56, v2
	v_mov_b32_e32 v51, v3
	v_or_b32_e32 v52, 58, v2
	v_mov_b32_e32 v53, v3
	v_or_b32_e32 v54, 60, v2
	v_mov_b32_e32 v55, v3
	v_or_b32_e32 v2, 62, v2
	v_lshlrev_b64 v[42:43], 12, v[42:43]
	v_lshlrev_b64 v[44:45], 12, v[44:45]
	v_lshlrev_b64 v[46:47], 12, v[46:47]
	v_lshlrev_b64 v[48:49], 12, v[48:49]
	v_lshlrev_b64 v[50:51], 12, v[50:51]
	v_lshlrev_b64 v[52:53], 12, v[52:53]
	v_lshlrev_b64 v[54:55], 12, v[54:55]
	v_lshlrev_b64 v[56:57], 12, v[2:3]
	v_lshl_add_u64 v[42:43], v[40:41], 0, v[42:43]
	v_lshl_add_u64 v[44:45], v[40:41], 0, v[44:45]
	v_lshl_add_u64 v[46:47], v[40:41], 0, v[46:47]
	v_lshl_add_u64 v[48:49], v[40:41], 0, v[48:49]
	v_lshl_add_u64 v[50:51], v[40:41], 0, v[50:51]
	v_lshl_add_u64 v[52:53], v[40:41], 0, v[52:53]
	v_lshl_add_u64 v[54:55], v[40:41], 0, v[54:55]
	v_lshl_add_u64 v[40:41], v[40:41], 0, v[56:57]
	global_load_dword v2, v[42:43], off nt
	s_nop 0
	global_load_dword v42, v[44:45], off nt
	global_load_dword v43, v[46:47], off nt
	s_nop 0
	global_load_dword v44, v[48:49], off nt
	global_load_dword v45, v[50:51], off nt
	global_load_dword v46, v[52:53], off nt
	global_load_dword v47, v[54:55], off nt
	s_nop 0
	global_load_dword v40, v[40:41], off nt
	s_waitcnt vmcnt(30)
; #define LAS __attribute__((address_space(3)))
; #define LDS_WAIT() asm volatile("s_waitcnt lgkmcnt(0)" ::: "memory")
; __device__ __forceinline__ unsigned pk2(float lo, float hi) { return f2bf(lo) | (f2bf(hi) << 16); }
; __device__ __forceinline__ void tr_item(const float* W, int N, bf16* WT, int dpitch, int koff, int drow0, int k0, int n0, LAS float* scr, int lane) {
;     ...
;     for (int i = 0; i < 32; ++i) scr[(2 * i + (lane >> 5)) * 33 + (lane & 31)] = tv[i];
;     LDS_WAIT(); asm volatile("" ::: "memory");
;     const int c = lane & 7;
; #pragma unroll
;     for (int j = 0; j < 4; ++j) { const int n = (lane >> 3) + 8 * j; const LAS float* s = scr + (8 * c) * 33 + n;
;         v4u o; o.x = pk2(s[0 * 33], s[1 * 33]); o.y = pk2(s[2 * 33], s[3 * 33]); o.z = pk2(s[4 * 33], s[5 * 33]); o.w = pk2(s[6 * 33], s[7 * 33]);
;         *(v4u*)(WT + (size_t)(drow0 + n) * dpitch + koff + k0 + 8 * c) = o; }
	ds_write2_b32 v28, v58, v59 offset1:66
	s_waitcnt vmcnt(28)
	ds_write2_b32 v28, v60, v61 offset0:132 offset1:198
	s_waitcnt vmcnt(26)
	ds_write2_b32 v33, v62, v63 offset0:8 offset1:74
	s_waitcnt vmcnt(24)
	ds_write2_b32 v33, v64, v65 offset0:140 offset1:206
	s_waitcnt vmcnt(22)
	ds_write2_b32 v34, v66, v67 offset0:16 offset1:82
	s_waitcnt vmcnt(20)
	ds_write2_b32 v34, v68, v69 offset0:148 offset1:214
	s_waitcnt vmcnt(18)
	ds_write2_b32 v35, v70, v71 offset0:24 offset1:90
	s_waitcnt vmcnt(16)
	ds_write2_b32 v35, v72, v73 offset0:156 offset1:222
	s_waitcnt vmcnt(14)
	ds_write2_b32 v36, v74, v75 offset0:32 offset1:98
	s_waitcnt vmcnt(12)
	ds_write2_b32 v36, v76, v77 offset0:164 offset1:230
	s_waitcnt vmcnt(10)
	ds_write2_b32 v37, v78, v79 offset0:40 offset1:106
	s_waitcnt vmcnt(8)
	ds_write2_b32 v37, v80, v81 offset0:172 offset1:238
	s_waitcnt vmcnt(6)
	ds_write2_b32 v38, v2, v42 offset0:48 offset1:114
	s_waitcnt vmcnt(4)
	ds_write2_b32 v38, v43, v44 offset0:180 offset1:246
	s_waitcnt vmcnt(2)
	ds_write2_b32 v39, v45, v46 offset0:56 offset1:122
	s_waitcnt vmcnt(0)
	ds_write2_b32 v39, v47, v40 offset0:188 offset1:254
	s_waitcnt lgkmcnt(0)
	ds_read2_b32 v[44:45], v29 offset1:8
	ds_read2_b32 v[48:49], v29 offset0:33 offset1:41
	ds_read2_b32 v[50:51], v29 offset0:66 offset1:74
	ds_read2_b32 v[52:53], v29 offset0:99 offset1:107
	ds_read2_b32 v[54:55], v29 offset0:132 offset1:140
	s_waitcnt lgkmcnt(4)
	v_bfe_u32 v2, v44, 16, 1
	v_add3_u32 v2, v44, v2, s14
	s_waitcnt lgkmcnt(3)
	v_bfe_u32 v40, v48, 16, 1
	v_lshrrev_b32_e32 v2, 16, v2
	v_add3_u32 v40, v48, v40, s14
	ds_read2_b32 v[56:57], v29 offset0:165 offset1:173
	v_and_or_b32 v40, v40, s15, v2
	s_waitcnt lgkmcnt(3)
	v_bfe_u32 v2, v50, 16, 1
	v_add3_u32 v2, v50, v2, s14
	s_waitcnt lgkmcnt(2)
	v_bfe_u32 v41, v52, 16, 1
	ds_read2_b32 v[58:59], v29 offset0:198 offset1:206
	v_lshrrev_b32_e32 v2, 16, v2
	v_add3_u32 v41, v52, v41, s14
	ds_read2_b32 v[60:61], v29 offset0:231 offset1:239
	v_and_or_b32 v41, v41, s15, v2
	s_waitcnt lgkmcnt(3)
	v_bfe_u32 v2, v54, 16, 1
	v_add3_u32 v2, v54, v2, s14
	s_waitcnt lgkmcnt(2)
	v_bfe_u32 v42, v56, 16, 1
	v_lshrrev_b32_e32 v2, 16, v2
	v_add3_u32 v42, v56, v42, s14
	v_and_or_b32 v42, v42, s15, v2
	s_waitcnt lgkmcnt(1)
	v_bfe_u32 v2, v58, 16, 1
	v_add3_u32 v2, v58, v2, s14
	s_waitcnt lgkmcnt(0)
	v_bfe_u32 v43, v60, 16, 1
	s_or_b32 s6, s9, 0x400
	v_lshrrev_b32_e32 v2, 16, v2
	v_add3_u32 v43, v60, v43, s14
	s_mov_b32 s9, s7
	v_and_or_b32 v43, v43, s15, v2
	v_or_b32_e32 v2, s6, v201
	v_lshl_add_u64 v[46:47], s[8:9], 1, v[20:21]
	v_lshlrev_b32_e32 v2, 11, v2
	v_lshl_add_u64 v[62:63], v[46:47], 0, v[2:3]
	v_bfe_u32 v2, v45, 16, 1
	global_store_dwordx4 v[62:63], v[40:43], off
	v_add3_u32 v2, v45, v2, s14
	v_lshrrev_b32_e32 v2, 16, v2
	v_bfe_u32 v40, v49, 16, 1
	v_add3_u32 v40, v49, v40, s14
	v_and_or_b32 v40, v40, s15, v2
	v_bfe_u32 v2, v51, 16, 1
	v_add3_u32 v2, v51, v2, s14
	v_bfe_u32 v41, v53, 16, 1
	v_lshrrev_b32_e32 v2, 16, v2
	v_add3_u32 v41, v53, v41, s14
	v_and_or_b32 v41, v41, s15, v2
	v_bfe_u32 v2, v55, 16, 1
	v_add3_u32 v2, v55, v2, s14
	v_bfe_u32 v42, v57, 16, 1
	v_lshrrev_b32_e32 v2, 16, v2
	v_add3_u32 v42, v57, v42, s14
	v_and_or_b32 v42, v42, s15, v2
	v_bfe_u32 v2, v59, 16, 1
	v_add3_u32 v2, v59, v2, s14
	v_bfe_u32 v43, v61, 16, 1
	v_lshrrev_b32_e32 v2, 16, v2
	v_add3_u32 v43, v61, v43, s14
	v_and_or_b32 v43, v43, s15, v2
	v_or_b32_e32 v2, s6, v30
	v_lshlrev_b32_e32 v2, 11, v2
	ds_read2_b32 v[44:45], v29 offset0:16 offset1:24
	v_lshl_add_u64 v[48:49], v[46:47], 0, v[2:3]
	global_store_dwordx4 v[48:49], v[40:43], off
	ds_read2_b32 v[48:49], v29 offset0:49 offset1:57
	ds_read2_b32 v[50:51], v29 offset0:82 offset1:90
	ds_read2_b32 v[52:53], v29 offset0:115 offset1:123
	s_waitcnt lgkmcnt(3)
	v_bfe_u32 v2, v44, 16, 1
	v_add3_u32 v2, v44, v2, s14
	s_waitcnt lgkmcnt(2)
	v_bfe_u32 v40, v48, 16, 1
	ds_read2_b32 v[54:55], v29 offset0:148 offset1:156
	v_lshrrev_b32_e32 v2, 16, v2
	v_add3_u32 v40, v48, v40, s14
	ds_read2_b32 v[56:57], v29 offset0:181 offset1:189
	v_and_or_b32 v40, v40, s15, v2
	s_waitcnt lgkmcnt(3)
	v_bfe_u32 v2, v50, 16, 1
	v_add3_u32 v2, v50, v2, s14
	s_waitcnt lgkmcnt(2)
	v_bfe_u32 v41, v52, 16, 1
	ds_read2_b32 v[58:59], v29 offset0:214 offset1:222
	v_lshrrev_b32_e32 v2, 16, v2
	v_add3_u32 v41, v52, v41, s14
	ds_read2_b32 v[60:61], v29 offset0:247 offset1:255
	v_and_or_b32 v41, v41, s15, v2
	s_waitcnt lgkmcnt(3)
	v_bfe_u32 v2, v54, 16, 1
	v_add3_u32 v2, v54, v2, s14
	s_waitcnt lgkmcnt(2)
	v_bfe_u32 v42, v56, 16, 1
	v_lshrrev_b32_e32 v2, 16, v2
	v_add3_u32 v42, v56, v42, s14
	v_and_or_b32 v42, v42, s15, v2
	s_waitcnt lgkmcnt(1)
	v_bfe_u32 v2, v58, 16, 1
	v_add3_u32 v2, v58, v2, s14
	s_waitcnt lgkmcnt(0)
	v_bfe_u32 v43, v60, 16, 1
	v_lshrrev_b32_e32 v2, 16, v2
	v_add3_u32 v43, v60, v43, s14
	v_and_or_b32 v43, v43, s15, v2
	v_or_b32_e32 v2, s6, v31
	v_lshlrev_b32_e32 v2, 11, v2
	v_lshl_add_u64 v[62:63], v[46:47], 0, v[2:3]
	v_bfe_u32 v2, v45, 16, 1
	global_store_dwordx4 v[62:63], v[40:43], off
	v_add3_u32 v2, v45, v2, s14
	v_lshrrev_b32_e32 v2, 16, v2
	v_bfe_u32 v40, v49, 16, 1
	v_add3_u32 v40, v49, v40, s14
	v_and_or_b32 v40, v40, s15, v2
	v_bfe_u32 v2, v51, 16, 1
	v_add3_u32 v2, v51, v2, s14
	v_bfe_u32 v41, v53, 16, 1
	v_lshrrev_b32_e32 v2, 16, v2
	v_add3_u32 v41, v53, v41, s14
	v_and_or_b32 v41, v41, s15, v2
	v_bfe_u32 v2, v55, 16, 1
	v_add3_u32 v2, v55, v2, s14
	v_bfe_u32 v42, v57, 16, 1
	v_lshrrev_b32_e32 v2, 16, v2
	v_add3_u32 v42, v57, v42, s14
	v_and_or_b32 v42, v42, s15, v2
	v_bfe_u32 v2, v59, 16, 1
	v_add3_u32 v2, v59, v2, s14
	v_bfe_u32 v43, v61, 16, 1
	v_lshrrev_b32_e32 v2, 16, v2
	v_add3_u32 v43, v61, v43, s14
	v_and_or_b32 v43, v43, s15, v2
	v_or_b32_e32 v2, s6, v32
	v_lshlrev_b32_e32 v2, 11, v2
	v_lshl_add_u64 v[44:45], v[46:47], 0, v[2:3]
	global_store_dwordx4 v[44:45], v[40:43], off
	s_waitcnt lgkmcnt(0)

; __device__ __forceinline__ void tr_item(const float* W, int N, bf16* WT, int dpitch, int koff, int drow0, int k0, int n0, LAS float* scr, int lane) {
;     ...
;     for (int i = 0; i < 32; ++i) tv[i] = W[(size_t)(k0 + 2 * i + (lane >> 5)) * N + n0 + (lane & 31)];
; #pragma unroll
;     for (int i = 0; i < 32; ++i) scr[(2 * i + (lane >> 5)) * 33 + (lane & 31)] = tv[i];
; __global__ void __launch_bounds__(512, 2) fwd_mega(Args a) {
;     ...
;             if (it < 512) { const int kb = it / 32, nb = it % 32; tr_item(INF(13) + (size_t)LL * D * D, D, WSP(WS_PAB), 1024, 0, 32 * nb, 64 * kb, 32 * nb, scr, lane); continue; } it -= 512;
.LBB0_1005:
	s_andn2_b64 vcc, exec, s[8:9]
	s_cbranch_vccnz .LBB0_1007
	s_and_b32 s6, s12, 0x1fc0
	s_add_i32 s8, s6, 0xffffeb00
	s_and_b32 s10, s4, 0x3e0
	v_or_b32_e32 v2, s8, v200
	s_lshl_b32 s6, s10, 2
	v_or_b32_e32 v44, 2, v2
	v_mov_b32_e32 v45, v3
	v_or_b32_e32 v46, 4, v2
	v_mov_b32_e32 v47, v3
	v_or_b32_e32 v48, 6, v2
	v_mov_b32_e32 v49, v3
	v_or_b32_e32 v50, 8, v2
	v_mov_b32_e32 v51, v3
	v_or_b32_e32 v52, 10, v2
	v_mov_b32_e32 v53, v3
	v_or_b32_e32 v54, 12, v2
	v_mov_b32_e32 v55, v3
	v_lshl_add_u64 v[40:41], v[22:23], 0, s[6:7]
	v_lshlrev_b64 v[42:43], 12, v[2:3]
	v_lshlrev_b64 v[44:45], 12, v[44:45]
	v_lshlrev_b64 v[46:47], 12, v[46:47]
	v_lshlrev_b64 v[48:49], 12, v[48:49]
	v_lshlrev_b64 v[50:51], 12, v[50:51]
	v_lshlrev_b64 v[52:53], 12, v[52:53]
	v_lshlrev_b64 v[54:55], 12, v[54:55]
	v_or_b32_e32 v56, 14, v2
	v_mov_b32_e32 v57, v3
	v_lshl_add_u64 v[42:43], v[40:41], 0, v[42:43]
	v_lshl_add_u64 v[44:45], v[40:41], 0, v[44:45]
	v_lshl_add_u64 v[46:47], v[40:41], 0, v[46:47]
	v_lshl_add_u64 v[48:49], v[40:41], 0, v[48:49]
	v_lshl_add_u64 v[50:51], v[40:41], 0, v[50:51]
	v_lshl_add_u64 v[52:53], v[40:41], 0, v[52:53]
	v_lshl_add_u64 v[54:55], v[40:41], 0, v[54:55]
	v_lshlrev_b64 v[56:57], 12, v[56:57]
	v_lshl_add_u64 v[56:57], v[40:41], 0, v[56:57]
	global_load_dword v58, v[42:43], off nt
	global_load_dword v59, v[44:45], off nt
	global_load_dword v60, v[46:47], off nt
	global_load_dword v61, v[48:49], off nt
	global_load_dword v62, v[50:51], off nt
	global_load_dword v63, v[52:53], off nt
	global_load_dword v64, v[54:55], off nt
	global_load_dword v65, v[56:57], off nt
	v_or_b32_e32 v42, 16, v2
	v_mov_b32_e32 v43, v3
	v_or_b32_e32 v44, 18, v2
	v_mov_b32_e32 v45, v3
	v_or_b32_e32 v46, 20, v2
	v_mov_b32_e32 v47, v3
	v_or_b32_e32 v48, 22, v2
	v_mov_b32_e32 v49, v3
	v_or_b32_e32 v50, 24, v2
	v_mov_b32_e32 v51, v3
	v_or_b32_e32 v52, 26, v2
	v_mov_b32_e32 v53, v3
	v_or_b32_e32 v54, 28, v2
	v_mov_b32_e32 v55, v3
	v_lshlrev_b64 v[42:43], 12, v[42:43]
	v_lshlrev_b64 v[44:45], 12, v[44:45]
	v_lshlrev_b64 v[46:47], 12, v[46:47]
	v_lshlrev_b64 v[48:49], 12, v[48:49]
	v_lshlrev_b64 v[50:51], 12, v[50:51]
	v_lshlrev_b64 v[52:53], 12, v[52:53]
	v_lshlrev_b64 v[54:55], 12, v[54:55]
	v_or_b32_e32 v56, 30, v2
	v_mov_b32_e32 v57, v3
	v_lshl_add_u64 v[42:43], v[40:41], 0, v[42:43]
	v_lshl_add_u64 v[44:45], v[40:41], 0, v[44:45]
	v_lshl_add_u64 v[46:47], v[40:41], 0, v[46:47]
	v_lshl_add_u64 v[48:49], v[40:41], 0, v[48:49]
	v_lshl_add_u64 v[50:51], v[40:41], 0, v[50:51]
	v_lshl_add_u64 v[52:53], v[40:41], 0, v[52:53]
	v_lshl_add_u64 v[54:55], v[40:41], 0, v[54:55]
	v_lshlrev_b64 v[56:57], 12, v[56:57]
	v_lshl_add_u64 v[56:57], v[40:41], 0, v[56:57]
	global_load_dword v66, v[42:43], off nt
	global_load_dword v67, v[44:45], off nt
	global_load_dword v68, v[46:47], off nt
	global_load_dword v69, v[48:49], off nt
	global_load_dword v70, v[50:51], off nt
	global_load_dword v71, v[52:53], off nt
	global_load_dword v72, v[54:55], off nt
	global_load_dword v73, v[56:57], off nt
	v_or_b32_e32 v42, 32, v2
	v_mov_b32_e32 v43, v3
	v_or_b32_e32 v44, 34, v2
	v_mov_b32_e32 v45, v3
	v_or_b32_e32 v46, 36, v2
	v_mov_b32_e32 v47, v3
	v_or_b32_e32 v48, 38, v2
	v_mov_b32_e32 v49, v3
	v_or_b32_e32 v50, 40, v2
	v_mov_b32_e32 v51, v3
	v_or_b32_e32 v52, 42, v2
	v_mov_b32_e32 v53, v3
	v_or_b32_e32 v54, 44, v2
	v_mov_b32_e32 v55, v3
	v_lshlrev_b64 v[42:43], 12, v[42:43]
	v_lshlrev_b64 v[44:45], 12, v[44:45]
	v_lshlrev_b64 v[46:47], 12, v[46:47]
	v_lshlrev_b64 v[48:49], 12, v[48:49]
	v_lshlrev_b64 v[50:51], 12, v[50:51]
	v_lshlrev_b64 v[52:53], 12, v[52:53]
	v_lshlrev_b64 v[54:55], 12, v[54:55]
	v_or_b32_e32 v56, 46, v2
	v_mov_b32_e32 v57, v3
	v_lshl_add_u64 v[42:43], v[40:41], 0, v[42:43]
	v_lshl_add_u64 v[44:45], v[40:41], 0, v[44:45]
	v_lshl_add_u64 v[46:47], v[40:41], 0, v[46:47]
	v_lshl_add_u64 v[48:49], v[40:41], 0, v[48:49]
	v_lshl_add_u64 v[50:51], v[40:41], 0, v[50:51]
	v_lshl_add_u64 v[52:53], v[40:41], 0, v[52:53]
	v_lshl_add_u64 v[54:55], v[40:41], 0, v[54:55]
	v_lshlrev_b64 v[56:57], 12, v[56:57]
	v_lshl_add_u64 v[56:57], v[40:41], 0, v[56:57]
	global_load_dword v74, v[42:43], off nt
	global_load_dword v75, v[44:45], off nt
	global_load_dword v76, v[46:47], off nt
	global_load_dword v77, v[48:49], off nt
	global_load_dword v78, v[50:51], off nt
	global_load_dword v79, v[52:53], off nt
	global_load_dword v80, v[54:55], off nt
	global_load_dword v81, v[56:57], off nt
	v_or_b32_e32 v42, 48, v2
	v_mov_b32_e32 v43, v3
	v_or_b32_e32 v44, 50, v2
	v_mov_b32_e32 v45, v3
	v_or_b32_e32 v46, 52, v2
	v_mov_b32_e32 v47, v3
	v_or_b32_e32 v48, 54, v2
	v_mov_b32_e32 v49, v3
	v_or_b32_e32 v50, 56, v2
	v_mov_b32_e32 v51, v3
	v_or_b32_e32 v52, 58, v2
	v_mov_b32_e32 v53, v3
	v_or_b32_e32 v54, 60, v2
	v_mov_b32_e32 v55, v3
	v_or_b32_e32 v2, 62, v2
	v_lshlrev_b64 v[42:43], 12, v[42:43]
	v_lshlrev_b64 v[44:45], 12, v[44:45]
	v_lshlrev_b64 v[46:47], 12, v[46:47]
	v_lshlrev_b64 v[48:49], 12, v[48:49]
	v_lshlrev_b64 v[50:51], 12, v[50:51]
	v_lshlrev_b64 v[52:53], 12, v[52:53]
	v_lshlrev_b64 v[54:55], 12, v[54:55]
	v_lshlrev_b64 v[56:57], 12, v[2:3]
	v_lshl_add_u64 v[42:43], v[40:41], 0, v[42:43]
	v_lshl_add_u64 v[44:45], v[40:41], 0, v[44:45]
	v_lshl_add_u64 v[46:47], v[40:41], 0, v[46:47]
	v_lshl_add_u64 v[48:49], v[40:41], 0, v[48:49]
	v_lshl_add_u64 v[50:51], v[40:41], 0, v[50:51]
	v_lshl_add_u64 v[52:53], v[40:41], 0, v[52:53]
	v_lshl_add_u64 v[54:55], v[40:41], 0, v[54:55]
	v_lshl_add_u64 v[40:41], v[40:41], 0, v[56:57]
	global_load_dword v2, v[42:43], off nt
	s_nop 0
	global_load_dword v42, v[44:45], off nt
	global_load_dword v43, v[46:47], off nt
	s_nop 0
	global_load_dword v44, v[48:49], off nt
	global_load_dword v45, v[50:51], off nt
	global_load_dword v46, v[52:53], off nt
	global_load_dword v47, v[54:55], off nt
	s_nop 0
	global_load_dword v40, v[40:41], off nt
	s_waitcnt vmcnt(30)
; #define LAS __attribute__((address_space(3)))
; #define LDS_WAIT() asm volatile("s_waitcnt lgkmcnt(0)" ::: "memory")
; __device__ __forceinline__ unsigned pk2(float lo, float hi) { return f2bf(lo) | (f2bf(hi) << 16); }
; __device__ __forceinline__ void tr_item(const float* W, int N, bf16* WT, int dpitch, int koff, int drow0, int k0, int n0, LAS float* scr, int lane) {
;     ...
;     for (int i = 0; i < 32; ++i) scr[(2 * i + (lane >> 5)) * 33 + (lane & 31)] = tv[i];
;     LDS_WAIT(); asm volatile("" ::: "memory");
;     const int c = lane & 7;
; #pragma unroll
;     for (int j = 0; j < 4; ++j) { const int n = (lane >> 3) + 8 * j; const LAS float* s = scr + (8 * c) * 33 + n;
;         v4u o; o.x = pk2(s[0 * 33], s[1 * 33]); o.y = pk2(s[2 * 33], s[3 * 33]); o.z = pk2(s[4 * 33], s[5 * 33]); o.w = pk2(s[6 * 33], s[7 * 33]);
;         *(v4u*)(WT + (size_t)(drow0 + n) * dpitch + koff + k0 + 8 * c) = o; }
	ds_write2_b32 v28, v58, v59 offset1:66
	s_waitcnt vmcnt(28)
	ds_write2_b32 v28, v60, v61 offset0:132 offset1:198
	s_waitcnt vmcnt(26)
	ds_write2_b32 v33, v62, v63 offset0:8 offset1:74
	s_waitcnt vmcnt(24)
	ds_write2_b32 v33, v64, v65 offset0:140 offset1:206
	s_waitcnt vmcnt(22)
	ds_write2_b32 v34, v66, v67 offset0:16 offset1:82
	s_waitcnt vmcnt(20)
	ds_write2_b32 v34, v68, v69 offset0:148 offset1:214
	s_waitcnt vmcnt(18)
	ds_write2_b32 v35, v70, v71 offset0:24 offset1:90
	s_waitcnt vmcnt(16)
	ds_write2_b32 v35, v72, v73 offset0:156 offset1:222
	s_waitcnt vmcnt(14)
	ds_write2_b32 v36, v74, v75 offset0:32 offset1:98
	s_waitcnt vmcnt(12)
	ds_write2_b32 v36, v76, v77 offset0:164 offset1:230
	s_waitcnt vmcnt(10)
	ds_write2_b32 v37, v78, v79 offset0:40 offset1:106
	s_waitcnt vmcnt(8)
	ds_write2_b32 v37, v80, v81 offset0:172 offset1:238
	s_waitcnt vmcnt(6)
	ds_write2_b32 v38, v2, v42 offset0:48 offset1:114
	s_waitcnt vmcnt(4)
	ds_write2_b32 v38, v43, v44 offset0:180 offset1:246
	s_waitcnt vmcnt(2)
	ds_write2_b32 v39, v45, v46 offset0:56 offset1:122
	s_waitcnt vmcnt(0)
	ds_write2_b32 v39, v47, v40 offset0:188 offset1:254
	s_waitcnt lgkmcnt(0)
	ds_read2_b32 v[44:45], v29 offset1:8
	ds_read2_b32 v[48:49], v29 offset0:33 offset1:41
	ds_read2_b32 v[50:51], v29 offset0:66 offset1:74
	ds_read2_b32 v[52:53], v29 offset0:99 offset1:107
	ds_read2_b32 v[54:55], v29 offset0:132 offset1:140
	s_waitcnt lgkmcnt(4)
	v_bfe_u32 v2, v44, 16, 1
	v_add3_u32 v2, v44, v2, s14
	s_waitcnt lgkmcnt(3)
	v_bfe_u32 v40, v48, 16, 1
	v_lshrrev_b32_e32 v2, 16, v2
	v_add3_u32 v40, v48, v40, s14
	ds_read2_b32 v[56:57], v29 offset0:165 offset1:173
	v_and_or_b32 v40, v40, s15, v2
	s_waitcnt lgkmcnt(3)
	v_bfe_u32 v2, v50, 16, 1
	v_add3_u32 v2, v50, v2, s14
	s_waitcnt lgkmcnt(2)
	v_bfe_u32 v41, v52, 16, 1
	ds_read2_b32 v[58:59], v29 offset0:198 offset1:206
	v_lshrrev_b32_e32 v2, 16, v2
	v_add3_u32 v41, v52, v41, s14
	ds_read2_b32 v[60:61], v29 offset0:231 offset1:239
	v_and_or_b32 v41, v41, s15, v2
	s_waitcnt lgkmcnt(3)
	v_bfe_u32 v2, v54, 16, 1
	v_add3_u32 v2, v54, v2, s14
	s_waitcnt lgkmcnt(2)
	v_bfe_u32 v42, v56, 16, 1
	v_lshrrev_b32_e32 v2, 16, v2
	v_add3_u32 v42, v56, v42, s14
	v_and_or_b32 v42, v42, s15, v2
	s_waitcnt lgkmcnt(1)
	v_bfe_u32 v2, v58, 16, 1
	v_add3_u32 v2, v58, v2, s14
	s_waitcnt lgkmcnt(0)
	v_bfe_u32 v43, v60, 16, 1
	v_lshrrev_b32_e32 v2, 16, v2
	v_add3_u32 v43, v60, v43, s14
	s_mov_b32 s9, s7
	v_and_or_b32 v43, v43, s15, v2
	v_or_b32_e32 v2, s10, v201
	v_lshl_add_u64 v[46:47], s[8:9], 1, v[20:21]
	v_lshlrev_b32_e32 v2, 11, v2
	v_lshl_add_u64 v[62:63], v[46:47], 0, v[2:3]
	v_bfe_u32 v2, v45, 16, 1
	global_store_dwordx4 v[62:63], v[40:43], off
	v_add3_u32 v2, v45, v2, s14
	v_lshrrev_b32_e32 v2, 16, v2
	v_bfe_u32 v40, v49, 16, 1
	v_add3_u32 v40, v49, v40, s14
	v_and_or_b32 v40, v40, s15, v2
	v_bfe_u32 v2, v51, 16, 1
	v_add3_u32 v2, v51, v2, s14
	v_bfe_u32 v41, v53, 16, 1
	v_lshrrev_b32_e32 v2, 16, v2
	v_add3_u32 v41, v53, v41, s14
	v_and_or_b32 v41, v41, s15, v2
	v_bfe_u32 v2, v55, 16, 1
	v_add3_u32 v2, v55, v2, s14
	v_bfe_u32 v42, v57, 16, 1
	v_lshrrev_b32_e32 v2, 16, v2
	v_add3_u32 v42, v57, v42, s14
	v_and_or_b32 v42, v42, s15, v2
	v_bfe_u32 v2, v59, 16, 1
	v_add3_u32 v2, v59, v2, s14
	v_bfe_u32 v43, v61, 16, 1
	v_lshrrev_b32_e32 v2, 16, v2
	v_add3_u32 v43, v61, v43, s14
	v_and_or_b32 v43, v43, s15, v2
	v_or_b32_e32 v2, s10, v30
	v_lshlrev_b32_e32 v2, 11, v2
	ds_read2_b32 v[44:45], v29 offset0:16 offset1:24
	v_lshl_add_u64 v[48:49], v[46:47], 0, v[2:3]
	global_store_dwordx4 v[48:49], v[40:43], off
	ds_read2_b32 v[48:49], v29 offset0:49 offset1:57
	ds_read2_b32 v[50:51], v29 offset0:82 offset1:90
	ds_read2_b32 v[52:53], v29 offset0:115 offset1:123
	s_waitcnt lgkmcnt(3)
	v_bfe_u32 v2, v44, 16, 1
	v_add3_u32 v2, v44, v2, s14
	s_waitcnt lgkmcnt(2)
	v_bfe_u32 v40, v48, 16, 1
	ds_read2_b32 v[54:55], v29 offset0:148 offset1:156
	v_lshrrev_b32_e32 v2, 16, v2
	v_add3_u32 v40, v48, v40, s14
	ds_read2_b32 v[56:57], v29 offset0:181 offset1:189
	v_and_or_b32 v40, v40, s15, v2
	s_waitcnt lgkmcnt(3)
	v_bfe_u32 v2, v50, 16, 1
	v_add3_u32 v2, v50, v2, s14
	s_waitcnt lgkmcnt(2)
	v_bfe_u32 v41, v52, 16, 1
	ds_read2_b32 v[58:59], v29 offset0:214 offset1:222
	v_lshrrev_b32_e32 v2, 16, v2
	v_add3_u32 v41, v52, v41, s14
	ds_read2_b32 v[60:61], v29 offset0:247 offset1:255
	v_and_or_b32 v41, v41, s15, v2
	s_waitcnt lgkmcnt(3)
	v_bfe_u32 v2, v54, 16, 1
	v_add3_u32 v2, v54, v2, s14
	s_waitcnt lgkmcnt(2)
	v_bfe_u32 v42, v56, 16, 1
	v_lshrrev_b32_e32 v2, 16, v2
	v_add3_u32 v42, v56, v42, s14
	v_and_or_b32 v42, v42, s15, v2
	s_waitcnt lgkmcnt(1)
	v_bfe_u32 v2, v58, 16, 1
	v_add3_u32 v2, v58, v2, s14
	s_waitcnt lgkmcnt(0)
	v_bfe_u32 v43, v60, 16, 1
	v_lshrrev_b32_e32 v2, 16, v2
	v_add3_u32 v43, v60, v43, s14
	v_and_or_b32 v43, v43, s15, v2
	v_or_b32_e32 v2, s10, v31
	v_lshlrev_b32_e32 v2, 11, v2
	v_lshl_add_u64 v[62:63], v[46:47], 0, v[2:3]
	v_bfe_u32 v2, v45, 16, 1
	global_store_dwordx4 v[62:63], v[40:43], off
	v_add3_u32 v2, v45, v2, s14
	v_lshrrev_b32_e32 v2, 16, v2
	v_bfe_u32 v40, v49, 16, 1
	v_add3_u32 v40, v49, v40, s14
	v_and_or_b32 v40, v40, s15, v2
	v_bfe_u32 v2, v51, 16, 1
	v_add3_u32 v2, v51, v2, s14
	v_bfe_u32 v41, v53, 16, 1
	v_lshrrev_b32_e32 v2, 16, v2
	v_add3_u32 v41, v53, v41, s14
	v_and_or_b32 v41, v41, s15, v2
	v_bfe_u32 v2, v55, 16, 1
	v_add3_u32 v2, v55, v2, s14
	v_bfe_u32 v42, v57, 16, 1
	v_lshrrev_b32_e32 v2, 16, v2
	v_add3_u32 v42, v57, v42, s14
	v_and_or_b32 v42, v42, s15, v2
	v_bfe_u32 v2, v59, 16, 1
	v_add3_u32 v2, v59, v2, s14
	v_bfe_u32 v43, v61, 16, 1
	v_lshrrev_b32_e32 v2, 16, v2
	v_add3_u32 v43, v61, v43, s14
	v_and_or_b32 v43, v43, s15, v2
	v_or_b32_e32 v2, s10, v32
	v_lshlrev_b32_e32 v2, 11, v2
	v_lshl_add_u64 v[44:45], v[46:47], 0, v[2:3]
	global_store_dwordx4 v[44:45], v[40:43], off
	s_waitcnt lgkmcnt(0)

; #define LAS __attribute__((address_space(3)))
; __device__ __forceinline__ void tr_item(const float* W, int N, bf16* WT, int dpitch, int koff, int drow0, int k0, int n0, LAS float* scr, int lane) {
;     float tv[32];
; #pragma unroll
;     for (int i = 0; i < 32; ++i) tv[i] = W[(size_t)(k0 + 2 * i + (lane >> 5)) * N + n0 + (lane & 31)];
; #pragma unroll
;     for (int i = 0; i < 32; ++i) scr[(2 * i + (lane >> 5)) * 33 + (lane & 31)] = tv[i];
; __global__ void __launch_bounds__(512, 2) fwd_mega(Args a) {
;     ...
;             if (it < 2688) { const int kb = it / 168, nb = it % 168; tr_item(INF(6) + (size_t)LL * D * INC, INC, WSP(WS_WIN), 1024, 0, 32 * nb, 64 * kb, 32 * nb, scr, lane); continue; } it -= 2688;
.LBB0_1008:
	s_andn2_b64 vcc, exec, s[8:9]
	s_cbranch_vccnz .LBB0_985
	s_mul_hi_i32 s6, s53, 0x30c30c31
	s_lshr_b32 s8, s6, 31
	s_ashr_i32 s6, s6, 5
	s_add_i32 s6, s6, s8
	s_mul_i32 s8, s6, 0xffffeb00
	s_add_i32 s8, s4, s8
	s_lshl_b32 s10, s6, 6
	v_or_b32_e32 v2, s10, v200
	s_ashr_i32 s9, s8, 31
	v_lshl_add_u64 v[40:41], s[8:9], 2, v[24:25]
	v_or_b32_e32 v44, 2, v2
	v_or_b32_e32 v46, 4, v2
	v_or_b32_e32 v48, 6, v2
	v_or_b32_e32 v50, 8, v2
	v_or_b32_e32 v52, 10, v2
	v_or_b32_e32 v54, 12, v2
	v_or_b32_e32 v56, 14, v2
	v_mad_i64_i32 v[42:43], s[54:55], v2, s52, v[40:41]
	v_mad_i64_i32 v[44:45], s[54:55], v44, s52, v[40:41]
	v_mad_i64_i32 v[46:47], s[54:55], v46, s52, v[40:41]
	v_mad_i64_i32 v[48:49], s[54:55], v48, s52, v[40:41]
	v_mad_i64_i32 v[50:51], s[54:55], v50, s52, v[40:41]
	v_mad_i64_i32 v[52:53], s[54:55], v52, s52, v[40:41]
	v_mad_i64_i32 v[54:55], s[54:55], v54, s52, v[40:41]
	v_mad_i64_i32 v[56:57], s[54:55], v56, s52, v[40:41]
	global_load_dword v58, v[42:43], off nt
	global_load_dword v59, v[44:45], off nt
	global_load_dword v60, v[46:47], off nt
	global_load_dword v61, v[48:49], off nt
	global_load_dword v62, v[50:51], off nt
	global_load_dword v63, v[52:53], off nt
	global_load_dword v64, v[54:55], off nt
	global_load_dword v65, v[56:57], off nt
	v_or_b32_e32 v42, 16, v2
	v_or_b32_e32 v44, 18, v2
	v_or_b32_e32 v46, 20, v2
	v_or_b32_e32 v48, 22, v2
	v_or_b32_e32 v50, 24, v2
	v_or_b32_e32 v52, 26, v2
	v_or_b32_e32 v54, 28, v2
	v_or_b32_e32 v56, 30, v2
	v_mad_i64_i32 v[42:43], s[54:55], v42, s52, v[40:41]
	v_mad_i64_i32 v[44:45], s[54:55], v44, s52, v[40:41]
	v_mad_i64_i32 v[46:47], s[54:55], v46, s52, v[40:41]
	v_mad_i64_i32 v[48:49], s[54:55], v48, s52, v[40:41]
	v_mad_i64_i32 v[50:51], s[54:55], v50, s52, v[40:41]
	v_mad_i64_i32 v[52:53], s[54:55], v52, s52, v[40:41]
	v_mad_i64_i32 v[54:55], s[54:55], v54, s52, v[40:41]
	v_mad_i64_i32 v[56:57], s[54:55], v56, s52, v[40:41]
	global_load_dword v66, v[42:43], off nt
	global_load_dword v67, v[44:45], off nt
	global_load_dword v68, v[46:47], off nt
	global_load_dword v69, v[48:49], off nt
	global_load_dword v70, v[50:51], off nt
	global_load_dword v71, v[52:53], off nt
	global_load_dword v72, v[54:55], off nt
	global_load_dword v73, v[56:57], off nt
	v_or_b32_e32 v42, 32, v2
	v_or_b32_e32 v44, 34, v2
	v_or_b32_e32 v46, 36, v2
	v_or_b32_e32 v48, 38, v2
	v_or_b32_e32 v50, 40, v2
	v_or_b32_e32 v52, 42, v2
	v_or_b32_e32 v54, 44, v2
	v_or_b32_e32 v56, 46, v2
	v_mad_i64_i32 v[42:43], s[54:55], v42, s52, v[40:41]
	v_mad_i64_i32 v[44:45], s[54:55], v44, s52, v[40:41]
	v_mad_i64_i32 v[46:47], s[54:55], v46, s52, v[40:41]
	v_mad_i64_i32 v[48:49], s[54:55], v48, s52, v[40:41]
	v_mad_i64_i32 v[50:51], s[54:55], v50, s52, v[40:41]
	v_mad_i64_i32 v[52:53], s[54:55], v52, s52, v[40:41]
	v_mad_i64_i32 v[54:55], s[54:55], v54, s52, v[40:41]
	v_mad_i64_i32 v[56:57], s[54:55], v56, s52, v[40:41]
	global_load_dword v74, v[42:43], off nt
	global_load_dword v75, v[44:45], off nt
	global_load_dword v76, v[46:47], off nt
	global_load_dword v77, v[48:49], off nt
	global_load_dword v78, v[50:51], off nt
	global_load_dword v79, v[52:53], off nt
	global_load_dword v80, v[54:55], off nt
	s_nop 0
	global_load_dword v56, v[56:57], off nt
	v_or_b32_e32 v42, 48, v2
	v_or_b32_e32 v44, 50, v2
	v_or_b32_e32 v46, 52, v2
	v_or_b32_e32 v48, 54, v2
	v_or_b32_e32 v50, 56, v2
	v_or_b32_e32 v52, 58, v2
	v_or_b32_e32 v54, 60, v2
	v_or_b32_e32 v2, 62, v2
	v_mad_i64_i32 v[42:43], s[54:55], v42, s52, v[40:41]
	v_mad_i64_i32 v[44:45], s[54:55], v44, s52, v[40:41]
	v_mad_i64_i32 v[46:47], s[54:55], v46, s52, v[40:41]
	v_mad_i64_i32 v[48:49], s[54:55], v48, s52, v[40:41]
	v_mad_i64_i32 v[50:51], s[54:55], v50, s52, v[40:41]
	v_mad_i64_i32 v[52:53], s[54:55], v52, s52, v[40:41]
	v_mad_i64_i32 v[54:55], s[54:55], v54, s52, v[40:41]
	v_mad_i64_i32 v[40:41], s[54:55], v2, s52, v[40:41]
	global_load_dword v2, v[42:43], off nt
	s_nop 0
	global_load_dword v42, v[44:45], off nt
	global_load_dword v43, v[46:47], off nt
	s_nop 0
	global_load_dword v44, v[48:49], off nt
	global_load_dword v45, v[50:51], off nt
	global_load_dword v46, v[52:53], off nt
	global_load_dword v47, v[54:55], off nt
	s_nop 0
	global_load_dword v40, v[40:41], off nt
	s_waitcnt vmcnt(30)
	ds_write2_b32 v28, v58, v59 offset1:66
	s_waitcnt vmcnt(28)
	ds_write2_b32 v28, v60, v61 offset0:132 offset1:198
	s_waitcnt vmcnt(26)
	ds_write2_b32 v33, v62, v63 offset0:8 offset1:74
	s_waitcnt vmcnt(24)
	ds_write2_b32 v33, v64, v65 offset0:140 offset1:206
	s_waitcnt vmcnt(22)
	ds_write2_b32 v34, v66, v67 offset0:16 offset1:82
	s_waitcnt vmcnt(20)
	ds_write2_b32 v34, v68, v69 offset0:148 offset1:214
	s_waitcnt vmcnt(18)
	ds_write2_b32 v35, v70, v71 offset0:24 offset1:90
	s_waitcnt vmcnt(16)
	ds_write2_b32 v35, v72, v73 offset0:156 offset1:222
	s_waitcnt vmcnt(14)
	ds_write2_b32 v36, v74, v75 offset0:32 offset1:98
	s_waitcnt vmcnt(12)
	ds_write2_b32 v36, v76, v77 offset0:164 offset1:230
	s_waitcnt vmcnt(10)
	ds_write2_b32 v37, v78, v79 offset0:40 offset1:106
	s_waitcnt vmcnt(8)
	ds_write2_b32 v37, v80, v56 offset0:172 offset1:238
	s_waitcnt vmcnt(6)
; #define LAS __attribute__((address_space(3)))
; #define LDS_WAIT() asm volatile("s_waitcnt lgkmcnt(0)" ::: "memory")
; __device__ __forceinline__ unsigned pk2(float lo, float hi) { return f2bf(lo) | (f2bf(hi) << 16); }
; __device__ __forceinline__ void tr_item(const float* W, int N, bf16* WT, int dpitch, int koff, int drow0, int k0, int n0, LAS float* scr, int lane) {
;     ...
;     for (int i = 0; i < 32; ++i) scr[(2 * i + (lane >> 5)) * 33 + (lane & 31)] = tv[i];
;     LDS_WAIT(); asm volatile("" ::: "memory");
;     const int c = lane & 7;
; #pragma unroll
;     for (int j = 0; j < 4; ++j) { const int n = (lane >> 3) + 8 * j; const LAS float* s = scr + (8 * c) * 33 + n;
;         v4u o; o.x = pk2(s[0 * 33], s[1 * 33]); o.y = pk2(s[2 * 33], s[3 * 33]); o.z = pk2(s[4 * 33], s[5 * 33]); o.w = pk2(s[6 * 33], s[7 * 33]);
;         *(v4u*)(WT + (size_t)(drow0 + n) * dpitch + koff + k0 + 8 * c) = o; }
;     LDS_WAIT(); asm volatile("" ::: "memory");
	ds_write2_b32 v38, v2, v42 offset0:48 offset1:114
	s_waitcnt vmcnt(4)
	ds_write2_b32 v38, v43, v44 offset0:180 offset1:246
	s_waitcnt vmcnt(2)
	ds_write2_b32 v39, v45, v46 offset0:56 offset1:122
	s_waitcnt vmcnt(0)
	ds_write2_b32 v39, v47, v40 offset0:188 offset1:254
	s_waitcnt lgkmcnt(0)
	ds_read2_b32 v[44:45], v29 offset1:8
	ds_read2_b32 v[48:49], v29 offset0:33 offset1:41
	ds_read2_b32 v[50:51], v29 offset0:66 offset1:74
	ds_read2_b32 v[52:53], v29 offset0:99 offset1:107
	ds_read2_b32 v[54:55], v29 offset0:132 offset1:140
	s_waitcnt lgkmcnt(4)
	v_bfe_u32 v2, v44, 16, 1
	v_add3_u32 v2, v44, v2, s14
	s_waitcnt lgkmcnt(3)
	v_bfe_u32 v40, v48, 16, 1
	v_lshrrev_b32_e32 v2, 16, v2
	v_add3_u32 v40, v48, v40, s14
	ds_read2_b32 v[56:57], v29 offset0:165 offset1:173
	v_and_or_b32 v40, v40, s15, v2
	s_waitcnt lgkmcnt(3)
	v_bfe_u32 v2, v50, 16, 1
	v_add3_u32 v2, v50, v2, s14
	s_waitcnt lgkmcnt(2)
	v_bfe_u32 v41, v52, 16, 1
	ds_read2_b32 v[58:59], v29 offset0:198 offset1:206
	v_lshrrev_b32_e32 v2, 16, v2
	v_add3_u32 v41, v52, v41, s14
	ds_read2_b32 v[60:61], v29 offset0:231 offset1:239
	v_and_or_b32 v41, v41, s15, v2
	s_waitcnt lgkmcnt(3)
	v_bfe_u32 v2, v54, 16, 1
	v_add3_u32 v2, v54, v2, s14
	s_waitcnt lgkmcnt(2)
	v_bfe_u32 v42, v56, 16, 1
	v_lshrrev_b32_e32 v2, 16, v2
	v_add3_u32 v42, v56, v42, s14
	v_and_or_b32 v42, v42, s15, v2
	s_waitcnt lgkmcnt(1)
	v_bfe_u32 v2, v58, 16, 1
	v_add_u32_e32 v62, s8, v201
	s_ashr_i32 s11, s10, 31
	v_add3_u32 v2, v58, v2, s14
	s_waitcnt lgkmcnt(0)
	v_bfe_u32 v43, v60, 16, 1
	v_ashrrev_i32_e32 v63, 31, v62
	v_lshl_add_u64 v[46:47], s[10:11], 1, v[26:27]
	v_lshrrev_b32_e32 v2, 16, v2
	v_add3_u32 v43, v60, v43, s14
	v_lshlrev_b64 v[64:65], 11, v[62:63]
	v_and_or_b32 v43, v43, s15, v2
	v_lshl_add_u64 v[64:65], v[46:47], 0, v[64:65]
	v_bfe_u32 v2, v45, 16, 1
	global_store_dwordx4 v[64:65], v[40:43], off
	v_add3_u32 v2, v45, v2, s14
	v_lshrrev_b32_e32 v2, 16, v2
	v_bfe_u32 v40, v49, 16, 1
	v_add3_u32 v40, v49, v40, s14
	v_and_or_b32 v40, v40, s15, v2
	v_bfe_u32 v2, v51, 16, 1
	v_add3_u32 v2, v51, v2, s14
	v_bfe_u32 v41, v53, 16, 1
	v_lshrrev_b32_e32 v2, 16, v2
	v_add3_u32 v41, v53, v41, s14
	v_and_or_b32 v41, v41, s15, v2
	v_bfe_u32 v2, v55, 16, 1
	v_add3_u32 v2, v55, v2, s14
	v_bfe_u32 v42, v57, 16, 1
	v_lshrrev_b32_e32 v2, 16, v2
	v_add3_u32 v42, v57, v42, s14
	v_and_or_b32 v42, v42, s15, v2
	v_bfe_u32 v2, v59, 16, 1
	v_add_u32_e32 v44, 8, v62
	v_add3_u32 v2, v59, v2, s14
	v_bfe_u32 v43, v61, 16, 1
	v_ashrrev_i32_e32 v45, 31, v44
	v_lshrrev_b32_e32 v2, 16, v2
	v_add3_u32 v43, v61, v43, s14
	v_lshlrev_b64 v[44:45], 11, v[44:45]
	v_and_or_b32 v43, v43, s15, v2
	ds_read2_b32 v[48:49], v29 offset0:16 offset1:24
	v_lshl_add_u64 v[44:45], v[46:47], 0, v[44:45]
	global_store_dwordx4 v[44:45], v[40:43], off
	ds_read2_b32 v[44:45], v29 offset0:49 offset1:57
	ds_read2_b32 v[50:51], v29 offset0:82 offset1:90
	ds_read2_b32 v[52:53], v29 offset0:115 offset1:123
	s_waitcnt lgkmcnt(3)
	v_bfe_u32 v2, v48, 16, 1
	v_add3_u32 v2, v48, v2, s14
	s_waitcnt lgkmcnt(2)
	v_bfe_u32 v40, v44, 16, 1
	ds_read2_b32 v[54:55], v29 offset0:148 offset1:156
	v_lshrrev_b32_e32 v2, 16, v2
	v_add3_u32 v40, v44, v40, s14
	ds_read2_b32 v[56:57], v29 offset0:181 offset1:189
	v_and_or_b32 v40, v40, s15, v2
	s_waitcnt lgkmcnt(3)
	v_bfe_u32 v2, v50, 16, 1
	v_add3_u32 v2, v50, v2, s14
	s_waitcnt lgkmcnt(2)
	v_bfe_u32 v41, v52, 16, 1
	ds_read2_b32 v[58:59], v29 offset0:214 offset1:222
	v_lshrrev_b32_e32 v2, 16, v2
	v_add3_u32 v41, v52, v41, s14
	ds_read2_b32 v[60:61], v29 offset0:247 offset1:255
	v_and_or_b32 v41, v41, s15, v2
	s_waitcnt lgkmcnt(3)
	v_bfe_u32 v2, v54, 16, 1
	v_add3_u32 v2, v54, v2, s14
	s_waitcnt lgkmcnt(2)
	v_bfe_u32 v42, v56, 16, 1
	v_lshrrev_b32_e32 v2, 16, v2
	v_add3_u32 v42, v56, v42, s14
	v_and_or_b32 v42, v42, s15, v2
	s_waitcnt lgkmcnt(1)
	v_bfe_u32 v2, v58, 16, 1
	v_add_u32_e32 v64, 16, v62
	v_add3_u32 v2, v58, v2, s14
	s_waitcnt lgkmcnt(0)
	v_bfe_u32 v43, v60, 16, 1
	v_ashrrev_i32_e32 v65, 31, v64
	v_lshrrev_b32_e32 v2, 16, v2
	v_add3_u32 v43, v60, v43, s14
	v_lshlrev_b64 v[64:65], 11, v[64:65]
	v_and_or_b32 v43, v43, s15, v2
	v_lshl_add_u64 v[64:65], v[46:47], 0, v[64:65]
	v_bfe_u32 v2, v49, 16, 1
	global_store_dwordx4 v[64:65], v[40:43], off
	v_add3_u32 v2, v49, v2, s14
	v_lshrrev_b32_e32 v2, 16, v2
	v_bfe_u32 v40, v45, 16, 1
	v_add3_u32 v40, v45, v40, s14
	v_and_or_b32 v40, v40, s15, v2
	v_bfe_u32 v2, v51, 16, 1
	v_add3_u32 v2, v51, v2, s14
	v_bfe_u32 v41, v53, 16, 1
	v_lshrrev_b32_e32 v2, 16, v2
	v_add3_u32 v41, v53, v41, s14
	v_and_or_b32 v41, v41, s15, v2
	v_bfe_u32 v2, v55, 16, 1
	v_add3_u32 v2, v55, v2, s14
	v_bfe_u32 v42, v57, 16, 1
	v_lshrrev_b32_e32 v2, 16, v2
	v_add3_u32 v42, v57, v42, s14
	v_and_or_b32 v42, v42, s15, v2
	v_bfe_u32 v2, v59, 16, 1
	v_add_u32_e32 v44, 24, v62
	v_add3_u32 v2, v59, v2, s14
	v_bfe_u32 v43, v61, 16, 1
	v_ashrrev_i32_e32 v45, 31, v44
	v_lshrrev_b32_e32 v2, 16, v2
	v_add3_u32 v43, v61, v43, s14
	v_lshlrev_b64 v[44:45], 11, v[44:45]
	v_and_or_b32 v43, v43, s15, v2
	v_lshl_add_u64 v[44:45], v[46:47], 0, v[44:45]
	global_store_dwordx4 v[44:45], v[40:43], off
	s_waitcnt lgkmcnt(0)
	s_branch .LBB0_985

; __device__ __forceinline__ unsigned cvt_pk_bf16(float lo, float hi) { unsigned r; asm volatile("v_cvt_pk_bf16_f32 %0, %1, %2" : "=v"(r) : "v"(lo), "v"(hi)); return r; }
; __device__ __forceinline__ float bf_lo(unsigned w) { return __uint_as_float(w << 16); }
; __device__ __forceinline__ float bf_hi(unsigned w) { return __uint_as_float(w & 0xffff0000u); }
; #define LAS __attribute__((address_space(3)))
; __device__ __forceinline__ void sgu_unit(LAS unsigned char* lds, bf16* U, const bf16* VS, const float* SGS, const float* lnw, const float* lnb, const v4u* WF, const float* bsl, int unit, int tid) {
;     ...
;         const int c8 = lane & 7, rp = lane >> 3, col = colbase + 8 * c8;
;         v4u sl[8][2];
; #pragma unroll
;         for (int i = 0; i < 8; ++i) { const int s0 = 2 * (rp + 8 * i); sl[i][0] = *(const v4u*)(VS + (size_t)(r0 + s0) * 1024 + col); sl[i][1] = *(const v4u*)(VS + (size_t)(r0 + s0 + 1) * 1024 + col); }
;         const f32x4 lw0 = *(const f32x4*)(lnw + col), lw1 = *(const f32x4*)(lnw + col + 4), lb0 = *(const f32x4*)(lnb + col), lb1 = *(const f32x4*)(lnb + col + 4);
;         const float lw[8] = {lw0.x, lw0.y, lw0.z, lw0.w, lw1.x, lw1.y, lw1.z, lw1.w}, lb[8] = {lb0.x, lb0.y, lb0.z, lb0.w, lb1.x, lb1.y, lb1.z, lb1.w};
;         __syncthreads();
;         LAS unsigned char* wbase = vt + c8 * SGU_VP + rp * 4;
; #pragma unroll
;         for (int i = 0; i < 8; ++i) {
;             const f32x4 st4 = *(const LAS f32x4*)(stat + 4 * (rp + 8 * i));
;             const v4u w0 = sl[i][0], w1 = sl[i][1];
;             const unsigned A0[4] = {w0.x, w0.y, w0.z, w0.w}, A1[4] = {w1.x, w1.y, w1.z, w1.w};
; #pragma unroll
;             for (int e = 0; e < 8; ++e) { typedef float f32x2p __attribute__((ext_vector_type(2)));
;                 f32x2p v; v.x = (e & 1) ? bf_hi(A0[e >> 1]) : bf_lo(A0[e >> 1]); v.y = (e & 1) ? bf_hi(A1[e >> 1]) : bf_lo(A1[e >> 1]);
;                 const f32x2p mn = {st4.x, st4.z}, rs = {st4.y, st4.w};
;                 const f32x2p o = ((v - mn) * rs) * lw[e] + lb[e];
;                 *(LAS unsigned*)(wbase + e * 8 * SGU_VP + i * 32) = cvt_pk_bf16(o.x, o.y); }
;         }
.LBB0_1401:
	s_or_b64 exec, exec, s[16:17]
	v_mov_b32_e32 v122, v214
	v_mov_b32_e32 v123, v215
	v_mov_b32_e32 v124, v216
	v_mov_b32_e32 v125, v217
	v_mov_b32_e32 v126, v218
	v_mov_b32_e32 v127, v219
	v_mov_b32_e32 v128, v220
	v_mov_b32_e32 v129, v221
	v_mov_b32_e32 v114, v222
	v_mov_b32_e32 v115, v223
	v_mov_b32_e32 v116, v224
	v_mov_b32_e32 v117, v225
	v_mov_b32_e32 v118, v226
	v_mov_b32_e32 v119, v227
	v_mov_b32_e32 v120, v228
	v_mov_b32_e32 v121, v229
	v_mov_b32_e32 v106, v230
	v_mov_b32_e32 v107, v231
	v_mov_b32_e32 v108, v232
	v_mov_b32_e32 v109, v233
	v_mov_b32_e32 v110, v234
	v_mov_b32_e32 v111, v235
	v_mov_b32_e32 v112, v236
	v_mov_b32_e32 v113, v237
	v_or_b32_e32 v158, v82, v168
	v_or_b32_e32 v82, v158, v170
	v_lshl_or_b32 v84, s18, 11, v180
	v_mov_b32_e32 v85, v147
	v_ashrrev_i32_e32 v83, 31, v82
	v_lshl_add_u64 v[84:85], s[38:39], 0, v[84:85]
	v_lshl_add_u64 v[90:91], v[82:83], 1, v[84:85]
	v_lshlrev_b64 v[82:83], 2, v[82:83]
	v_lshl_add_u64 v[84:85], s[30:31], 0, v[82:83]
	v_lshl_add_u64 v[86:87], s[40:41], 0, v[82:83]
	global_load_dwordx4 v[98:101], v[86:87], off
	global_load_dwordx4 v[102:105], v[84:85], off
	s_nop 0
	global_load_dwordx4 v[82:85], v[84:85], off offset:16
	s_nop 0
	global_load_dwordx4 v[86:89], v[86:87], off offset:16
	v_add_co_u32_e32 v92, vcc, 0x8000, v90
	s_mov_b64 s[16:17], 0
	s_nop 0
	v_addc_co_u32_e32 v93, vcc, 0, v91, vcc
	v_add_co_u32_e32 v94, vcc, 0x10000, v90
	s_waitcnt vmcnt(7)
	v_and_b32_e32 v220, 0xffff0000, v198
	v_addc_co_u32_e32 v95, vcc, 0, v91, vcc
	v_add_co_u32_e32 v92, vcc, 0x18000, v90
	s_waitcnt vmcnt(8)
	v_and_b32_e32 v221, 0xffff0000, v202
	v_addc_co_u32_e32 v93, vcc, 0, v91, vcc
	v_add_co_u32_e32 v94, vcc, 0x20000, v90
	v_addc_co_u32_e32 v95, vcc, 0, v91, vcc
	v_add_co_u32_e32 v92, vcc, 0x28000, v90
	v_addc_co_u32_e32 v93, vcc, 0, v91, vcc
	v_add_co_u32_e32 v94, vcc, 0x30000, v90
	v_addc_co_u32_e32 v95, vcc, 0, v91, vcc
	v_add_co_u32_e32 v96, vcc, 0x38000, v90
	v_addc_co_u32_e32 v97, vcc, 0, v91, vcc
	v_mov_b32_e32 v90, v248
	v_mov_b32_e32 v91, v249
	v_mov_b32_e32 v92, v250
	v_mov_b32_e32 v93, v251
	s_nop 0
	v_mov_b32_e32 v94, v252
	v_mov_b32_e32 v95, v253
	v_mov_b32_e32 v96, v254
	v_mov_b32_e32 v97, v255
	s_waitcnt lgkmcnt(0)
	s_barrier
	ds_read_b128 v[214:217], v181
	v_lshlrev_b32_e32 v222, 16, v199
	v_lshlrev_b32_e32 v223, 16, v203
	s_waitcnt vmcnt(2)
	v_mov_b32_e32 v160, v105
	v_mov_b32_e32 v162, v101
	s_waitcnt lgkmcnt(0)
	v_mov_b32_e32 v218, v214
	v_mov_b32_e32 v219, v216
	v_mov_b32_e32 v216, v215
	v_lshlrev_b32_e32 v214, 16, v198
	v_lshlrev_b32_e32 v215, 16, v202
	v_pk_add_f32 v[214:215], v[214:215], v[218:219] neg_lo:[0,1] neg_hi:[0,1]
	v_and_b32_e32 v198, 0xffff0000, v199
	v_and_b32_e32 v199, 0xffff0000, v203
	v_pk_add_f32 v[220:221], v[220:221], v[218:219] neg_lo:[0,1] neg_hi:[0,1]
	v_pk_mul_f32 v[214:215], v[216:217], v[214:215]
	v_pk_add_f32 v[198:199], v[198:199], v[218:219] neg_lo:[0,1] neg_hi:[0,1]
	v_pk_add_f32 v[222:223], v[222:223], v[218:219] neg_lo:[0,1] neg_hi:[0,1]
	v_pk_mul_f32 v[220:221], v[216:217], v[220:221]
	v_pk_fma_f32 v[214:215], v[102:103], v[214:215], v[98:99] op_sel_hi:[0,1,0]
	v_cvt_pk_bf16_f32 v159, v214, v215
	v_pk_mul_f32 v[198:199], v[216:217], v[198:199]
	v_pk_mul_f32 v[222:223], v[216:217], v[222:223]
	v_pk_fma_f32 v[220:221], v[102:103], v[220:221], v[98:99] op_sel:[1,0,1]
	ds_write_b32 v177, v159 offset:1024
	v_cvt_pk_bf16_f32 v159, v220, v221
	v_pk_fma_f32 v[198:199], v[160:161], v[198:199], v[162:163] op_sel_hi:[0,1,0]
	v_pk_fma_f32 v[222:223], v[104:105], v[222:223], v[100:101] op_sel_hi:[0,1,0]
	ds_write_b32 v177, v159 offset:3200
	v_cvt_pk_bf16_f32 v159, v222, v223
	ds_write_b32 v177, v159 offset:5376
	v_cvt_pk_bf16_f32 v101, v198, v199
	v_lshlrev_b32_e32 v198, 16, v200
	v_lshlrev_b32_e32 v199, 16, v204
	v_pk_add_f32 v[198:199], v[198:199], v[218:219] neg_lo:[0,1] neg_hi:[0,1]
	ds_write_b32 v177, v101 offset:7552
	v_pk_mul_f32 v[198:199], v[216:217], v[198:199]
	s_waitcnt vmcnt(1)
	v_mov_b32_e32 v164, v85
	s_waitcnt vmcnt(0)
	v_pk_fma_f32 v[198:199], v[82:83], v[198:199], v[86:87] op_sel_hi:[0,1,0]
	v_cvt_pk_bf16_f32 v101, v198, v199
	v_and_b32_e32 v198, 0xffff0000, v200
	v_and_b32_e32 v199, 0xffff0000, v204
	v_pk_add_f32 v[198:199], v[198:199], v[218:219] neg_lo:[0,1] neg_hi:[0,1]
	ds_write_b32 v177, v101 offset:9728
	v_pk_mul_f32 v[198:199], v[216:217], v[198:199]
	v_mov_b32_e32 v166, v89
	v_pk_fma_f32 v[198:199], v[82:83], v[198:199], v[86:87] op_sel:[1,0,1]
	v_ashrrev_i32_e32 v159, 31, v158
	v_cvt_pk_bf16_f32 v101, v198, v199
	v_lshlrev_b32_e32 v198, 16, v201
	v_lshlrev_b32_e32 v199, 16, v205
	v_pk_add_f32 v[198:199], v[198:199], v[218:219] neg_lo:[0,1] neg_hi:[0,1]
	ds_write_b32 v177, v101 offset:11904
	v_pk_mul_f32 v[198:199], v[216:217], v[198:199]
	s_nop 0
	v_pk_fma_f32 v[198:199], v[84:85], v[198:199], v[88:89] op_sel_hi:[0,1,0]
	v_cvt_pk_bf16_f32 v101, v198, v199
	v_and_b32_e32 v198, 0xffff0000, v201
	v_and_b32_e32 v199, 0xffff0000, v205
	v_pk_add_f32 v[198:199], v[198:199], v[218:219] neg_lo:[0,1] neg_hi:[0,1]
	ds_write_b32 v177, v101 offset:14080
	v_pk_mul_f32 v[198:199], v[216:217], v[198:199]
	s_nop 0
	v_pk_fma_f32 v[198:199], v[164:165], v[198:199], v[166:167] op_sel_hi:[0,1,0]
	v_cvt_pk_bf16_f32 v85, v198, v199
	ds_write_b32 v177, v85 offset:16256
	ds_read_b128 v[198:201], v181 offset:128
	s_waitcnt lgkmcnt(0)
	v_mov_b32_e32 v202, v198
	v_mov_b32_e32 v203, v200
	v_mov_b32_e32 v200, v199
	s_waitcnt vmcnt(13)
	v_lshlrev_b32_e32 v198, 16, v206
	s_waitcnt vmcnt(12)
; __device__ __forceinline__ unsigned cvt_pk_bf16(float lo, float hi) { unsigned r; asm volatile("v_cvt_pk_bf16_f32 %0, %1, %2" : "=v"(r) : "v"(lo), "v"(hi)); return r; }
; __device__ __forceinline__ float bf_lo(unsigned w) { return __uint_as_float(w << 16); }
; __device__ __forceinline__ float bf_hi(unsigned w) { return __uint_as_float(w & 0xffff0000u); }
; #define LAS __attribute__((address_space(3)))
; __device__ __forceinline__ void sgu_unit(LAS unsigned char* lds, bf16* U, const bf16* VS, const float* SGS, const float* lnw, const float* lnb, const v4u* WF, const float* bsl, int unit, int tid) {
;     ...
;         for (int i = 0; i < 8; ++i) {
;             const f32x4 st4 = *(const LAS f32x4*)(stat + 4 * (rp + 8 * i));
;             const v4u w0 = sl[i][0], w1 = sl[i][1];
;             const unsigned A0[4] = {w0.x, w0.y, w0.z, w0.w}, A1[4] = {w1.x, w1.y, w1.z, w1.w};
; #pragma unroll
;             for (int e = 0; e < 8; ++e) { typedef float f32x2p __attribute__((ext_vector_type(2)));
;                 f32x2p v; v.x = (e & 1) ? bf_hi(A0[e >> 1]) : bf_lo(A0[e >> 1]); v.y = (e & 1) ? bf_hi(A1[e >> 1]) : bf_lo(A1[e >> 1]);
;                 const f32x2p mn = {st4.x, st4.z}, rs = {st4.y, st4.w};
;                 const f32x2p o = ((v - mn) * rs) * lw[e] + lb[e];
;                 *(LAS unsigned*)(wbase + e * 8 * SGU_VP + i * 32) = cvt_pk_bf16(o.x, o.y); }
;         }
	v_lshlrev_b32_e32 v199, 16, v210
	v_pk_add_f32 v[198:199], v[198:199], v[202:203] neg_lo:[0,1] neg_hi:[0,1]
	s_nop 0
	v_pk_mul_f32 v[198:199], v[200:201], v[198:199]
	s_nop 0
	v_pk_fma_f32 v[198:199], v[102:103], v[198:199], v[98:99] op_sel_hi:[0,1,0]
	v_cvt_pk_bf16_f32 v85, v198, v199
	v_and_b32_e32 v198, 0xffff0000, v206
	v_and_b32_e32 v199, 0xffff0000, v210
	v_pk_add_f32 v[198:199], v[198:199], v[202:203] neg_lo:[0,1] neg_hi:[0,1]
	ds_write_b32 v177, v85 offset:1056
	v_pk_mul_f32 v[198:199], v[200:201], v[198:199]
	s_nop 0
	v_pk_fma_f32 v[198:199], v[102:103], v[198:199], v[98:99] op_sel:[1,0,1]
	s_nop 0
	v_cvt_pk_bf16_f32 v85, v198, v199
	v_lshlrev_b32_e32 v198, 16, v207
	v_lshlrev_b32_e32 v199, 16, v211
	v_pk_add_f32 v[198:199], v[198:199], v[202:203] neg_lo:[0,1] neg_hi:[0,1]
	ds_write_b32 v177, v85 offset:3232
	v_pk_mul_f32 v[198:199], v[200:201], v[198:199]
	s_nop 0
	v_pk_fma_f32 v[198:199], v[104:105], v[198:199], v[100:101] op_sel_hi:[0,1,0]
	v_cvt_pk_bf16_f32 v85, v198, v199
	v_and_b32_e32 v198, 0xffff0000, v207
	v_and_b32_e32 v199, 0xffff0000, v211
	v_pk_add_f32 v[198:199], v[198:199], v[202:203] neg_lo:[0,1] neg_hi:[0,1]
	ds_write_b32 v177, v85 offset:5408
	v_pk_mul_f32 v[198:199], v[200:201], v[198:199]
	s_nop 0
	v_pk_fma_f32 v[198:199], v[160:161], v[198:199], v[162:163] op_sel_hi:[0,1,0]
	v_cvt_pk_bf16_f32 v85, v198, v199
	v_lshlrev_b32_e32 v198, 16, v208
	v_lshlrev_b32_e32 v199, 16, v212
	v_pk_add_f32 v[198:199], v[198:199], v[202:203] neg_lo:[0,1] neg_hi:[0,1]
	ds_write_b32 v177, v85 offset:7584
	v_pk_mul_f32 v[198:199], v[200:201], v[198:199]
	s_nop 0
	v_pk_fma_f32 v[198:199], v[82:83], v[198:199], v[86:87] op_sel_hi:[0,1,0]
	v_cvt_pk_bf16_f32 v85, v198, v199
	v_and_b32_e32 v198, 0xffff0000, v208
	v_and_b32_e32 v199, 0xffff0000, v212
	v_pk_add_f32 v[198:199], v[198:199], v[202:203] neg_lo:[0,1] neg_hi:[0,1]
	ds_write_b32 v177, v85 offset:9760
	v_pk_mul_f32 v[198:199], v[200:201], v[198:199]
	s_nop 0
	v_pk_fma_f32 v[198:199], v[82:83], v[198:199], v[86:87] op_sel:[1,0,1]
	s_nop 0
	v_cvt_pk_bf16_f32 v85, v198, v199
	v_lshlrev_b32_e32 v198, 16, v209
	v_lshlrev_b32_e32 v199, 16, v213
	v_pk_add_f32 v[198:199], v[198:199], v[202:203] neg_lo:[0,1] neg_hi:[0,1]
	ds_write_b32 v177, v85 offset:11936
	v_pk_mul_f32 v[198:199], v[200:201], v[198:199]
	s_nop 0
	v_pk_fma_f32 v[198:199], v[84:85], v[198:199], v[88:89] op_sel_hi:[0,1,0]
	v_cvt_pk_bf16_f32 v85, v198, v199
	v_and_b32_e32 v198, 0xffff0000, v209
	v_and_b32_e32 v199, 0xffff0000, v213
	v_pk_add_f32 v[198:199], v[198:199], v[202:203] neg_lo:[0,1] neg_hi:[0,1]
	ds_write_b32 v177, v85 offset:14112
	v_pk_mul_f32 v[198:199], v[200:201], v[198:199]
	s_nop 0
	v_pk_fma_f32 v[198:199], v[164:165], v[198:199], v[166:167] op_sel_hi:[0,1,0]
	v_cvt_pk_bf16_f32 v85, v198, v199
	ds_write_b32 v177, v85 offset:16288
	ds_read_b128 v[198:201], v181 offset:256
	s_waitcnt lgkmcnt(0)
	v_mov_b32_e32 v202, v198
	v_mov_b32_e32 v203, v200
	v_mov_b32_e32 v200, v199
	s_waitcnt vmcnt(11)
	v_lshlrev_b32_e32 v198, 16, v138
	s_waitcnt vmcnt(10)
	v_lshlrev_b32_e32 v199, 16, v142
	v_pk_add_f32 v[198:199], v[198:199], v[202:203] neg_lo:[0,1] neg_hi:[0,1]
	s_nop 0
	v_pk_mul_f32 v[198:199], v[200:201], v[198:199]
	s_nop 0
	v_pk_fma_f32 v[198:199], v[102:103], v[198:199], v[98:99] op_sel_hi:[0,1,0]
	v_cvt_pk_bf16_f32 v85, v198, v199
	v_and_b32_e32 v198, 0xffff0000, v138
	v_and_b32_e32 v199, 0xffff0000, v142
	v_pk_add_f32 v[198:199], v[198:199], v[202:203] neg_lo:[0,1] neg_hi:[0,1]
	ds_write_b32 v177, v85 offset:1088
	v_pk_mul_f32 v[198:199], v[200:201], v[198:199]
	v_and_b32_e32 v138, 0xffff0000, v139
	v_pk_fma_f32 v[198:199], v[102:103], v[198:199], v[98:99] op_sel:[1,0,1]
	s_nop 0
	v_cvt_pk_bf16_f32 v85, v198, v199
	v_lshlrev_b32_e32 v198, 16, v139
	v_lshlrev_b32_e32 v199, 16, v143
	v_and_b32_e32 v139, 0xffff0000, v143
	v_pk_add_f32 v[198:199], v[198:199], v[202:203] neg_lo:[0,1] neg_hi:[0,1]
	v_pk_add_f32 v[138:139], v[138:139], v[202:203] neg_lo:[0,1] neg_hi:[0,1]
	v_pk_mul_f32 v[198:199], v[200:201], v[198:199]
	v_pk_mul_f32 v[138:139], v[200:201], v[138:139]
	ds_write_b32 v177, v85 offset:3264
	v_pk_fma_f32 v[198:199], v[104:105], v[198:199], v[100:101] op_sel_hi:[0,1,0]
	v_cvt_pk_bf16_f32 v85, v198, v199
	v_pk_fma_f32 v[138:139], v[160:161], v[138:139], v[162:163] op_sel_hi:[0,1,0]
	ds_write_b32 v177, v85 offset:5440
	v_cvt_pk_bf16_f32 v85, v138, v139
	v_lshlrev_b32_e32 v138, 16, v140
	v_lshlrev_b32_e32 v139, 16, v144
	v_pk_add_f32 v[138:139], v[138:139], v[202:203] neg_lo:[0,1] neg_hi:[0,1]
	ds_write_b32 v177, v85 offset:7616
	v_pk_mul_f32 v[138:139], v[200:201], v[138:139]
	s_nop 0
	v_pk_fma_f32 v[138:139], v[82:83], v[138:139], v[86:87] op_sel_hi:[0,1,0]
	v_cvt_pk_bf16_f32 v85, v138, v139
	v_and_b32_e32 v138, 0xffff0000, v140
	v_and_b32_e32 v139, 0xffff0000, v144
	v_pk_add_f32 v[138:139], v[138:139], v[202:203] neg_lo:[0,1] neg_hi:[0,1]
	ds_write_b32 v177, v85 offset:9792
	v_pk_mul_f32 v[138:139], v[200:201], v[138:139]
	s_nop 0
	v_pk_fma_f32 v[138:139], v[82:83], v[138:139], v[86:87] op_sel:[1,0,1]
	s_nop 0
	v_cvt_pk_bf16_f32 v85, v138, v139
	v_lshlrev_b32_e32 v138, 16, v141
	v_lshlrev_b32_e32 v139, 16, v145
	v_pk_add_f32 v[138:139], v[138:139], v[202:203] neg_lo:[0,1] neg_hi:[0,1]
	ds_write_b32 v177, v85 offset:11968
	v_pk_mul_f32 v[138:139], v[200:201], v[138:139]
	s_nop 0
	v_pk_fma_f32 v[138:139], v[84:85], v[138:139], v[88:89] op_sel_hi:[0,1,0]
	v_cvt_pk_bf16_f32 v85, v138, v139
	v_and_b32_e32 v138, 0xffff0000, v141
	v_and_b32_e32 v139, 0xffff0000, v145
	v_pk_add_f32 v[138:139], v[138:139], v[202:203] neg_lo:[0,1] neg_hi:[0,1]
	ds_write_b32 v177, v85 offset:14144
	v_pk_mul_f32 v[138:139], v[200:201], v[138:139]
	s_nop 0
	v_pk_fma_f32 v[138:139], v[164:165], v[138:139], v[166:167] op_sel_hi:[0,1,0]
	v_cvt_pk_bf16_f32 v85, v138, v139
	ds_write_b32 v177, v85 offset:16320
	ds_read_b128 v[138:141], v181 offset:384
	s_waitcnt lgkmcnt(0)
; __device__ __forceinline__ unsigned cvt_pk_bf16(float lo, float hi) { unsigned r; asm volatile("v_cvt_pk_bf16_f32 %0, %1, %2" : "=v"(r) : "v"(lo), "v"(hi)); return r; }
; __device__ __forceinline__ float bf_lo(unsigned w) { return __uint_as_float(w << 16); }
; __device__ __forceinline__ float bf_hi(unsigned w) { return __uint_as_float(w & 0xffff0000u); }
; #define LAS __attribute__((address_space(3)))
; __device__ __forceinline__ void sgu_unit(LAS unsigned char* lds, bf16* U, const bf16* VS, const float* SGS, const float* lnw, const float* lnb, const v4u* WF, const float* bsl, int unit, int tid) {
;     ...
;         for (int i = 0; i < 8; ++i) {
;             const f32x4 st4 = *(const LAS f32x4*)(stat + 4 * (rp + 8 * i));
;             const v4u w0 = sl[i][0], w1 = sl[i][1];
;             const unsigned A0[4] = {w0.x, w0.y, w0.z, w0.w}, A1[4] = {w1.x, w1.y, w1.z, w1.w};
; #pragma unroll
;             for (int e = 0; e < 8; ++e) { typedef float f32x2p __attribute__((ext_vector_type(2)));
;                 f32x2p v; v.x = (e & 1) ? bf_hi(A0[e >> 1]) : bf_lo(A0[e >> 1]); v.y = (e & 1) ? bf_hi(A1[e >> 1]) : bf_lo(A1[e >> 1]);
;                 const f32x2p mn = {st4.x, st4.z}, rs = {st4.y, st4.w};
;                 const f32x2p o = ((v - mn) * rs) * lw[e] + lb[e];
;                 *(LAS unsigned*)(wbase + e * 8 * SGU_VP + i * 32) = cvt_pk_bf16(o.x, o.y); }
;         }
	v_mov_b32_e32 v142, v138
	v_mov_b32_e32 v143, v140
	v_mov_b32_e32 v140, v139
	s_waitcnt vmcnt(9)
	v_lshlrev_b32_e32 v138, 16, v130
	s_waitcnt vmcnt(8)
	v_lshlrev_b32_e32 v139, 16, v134
	v_pk_add_f32 v[138:139], v[138:139], v[142:143] neg_lo:[0,1] neg_hi:[0,1]
	s_nop 0
	v_pk_mul_f32 v[138:139], v[140:141], v[138:139]
	s_nop 0
	v_pk_fma_f32 v[138:139], v[102:103], v[138:139], v[98:99] op_sel_hi:[0,1,0]
	v_cvt_pk_bf16_f32 v85, v138, v139
	v_and_b32_e32 v138, 0xffff0000, v130
	v_and_b32_e32 v139, 0xffff0000, v134
	v_pk_add_f32 v[138:139], v[138:139], v[142:143] neg_lo:[0,1] neg_hi:[0,1]
	ds_write_b32 v177, v85 offset:1120
	v_pk_mul_f32 v[138:139], v[140:141], v[138:139]
	v_and_b32_e32 v130, 0xffff0000, v131
	v_pk_fma_f32 v[138:139], v[102:103], v[138:139], v[98:99] op_sel:[1,0,1]
	s_nop 0
	v_cvt_pk_bf16_f32 v85, v138, v139
	v_lshlrev_b32_e32 v138, 16, v131
	v_lshlrev_b32_e32 v139, 16, v135
	v_and_b32_e32 v131, 0xffff0000, v135
	v_pk_add_f32 v[138:139], v[138:139], v[142:143] neg_lo:[0,1] neg_hi:[0,1]
	v_pk_add_f32 v[130:131], v[130:131], v[142:143] neg_lo:[0,1] neg_hi:[0,1]
	v_pk_mul_f32 v[138:139], v[140:141], v[138:139]
	v_pk_mul_f32 v[130:131], v[140:141], v[130:131]
	ds_write_b32 v177, v85 offset:3296
	v_pk_fma_f32 v[138:139], v[104:105], v[138:139], v[100:101] op_sel_hi:[0,1,0]
	v_cvt_pk_bf16_f32 v85, v138, v139
	v_pk_fma_f32 v[130:131], v[160:161], v[130:131], v[162:163] op_sel_hi:[0,1,0]
	ds_write_b32 v177, v85 offset:5472
	v_cvt_pk_bf16_f32 v85, v130, v131
	v_lshlrev_b32_e32 v130, 16, v132
	v_lshlrev_b32_e32 v131, 16, v136
	v_pk_add_f32 v[130:131], v[130:131], v[142:143] neg_lo:[0,1] neg_hi:[0,1]
	ds_write_b32 v177, v85 offset:7648
	v_pk_mul_f32 v[130:131], v[140:141], v[130:131]
	s_nop 0
	v_pk_fma_f32 v[130:131], v[82:83], v[130:131], v[86:87] op_sel_hi:[0,1,0]
	v_cvt_pk_bf16_f32 v85, v130, v131
	v_and_b32_e32 v130, 0xffff0000, v132
	v_and_b32_e32 v131, 0xffff0000, v136
	v_pk_add_f32 v[130:131], v[130:131], v[142:143] neg_lo:[0,1] neg_hi:[0,1]
	ds_write_b32 v177, v85 offset:9824
	v_pk_mul_f32 v[130:131], v[140:141], v[130:131]
	s_nop 0
	v_pk_fma_f32 v[130:131], v[82:83], v[130:131], v[86:87] op_sel:[1,0,1]
	s_nop 0
	v_cvt_pk_bf16_f32 v85, v130, v131
	v_lshlrev_b32_e32 v130, 16, v133
	v_lshlrev_b32_e32 v131, 16, v137
	v_pk_add_f32 v[130:131], v[130:131], v[142:143] neg_lo:[0,1] neg_hi:[0,1]
	ds_write_b32 v177, v85 offset:12000
	v_pk_mul_f32 v[130:131], v[140:141], v[130:131]
	s_nop 0
	v_pk_fma_f32 v[130:131], v[84:85], v[130:131], v[88:89] op_sel_hi:[0,1,0]
	v_cvt_pk_bf16_f32 v85, v130, v131
	v_and_b32_e32 v130, 0xffff0000, v133
	v_and_b32_e32 v131, 0xffff0000, v137
	v_pk_add_f32 v[130:131], v[130:131], v[142:143] neg_lo:[0,1] neg_hi:[0,1]
	ds_write_b32 v177, v85 offset:14176
	v_pk_mul_f32 v[130:131], v[140:141], v[130:131]
	s_nop 0
	v_pk_fma_f32 v[130:131], v[164:165], v[130:131], v[166:167] op_sel_hi:[0,1,0]
	v_cvt_pk_bf16_f32 v85, v130, v131
	ds_write_b32 v177, v85 offset:16352
	ds_read_b128 v[130:133], v181 offset:512
	s_waitcnt lgkmcnt(0)
	v_mov_b32_e32 v134, v130
	v_mov_b32_e32 v135, v132
	v_mov_b32_e32 v132, v131
	s_waitcnt vmcnt(7)
	v_lshlrev_b32_e32 v130, 16, v122
	s_waitcnt vmcnt(6)
	v_lshlrev_b32_e32 v131, 16, v126
	v_pk_add_f32 v[130:131], v[130:131], v[134:135] neg_lo:[0,1] neg_hi:[0,1]
	s_nop 0
	v_pk_mul_f32 v[130:131], v[132:133], v[130:131]
	s_nop 0
	v_pk_fma_f32 v[130:131], v[102:103], v[130:131], v[98:99] op_sel_hi:[0,1,0]
	v_cvt_pk_bf16_f32 v85, v130, v131
	v_and_b32_e32 v130, 0xffff0000, v122
	v_and_b32_e32 v131, 0xffff0000, v126
	v_pk_add_f32 v[130:131], v[130:131], v[134:135] neg_lo:[0,1] neg_hi:[0,1]
	ds_write_b32 v177, v85 offset:1152
	v_pk_mul_f32 v[130:131], v[132:133], v[130:131]
	v_and_b32_e32 v122, 0xffff0000, v123
	v_pk_fma_f32 v[130:131], v[102:103], v[130:131], v[98:99] op_sel:[1,0,1]
	s_nop 0
	v_cvt_pk_bf16_f32 v85, v130, v131
	v_lshlrev_b32_e32 v130, 16, v123
	v_lshlrev_b32_e32 v131, 16, v127
	v_and_b32_e32 v123, 0xffff0000, v127
	v_pk_add_f32 v[130:131], v[130:131], v[134:135] neg_lo:[0,1] neg_hi:[0,1]
	v_pk_add_f32 v[122:123], v[122:123], v[134:135] neg_lo:[0,1] neg_hi:[0,1]
	v_pk_mul_f32 v[130:131], v[132:133], v[130:131]
	v_pk_mul_f32 v[122:123], v[132:133], v[122:123]
	ds_write_b32 v177, v85 offset:3328
	v_pk_fma_f32 v[130:131], v[104:105], v[130:131], v[100:101] op_sel_hi:[0,1,0]
	v_cvt_pk_bf16_f32 v85, v130, v131
	v_pk_fma_f32 v[122:123], v[160:161], v[122:123], v[162:163] op_sel_hi:[0,1,0]
	ds_write_b32 v177, v85 offset:5504
	v_cvt_pk_bf16_f32 v85, v122, v123
	v_lshlrev_b32_e32 v122, 16, v124
	v_lshlrev_b32_e32 v123, 16, v128
	v_pk_add_f32 v[122:123], v[122:123], v[134:135] neg_lo:[0,1] neg_hi:[0,1]
	ds_write_b32 v177, v85 offset:7680
	v_pk_mul_f32 v[122:123], v[132:133], v[122:123]
	s_nop 0
	v_pk_fma_f32 v[122:123], v[82:83], v[122:123], v[86:87] op_sel_hi:[0,1,0]
	v_cvt_pk_bf16_f32 v85, v122, v123
	v_and_b32_e32 v122, 0xffff0000, v124
	v_and_b32_e32 v123, 0xffff0000, v128
	v_pk_add_f32 v[122:123], v[122:123], v[134:135] neg_lo:[0,1] neg_hi:[0,1]
	ds_write_b32 v177, v85 offset:9856
	v_pk_mul_f32 v[122:123], v[132:133], v[122:123]
	s_nop 0
	v_pk_fma_f32 v[122:123], v[82:83], v[122:123], v[86:87] op_sel:[1,0,1]
	s_nop 0
	v_cvt_pk_bf16_f32 v85, v122, v123
	v_lshlrev_b32_e32 v122, 16, v125
	v_lshlrev_b32_e32 v123, 16, v129
	v_pk_add_f32 v[122:123], v[122:123], v[134:135] neg_lo:[0,1] neg_hi:[0,1]
	ds_write_b32 v177, v85 offset:12032
	v_pk_mul_f32 v[122:123], v[132:133], v[122:123]
	s_nop 0
	v_pk_fma_f32 v[122:123], v[84:85], v[122:123], v[88:89] op_sel_hi:[0,1,0]
	v_cvt_pk_bf16_f32 v85, v122, v123
	v_and_b32_e32 v122, 0xffff0000, v125
	v_and_b32_e32 v123, 0xffff0000, v129
	v_pk_add_f32 v[122:123], v[122:123], v[134:135] neg_lo:[0,1] neg_hi:[0,1]
	ds_write_b32 v177, v85 offset:14208
	v_pk_mul_f32 v[122:123], v[132:133], v[122:123]
	s_nop 0
	v_pk_fma_f32 v[122:123], v[164:165], v[122:123], v[166:167] op_sel_hi:[0,1,0]
	v_cvt_pk_bf16_f32 v85, v122, v123
	ds_write_b32 v177, v85 offset:16384
	ds_read_b128 v[122:125], v181 offset:640
	s_waitcnt lgkmcnt(0)
; __device__ __forceinline__ unsigned cvt_pk_bf16(float lo, float hi) { unsigned r; asm volatile("v_cvt_pk_bf16_f32 %0, %1, %2" : "=v"(r) : "v"(lo), "v"(hi)); return r; }
; __device__ __forceinline__ float bf_lo(unsigned w) { return __uint_as_float(w << 16); }
; __device__ __forceinline__ float bf_hi(unsigned w) { return __uint_as_float(w & 0xffff0000u); }
; #define LAS __attribute__((address_space(3)))
; __device__ __forceinline__ void sgu_unit(LAS unsigned char* lds, bf16* U, const bf16* VS, const float* SGS, const float* lnw, const float* lnb, const v4u* WF, const float* bsl, int unit, int tid) {
;     ...
;         for (int i = 0; i < 8; ++i) {
;             const f32x4 st4 = *(const LAS f32x4*)(stat + 4 * (rp + 8 * i));
;             const v4u w0 = sl[i][0], w1 = sl[i][1];
;             const unsigned A0[4] = {w0.x, w0.y, w0.z, w0.w}, A1[4] = {w1.x, w1.y, w1.z, w1.w};
; #pragma unroll
;             for (int e = 0; e < 8; ++e) { typedef float f32x2p __attribute__((ext_vector_type(2)));
;                 f32x2p v; v.x = (e & 1) ? bf_hi(A0[e >> 1]) : bf_lo(A0[e >> 1]); v.y = (e & 1) ? bf_hi(A1[e >> 1]) : bf_lo(A1[e >> 1]);
;                 const f32x2p mn = {st4.x, st4.z}, rs = {st4.y, st4.w};
;                 const f32x2p o = ((v - mn) * rs) * lw[e] + lb[e];
;                 *(LAS unsigned*)(wbase + e * 8 * SGU_VP + i * 32) = cvt_pk_bf16(o.x, o.y); }
;         }
	v_mov_b32_e32 v126, v122
	v_mov_b32_e32 v127, v124
	v_mov_b32_e32 v124, v123
	s_waitcnt vmcnt(5)
	v_lshlrev_b32_e32 v122, 16, v114
	s_waitcnt vmcnt(4)
	v_lshlrev_b32_e32 v123, 16, v118
	v_pk_add_f32 v[122:123], v[122:123], v[126:127] neg_lo:[0,1] neg_hi:[0,1]
	s_nop 0
	v_pk_mul_f32 v[122:123], v[124:125], v[122:123]
	s_nop 0
	v_pk_fma_f32 v[122:123], v[102:103], v[122:123], v[98:99] op_sel_hi:[0,1,0]
	v_cvt_pk_bf16_f32 v85, v122, v123
	v_and_b32_e32 v122, 0xffff0000, v114
	v_and_b32_e32 v123, 0xffff0000, v118
	v_pk_add_f32 v[122:123], v[122:123], v[126:127] neg_lo:[0,1] neg_hi:[0,1]
	ds_write_b32 v177, v85 offset:1184
	v_pk_mul_f32 v[122:123], v[124:125], v[122:123]
	v_and_b32_e32 v114, 0xffff0000, v115
	v_pk_fma_f32 v[122:123], v[102:103], v[122:123], v[98:99] op_sel:[1,0,1]
	s_nop 0
	v_cvt_pk_bf16_f32 v85, v122, v123
	v_lshlrev_b32_e32 v122, 16, v115
	v_lshlrev_b32_e32 v123, 16, v119
	v_and_b32_e32 v115, 0xffff0000, v119
	v_pk_add_f32 v[122:123], v[122:123], v[126:127] neg_lo:[0,1] neg_hi:[0,1]
	v_pk_add_f32 v[114:115], v[114:115], v[126:127] neg_lo:[0,1] neg_hi:[0,1]
	v_pk_mul_f32 v[122:123], v[124:125], v[122:123]
	v_pk_mul_f32 v[114:115], v[124:125], v[114:115]
	ds_write_b32 v177, v85 offset:3360
	v_pk_fma_f32 v[122:123], v[104:105], v[122:123], v[100:101] op_sel_hi:[0,1,0]
	v_cvt_pk_bf16_f32 v85, v122, v123
	v_pk_fma_f32 v[114:115], v[160:161], v[114:115], v[162:163] op_sel_hi:[0,1,0]
	ds_write_b32 v177, v85 offset:5536
	v_cvt_pk_bf16_f32 v85, v114, v115
	v_lshlrev_b32_e32 v114, 16, v116
	v_lshlrev_b32_e32 v115, 16, v120
	v_pk_add_f32 v[114:115], v[114:115], v[126:127] neg_lo:[0,1] neg_hi:[0,1]
	ds_write_b32 v177, v85 offset:7712
	v_pk_mul_f32 v[114:115], v[124:125], v[114:115]
	s_nop 0
	v_pk_fma_f32 v[114:115], v[82:83], v[114:115], v[86:87] op_sel_hi:[0,1,0]
	v_cvt_pk_bf16_f32 v85, v114, v115
	v_and_b32_e32 v114, 0xffff0000, v116
	v_and_b32_e32 v115, 0xffff0000, v120
	v_pk_add_f32 v[114:115], v[114:115], v[126:127] neg_lo:[0,1] neg_hi:[0,1]
	ds_write_b32 v177, v85 offset:9888
	v_pk_mul_f32 v[114:115], v[124:125], v[114:115]
	s_nop 0
	v_pk_fma_f32 v[114:115], v[82:83], v[114:115], v[86:87] op_sel:[1,0,1]
	s_nop 0
	v_cvt_pk_bf16_f32 v85, v114, v115
	v_lshlrev_b32_e32 v114, 16, v117
	v_lshlrev_b32_e32 v115, 16, v121
	v_pk_add_f32 v[114:115], v[114:115], v[126:127] neg_lo:[0,1] neg_hi:[0,1]
	ds_write_b32 v177, v85 offset:12064
	v_pk_mul_f32 v[114:115], v[124:125], v[114:115]
	s_nop 0
	v_pk_fma_f32 v[114:115], v[84:85], v[114:115], v[88:89] op_sel_hi:[0,1,0]
	v_cvt_pk_bf16_f32 v85, v114, v115
	v_and_b32_e32 v114, 0xffff0000, v117
	v_and_b32_e32 v115, 0xffff0000, v121
	v_pk_add_f32 v[114:115], v[114:115], v[126:127] neg_lo:[0,1] neg_hi:[0,1]
	ds_write_b32 v177, v85 offset:14240
	v_pk_mul_f32 v[114:115], v[124:125], v[114:115]
	s_nop 0
	v_pk_fma_f32 v[114:115], v[164:165], v[114:115], v[166:167] op_sel_hi:[0,1,0]
	v_cvt_pk_bf16_f32 v85, v114, v115
	ds_write_b32 v177, v85 offset:16416
	ds_read_b128 v[114:117], v181 offset:768
	s_waitcnt lgkmcnt(0)
	v_mov_b32_e32 v118, v114
	v_mov_b32_e32 v119, v116
	v_mov_b32_e32 v116, v115
	s_waitcnt vmcnt(3)
	v_lshlrev_b32_e32 v114, 16, v106
	s_waitcnt vmcnt(2)
	v_lshlrev_b32_e32 v115, 16, v110
	v_pk_add_f32 v[114:115], v[114:115], v[118:119] neg_lo:[0,1] neg_hi:[0,1]
	s_nop 0
	v_pk_mul_f32 v[114:115], v[116:117], v[114:115]
	s_nop 0
	v_pk_fma_f32 v[114:115], v[102:103], v[114:115], v[98:99] op_sel_hi:[0,1,0]
	v_cvt_pk_bf16_f32 v85, v114, v115
	v_and_b32_e32 v114, 0xffff0000, v106
	v_and_b32_e32 v115, 0xffff0000, v110
	v_pk_add_f32 v[114:115], v[114:115], v[118:119] neg_lo:[0,1] neg_hi:[0,1]
	ds_write_b32 v177, v85 offset:1216
	v_pk_mul_f32 v[114:115], v[116:117], v[114:115]
	v_and_b32_e32 v106, 0xffff0000, v107
	v_pk_fma_f32 v[114:115], v[102:103], v[114:115], v[98:99] op_sel:[1,0,1]
	s_nop 0
	v_cvt_pk_bf16_f32 v85, v114, v115
	v_lshlrev_b32_e32 v114, 16, v107
	v_lshlrev_b32_e32 v115, 16, v111
	v_and_b32_e32 v107, 0xffff0000, v111
	v_pk_add_f32 v[114:115], v[114:115], v[118:119] neg_lo:[0,1] neg_hi:[0,1]
	v_pk_add_f32 v[106:107], v[106:107], v[118:119] neg_lo:[0,1] neg_hi:[0,1]
	v_pk_mul_f32 v[114:115], v[116:117], v[114:115]
	v_pk_mul_f32 v[106:107], v[116:117], v[106:107]
	ds_write_b32 v177, v85 offset:3392
	v_pk_fma_f32 v[114:115], v[104:105], v[114:115], v[100:101] op_sel_hi:[0,1,0]
	v_cvt_pk_bf16_f32 v85, v114, v115
	v_pk_fma_f32 v[106:107], v[160:161], v[106:107], v[162:163] op_sel_hi:[0,1,0]
	ds_write_b32 v177, v85 offset:5568
	v_cvt_pk_bf16_f32 v85, v106, v107
	v_lshlrev_b32_e32 v106, 16, v108
	v_lshlrev_b32_e32 v107, 16, v112
	v_pk_add_f32 v[106:107], v[106:107], v[118:119] neg_lo:[0,1] neg_hi:[0,1]
	ds_write_b32 v177, v85 offset:7744
	v_pk_mul_f32 v[106:107], v[116:117], v[106:107]
	s_nop 0
	v_pk_fma_f32 v[106:107], v[82:83], v[106:107], v[86:87] op_sel_hi:[0,1,0]
	v_cvt_pk_bf16_f32 v85, v106, v107
	v_and_b32_e32 v106, 0xffff0000, v108
	v_and_b32_e32 v107, 0xffff0000, v112
	v_pk_add_f32 v[106:107], v[106:107], v[118:119] neg_lo:[0,1] neg_hi:[0,1]
	ds_write_b32 v177, v85 offset:9920
	v_pk_mul_f32 v[106:107], v[116:117], v[106:107]
	s_nop 0
	v_pk_fma_f32 v[106:107], v[82:83], v[106:107], v[86:87] op_sel:[1,0,1]
	s_nop 0
	v_cvt_pk_bf16_f32 v85, v106, v107
	v_lshlrev_b32_e32 v106, 16, v109
	v_lshlrev_b32_e32 v107, 16, v113
	v_pk_add_f32 v[106:107], v[106:107], v[118:119] neg_lo:[0,1] neg_hi:[0,1]
	ds_write_b32 v177, v85 offset:12096
	v_pk_mul_f32 v[106:107], v[116:117], v[106:107]
	s_nop 0
	v_pk_fma_f32 v[106:107], v[84:85], v[106:107], v[88:89] op_sel_hi:[0,1,0]
	v_cvt_pk_bf16_f32 v85, v106, v107
	v_and_b32_e32 v106, 0xffff0000, v109
	v_and_b32_e32 v107, 0xffff0000, v113
	v_pk_add_f32 v[106:107], v[106:107], v[118:119] neg_lo:[0,1] neg_hi:[0,1]
	ds_write_b32 v177, v85 offset:14272
	v_pk_mul_f32 v[106:107], v[116:117], v[106:107]
	s_nop 0
	v_pk_fma_f32 v[106:107], v[164:165], v[106:107], v[166:167] op_sel_hi:[0,1,0]
	v_cvt_pk_bf16_f32 v85, v106, v107
	ds_write_b32 v177, v85 offset:16448
	ds_read_b128 v[106:109], v181 offset:896
	s_waitcnt lgkmcnt(0)
; __device__ __forceinline__ unsigned cvt_pk_bf16(float lo, float hi) { unsigned r; asm volatile("v_cvt_pk_bf16_f32 %0, %1, %2" : "=v"(r) : "v"(lo), "v"(hi)); return r; }
; __device__ __forceinline__ float bf_lo(unsigned w) { return __uint_as_float(w << 16); }
; __device__ __forceinline__ float bf_hi(unsigned w) { return __uint_as_float(w & 0xffff0000u); }
; #define LAS __attribute__((address_space(3)))
; #define LDS_WAIT() asm volatile("s_waitcnt lgkmcnt(0)" ::: "memory")
; __device__ __forceinline__ void sgu_unit(LAS unsigned char* lds, bf16* U, const bf16* VS, const float* SGS, const float* lnw, const float* lnb, const v4u* WF, const float* bsl, int unit, int tid) {
;     ...
;         for (int i = 0; i < 8; ++i) {
;             const f32x4 st4 = *(const LAS f32x4*)(stat + 4 * (rp + 8 * i));
;             const v4u w0 = sl[i][0], w1 = sl[i][1];
;             const unsigned A0[4] = {w0.x, w0.y, w0.z, w0.w}, A1[4] = {w1.x, w1.y, w1.z, w1.w};
; #pragma unroll
;             for (int e = 0; e < 8; ++e) { typedef float f32x2p __attribute__((ext_vector_type(2)));
;                 f32x2p v; v.x = (e & 1) ? bf_hi(A0[e >> 1]) : bf_lo(A0[e >> 1]); v.y = (e & 1) ? bf_hi(A1[e >> 1]) : bf_lo(A1[e >> 1]);
;                 const f32x2p mn = {st4.x, st4.z}, rs = {st4.y, st4.w};
;                 const f32x2p o = ((v - mn) * rs) * lw[e] + lb[e];
;                 *(LAS unsigned*)(wbase + e * 8 * SGU_VP + i * 32) = cvt_pk_bf16(o.x, o.y); }
;         }
;     }
;     v2u uu[8][4];
; #pragma unroll
;     for (int mt = 0; mt < 8; ++mt)
; #pragma unroll
;         for (int nt = 0; nt < 4; ++nt) uu[mt][nt] = *(const v2u*)(U + (size_t)(r0 + 16 * mt + fr) * 1024 + colbase + 16 * nt + 4 * fq);
;     LDS_WAIT(); asm volatile("" ::: "memory");
	v_mov_b32_e32 v110, v106
	v_mov_b32_e32 v111, v108
	v_mov_b32_e32 v108, v107
	s_waitcnt vmcnt(1)
	v_lshlrev_b32_e32 v106, 16, v90
	s_waitcnt vmcnt(0)
	v_lshlrev_b32_e32 v107, 16, v94
	v_pk_add_f32 v[106:107], v[106:107], v[110:111] neg_lo:[0,1] neg_hi:[0,1]
	s_nop 0
	v_pk_mul_f32 v[106:107], v[108:109], v[106:107]
	s_nop 0
	v_pk_fma_f32 v[106:107], v[102:103], v[106:107], v[98:99] op_sel_hi:[0,1,0]
	v_cvt_pk_bf16_f32 v85, v106, v107
	v_and_b32_e32 v106, 0xffff0000, v90
	v_and_b32_e32 v107, 0xffff0000, v94
	v_pk_add_f32 v[106:107], v[106:107], v[110:111] neg_lo:[0,1] neg_hi:[0,1]
	ds_write_b32 v177, v85 offset:1248
	v_pk_mul_f32 v[106:107], v[108:109], v[106:107]
	v_and_b32_e32 v90, 0xffff0000, v91
	v_pk_fma_f32 v[98:99], v[102:103], v[106:107], v[98:99] op_sel:[1,0,1]
	s_nop 0
	v_cvt_pk_bf16_f32 v85, v98, v99
	v_lshlrev_b32_e32 v98, 16, v91
	v_lshlrev_b32_e32 v99, 16, v95
	v_and_b32_e32 v91, 0xffff0000, v95
	v_pk_add_f32 v[98:99], v[98:99], v[110:111] neg_lo:[0,1] neg_hi:[0,1]
	v_pk_add_f32 v[90:91], v[90:91], v[110:111] neg_lo:[0,1] neg_hi:[0,1]
	v_pk_mul_f32 v[98:99], v[108:109], v[98:99]
	v_pk_mul_f32 v[90:91], v[108:109], v[90:91]
	ds_write_b32 v177, v85 offset:3424
	v_pk_fma_f32 v[98:99], v[104:105], v[98:99], v[100:101] op_sel_hi:[0,1,0]
	v_cvt_pk_bf16_f32 v85, v98, v99
	v_pk_fma_f32 v[90:91], v[160:161], v[90:91], v[162:163] op_sel_hi:[0,1,0]
	ds_write_b32 v177, v85 offset:5600
	v_cvt_pk_bf16_f32 v85, v90, v91
	v_lshlrev_b32_e32 v90, 16, v92
	v_lshlrev_b32_e32 v91, 16, v96
	v_pk_add_f32 v[90:91], v[90:91], v[110:111] neg_lo:[0,1] neg_hi:[0,1]
	ds_write_b32 v177, v85 offset:7776
	v_pk_mul_f32 v[90:91], v[108:109], v[90:91]
	s_nop 0
	v_pk_fma_f32 v[90:91], v[82:83], v[90:91], v[86:87] op_sel_hi:[0,1,0]
	v_cvt_pk_bf16_f32 v85, v90, v91
	v_and_b32_e32 v90, 0xffff0000, v92
	v_and_b32_e32 v91, 0xffff0000, v96
	v_pk_add_f32 v[90:91], v[90:91], v[110:111] neg_lo:[0,1] neg_hi:[0,1]
	ds_write_b32 v177, v85 offset:9952
	v_pk_mul_f32 v[90:91], v[108:109], v[90:91]
	s_nop 0
	v_pk_fma_f32 v[82:83], v[82:83], v[90:91], v[86:87] op_sel:[1,0,1]
	s_nop 0
	v_cvt_pk_bf16_f32 v82, v82, v83
	ds_write_b32 v177, v82 offset:12128
	v_lshlrev_b32_e32 v82, 16, v93
	v_lshlrev_b32_e32 v83, 16, v97
	v_pk_add_f32 v[82:83], v[82:83], v[110:111] neg_lo:[0,1] neg_hi:[0,1]
	s_nop 0
	v_pk_mul_f32 v[82:83], v[108:109], v[82:83]
	s_nop 0
	v_pk_fma_f32 v[82:83], v[84:85], v[82:83], v[88:89] op_sel_hi:[0,1,0]
	v_cvt_pk_bf16_f32 v82, v82, v83
	ds_write_b32 v177, v82 offset:14304
	v_and_b32_e32 v82, 0xffff0000, v93
	v_and_b32_e32 v83, 0xffff0000, v97
	v_pk_add_f32 v[82:83], v[82:83], v[110:111] neg_lo:[0,1] neg_hi:[0,1]
	v_or_b32_e32 v84, s18, v163
	v_pk_mul_f32 v[82:83], v[108:109], v[82:83]
	v_lshlrev_b32_e32 v84, 11, v84
	v_pk_fma_f32 v[82:83], v[164:165], v[82:83], v[166:167] op_sel_hi:[0,1,0]
	v_cvt_pk_bf16_f32 v82, v82, v83
	ds_write_b32 v177, v82 offset:16480
	v_lshl_add_u64 v[82:83], v[158:159], 1, v[150:151]
	v_mov_b32_e32 v85, v147
	v_lshl_add_u64 v[144:145], v[82:83], 0, v[84:85]
	global_load_dwordx2 v[158:159], v[144:145], off nt
	global_load_dwordx2 v[210:211], v[144:145], off offset:32 nt
	global_load_dwordx2 v[212:213], v[144:145], off offset:64 nt
	global_load_dwordx2 v[214:215], v[144:145], off offset:96 nt
	v_add_co_u32_e32 v216, vcc, s43, v144
	s_waitcnt vmcnt(3)
	v_lshlrev_b32_e32 v160, 16, v158
	v_addc_co_u32_e32 v217, vcc, 0, v145, vcc
	global_load_dwordx2 v[218:219], v[216:217], off nt
	global_load_dwordx2 v[220:221], v[216:217], off offset:32 nt
	global_load_dwordx2 v[222:223], v[216:217], off offset:64 nt
	global_load_dwordx2 v[224:225], v[216:217], off offset:96 nt
	v_add_co_u32_e32 v130, vcc, s53, v144
	v_and_b32_e32 v158, 0xffff0000, v158
	s_nop 0
	v_addc_co_u32_e32 v131, vcc, 0, v145, vcc
	v_add_co_u32_e32 v120, vcc, s54, v144
	global_load_dwordx2 v[226:227], v[130:131], off nt
	global_load_dwordx2 v[138:139], v[130:131], off offset:32 nt
	global_load_dwordx2 v[136:137], v[130:131], off offset:64 nt
	global_load_dwordx2 v[134:135], v[130:131], off offset:96 nt
	v_addc_co_u32_e32 v121, vcc, 0, v145, vcc
	v_add_co_u32_e32 v110, vcc, s55, v144
	global_load_dwordx2 v[132:133], v[120:121], off nt
	global_load_dwordx2 v[128:129], v[120:121], off offset:32 nt
	global_load_dwordx2 v[126:127], v[120:121], off offset:64 nt
	global_load_dwordx2 v[124:125], v[120:121], off offset:96 nt
	v_addc_co_u32_e32 v111, vcc, 0, v145, vcc
	v_add_co_u32_e32 v100, vcc, s56, v144
	global_load_dwordx2 v[122:123], v[110:111], off nt
	global_load_dwordx2 v[118:119], v[110:111], off offset:32 nt
	global_load_dwordx2 v[116:117], v[110:111], off offset:64 nt
	global_load_dwordx2 v[114:115], v[110:111], off offset:96 nt
	v_addc_co_u32_e32 v101, vcc, 0, v145, vcc
	v_add_co_u32_e32 v90, vcc, s57, v144
	global_load_dwordx2 v[112:113], v[100:101], off nt
	global_load_dwordx2 v[108:109], v[100:101], off offset:32 nt
	global_load_dwordx2 v[106:107], v[100:101], off offset:64 nt
	global_load_dwordx2 v[104:105], v[100:101], off offset:96 nt
	v_addc_co_u32_e32 v91, vcc, 0, v145, vcc
	v_lshrrev_b32_e32 v236, 4, v0
	v_and_b32_e32 v236, 1, v236
	v_mul_u32_u24_e32 v236, 24, v236
	v_mov_b32_e32 v237, 0
	v_add_co_u32_e32 v82, vcc, s58, v144
	global_load_dwordx2 v[102:103], v[90:91], off nt
	global_load_dwordx2 v[98:99], v[90:91], off offset:32 nt
	global_load_dwordx2 v[96:97], v[90:91], off offset:64 nt
	global_load_dwordx2 v[94:95], v[90:91], off offset:96 nt
	v_addc_co_u32_e32 v83, vcc, 0, v145, vcc
	global_load_dwordx2 v[92:93], v[82:83], off nt
	global_load_dwordx2 v[88:89], v[82:83], off offset:32 nt
	global_load_dwordx2 v[86:87], v[82:83], off offset:64 nt
	global_load_dwordx2 v[84:85], v[82:83], off offset:96 nt
	s_waitcnt lgkmcnt(0)
; __device__ __forceinline__ unsigned cvt_pk_bf16(float lo, float hi) { unsigned r; asm volatile("v_cvt_pk_bf16_f32 %0, %1, %2" : "=v"(r) : "v"(lo), "v"(hi)); return r; }
; __device__ __forceinline__ float bf_lo(unsigned w) { return __uint_as_float(w << 16); }
; __device__ __forceinline__ float bf_hi(unsigned w) { return __uint_as_float(w & 0xffff0000u); }
; #define LAS __attribute__((address_space(3)))
; __device__ __forceinline__ void sgu_unit(LAS unsigned char* lds, bf16* U, const bf16* VS, const float* SGS, const float* lnw, const float* lnb, const v4u* WF, const float* bsl, int unit, int tid) {
;     ...
;     {
;         int q = 0;
; #pragma unroll
;         for (int mt = 0; mt < 8; ++mt) {
;             const int t = 16 * mt + fr;
;             f32x4 acc[4];
; #pragma unroll
;             for (int nt = 0; nt < 4; ++nt) acc[nt] = (f32x4){0.f, 0.f, 0.f, 0.f};
; #pragma unroll
;             for (int ks = 0; ks <= (mt >> 1); ++ks) {
;                 const int sb = 32 * ks + 8 * fq; const bf16x8_t wf = __builtin_bit_cast(bf16x8_t, wfr[q++]);
; #pragma unroll
;                 for (int nt = 0; nt < 4; ++nt) { const bf16x8_t vf = *(const LAS bf16x8_t*)(vt + ((fr >> 3) + 8 * (fr & 7) + 2 * nt) * SGU_VP + sb * 2);
;                     acc[nt] = __builtin_amdgcn_mfma_f32_16x16x32_bf16(vf, wf, acc[nt], 0, 0, 0); }
;             }
;             const float bb = bbv[mt];
; #pragma unroll
;             for (int nt = 0; nt < 4; ++nt) { const v2u u2 = uu[mt][nt]; v2u w; w.x = cvt_pk_bf16(bf_lo(u2.x) * (acc[nt][0] + bb), bf_hi(u2.x) * (acc[nt][1] + bb)); w.y = cvt_pk_bf16(bf_lo(u2.y) * (acc[nt][2] + bb), bf_hi(u2.y) * (acc[nt][3] + bb));
;                 *(v2u*)(U + (size_t)(r0 + t) * 1024 + colbase + 16 * nt + 4 * fq) = w; }
;         }
	ds_read_b128 v[140:143], v182 offset:1024
	ds_read_b128 v[198:201], v182 offset:1568
	s_waitcnt lgkmcnt(1)
	v_mfma_f32_16x16x32_bf16 v[140:143], v[140:143], v[78:81], 0
	ds_read_b128 v[202:205], v182 offset:2112
	ds_read_b128 v[206:209], v182 offset:2656
	s_nop 5
	v_add_f32_e32 v140, v197, v140
	v_add_f32_e32 v141, v197, v141
	s_waitcnt lgkmcnt(2)
	v_mfma_f32_16x16x32_bf16 v[198:201], v[198:201], v[78:81], 0
	v_mul_f32_e32 v140, v140, v160
	v_mul_f32_e32 v141, v141, v158
	v_cvt_pk_bf16_f32 v248, v140, v141
	v_lshlrev_b32_e32 v141, 16, v159
	v_add_f32_e32 v142, v197, v142
	v_mul_f32_e32 v141, v142, v141
	v_and_b32_e32 v142, 0xffff0000, v159
	v_add_f32_e32 v143, v197, v143
	v_mul_f32_e32 v142, v143, v142
	v_cvt_pk_bf16_f32 v249, v141, v142
	v_lshl_add_u64 v[238:239], v[144:145], 0, v[236:237]
	s_waitcnt vmcnt(30)
	v_lshlrev_b32_e32 v140, 16, v210
	v_add_f32_e32 v141, v197, v198
	v_mul_f32_e32 v140, v141, v140
	v_and_b32_e32 v141, 0xffff0000, v210
	v_add_f32_e32 v142, v197, v199
	s_waitcnt lgkmcnt(1)
	v_mfma_f32_16x16x32_bf16 v[202:205], v[202:205], v[78:81], 0
	v_mul_f32_e32 v141, v142, v141
	v_cvt_pk_bf16_f32 v250, v140, v141
	v_lshlrev_b32_e32 v141, 16, v211
	v_add_f32_e32 v142, v197, v200
	v_mul_f32_e32 v141, v142, v141
	v_and_b32_e32 v142, 0xffff0000, v211
	v_add_f32_e32 v143, v197, v201
	v_mul_f32_e32 v142, v143, v142
	v_cvt_pk_bf16_f32 v251, v141, v142
	s_nop 1
	v_permlane16_swap_b32_e32 v248, v250
	v_permlane16_swap_b32_e32 v249, v251
	global_store_dwordx4 v[238:239], v[248:251], off
	s_waitcnt vmcnt(30)
	v_lshlrev_b32_e32 v140, 16, v212
	v_add_f32_e32 v141, v197, v202
	s_waitcnt lgkmcnt(0)
	v_mfma_f32_16x16x32_bf16 v[78:81], v[206:209], v[78:81], 0
	v_mul_f32_e32 v140, v141, v140
	v_and_b32_e32 v141, 0xffff0000, v212
	v_add_f32_e32 v142, v197, v203
	v_mul_f32_e32 v141, v142, v141
	v_cvt_pk_bf16_f32 v252, v140, v141
	v_lshlrev_b32_e32 v141, 16, v213
	v_add_f32_e32 v142, v197, v204
	v_mul_f32_e32 v141, v142, v141
	v_and_b32_e32 v142, 0xffff0000, v213
	v_add_f32_e32 v143, v197, v205
	v_mul_f32_e32 v142, v143, v142
	v_cvt_pk_bf16_f32 v253, v141, v142
	s_waitcnt vmcnt(29)
	v_lshlrev_b32_e32 v140, 16, v214
	v_add_f32_e32 v78, v197, v78
	v_mul_f32_e32 v78, v78, v140
	v_and_b32_e32 v140, 0xffff0000, v214
	v_add_f32_e32 v79, v197, v79
	v_mul_f32_e32 v79, v79, v140
	v_cvt_pk_bf16_f32 v254, v78, v79
	v_lshlrev_b32_e32 v78, 16, v215
	v_add_f32_e32 v79, v197, v80
	v_mul_f32_e32 v78, v79, v78
	v_and_b32_e32 v79, 0xffff0000, v215
	v_add_f32_e32 v80, v197, v81
	v_mul_f32_e32 v79, v80, v79
	v_cvt_pk_bf16_f32 v255, v78, v79
	ds_read_b128 v[78:81], v182 offset:1024
	ds_read_b128 v[140:143], v182 offset:1568
	s_waitcnt lgkmcnt(1)
	v_mfma_f32_16x16x32_bf16 v[78:81], v[78:81], v[74:77], 0
	ds_read_b128 v[198:201], v182 offset:2112
	ds_read_b128 v[202:205], v182 offset:2656
	s_nop 1
	v_permlane16_swap_b32_e32 v252, v254
	v_permlane16_swap_b32_e32 v253, v255
	global_store_dwordx4 v[238:239], v[252:255], off offset:64
	s_waitcnt vmcnt(29)
	v_lshlrev_b32_e32 v144, 16, v218
	s_nop 2
	v_add_f32_e32 v78, v196, v78
	v_mul_f32_e32 v78, v78, v144
	v_and_b32_e32 v144, 0xffff0000, v218
	v_add_f32_e32 v79, v196, v79
	s_waitcnt lgkmcnt(2)
	v_mfma_f32_16x16x32_bf16 v[140:143], v[140:143], v[74:77], 0
	v_mul_f32_e32 v79, v79, v144
	v_cvt_pk_bf16_f32 v248, v78, v79
	v_lshlrev_b32_e32 v79, 16, v219
	v_add_f32_e32 v80, v196, v80
	v_mul_f32_e32 v79, v80, v79
	v_and_b32_e32 v80, 0xffff0000, v219
	v_add_f32_e32 v81, v196, v81
	v_mul_f32_e32 v80, v81, v80
	v_cvt_pk_bf16_f32 v249, v79, v80
	v_lshl_add_u64 v[238:239], v[216:217], 0, v[236:237]
	s_waitcnt vmcnt(28)
	v_lshlrev_b32_e32 v78, 16, v220
	v_add_f32_e32 v79, v196, v140
	v_mul_f32_e32 v78, v79, v78
	v_and_b32_e32 v79, 0xffff0000, v220
	v_add_f32_e32 v80, v196, v141
	s_waitcnt lgkmcnt(1)
	v_mfma_f32_16x16x32_bf16 v[198:201], v[198:201], v[74:77], 0
	v_mul_f32_e32 v79, v80, v79
	v_cvt_pk_bf16_f32 v250, v78, v79
	v_lshlrev_b32_e32 v79, 16, v221
	v_add_f32_e32 v80, v196, v142
	v_mul_f32_e32 v79, v80, v79
	v_and_b32_e32 v80, 0xffff0000, v221
	v_add_f32_e32 v81, v196, v143
	v_mul_f32_e32 v80, v81, v80
	v_cvt_pk_bf16_f32 v251, v79, v80
	s_nop 1
	v_permlane16_swap_b32_e32 v248, v250
	v_permlane16_swap_b32_e32 v249, v251
	global_store_dwordx4 v[238:239], v[248:251], off
	s_waitcnt vmcnt(28)
	v_lshlrev_b32_e32 v78, 16, v222
	v_add_f32_e32 v79, v196, v198
	s_waitcnt lgkmcnt(0)
	v_mfma_f32_16x16x32_bf16 v[74:77], v[202:205], v[74:77], 0
	v_mul_f32_e32 v78, v79, v78
	v_and_b32_e32 v79, 0xffff0000, v222
	v_add_f32_e32 v80, v196, v199
	v_mul_f32_e32 v79, v80, v79
	v_cvt_pk_bf16_f32 v252, v78, v79
	v_lshlrev_b32_e32 v79, 16, v223
	v_add_f32_e32 v80, v196, v200
	v_mul_f32_e32 v79, v80, v79
	v_and_b32_e32 v80, 0xffff0000, v223
	v_add_f32_e32 v81, v196, v201
	v_mul_f32_e32 v80, v81, v80
	v_cvt_pk_bf16_f32 v253, v79, v80
	s_waitcnt vmcnt(27)
	v_lshlrev_b32_e32 v78, 16, v224
	v_add_f32_e32 v74, v196, v74
	v_mul_f32_e32 v74, v74, v78
	v_and_b32_e32 v78, 0xffff0000, v224
	v_add_f32_e32 v75, v196, v75
	v_mul_f32_e32 v75, v75, v78
	v_cvt_pk_bf16_f32 v254, v74, v75
	v_lshlrev_b32_e32 v74, 16, v225
	v_add_f32_e32 v75, v196, v76
	v_mul_f32_e32 v74, v75, v74
	v_and_b32_e32 v75, 0xffff0000, v225
	v_add_f32_e32 v76, v196, v77
	v_mul_f32_e32 v75, v76, v75
	v_cvt_pk_bf16_f32 v255, v74, v75
	ds_read_b128 v[74:77], v182 offset:1024
	ds_read_b128 v[78:81], v182 offset:1088
	s_waitcnt lgkmcnt(1)
	v_mfma_f32_16x16x32_bf16 v[74:77], v[74:77], v[70:73], 0
	ds_read_b128 v[140:143], v182 offset:1568
	ds_read_b128 v[196:199], v182 offset:1632
	ds_read_b128 v[200:203], v182 offset:2112
	ds_read_b128 v[204:207], v182 offset:2176
	ds_read_b128 v[208:211], v182 offset:2656
	ds_read_b128 v[212:215], v182 offset:2720
	s_waitcnt lgkmcnt(5)
; __device__ __forceinline__ unsigned cvt_pk_bf16(float lo, float hi) { unsigned r; asm volatile("v_cvt_pk_bf16_f32 %0, %1, %2" : "=v"(r) : "v"(lo), "v"(hi)); return r; }
; __device__ __forceinline__ float bf_lo(unsigned w) { return __uint_as_float(w << 16); }
; __device__ __forceinline__ float bf_hi(unsigned w) { return __uint_as_float(w & 0xffff0000u); }
; #define LAS __attribute__((address_space(3)))
; __device__ __forceinline__ void sgu_unit(LAS unsigned char* lds, bf16* U, const bf16* VS, const float* SGS, const float* lnw, const float* lnb, const v4u* WF, const float* bsl, int unit, int tid) {
;     ...
;     {
;         int q = 0;
; #pragma unroll
;         for (int mt = 0; mt < 8; ++mt) {
;             const int t = 16 * mt + fr;
;             f32x4 acc[4];
; #pragma unroll
;             for (int nt = 0; nt < 4; ++nt) acc[nt] = (f32x4){0.f, 0.f, 0.f, 0.f};
; #pragma unroll
;             for (int ks = 0; ks <= (mt >> 1); ++ks) {
;                 const int sb = 32 * ks + 8 * fq; const bf16x8_t wf = __builtin_bit_cast(bf16x8_t, wfr[q++]);
; #pragma unroll
;                 for (int nt = 0; nt < 4; ++nt) { const bf16x8_t vf = *(const LAS bf16x8_t*)(vt + ((fr >> 3) + 8 * (fr & 7) + 2 * nt) * SGU_VP + sb * 2);
;                     acc[nt] = __builtin_amdgcn_mfma_f32_16x16x32_bf16(vf, wf, acc[nt], 0, 0, 0); }
;             }
;             const float bb = bbv[mt];
; #pragma unroll
;             for (int nt = 0; nt < 4; ++nt) { const v2u u2 = uu[mt][nt]; v2u w; w.x = cvt_pk_bf16(bf_lo(u2.x) * (acc[nt][0] + bb), bf_hi(u2.x) * (acc[nt][1] + bb)); w.y = cvt_pk_bf16(bf_lo(u2.y) * (acc[nt][2] + bb), bf_hi(u2.y) * (acc[nt][3] + bb));
;                 *(v2u*)(U + (size_t)(r0 + t) * 1024 + colbase + 16 * nt + 4 * fq) = w; }
;         }
	v_mfma_f32_16x16x32_bf16 v[140:143], v[140:143], v[70:73], 0
	s_nop 1
	v_permlane16_swap_b32_e32 v252, v254
	v_permlane16_swap_b32_e32 v253, v255
	global_store_dwordx4 v[238:239], v[252:255], off offset:64
	s_waitcnt lgkmcnt(3)
	v_mfma_f32_16x16x32_bf16 v[200:203], v[200:203], v[70:73], 0
	s_waitcnt lgkmcnt(1)
	v_mfma_f32_16x16x32_bf16 v[70:73], v[208:211], v[70:73], 0
	v_mfma_f32_16x16x32_bf16 v[74:77], v[78:81], v[66:69], v[74:77]
	v_mfma_f32_16x16x32_bf16 v[78:81], v[196:199], v[66:69], v[140:143]
	v_mfma_f32_16x16x32_bf16 v[140:143], v[204:207], v[66:69], v[200:203]
	s_waitcnt lgkmcnt(0)
	v_mfma_f32_16x16x32_bf16 v[66:69], v[212:215], v[66:69], v[70:73]
	s_waitcnt vmcnt(27)
	s_nop 1
	v_lshlrev_b32_e32 v70, 16, v226
	v_add_f32_e32 v71, v195, v74
	v_mul_f32_e32 v70, v71, v70
	v_and_b32_e32 v71, 0xffff0000, v226
	v_add_f32_e32 v72, v195, v75
	v_mul_f32_e32 v71, v72, v71
	v_cvt_pk_bf16_f32 v248, v70, v71
	v_lshlrev_b32_e32 v71, 16, v227
	v_add_f32_e32 v72, v195, v76
	v_mul_f32_e32 v71, v72, v71
	v_and_b32_e32 v72, 0xffff0000, v227
	v_add_f32_e32 v73, v195, v77
	v_mul_f32_e32 v72, v73, v72
	v_cvt_pk_bf16_f32 v249, v71, v72
	v_lshl_add_u64 v[238:239], v[130:131], 0, v[236:237]
	s_waitcnt vmcnt(26)
	v_lshlrev_b32_e32 v70, 16, v138
	v_add_f32_e32 v71, v195, v78
	v_mul_f32_e32 v70, v71, v70
	v_and_b32_e32 v71, 0xffff0000, v138
	v_add_f32_e32 v72, v195, v79
	v_mul_f32_e32 v71, v72, v71
	v_cvt_pk_bf16_f32 v250, v70, v71
	v_lshlrev_b32_e32 v71, 16, v139
	v_add_f32_e32 v72, v195, v80
	v_mul_f32_e32 v71, v72, v71
	v_and_b32_e32 v72, 0xffff0000, v139
	v_add_f32_e32 v73, v195, v81
	v_mul_f32_e32 v72, v73, v72
	v_cvt_pk_bf16_f32 v251, v71, v72
	s_nop 1
	v_permlane16_swap_b32_e32 v248, v250
	v_permlane16_swap_b32_e32 v249, v251
	global_store_dwordx4 v[238:239], v[248:251], off
	s_waitcnt vmcnt(26)
	v_lshlrev_b32_e32 v70, 16, v136
	v_add_f32_e32 v71, v195, v140
	v_mul_f32_e32 v70, v71, v70
	v_and_b32_e32 v71, 0xffff0000, v136
	v_add_f32_e32 v72, v195, v141
	v_mul_f32_e32 v71, v72, v71
	v_cvt_pk_bf16_f32 v252, v70, v71
	v_lshlrev_b32_e32 v71, 16, v137
	v_add_f32_e32 v72, v195, v142
	v_mul_f32_e32 v71, v72, v71
	v_and_b32_e32 v72, 0xffff0000, v137
	v_add_f32_e32 v73, v195, v143
	v_mul_f32_e32 v72, v73, v72
	v_cvt_pk_bf16_f32 v253, v71, v72
	s_waitcnt vmcnt(25)
	v_lshlrev_b32_e32 v70, 16, v134
	v_add_f32_e32 v66, v195, v66
	v_mul_f32_e32 v66, v66, v70
	v_and_b32_e32 v70, 0xffff0000, v134
	v_add_f32_e32 v67, v195, v67
	v_mul_f32_e32 v67, v67, v70
	v_cvt_pk_bf16_f32 v254, v66, v67
	v_lshlrev_b32_e32 v66, 16, v135
	v_add_f32_e32 v67, v195, v68
	v_mul_f32_e32 v66, v67, v66
	v_and_b32_e32 v67, 0xffff0000, v135
	v_add_f32_e32 v68, v195, v69
	v_mul_f32_e32 v67, v68, v67
	v_cvt_pk_bf16_f32 v255, v66, v67
	ds_read_b128 v[66:69], v182 offset:1024
	ds_read_b128 v[70:73], v182 offset:1088
	s_waitcnt lgkmcnt(1)
	v_mfma_f32_16x16x32_bf16 v[66:69], v[66:69], v[62:65], 0
	ds_read_b128 v[74:77], v182 offset:1568
	ds_read_b128 v[78:81], v182 offset:1632
	ds_read_b128 v[134:137], v182 offset:2112
	ds_read_b128 v[138:141], v182 offset:2176
	ds_read_b128 v[142:145], v182 offset:2656
	ds_read_b128 v[196:199], v182 offset:2720
	s_waitcnt lgkmcnt(5)
	v_mfma_f32_16x16x32_bf16 v[74:77], v[74:77], v[62:65], 0
	s_nop 1
	v_permlane16_swap_b32_e32 v252, v254
	v_permlane16_swap_b32_e32 v253, v255
	global_store_dwordx4 v[238:239], v[252:255], off offset:64
	s_waitcnt lgkmcnt(3)
	v_mfma_f32_16x16x32_bf16 v[134:137], v[134:137], v[62:65], 0
	s_waitcnt lgkmcnt(1)
	v_mfma_f32_16x16x32_bf16 v[62:65], v[142:145], v[62:65], 0
	v_mfma_f32_16x16x32_bf16 v[66:69], v[70:73], v[58:61], v[66:69]
	v_mfma_f32_16x16x32_bf16 v[70:73], v[78:81], v[58:61], v[74:77]
	v_mfma_f32_16x16x32_bf16 v[74:77], v[138:141], v[58:61], v[134:137]
	s_waitcnt lgkmcnt(0)
	v_mfma_f32_16x16x32_bf16 v[58:61], v[196:199], v[58:61], v[62:65]
	s_waitcnt vmcnt(25)
	s_nop 1
	v_lshlrev_b32_e32 v62, 16, v132
	v_add_f32_e32 v63, v194, v66
	v_mul_f32_e32 v62, v63, v62
	v_and_b32_e32 v63, 0xffff0000, v132
	v_add_f32_e32 v64, v194, v67
	v_mul_f32_e32 v63, v64, v63
	v_cvt_pk_bf16_f32 v248, v62, v63
	v_lshlrev_b32_e32 v63, 16, v133
	v_add_f32_e32 v64, v194, v68
	v_mul_f32_e32 v63, v64, v63
	v_and_b32_e32 v64, 0xffff0000, v133
	v_add_f32_e32 v65, v194, v69
	v_mul_f32_e32 v64, v65, v64
	v_cvt_pk_bf16_f32 v249, v63, v64
	v_lshl_add_u64 v[238:239], v[120:121], 0, v[236:237]
	s_waitcnt vmcnt(24)
	v_lshlrev_b32_e32 v62, 16, v128
	v_add_f32_e32 v63, v194, v70
	v_mul_f32_e32 v62, v63, v62
	v_and_b32_e32 v63, 0xffff0000, v128
	v_add_f32_e32 v64, v194, v71
	v_mul_f32_e32 v63, v64, v63
	v_cvt_pk_bf16_f32 v250, v62, v63
	v_lshlrev_b32_e32 v63, 16, v129
	v_add_f32_e32 v64, v194, v72
	v_mul_f32_e32 v63, v64, v63
	v_and_b32_e32 v64, 0xffff0000, v129
	v_add_f32_e32 v65, v194, v73
	v_mul_f32_e32 v64, v65, v64
	v_cvt_pk_bf16_f32 v251, v63, v64
	s_nop 1
	v_permlane16_swap_b32_e32 v248, v250
	v_permlane16_swap_b32_e32 v249, v251
	global_store_dwordx4 v[238:239], v[248:251], off
	s_waitcnt vmcnt(24)
	v_lshlrev_b32_e32 v62, 16, v126
	v_add_f32_e32 v63, v194, v74
	v_mul_f32_e32 v62, v63, v62
	v_and_b32_e32 v63, 0xffff0000, v126
	v_add_f32_e32 v64, v194, v75
	v_mul_f32_e32 v63, v64, v63
	v_cvt_pk_bf16_f32 v252, v62, v63
	v_lshlrev_b32_e32 v63, 16, v127
	v_add_f32_e32 v64, v194, v76
	v_mul_f32_e32 v63, v64, v63
	v_and_b32_e32 v64, 0xffff0000, v127
	v_add_f32_e32 v65, v194, v77
	v_mul_f32_e32 v64, v65, v64
	v_cvt_pk_bf16_f32 v253, v63, v64
	s_waitcnt vmcnt(23)
; __device__ __forceinline__ unsigned cvt_pk_bf16(float lo, float hi) { unsigned r; asm volatile("v_cvt_pk_bf16_f32 %0, %1, %2" : "=v"(r) : "v"(lo), "v"(hi)); return r; }
; __device__ __forceinline__ float bf_lo(unsigned w) { return __uint_as_float(w << 16); }
; __device__ __forceinline__ float bf_hi(unsigned w) { return __uint_as_float(w & 0xffff0000u); }
; #define LAS __attribute__((address_space(3)))
; __device__ __forceinline__ void sgu_unit(LAS unsigned char* lds, bf16* U, const bf16* VS, const float* SGS, const float* lnw, const float* lnb, const v4u* WF, const float* bsl, int unit, int tid) {
;     ...
;     {
;         int q = 0;
; #pragma unroll
;         for (int mt = 0; mt < 8; ++mt) {
;             const int t = 16 * mt + fr;
;             f32x4 acc[4];
; #pragma unroll
;             for (int nt = 0; nt < 4; ++nt) acc[nt] = (f32x4){0.f, 0.f, 0.f, 0.f};
; #pragma unroll
;             for (int ks = 0; ks <= (mt >> 1); ++ks) {
;                 const int sb = 32 * ks + 8 * fq; const bf16x8_t wf = __builtin_bit_cast(bf16x8_t, wfr[q++]);
; #pragma unroll
;                 for (int nt = 0; nt < 4; ++nt) { const bf16x8_t vf = *(const LAS bf16x8_t*)(vt + ((fr >> 3) + 8 * (fr & 7) + 2 * nt) * SGU_VP + sb * 2);
;                     acc[nt] = __builtin_amdgcn_mfma_f32_16x16x32_bf16(vf, wf, acc[nt], 0, 0, 0); }
;             }
;             const float bb = bbv[mt];
; #pragma unroll
;             for (int nt = 0; nt < 4; ++nt) { const v2u u2 = uu[mt][nt]; v2u w; w.x = cvt_pk_bf16(bf_lo(u2.x) * (acc[nt][0] + bb), bf_hi(u2.x) * (acc[nt][1] + bb)); w.y = cvt_pk_bf16(bf_lo(u2.y) * (acc[nt][2] + bb), bf_hi(u2.y) * (acc[nt][3] + bb));
;                 *(v2u*)(U + (size_t)(r0 + t) * 1024 + colbase + 16 * nt + 4 * fq) = w; }
;         }
	v_lshlrev_b32_e32 v62, 16, v124
	v_add_f32_e32 v58, v194, v58
	v_mul_f32_e32 v58, v58, v62
	v_and_b32_e32 v62, 0xffff0000, v124
	v_add_f32_e32 v59, v194, v59
	v_mul_f32_e32 v59, v59, v62
	v_cvt_pk_bf16_f32 v254, v58, v59
	v_lshlrev_b32_e32 v58, 16, v125
	v_add_f32_e32 v59, v194, v60
	v_mul_f32_e32 v58, v59, v58
	v_and_b32_e32 v59, 0xffff0000, v125
	v_add_f32_e32 v60, v194, v61
	v_mul_f32_e32 v59, v60, v59
	v_cvt_pk_bf16_f32 v255, v58, v59
	ds_read_b128 v[58:61], v182 offset:1024
	ds_read_b128 v[62:65], v182 offset:1088
	s_waitcnt lgkmcnt(1)
	v_mfma_f32_16x16x32_bf16 v[58:61], v[58:61], v[50:53], 0
	ds_read_b128 v[66:69], v182 offset:1568
	ds_read_b128 v[70:73], v182 offset:1152
	ds_read_b128 v[74:77], v182 offset:2112
	ds_read_b128 v[78:81], v182 offset:2176
	ds_read_b128 v[124:127], v182 offset:2656
	ds_read_b128 v[128:131], v182 offset:2240
	s_waitcnt lgkmcnt(5)
	v_mfma_f32_16x16x32_bf16 v[66:69], v[66:69], v[50:53], 0
	s_waitcnt lgkmcnt(3)
	v_mfma_f32_16x16x32_bf16 v[74:77], v[74:77], v[50:53], 0
	s_waitcnt lgkmcnt(1)
	v_mfma_f32_16x16x32_bf16 v[50:53], v[124:127], v[50:53], 0
	v_mfma_f32_16x16x32_bf16 v[58:61], v[62:65], v[54:57], v[58:61]
	ds_read_b128 v[62:65], v182 offset:1632
	ds_read_b128 v[124:127], v182 offset:1696
	s_waitcnt lgkmcnt(1)
	v_mfma_f32_16x16x32_bf16 v[62:65], v[62:65], v[54:57], v[66:69]
	v_mfma_f32_16x16x32_bf16 v[66:69], v[78:81], v[54:57], v[74:77]
	s_nop 2
	ds_read_b128 v[74:77], v182 offset:2720
	ds_read_b128 v[78:81], v182 offset:2784
	s_nop 1
	v_permlane16_swap_b32_e32 v252, v254
	v_permlane16_swap_b32_e32 v253, v255
	global_store_dwordx4 v[238:239], v[252:255], off offset:64
	s_waitcnt lgkmcnt(1)
	v_mfma_f32_16x16x32_bf16 v[50:53], v[74:77], v[54:57], v[50:53]
	v_mfma_f32_16x16x32_bf16 v[54:57], v[70:73], v[46:49], v[58:61]
	v_mfma_f32_16x16x32_bf16 v[58:61], v[124:127], v[46:49], v[62:65]
	v_mfma_f32_16x16x32_bf16 v[62:65], v[128:131], v[46:49], v[66:69]
	s_waitcnt lgkmcnt(0)
	v_mfma_f32_16x16x32_bf16 v[46:49], v[78:81], v[46:49], v[50:53]
	s_waitcnt vmcnt(23)
	s_nop 1
	v_lshlrev_b32_e32 v50, 16, v122
	v_add_f32_e32 v51, v193, v54
	v_mul_f32_e32 v50, v51, v50
	v_and_b32_e32 v51, 0xffff0000, v122
	v_add_f32_e32 v52, v193, v55
	v_mul_f32_e32 v51, v52, v51
	v_cvt_pk_bf16_f32 v248, v50, v51
	v_lshlrev_b32_e32 v51, 16, v123
	v_add_f32_e32 v52, v193, v56
	v_mul_f32_e32 v51, v52, v51
	v_and_b32_e32 v52, 0xffff0000, v123
	v_add_f32_e32 v53, v193, v57
	v_mul_f32_e32 v52, v53, v52
	v_cvt_pk_bf16_f32 v249, v51, v52
	v_lshl_add_u64 v[238:239], v[110:111], 0, v[236:237]
	s_waitcnt vmcnt(22)
	v_lshlrev_b32_e32 v50, 16, v118
	v_add_f32_e32 v51, v193, v58
	v_mul_f32_e32 v50, v51, v50
	v_and_b32_e32 v51, 0xffff0000, v118
	v_add_f32_e32 v52, v193, v59
	v_mul_f32_e32 v51, v52, v51
	v_cvt_pk_bf16_f32 v250, v50, v51
	v_lshlrev_b32_e32 v51, 16, v119
	v_add_f32_e32 v52, v193, v60
	v_mul_f32_e32 v51, v52, v51
	v_and_b32_e32 v52, 0xffff0000, v119
	v_add_f32_e32 v53, v193, v61
	v_mul_f32_e32 v52, v53, v52
	v_cvt_pk_bf16_f32 v251, v51, v52
	s_nop 1
	v_permlane16_swap_b32_e32 v248, v250
	v_permlane16_swap_b32_e32 v249, v251
	global_store_dwordx4 v[238:239], v[248:251], off
	s_waitcnt vmcnt(22)
	v_lshlrev_b32_e32 v50, 16, v116
	v_add_f32_e32 v51, v193, v62
	v_mul_f32_e32 v50, v51, v50
	v_and_b32_e32 v51, 0xffff0000, v116
	v_add_f32_e32 v52, v193, v63
	v_mul_f32_e32 v51, v52, v51
	v_cvt_pk_bf16_f32 v252, v50, v51
	v_lshlrev_b32_e32 v51, 16, v117
	v_add_f32_e32 v52, v193, v64
	v_mul_f32_e32 v51, v52, v51
	v_and_b32_e32 v52, 0xffff0000, v117
	v_add_f32_e32 v53, v193, v65
	v_mul_f32_e32 v52, v53, v52
	v_cvt_pk_bf16_f32 v253, v51, v52
	s_waitcnt vmcnt(21)
	v_lshlrev_b32_e32 v50, 16, v114
	v_add_f32_e32 v46, v193, v46
	v_mul_f32_e32 v46, v46, v50
	v_and_b32_e32 v50, 0xffff0000, v114
	v_add_f32_e32 v47, v193, v47
	v_mul_f32_e32 v47, v47, v50
	v_cvt_pk_bf16_f32 v254, v46, v47
	v_lshlrev_b32_e32 v46, 16, v115
	v_add_f32_e32 v47, v193, v48
	v_mul_f32_e32 v46, v47, v46
	v_and_b32_e32 v47, 0xffff0000, v115
	v_add_f32_e32 v48, v193, v49
	v_mul_f32_e32 v47, v48, v47
	v_cvt_pk_bf16_f32 v255, v46, v47
	ds_read_b128 v[46:49], v182 offset:1024
	ds_read_b128 v[50:53], v182 offset:1088
	s_waitcnt lgkmcnt(1)
	v_mfma_f32_16x16x32_bf16 v[46:49], v[46:49], v[42:45], 0
	ds_read_b128 v[54:57], v182 offset:1568
	ds_read_b128 v[58:61], v182 offset:1152
	ds_read_b128 v[62:65], v182 offset:2112
	ds_read_b128 v[66:69], v182 offset:2176
	ds_read_b128 v[70:73], v182 offset:2656
	ds_read_b128 v[74:77], v182 offset:2240
	s_waitcnt lgkmcnt(5)
	v_mfma_f32_16x16x32_bf16 v[54:57], v[54:57], v[42:45], 0
	s_waitcnt lgkmcnt(3)
	v_mfma_f32_16x16x32_bf16 v[62:65], v[62:65], v[42:45], 0
	s_waitcnt lgkmcnt(1)
	v_mfma_f32_16x16x32_bf16 v[42:45], v[70:73], v[42:45], 0
	v_mfma_f32_16x16x32_bf16 v[46:49], v[50:53], v[34:37], v[46:49]
	ds_read_b128 v[50:53], v182 offset:1632
	ds_read_b128 v[70:73], v182 offset:1696
	s_waitcnt lgkmcnt(1)
	v_mfma_f32_16x16x32_bf16 v[50:53], v[50:53], v[34:37], v[54:57]
	v_mfma_f32_16x16x32_bf16 v[54:57], v[66:69], v[34:37], v[62:65]
	s_nop 2
	ds_read_b128 v[62:65], v182 offset:2720
	ds_read_b128 v[66:69], v182 offset:2784
	s_nop 1
	v_permlane16_swap_b32_e32 v252, v254
	v_permlane16_swap_b32_e32 v253, v255
	global_store_dwordx4 v[238:239], v[252:255], off offset:64
	s_waitcnt lgkmcnt(1)
	v_mfma_f32_16x16x32_bf16 v[34:37], v[62:65], v[34:37], v[42:45]
	v_mfma_f32_16x16x32_bf16 v[42:45], v[58:61], v[38:41], v[46:49]
	v_mfma_f32_16x16x32_bf16 v[46:49], v[70:73], v[38:41], v[50:53]
	v_mfma_f32_16x16x32_bf16 v[50:53], v[74:77], v[38:41], v[54:57]
	s_waitcnt lgkmcnt(0)
	v_mfma_f32_16x16x32_bf16 v[34:37], v[66:69], v[38:41], v[34:37]
	s_waitcnt vmcnt(21)
; __device__ __forceinline__ unsigned cvt_pk_bf16(float lo, float hi) { unsigned r; asm volatile("v_cvt_pk_bf16_f32 %0, %1, %2" : "=v"(r) : "v"(lo), "v"(hi)); return r; }
; __device__ __forceinline__ float bf_lo(unsigned w) { return __uint_as_float(w << 16); }
; __device__ __forceinline__ float bf_hi(unsigned w) { return __uint_as_float(w & 0xffff0000u); }
; #define LAS __attribute__((address_space(3)))
; __device__ __forceinline__ void sgu_unit(LAS unsigned char* lds, bf16* U, const bf16* VS, const float* SGS, const float* lnw, const float* lnb, const v4u* WF, const float* bsl, int unit, int tid) {
;     ...
;     {
;         int q = 0;
; #pragma unroll
;         for (int mt = 0; mt < 8; ++mt) {
;             const int t = 16 * mt + fr;
;             f32x4 acc[4];
; #pragma unroll
;             for (int nt = 0; nt < 4; ++nt) acc[nt] = (f32x4){0.f, 0.f, 0.f, 0.f};
; #pragma unroll
;             for (int ks = 0; ks <= (mt >> 1); ++ks) {
;                 const int sb = 32 * ks + 8 * fq; const bf16x8_t wf = __builtin_bit_cast(bf16x8_t, wfr[q++]);
; #pragma unroll
;                 for (int nt = 0; nt < 4; ++nt) { const bf16x8_t vf = *(const LAS bf16x8_t*)(vt + ((fr >> 3) + 8 * (fr & 7) + 2 * nt) * SGU_VP + sb * 2);
;                     acc[nt] = __builtin_amdgcn_mfma_f32_16x16x32_bf16(vf, wf, acc[nt], 0, 0, 0); }
;             }
;             const float bb = bbv[mt];
; #pragma unroll
;             for (int nt = 0; nt < 4; ++nt) { const v2u u2 = uu[mt][nt]; v2u w; w.x = cvt_pk_bf16(bf_lo(u2.x) * (acc[nt][0] + bb), bf_hi(u2.x) * (acc[nt][1] + bb)); w.y = cvt_pk_bf16(bf_lo(u2.y) * (acc[nt][2] + bb), bf_hi(u2.y) * (acc[nt][3] + bb));
;                 *(v2u*)(U + (size_t)(r0 + t) * 1024 + colbase + 16 * nt + 4 * fq) = w; }
;         }
	v_lshlrev_b32_e32 v38, 16, v112
	s_nop 1
	v_add_f32_e32 v39, v192, v42
	v_mul_f32_e32 v38, v39, v38
	v_and_b32_e32 v39, 0xffff0000, v112
	v_add_f32_e32 v40, v192, v43
	v_mul_f32_e32 v39, v40, v39
	v_cvt_pk_bf16_f32 v248, v38, v39
	v_lshlrev_b32_e32 v39, 16, v113
	v_add_f32_e32 v40, v192, v44
	v_mul_f32_e32 v39, v40, v39
	v_and_b32_e32 v40, 0xffff0000, v113
	v_add_f32_e32 v41, v192, v45
	v_mul_f32_e32 v40, v41, v40
	v_cvt_pk_bf16_f32 v249, v39, v40
	v_lshl_add_u64 v[238:239], v[100:101], 0, v[236:237]
	s_waitcnt vmcnt(20)
	v_lshlrev_b32_e32 v38, 16, v108
	v_add_f32_e32 v39, v192, v46
	v_mul_f32_e32 v38, v39, v38
	v_and_b32_e32 v39, 0xffff0000, v108
	v_add_f32_e32 v40, v192, v47
	v_mul_f32_e32 v39, v40, v39
	v_cvt_pk_bf16_f32 v250, v38, v39
	v_lshlrev_b32_e32 v39, 16, v109
	v_add_f32_e32 v40, v192, v48
	v_mul_f32_e32 v39, v40, v39
	v_and_b32_e32 v40, 0xffff0000, v109
	v_add_f32_e32 v41, v192, v49
	v_mul_f32_e32 v40, v41, v40
	v_cvt_pk_bf16_f32 v251, v39, v40
	s_nop 1
	v_permlane16_swap_b32_e32 v248, v250
	v_permlane16_swap_b32_e32 v249, v251
	global_store_dwordx4 v[238:239], v[248:251], off
	s_waitcnt vmcnt(20)
	v_lshlrev_b32_e32 v38, 16, v106
	v_add_f32_e32 v39, v192, v50
	v_mul_f32_e32 v38, v39, v38
	v_and_b32_e32 v39, 0xffff0000, v106
	v_add_f32_e32 v40, v192, v51
	v_mul_f32_e32 v39, v40, v39
	v_cvt_pk_bf16_f32 v252, v38, v39
	v_lshlrev_b32_e32 v39, 16, v107
	v_add_f32_e32 v40, v192, v52
	v_mul_f32_e32 v39, v40, v39
	v_and_b32_e32 v40, 0xffff0000, v107
	v_add_f32_e32 v41, v192, v53
	v_mul_f32_e32 v40, v41, v40
	v_cvt_pk_bf16_f32 v253, v39, v40
	s_waitcnt vmcnt(19)
	v_lshlrev_b32_e32 v38, 16, v104
	v_add_f32_e32 v34, v192, v34
	v_mul_f32_e32 v34, v34, v38
	v_and_b32_e32 v38, 0xffff0000, v104
	v_add_f32_e32 v35, v192, v35
	v_mul_f32_e32 v35, v35, v38
	v_cvt_pk_bf16_f32 v254, v34, v35
	v_lshlrev_b32_e32 v34, 16, v105
	v_add_f32_e32 v35, v192, v36
	v_mul_f32_e32 v34, v35, v34
	v_and_b32_e32 v35, 0xffff0000, v105
	v_add_f32_e32 v36, v192, v37
	v_mul_f32_e32 v35, v36, v35
	v_cvt_pk_bf16_f32 v255, v34, v35
	ds_read_b128 v[34:37], v182 offset:1024
	ds_read_b128 v[38:41], v182 offset:1088
	ds_read_b128 v[42:45], v182 offset:1568
	ds_read_b128 v[46:49], v182 offset:1632
	ds_read_b128 v[50:53], v182 offset:2112
	ds_read_b128 v[54:57], v182 offset:2176
	ds_read_b128 v[58:61], v182 offset:2656
	ds_read_b128 v[62:65], v182 offset:2720
	s_waitcnt lgkmcnt(7)
	v_mfma_f32_16x16x32_bf16 v[34:37], v[34:37], v[30:33], 0
	s_waitcnt lgkmcnt(5)
	v_mfma_f32_16x16x32_bf16 v[42:45], v[42:45], v[30:33], 0
	s_waitcnt lgkmcnt(3)
	v_mfma_f32_16x16x32_bf16 v[50:53], v[50:53], v[30:33], 0
	s_waitcnt lgkmcnt(1)
	v_mfma_f32_16x16x32_bf16 v[30:33], v[58:61], v[30:33], 0
	v_mfma_f32_16x16x32_bf16 v[34:37], v[38:41], v[26:29], v[34:37]
	v_mfma_f32_16x16x32_bf16 v[38:41], v[46:49], v[26:29], v[42:45]
	v_mfma_f32_16x16x32_bf16 v[42:45], v[54:57], v[26:29], v[50:53]
	s_waitcnt lgkmcnt(0)
	v_mfma_f32_16x16x32_bf16 v[26:29], v[62:65], v[26:29], v[30:33]
	s_nop 2
	ds_read_b128 v[30:33], v182 offset:1152
	ds_read_b128 v[46:49], v182 offset:1216
	s_waitcnt lgkmcnt(1)
	v_mfma_f32_16x16x32_bf16 v[30:33], v[30:33], v[22:25], v[34:37]
	s_nop 2
	ds_read_b128 v[34:37], v182 offset:1696
	ds_read_b128 v[50:53], v182 offset:1760
	s_waitcnt lgkmcnt(1)
	v_mfma_f32_16x16x32_bf16 v[34:37], v[34:37], v[22:25], v[38:41]
	s_nop 2
	ds_read_b128 v[38:41], v182 offset:2240
	ds_read_b128 v[54:57], v182 offset:2304
	s_waitcnt lgkmcnt(1)
	v_mfma_f32_16x16x32_bf16 v[38:41], v[38:41], v[22:25], v[42:45]
	s_nop 2
	ds_read_b128 v[42:45], v182 offset:2784
	ds_read_b128 v[58:61], v182 offset:2848
	s_nop 1
	v_permlane16_swap_b32_e32 v252, v254
	v_permlane16_swap_b32_e32 v253, v255
	global_store_dwordx4 v[238:239], v[252:255], off offset:64
	s_waitcnt lgkmcnt(1)
	v_mfma_f32_16x16x32_bf16 v[22:25], v[42:45], v[22:25], v[26:29]
	v_mfma_f32_16x16x32_bf16 v[26:29], v[46:49], v[18:21], v[30:33]
	v_mfma_f32_16x16x32_bf16 v[30:33], v[50:53], v[18:21], v[34:37]
	v_mfma_f32_16x16x32_bf16 v[34:37], v[54:57], v[18:21], v[38:41]
	s_waitcnt lgkmcnt(0)
	v_mfma_f32_16x16x32_bf16 v[18:21], v[58:61], v[18:21], v[22:25]
	s_waitcnt vmcnt(19)
	s_nop 1
	v_lshlrev_b32_e32 v22, 16, v102
	v_add_f32_e32 v23, v191, v26
	v_mul_f32_e32 v22, v23, v22
	v_and_b32_e32 v23, 0xffff0000, v102
	v_add_f32_e32 v24, v191, v27
	v_mul_f32_e32 v23, v24, v23
	v_cvt_pk_bf16_f32 v248, v22, v23
	v_lshlrev_b32_e32 v23, 16, v103
	v_add_f32_e32 v24, v191, v28
	v_mul_f32_e32 v23, v24, v23
	v_and_b32_e32 v24, 0xffff0000, v103
	v_add_f32_e32 v25, v191, v29
	v_mul_f32_e32 v24, v25, v24
	v_cvt_pk_bf16_f32 v249, v23, v24
	v_lshl_add_u64 v[238:239], v[90:91], 0, v[236:237]
	s_waitcnt vmcnt(18)
	v_lshlrev_b32_e32 v22, 16, v98
	v_add_f32_e32 v23, v191, v30
	v_mul_f32_e32 v22, v23, v22
	v_and_b32_e32 v23, 0xffff0000, v98
	v_add_f32_e32 v24, v191, v31
	v_mul_f32_e32 v23, v24, v23
	v_cvt_pk_bf16_f32 v250, v22, v23
	v_lshlrev_b32_e32 v23, 16, v99
	v_add_f32_e32 v24, v191, v32
	v_mul_f32_e32 v23, v24, v23
	v_and_b32_e32 v24, 0xffff0000, v99
	v_add_f32_e32 v25, v191, v33
	v_mul_f32_e32 v24, v25, v24
	v_cvt_pk_bf16_f32 v251, v23, v24
	s_nop 1
	v_permlane16_swap_b32_e32 v248, v250
	v_permlane16_swap_b32_e32 v249, v251
	global_store_dwordx4 v[238:239], v[248:251], off
	s_waitcnt vmcnt(18)
; __device__ __forceinline__ unsigned cvt_pk_bf16(float lo, float hi) { unsigned r; asm volatile("v_cvt_pk_bf16_f32 %0, %1, %2" : "=v"(r) : "v"(lo), "v"(hi)); return r; }
; __device__ __forceinline__ float bf_lo(unsigned w) { return __uint_as_float(w << 16); }
; __device__ __forceinline__ float bf_hi(unsigned w) { return __uint_as_float(w & 0xffff0000u); }
; #define LAS __attribute__((address_space(3)))
; __device__ __forceinline__ void sgu_unit(LAS unsigned char* lds, bf16* U, const bf16* VS, const float* SGS, const float* lnw, const float* lnb, const v4u* WF, const float* bsl, int unit, int tid) {
;     ...
;     {
;         int q = 0;
; #pragma unroll
;         for (int mt = 0; mt < 8; ++mt) {
;             const int t = 16 * mt + fr;
;             f32x4 acc[4];
; #pragma unroll
;             for (int nt = 0; nt < 4; ++nt) acc[nt] = (f32x4){0.f, 0.f, 0.f, 0.f};
; #pragma unroll
;             for (int ks = 0; ks <= (mt >> 1); ++ks) {
;                 const int sb = 32 * ks + 8 * fq; const bf16x8_t wf = __builtin_bit_cast(bf16x8_t, wfr[q++]);
; #pragma unroll
;                 for (int nt = 0; nt < 4; ++nt) { const bf16x8_t vf = *(const LAS bf16x8_t*)(vt + ((fr >> 3) + 8 * (fr & 7) + 2 * nt) * SGU_VP + sb * 2);
;                     acc[nt] = __builtin_amdgcn_mfma_f32_16x16x32_bf16(vf, wf, acc[nt], 0, 0, 0); }
;             }
;             const float bb = bbv[mt];
; #pragma unroll
;             for (int nt = 0; nt < 4; ++nt) { const v2u u2 = uu[mt][nt]; v2u w; w.x = cvt_pk_bf16(bf_lo(u2.x) * (acc[nt][0] + bb), bf_hi(u2.x) * (acc[nt][1] + bb)); w.y = cvt_pk_bf16(bf_lo(u2.y) * (acc[nt][2] + bb), bf_hi(u2.y) * (acc[nt][3] + bb));
;                 *(v2u*)(U + (size_t)(r0 + t) * 1024 + colbase + 16 * nt + 4 * fq) = w; }
;         }
;     }
;     __syncthreads();
	v_lshlrev_b32_e32 v22, 16, v96
	v_add_f32_e32 v23, v191, v34
	v_mul_f32_e32 v22, v23, v22
	v_and_b32_e32 v23, 0xffff0000, v96
	v_add_f32_e32 v24, v191, v35
	v_mul_f32_e32 v23, v24, v23
	v_cvt_pk_bf16_f32 v252, v22, v23
	v_lshlrev_b32_e32 v23, 16, v97
	v_add_f32_e32 v24, v191, v36
	v_mul_f32_e32 v23, v24, v23
	v_and_b32_e32 v24, 0xffff0000, v97
	v_add_f32_e32 v25, v191, v37
	v_mul_f32_e32 v24, v25, v24
	v_cvt_pk_bf16_f32 v253, v23, v24
	s_waitcnt vmcnt(17)
	v_lshlrev_b32_e32 v22, 16, v94
	v_add_f32_e32 v18, v191, v18
	v_mul_f32_e32 v18, v18, v22
	v_and_b32_e32 v22, 0xffff0000, v94
	v_add_f32_e32 v19, v191, v19
	v_mul_f32_e32 v19, v19, v22
	v_cvt_pk_bf16_f32 v254, v18, v19
	v_lshlrev_b32_e32 v18, 16, v95
	v_add_f32_e32 v19, v191, v20
	v_mul_f32_e32 v18, v19, v18
	v_and_b32_e32 v19, 0xffff0000, v95
	v_add_f32_e32 v20, v191, v21
	v_mul_f32_e32 v19, v20, v19
	v_cvt_pk_bf16_f32 v255, v18, v19
	ds_read_b128 v[18:21], v182 offset:1024
	ds_read_b128 v[22:25], v182 offset:1088
	ds_read_b128 v[26:29], v182 offset:1568
	ds_read_b128 v[30:33], v182 offset:1632
	ds_read_b128 v[34:37], v182 offset:2112
	ds_read_b128 v[38:41], v182 offset:2176
	ds_read_b128 v[42:45], v182 offset:2656
	ds_read_b128 v[46:49], v182 offset:2720
	s_waitcnt lgkmcnt(7)
	v_mfma_f32_16x16x32_bf16 v[18:21], v[18:21], v[14:17], 0
	s_waitcnt lgkmcnt(5)
	v_mfma_f32_16x16x32_bf16 v[26:29], v[26:29], v[14:17], 0
	s_waitcnt lgkmcnt(3)
	v_mfma_f32_16x16x32_bf16 v[34:37], v[34:37], v[14:17], 0
	s_waitcnt lgkmcnt(1)
	v_mfma_f32_16x16x32_bf16 v[14:17], v[42:45], v[14:17], 0
	v_mfma_f32_16x16x32_bf16 v[18:21], v[22:25], v[10:13], v[18:21]
	v_mfma_f32_16x16x32_bf16 v[22:25], v[30:33], v[10:13], v[26:29]
	v_mfma_f32_16x16x32_bf16 v[26:29], v[38:41], v[10:13], v[34:37]
	s_waitcnt lgkmcnt(0)
	v_mfma_f32_16x16x32_bf16 v[10:13], v[46:49], v[10:13], v[14:17]
	s_nop 2
	ds_read_b128 v[14:17], v182 offset:1152
	ds_read_b128 v[30:33], v182 offset:1216
	s_waitcnt lgkmcnt(1)
	v_mfma_f32_16x16x32_bf16 v[14:17], v[14:17], v[6:9], v[18:21]
	s_nop 2
	ds_read_b128 v[18:21], v182 offset:1696
	ds_read_b128 v[34:37], v182 offset:1760
	s_waitcnt lgkmcnt(1)
	v_mfma_f32_16x16x32_bf16 v[18:21], v[18:21], v[6:9], v[22:25]
	s_nop 2
	ds_read_b128 v[22:25], v182 offset:2240
	ds_read_b128 v[38:41], v182 offset:2304
	s_waitcnt lgkmcnt(1)
	v_mfma_f32_16x16x32_bf16 v[22:25], v[22:25], v[6:9], v[26:29]
	s_nop 2
	ds_read_b128 v[26:29], v182 offset:2784
	ds_read_b128 v[42:45], v182 offset:2848
	s_nop 1
	v_permlane16_swap_b32_e32 v252, v254
	v_permlane16_swap_b32_e32 v253, v255
	global_store_dwordx4 v[238:239], v[252:255], off offset:64
	s_waitcnt lgkmcnt(1)
	v_mfma_f32_16x16x32_bf16 v[6:9], v[26:29], v[6:9], v[10:13]
	v_mfma_f32_16x16x32_bf16 v[10:13], v[30:33], v[2:5], v[14:17]
	v_mfma_f32_16x16x32_bf16 v[14:17], v[34:37], v[2:5], v[18:21]
	v_mfma_f32_16x16x32_bf16 v[18:21], v[38:41], v[2:5], v[22:25]
	s_waitcnt lgkmcnt(0)
	v_mfma_f32_16x16x32_bf16 v[2:5], v[42:45], v[2:5], v[6:9]
	s_waitcnt vmcnt(17)
	s_nop 1
	v_lshlrev_b32_e32 v6, 16, v92
	v_add_f32_e32 v7, v157, v10
	v_mul_f32_e32 v6, v7, v6
	v_and_b32_e32 v7, 0xffff0000, v92
	v_add_f32_e32 v8, v157, v11
	v_mul_f32_e32 v7, v8, v7
	v_cvt_pk_bf16_f32 v248, v6, v7
	v_lshlrev_b32_e32 v7, 16, v93
	v_add_f32_e32 v8, v157, v12
	v_mul_f32_e32 v7, v8, v7
	v_and_b32_e32 v8, 0xffff0000, v93
	v_add_f32_e32 v9, v157, v13
	v_mul_f32_e32 v8, v9, v8
	v_cvt_pk_bf16_f32 v249, v7, v8
	v_lshl_add_u64 v[238:239], v[82:83], 0, v[236:237]
	s_waitcnt vmcnt(16)
	v_lshlrev_b32_e32 v6, 16, v88
	v_add_f32_e32 v7, v157, v14
	v_mul_f32_e32 v6, v7, v6
	v_and_b32_e32 v7, 0xffff0000, v88
	v_add_f32_e32 v8, v157, v15
	v_mul_f32_e32 v7, v8, v7
	v_cvt_pk_bf16_f32 v250, v6, v7
	v_lshlrev_b32_e32 v7, 16, v89
	v_add_f32_e32 v8, v157, v16
	v_mul_f32_e32 v7, v8, v7
	v_and_b32_e32 v8, 0xffff0000, v89
	v_add_f32_e32 v9, v157, v17
	v_mul_f32_e32 v8, v9, v8
	v_cvt_pk_bf16_f32 v251, v7, v8
	s_nop 1
	v_permlane16_swap_b32_e32 v248, v250
	v_permlane16_swap_b32_e32 v249, v251
	global_store_dwordx4 v[238:239], v[248:251], off
	s_waitcnt vmcnt(16)
	v_lshlrev_b32_e32 v6, 16, v86
	v_add_f32_e32 v7, v157, v18
	v_mul_f32_e32 v6, v7, v6
	v_and_b32_e32 v7, 0xffff0000, v86
	v_add_f32_e32 v8, v157, v19
	v_mul_f32_e32 v7, v8, v7
	v_cvt_pk_bf16_f32 v252, v6, v7
	v_lshlrev_b32_e32 v7, 16, v87
	v_add_f32_e32 v8, v157, v20
	v_mul_f32_e32 v7, v8, v7
	v_and_b32_e32 v8, 0xffff0000, v87
	v_add_f32_e32 v9, v157, v21
	v_mul_f32_e32 v8, v9, v8
	v_cvt_pk_bf16_f32 v253, v7, v8
	s_waitcnt vmcnt(15)
	v_lshlrev_b32_e32 v6, 16, v84
	v_add_f32_e32 v2, v157, v2
	v_mul_f32_e32 v2, v2, v6
	v_and_b32_e32 v6, 0xffff0000, v84
	v_add_f32_e32 v3, v157, v3
	v_mul_f32_e32 v3, v3, v6
	v_cvt_pk_bf16_f32 v254, v2, v3
	v_lshlrev_b32_e32 v3, 16, v85
	v_add_f32_e32 v4, v157, v4
	v_mul_f32_e32 v3, v4, v3
	v_and_b32_e32 v4, 0xffff0000, v85
	v_add_f32_e32 v5, v157, v5
	v_mul_f32_e32 v4, v5, v4
	v_cvt_pk_bf16_f32 v255, v3, v4
	s_nop 1
	v_permlane16_swap_b32_e32 v252, v254
	v_permlane16_swap_b32_e32 v253, v255
	global_store_dwordx4 v[238:239], v[252:255], off offset:64
	s_barrier

; __device__ __forceinline__ float bf_lo(unsigned w) { return __uint_as_float(w << 16); }
; __device__ __forceinline__ float bf_hi(unsigned w) { return __uint_as_float(w & 0xffff0000u); }
;     __device__ __forceinline__ void fused(f32x4 (&acc)[2][2][4][2], const Unit& u, int wr, int wc, int fr, int fq, PG8_LAS unsigned char* lds, int wid, int lane) const {
;     ...
;         const int col0 = u.pn * BM + wc * 32 + 8 * fq, b = u.pm >> 4;
;         {
;             f32x4 gv[2][2];
; #pragma unroll
;             for (int bj = 0; bj < 2; ++bj)
; #pragma unroll
;                 for (int n = 0; n < 2; ++n) gv[bj][n] = *(const f32x4*)(g + (size_t)b * 6144 + col0 + bj * HALF + 4 * n);
; #pragma unroll
;             for (int ai = 0; ai < 2; ++ai)
; #pragma unroll
;                 for (int m = 0; m < 4; ++m) { const int r = ai * HALF + wr * 64 + m * 16 + fr; const size_t off = (size_t)(u.pm * BM + r) * 1024 + col0;
; #pragma unroll
;                     for (int bj = 0; bj < 2; ++bj) { f32x4 b0, b1;
;                         if (XIN_BF16) { const u32x4 w = *(const u32x4*)((const bf16_t*)xin + off + bj * HALF); b0 = (f32x4){bf_lo(w.x), bf_hi(w.x), bf_lo(w.y), bf_hi(w.y)}; b1 = (f32x4){bf_lo(w.z), bf_hi(w.z), bf_lo(w.w), bf_hi(w.w)}; }
;                         else { b0 = *(const f32x4*)((const float*)xin + off + bj * HALF); b1 = *(const f32x4*)((const float*)xin + off + bj * HALF + 4); }
;                         acc[ai][bj][m][0] = b0 + gv[bj][0] * acc[ai][bj][m][0]; acc[ai][bj][m][1] = b1 + gv[bj][1] * acc[ai][bj][m][1]; }
;                     asm volatile("" : "+v"(acc[ai][0][m][0]), "+v"(acc[ai][0][m][1]), "+v"(acc[ai][1][m][0]), "+v"(acc[ai][1][m][1]));
;                     if (m == 3) asm volatile("" ::: "memory"); }
.LBB0_1635:
	s_lshl_b32 s6, s19, 5
	s_lshl_b32 s7, s10, 8
	v_lshrrev_b32_e32 v130, 1, v168
	s_or_b32 s6, s7, s6
	v_and_or_b32 v156, v130, 24, s6
	s_ashr_i32 s6, s18, 4
	s_mul_i32 s34, s6, 0x6000
	s_mul_hi_i32 s25, s6, 0x6000
	s_add_u32 s6, s14, s34
	s_addc_u32 s7, s15, s25
	s_lshl_b32 s28, s18, 8
	v_add_u32_e32 v164, s28, v166
	v_ashrrev_i32_e32 v165, 31, v164
	v_ashrrev_i32_e32 v157, 31, v156
	v_lshlrev_b64 v[150:151], 11, v[164:165]
	v_lshl_add_u64 v[130:131], s[12:13], 0, v[150:151]
	v_lshlrev_b64 v[146:147], 1, v[156:157]
	v_lshl_add_u64 v[130:131], v[130:131], 0, v[146:147]
	v_lshl_add_u64 v[132:133], v[156:157], 2, s[6:7]
	s_mov_b32 s8, 0x1a000
	s_barrier
	s_mov_b64 s[98:99], 0x8000
	v_lshl_add_u64 v[244:245], v[130:131], 0, s[98:99]
	global_load_dwordx4 v[196:199], v[244:245], off nt
	global_load_dwordx4 v[200:203], v[244:245], off offset:256 nt
	s_mov_b64 s[98:99], 0x10000
	v_lshl_add_u64 v[244:245], v[130:131], 0, s[98:99]
	global_load_dwordx4 v[204:207], v[244:245], off nt
	global_load_dwordx4 v[208:211], v[244:245], off offset:256 nt
	s_mov_b64 s[98:99], 0x18000
	v_lshl_add_u64 v[244:245], v[130:131], 0, s[98:99]
	global_load_dwordx4 v[212:215], v[244:245], off nt
	global_load_dwordx4 v[216:219], v[244:245], off offset:256 nt
	s_mov_b64 s[98:99], 0x40000
	v_lshl_add_u64 v[244:245], v[130:131], 0, s[98:99]
	global_load_dwordx4 v[220:223], v[244:245], off nt
	global_load_dwordx4 v[224:227], v[244:245], off offset:256 nt
	s_mov_b64 s[98:99], 0x48000
	v_lshl_add_u64 v[244:245], v[130:131], 0, s[98:99]
	global_load_dwordx4 v[228:231], v[244:245], off nt
	global_load_dwordx4 v[232:235], v[244:245], off offset:256 nt
	s_mov_b64 s[98:99], 0x50000
	v_lshl_add_u64 v[244:245], v[130:131], 0, s[98:99]
	global_load_dwordx4 v[236:239], v[244:245], off nt
	global_load_dwordx4 v[240:243], v[244:245], off offset:256 nt
	s_mov_b64 s[98:99], 0x58000
	v_lshl_add_u64 v[244:245], v[130:131], 0, s[98:99]
	global_load_dwordx4 v[248:251], v[244:245], off nt
	global_load_dwordx4 v[252:255], v[244:245], off offset:256 nt
	global_load_dwordx4 v[152:155], v[130:131], off nt
	global_load_dwordx4 v[158:161], v[130:131], off offset:256 nt
	v_add_co_u32_e32 v130, vcc, s8, v132
	s_mov_b64 s[6:7], 0x1a000
	s_nop 0
	v_addc_co_u32_e32 v131, vcc, 0, v133, vcc
	global_load_dwordx4 v[138:141], v[130:131], off nt
	v_lshl_add_u64 v[130:131], v[132:133], 0, s[6:7]
	global_load_dwordx4 v[142:145], v[130:131], off offset:16 nt
	global_load_dwordx4 v[134:137], v[130:131], off offset:512 nt
	s_nop 0
	global_load_dwordx4 v[130:133], v[130:131], off offset:528 nt
	v_add_u32_e32 v148, 16, v164
	v_ashrrev_i32_e32 v149, 31, v148
	v_lshlrev_b64 v[148:149], 11, v[148:149]
	v_lshl_add_u64 v[162:163], s[12:13], 0, v[148:149]
	v_lshl_add_u64 v[162:163], v[162:163], 0, v[146:147]
	v_mbcnt_hi_u32_b32 v192, -1, v1
	v_and_b32_e32 v169, 64, v192
	v_xor_b32_e32 v165, 16, v192
	v_add_u32_e32 v193, 64, v169
	v_cmp_lt_i32_e32 vcc, v165, v193
	s_lshl_b32 s6, s19, 3
	s_add_i32 s8, s6, 0
	v_cndmask_b32_e32 v165, v192, v165, vcc
	v_lshlrev_b32_e32 v169, 2, v165
	s_waitcnt vmcnt(0)
	v_lshlrev_b32_e32 v170, 16, v152
	v_and_b32_e32 v171, 0xffff0000, v152
	v_lshlrev_b32_e32 v152, 16, v153
	v_and_b32_e32 v153, 0xffff0000, v153
	v_lshlrev_b32_e32 v172, 16, v154
	v_and_b32_e32 v173, 0xffff0000, v154
	v_lshlrev_b32_e32 v154, 16, v155
	v_and_b32_e32 v155, 0xffff0000, v155
	v_lshlrev_b32_e32 v174, 16, v158
	v_and_b32_e32 v175, 0xffff0000, v158
	v_lshlrev_b32_e32 v158, 16, v159
	v_and_b32_e32 v159, 0xffff0000, v159
	v_lshlrev_b32_e32 v176, 16, v160
	v_and_b32_e32 v177, 0xffff0000, v160
	v_lshlrev_b32_e32 v160, 16, v161
	v_and_b32_e32 v161, 0xffff0000, v161
	v_pk_fma_f32 v[58:59], v[58:59], v[138:139], v[170:171]
	v_pk_fma_f32 v[60:61], v[60:61], v[140:141], v[152:153]
	v_pk_fma_f32 v[64:65], v[64:65], v[144:145], v[154:155]
	v_pk_fma_f32 v[62:63], v[62:63], v[142:143], v[172:173]
	v_pk_fma_f32 v[56:57], v[56:57], v[136:137], v[158:159]
	v_pk_fma_f32 v[54:55], v[54:55], v[134:135], v[174:175]
	v_pk_fma_f32 v[48:49], v[48:49], v[132:133], v[160:161]
	v_pk_fma_f32 v[46:47], v[46:47], v[130:131], v[176:177]
	v_add_u32_e32 v152, 32, v164
	v_mov_b32_e32 v158, v196
	v_mov_b32_e32 v159, v197
	v_mov_b32_e32 v160, v198
	v_mov_b32_e32 v161, v199
	v_mov_b32_e32 v170, v200
	v_mov_b32_e32 v171, v201
	v_mov_b32_e32 v172, v202
	v_mov_b32_e32 v173, v203
	v_ashrrev_i32_e32 v153, 31, v152
	v_lshlrev_b64 v[152:153], 11, v[152:153]
	v_lshl_add_u64 v[154:155], s[12:13], 0, v[152:153]
	v_lshl_add_u64 v[154:155], v[154:155], 0, v[146:147]
	s_waitcnt vmcnt(1)
	v_lshlrev_b32_e32 v162, 16, v158
	v_and_b32_e32 v163, 0xffff0000, v158
	v_lshlrev_b32_e32 v158, 16, v159
	v_and_b32_e32 v159, 0xffff0000, v159
	v_lshlrev_b32_e32 v174, 16, v160
	v_and_b32_e32 v175, 0xffff0000, v160
	v_lshlrev_b32_e32 v160, 16, v161
	v_and_b32_e32 v161, 0xffff0000, v161
	s_waitcnt vmcnt(0)
	v_lshlrev_b32_e32 v176, 16, v170
	v_and_b32_e32 v177, 0xffff0000, v170
	v_lshlrev_b32_e32 v170, 16, v171
	v_and_b32_e32 v171, 0xffff0000, v171
	v_lshlrev_b32_e32 v178, 16, v172
	v_and_b32_e32 v179, 0xffff0000, v172
	v_lshlrev_b32_e32 v172, 16, v173
	v_and_b32_e32 v173, 0xffff0000, v173
	v_pk_fma_f32 v[80:81], v[80:81], v[140:141], v[158:159]
	v_pk_fma_f32 v[78:79], v[78:79], v[138:139], v[162:163]
	v_pk_fma_f32 v[72:73], v[72:73], v[144:145], v[160:161]
	v_pk_fma_f32 v[70:71], v[70:71], v[142:143], v[174:175]
	v_pk_fma_f32 v[52:53], v[52:53], v[136:137], v[170:171]
	v_pk_fma_f32 v[50:51], v[50:51], v[134:135], v[176:177]
	v_pk_fma_f32 v[44:45], v[44:45], v[132:133], v[172:173]
	v_pk_fma_f32 v[42:43], v[42:43], v[130:131], v[178:179]
	s_nop 0
	v_mov_b32_e32 v158, v204
	v_mov_b32_e32 v159, v205
	v_mov_b32_e32 v160, v206
	v_mov_b32_e32 v161, v207
	v_mov_b32_e32 v170, v208
	v_mov_b32_e32 v171, v209
	v_mov_b32_e32 v172, v210
	v_mov_b32_e32 v173, v211
	v_add_u32_e32 v154, 48, v164
	v_ashrrev_i32_e32 v155, 31, v154
	v_lshlrev_b64 v[154:155], 11, v[154:155]
	v_lshl_add_u64 v[162:163], s[12:13], 0, v[154:155]
	v_lshl_add_u64 v[174:175], v[162:163], 0, v[146:147]
	s_waitcnt vmcnt(1)
; __device__ __forceinline__ float bf_lo(unsigned w) { return __uint_as_float(w << 16); }
; __device__ __forceinline__ float bf_hi(unsigned w) { return __uint_as_float(w & 0xffff0000u); }
;     __device__ __forceinline__ void fused(f32x4 (&acc)[2][2][4][2], const Unit& u, int wr, int wc, int fr, int fq, PG8_LAS unsigned char* lds, int wid, int lane) const {
;     ...
; #pragma unroll
;             for (int ai = 0; ai < 2; ++ai)
; #pragma unroll
;                 for (int m = 0; m < 4; ++m) { const int r = ai * HALF + wr * 64 + m * 16 + fr; const size_t off = (size_t)(u.pm * BM + r) * 1024 + col0;
; #pragma unroll
;                     for (int bj = 0; bj < 2; ++bj) { f32x4 b0, b1;
;                         if (XIN_BF16) { const u32x4 w = *(const u32x4*)((const bf16_t*)xin + off + bj * HALF); b0 = (f32x4){bf_lo(w.x), bf_hi(w.x), bf_lo(w.y), bf_hi(w.y)}; b1 = (f32x4){bf_lo(w.z), bf_hi(w.z), bf_lo(w.w), bf_hi(w.w)}; }
;                         else { b0 = *(const f32x4*)((const float*)xin + off + bj * HALF); b1 = *(const f32x4*)((const float*)xin + off + bj * HALF + 4); }
;                         acc[ai][bj][m][0] = b0 + gv[bj][0] * acc[ai][bj][m][0]; acc[ai][bj][m][1] = b1 + gv[bj][1] * acc[ai][bj][m][1]; }
;                     asm volatile("" : "+v"(acc[ai][0][m][0]), "+v"(acc[ai][0][m][1]), "+v"(acc[ai][1][m][0]), "+v"(acc[ai][1][m][1]));
;                     if (m == 3) asm volatile("" ::: "memory"); }
	v_lshlrev_b32_e32 v162, 16, v158
	v_and_b32_e32 v163, 0xffff0000, v158
	v_lshlrev_b32_e32 v158, 16, v159
	v_and_b32_e32 v159, 0xffff0000, v159
	v_lshlrev_b32_e32 v176, 16, v160
	v_and_b32_e32 v177, 0xffff0000, v160
	v_lshlrev_b32_e32 v160, 16, v161
	v_and_b32_e32 v161, 0xffff0000, v161
	s_waitcnt vmcnt(0)
	v_lshlrev_b32_e32 v178, 16, v170
	v_and_b32_e32 v179, 0xffff0000, v170
	v_lshlrev_b32_e32 v170, 16, v171
	v_and_b32_e32 v171, 0xffff0000, v171
	v_lshlrev_b32_e32 v180, 16, v172
	v_and_b32_e32 v181, 0xffff0000, v172
	v_lshlrev_b32_e32 v172, 16, v173
	v_and_b32_e32 v173, 0xffff0000, v173
	v_pk_fma_f32 v[100:101], v[100:101], v[140:141], v[158:159]
	v_pk_fma_f32 v[98:99], v[98:99], v[138:139], v[162:163]
	v_pk_fma_f32 v[92:93], v[92:93], v[144:145], v[160:161]
	v_pk_fma_f32 v[90:91], v[90:91], v[142:143], v[176:177]
	v_pk_fma_f32 v[76:77], v[76:77], v[136:137], v[170:171]
	v_pk_fma_f32 v[74:75], v[74:75], v[134:135], v[178:179]
	v_pk_fma_f32 v[68:69], v[68:69], v[132:133], v[172:173]
	v_pk_fma_f32 v[66:67], v[66:67], v[130:131], v[180:181]
	v_add_u32_e32 v158, 0x80, v164
	v_mov_b32_e32 v160, v212
	v_mov_b32_e32 v161, v213
	v_mov_b32_e32 v162, v214
	v_mov_b32_e32 v163, v215
	v_mov_b32_e32 v170, v216
	v_mov_b32_e32 v171, v217
	v_mov_b32_e32 v172, v218
	v_mov_b32_e32 v173, v219
	v_ashrrev_i32_e32 v159, 31, v158
	v_lshlrev_b64 v[158:159], 11, v[158:159]
	v_lshl_add_u64 v[174:175], s[12:13], 0, v[158:159]
	v_lshl_add_u64 v[174:175], v[174:175], 0, v[146:147]
	s_waitcnt vmcnt(1)
	v_lshlrev_b32_e32 v176, 16, v160
	v_and_b32_e32 v177, 0xffff0000, v160
	v_lshlrev_b32_e32 v160, 16, v161
	v_and_b32_e32 v161, 0xffff0000, v161
	v_lshlrev_b32_e32 v178, 16, v162
	v_and_b32_e32 v179, 0xffff0000, v162
	v_lshlrev_b32_e32 v162, 16, v163
	v_and_b32_e32 v163, 0xffff0000, v163
	s_waitcnt vmcnt(0)
	v_lshlrev_b32_e32 v180, 16, v170
	v_and_b32_e32 v181, 0xffff0000, v170
	v_lshlrev_b32_e32 v170, 16, v171
	v_and_b32_e32 v171, 0xffff0000, v171
	v_lshlrev_b32_e32 v182, 16, v172
	v_and_b32_e32 v183, 0xffff0000, v172
	v_lshlrev_b32_e32 v172, 16, v173
	v_and_b32_e32 v173, 0xffff0000, v173
	v_pk_fma_f32 v[116:117], v[116:117], v[140:141], v[160:161]
	v_pk_fma_f32 v[114:115], v[114:115], v[138:139], v[176:177]
	v_pk_fma_f32 v[108:109], v[108:109], v[144:145], v[162:163]
	v_pk_fma_f32 v[106:107], v[106:107], v[142:143], v[178:179]
	v_pk_fma_f32 v[104:105], v[104:105], v[136:137], v[170:171]
	v_pk_fma_f32 v[102:103], v[102:103], v[134:135], v[180:181]
	v_pk_fma_f32 v[96:97], v[96:97], v[132:133], v[172:173]
	v_pk_fma_f32 v[94:95], v[94:95], v[130:131], v[182:183]
	v_add_u32_e32 v160, 0x90, v164
	v_mov_b32_e32 v170, v220
	v_mov_b32_e32 v171, v221
	v_mov_b32_e32 v172, v222
	v_mov_b32_e32 v173, v223
	s_nop 0
	v_mov_b32_e32 v174, v224
	v_mov_b32_e32 v175, v225
	v_mov_b32_e32 v176, v226
	v_mov_b32_e32 v177, v227
	v_ashrrev_i32_e32 v161, 31, v160
	v_lshlrev_b64 v[160:161], 11, v[160:161]
	v_lshl_add_u64 v[162:163], s[12:13], 0, v[160:161]
	v_lshl_add_u64 v[162:163], v[162:163], 0, v[146:147]
	s_waitcnt vmcnt(1)
	v_lshlrev_b32_e32 v178, 16, v170
	v_and_b32_e32 v179, 0xffff0000, v170
	v_lshlrev_b32_e32 v170, 16, v171
	v_and_b32_e32 v171, 0xffff0000, v171
	v_lshlrev_b32_e32 v180, 16, v172
	v_and_b32_e32 v181, 0xffff0000, v172
	v_lshlrev_b32_e32 v172, 16, v173
	v_and_b32_e32 v173, 0xffff0000, v173
	s_waitcnt vmcnt(0)
	v_lshlrev_b32_e32 v182, 16, v174
	v_and_b32_e32 v183, 0xffff0000, v174
	v_lshlrev_b32_e32 v174, 16, v175
	v_and_b32_e32 v175, 0xffff0000, v175
	v_lshlrev_b32_e32 v184, 16, v176
	v_and_b32_e32 v185, 0xffff0000, v176
	v_lshlrev_b32_e32 v176, 16, v177
	v_and_b32_e32 v177, 0xffff0000, v177
	v_pk_fma_f32 v[128:129], v[128:129], v[140:141], v[170:171]
	v_pk_fma_f32 v[126:127], v[126:127], v[138:139], v[178:179]
	v_pk_fma_f32 v[124:125], v[124:125], v[144:145], v[172:173]
	v_pk_fma_f32 v[122:123], v[122:123], v[142:143], v[180:181]
	v_pk_fma_f32 v[120:121], v[120:121], v[136:137], v[174:175]
	v_pk_fma_f32 v[118:119], v[118:119], v[134:135], v[182:183]
	v_pk_fma_f32 v[112:113], v[112:113], v[132:133], v[176:177]
	v_pk_fma_f32 v[110:111], v[110:111], v[130:131], v[184:185]
	s_nop 0
	v_mov_b32_e32 v170, v228
	v_mov_b32_e32 v171, v229
	v_mov_b32_e32 v172, v230
	v_mov_b32_e32 v173, v231
	v_mov_b32_e32 v174, v232
	v_mov_b32_e32 v175, v233
	v_mov_b32_e32 v176, v234
	v_mov_b32_e32 v177, v235
	v_add_u32_e32 v162, 0xa0, v164
	v_ashrrev_i32_e32 v163, 31, v162
	v_lshlrev_b64 v[162:163], 11, v[162:163]
	v_lshl_add_u64 v[178:179], s[12:13], 0, v[162:163]
	v_lshl_add_u64 v[178:179], v[178:179], 0, v[146:147]
	v_add_u32_e32 v164, 0xb0, v164
	v_ashrrev_i32_e32 v165, 31, v164
	v_lshlrev_b64 v[164:165], 11, v[164:165]
	s_waitcnt vmcnt(1)
	v_lshlrev_b32_e32 v180, 16, v170
	v_and_b32_e32 v181, 0xffff0000, v170
	v_lshlrev_b32_e32 v170, 16, v171
	v_and_b32_e32 v171, 0xffff0000, v171
	v_lshlrev_b32_e32 v182, 16, v172
	v_and_b32_e32 v183, 0xffff0000, v172
	v_lshlrev_b32_e32 v172, 16, v173
	v_and_b32_e32 v173, 0xffff0000, v173
	s_waitcnt vmcnt(0)
	v_lshlrev_b32_e32 v184, 16, v174
	v_and_b32_e32 v185, 0xffff0000, v174
	v_lshlrev_b32_e32 v174, 16, v175
	v_and_b32_e32 v175, 0xffff0000, v175
	v_lshlrev_b32_e32 v186, 16, v176
	v_and_b32_e32 v187, 0xffff0000, v176
	v_lshlrev_b32_e32 v176, 16, v177
	v_and_b32_e32 v177, 0xffff0000, v177
	v_pk_fma_f32 v[88:89], v[88:89], v[140:141], v[170:171]
	v_pk_fma_f32 v[86:87], v[86:87], v[138:139], v[180:181]
	v_pk_fma_f32 v[84:85], v[84:85], v[144:145], v[172:173]
	v_pk_fma_f32 v[82:83], v[82:83], v[142:143], v[182:183]
	v_pk_fma_f32 v[40:41], v[40:41], v[136:137], v[174:175]
	v_pk_fma_f32 v[38:39], v[38:39], v[134:135], v[184:185]
	v_pk_fma_f32 v[36:37], v[36:37], v[132:133], v[176:177]
	v_pk_fma_f32 v[34:35], v[34:35], v[130:131], v[186:187]
	v_mov_b32_e32 v184, v59
	v_mov_b32_e32 v170, v236
	v_mov_b32_e32 v171, v237
	v_mov_b32_e32 v172, v238
	v_mov_b32_e32 v173, v239
	v_mov_b32_e32 v174, v240
	v_mov_b32_e32 v175, v241
	v_mov_b32_e32 v176, v242
	v_mov_b32_e32 v177, v243
	v_lshl_add_u64 v[178:179], s[12:13], 0, v[164:165]
	v_lshl_add_u64 v[180:181], v[178:179], 0, v[146:147]
	v_mov_b32_e32 v185, v60
	v_mov_b32_e32 v186, v58
	v_mov_b32_e32 v187, v61
	v_pk_add_f32 v[184:185], v[184:185], v[186:187]
	s_waitcnt vmcnt(1)
;     template <class Mid> __device__ __forceinline__ bool run(const f32x4 (&v)[2][2][4][2], const Unit& u, int wr, int wc, int fr, int fq, PG8_LAS unsigned char* lds, int wid, int lane, const Mid& mid) const {
;     ...
; #pragma unroll
;         for (int ai = 0; ai < 2; ++ai)
; #pragma unroll
;             for (int m = 0; m < 4; ++m) {
;                 float s = 0.f;
; #pragma unroll
;                 for (int bj = 0; bj < 2; ++bj)
; #pragma unroll
;                     for (int n = 0; n < 2; ++n) { const f32x4 x = v[ai][bj][m][n]; s += (x[0] + x[1]) + (x[2] + x[3]); }
;                 s += __shfl_xor(s, 16); s += __shfl_xor(s, 32);
;                 const float mw = s * (1.0f / 64.0f); float q = 0.f;
; #pragma unroll
;                 for (int bj = 0; bj < 2; ++bj)
; #pragma unroll
;                     for (int n = 0; n < 2; ++n) { const f32x4 d = v[ai][bj][m][n] - mw; q += (d[0] * d[0] + d[1] * d[1]) + (d[2] * d[2] + d[3] * d[3]); }
;                 q += __shfl_xor(q, 16); q += __shfl_xor(q, 32);
;                 if (fq == 0) P[(ai * HALF + wr * 64 + m * 16 + fr) * 4 + wc] = (f32x2v){mw, q};
;     __device__ __forceinline__ void fused(f32x4 (&acc)[2][2][4][2], const Unit& u, int wr, int wc, int fr, int fq, PG8_LAS unsigned char* lds, int wid, int lane) const {
;     ...
; #pragma unroll
;             for (int ai = 0; ai < 2; ++ai)
; #pragma unroll
;                 for (int m = 0; m < 4; ++m) { const int r = ai * HALF + wr * 64 + m * 16 + fr; const size_t off = (size_t)(u.pm * BM + r) * 1024 + col0;
; #pragma unroll
;                     for (int bj = 0; bj < 2; ++bj) { f32x4 b0, b1;
;                         if (XIN_BF16) { const u32x4 w = *(const u32x4*)((const bf16_t*)xin + off + bj * HALF); b0 = (f32x4){bf_lo(w.x), bf_hi(w.x), bf_lo(w.y), bf_hi(w.y)}; b1 = (f32x4){bf_lo(w.z), bf_hi(w.z), bf_lo(w.w), bf_hi(w.w)}; }
;                         else { b0 = *(const f32x4*)((const float*)xin + off + bj * HALF); b1 = *(const f32x4*)((const float*)xin + off + bj * HALF + 4); }
;                         acc[ai][bj][m][0] = b0 + gv[bj][0] * acc[ai][bj][m][0]; acc[ai][bj][m][1] = b1 + gv[bj][1] * acc[ai][bj][m][1]; }
;                     asm volatile("" : "+v"(acc[ai][0][m][0]), "+v"(acc[ai][0][m][1]), "+v"(acc[ai][1][m][0]), "+v"(acc[ai][1][m][1]));
;                     if (m == 3) asm volatile("" ::: "memory"); }
	v_lshlrev_b32_e32 v178, 16, v170
	v_and_b32_e32 v179, 0xffff0000, v170
	v_lshlrev_b32_e32 v170, 16, v171
	v_and_b32_e32 v171, 0xffff0000, v171
	v_lshlrev_b32_e32 v182, 16, v172
	v_and_b32_e32 v183, 0xffff0000, v172
	v_lshlrev_b32_e32 v172, 16, v173
	v_and_b32_e32 v173, 0xffff0000, v173
	s_waitcnt vmcnt(0)
	v_lshlrev_b32_e32 v188, 16, v174
	v_and_b32_e32 v189, 0xffff0000, v174
	v_lshlrev_b32_e32 v174, 16, v175
	v_and_b32_e32 v175, 0xffff0000, v175
	v_lshlrev_b32_e32 v190, 16, v176
	v_and_b32_e32 v191, 0xffff0000, v176
	v_lshlrev_b32_e32 v176, 16, v177
	v_and_b32_e32 v177, 0xffff0000, v177
	v_pk_fma_f32 v[32:33], v[32:33], v[140:141], v[170:171]
	v_pk_fma_f32 v[30:31], v[30:31], v[138:139], v[178:179]
	v_pk_fma_f32 v[28:29], v[28:29], v[144:145], v[172:173]
	v_pk_fma_f32 v[26:27], v[26:27], v[142:143], v[182:183]
	v_pk_fma_f32 v[24:25], v[24:25], v[136:137], v[174:175]
	v_pk_fma_f32 v[22:23], v[22:23], v[134:135], v[188:189]
	v_pk_fma_f32 v[20:21], v[20:21], v[132:133], v[176:177]
	v_pk_fma_f32 v[18:19], v[18:19], v[130:131], v[190:191]
	v_mov_b32_e32 v170, v63
	v_mov_b32_e32 v176, v248
	v_mov_b32_e32 v177, v249
	v_mov_b32_e32 v178, v250
	v_mov_b32_e32 v179, v251
	v_mov_b32_e32 v171, v64
	v_mov_b32_e32 v180, v252
	v_mov_b32_e32 v181, v253
	v_mov_b32_e32 v182, v254
	v_mov_b32_e32 v183, v255
	v_mov_b32_e32 v172, v62
	v_mov_b32_e32 v173, v65
	v_add_f32_e32 v175, v54, v55
	v_add_f32_e32 v189, v56, v57
	v_mov_b32_e32 v174, v46
	v_mov_b32_e32 v188, v47
	v_pk_add_f32 v[170:171], v[170:171], v[172:173]
	v_pk_add_f32 v[172:173], v[174:175], v[188:189]
	v_add_f32_e32 v174, v184, v185
	v_pk_add_f32 v[170:171], v[170:171], v[170:171] op_sel_hi:[0,1]
	v_mov_b32_e32 v190, v49
	v_add_f32_e32 v191, 0, v174
	v_mov_b32_e32 v170, v48
	v_pk_add_f32 v[170:171], v[170:171], v[190:191]
	s_nop 0
	v_pk_add_f32 v[170:171], v[172:173], v[170:171]
	s_nop 0
	v_add_f32_e32 v170, v170, v171
	ds_bpermute_b32 v172, v169, v170
	v_xor_b32_e32 v171, 32, v192
	v_cmp_lt_i32_e32 vcc, v171, v193
	s_waitcnt lgkmcnt(0)
	v_add_f32_e32 v170, v170, v172
	v_cndmask_b32_e32 v171, v192, v171, vcc
	v_lshlrev_b32_e32 v171, 2, v171
	ds_bpermute_b32 v172, v171, v170
	s_waitcnt lgkmcnt(0)
	v_add_f32_e32 v172, v170, v172
	v_fmamk_f32 v173, v172, 0xbc800000, v61
	v_fmamk_f32 v175, v172, 0xbc800000, v59
	v_fmamk_f32 v185, v172, 0xbc800000, v65
	v_fmamk_f32 v187, v172, 0xbc800000, v63
	v_fmamk_f32 v170, v172, 0xbc800000, v60
	v_fmamk_f32 v174, v172, 0xbc800000, v58
	v_fmamk_f32 v184, v172, 0xbc800000, v64
	v_fmamk_f32 v186, v172, 0xbc800000, v62
	v_fmamk_f32 v189, v172, 0xbc800000, v57
	v_fmamk_f32 v191, v172, 0xbc800000, v55
	v_mul_f32_e32 v175, v175, v175
	v_mul_f32_e32 v173, v173, v173
	v_mul_f32_e32 v187, v187, v187
	v_mul_f32_e32 v185, v185, v185
	v_fmamk_f32 v188, v172, 0xbc800000, v56
	v_fmamk_f32 v190, v172, 0xbc800000, v54
	v_fmamk_f32 v193, v172, 0xbc800000, v49
	v_fmamk_f32 v195, v172, 0xbc800000, v47
	v_mul_f32_e32 v191, v191, v191
	v_mul_f32_e32 v189, v189, v189
	v_fmac_f32_e32 v175, v174, v174
	v_fmac_f32_e32 v173, v170, v170
	v_fmac_f32_e32 v187, v186, v186
	v_fmac_f32_e32 v185, v184, v184
	v_fmamk_f32 v192, v172, 0xbc800000, v48
	v_fmamk_f32 v194, v172, 0xbc800000, v46
	v_mul_f32_e32 v195, v195, v195
	v_mul_f32_e32 v193, v193, v193
	v_fmac_f32_e32 v191, v190, v190
	v_fmac_f32_e32 v189, v188, v188
	v_add_f32_e32 v170, v175, v173
	v_add_f32_e32 v173, v187, v185
	v_fmac_f32_e32 v195, v194, v194
	v_fmac_f32_e32 v193, v192, v192
	v_add_f32_e32 v174, v191, v189
	v_add_f32_e32 v170, v170, v173
	v_add_f32_e32 v175, v195, v193
	v_add_f32_e32 v170, v174, v170
	v_add_f32_e32 v173, v175, v170
	ds_bpermute_b32 v174, v169, v173
	v_and_b32_e32 v170, 63, v168
	v_cmp_gt_u32_e32 vcc, 16, v170
	s_waitcnt lgkmcnt(0)
	v_add_f32_e32 v173, v173, v174
	ds_bpermute_b32 v174, v171, v173
	s_waitcnt vmcnt(1)
	v_lshlrev_b32_e32 v184, 16, v176
	v_and_b32_e32 v185, 0xffff0000, v176
	v_lshlrev_b32_e32 v176, 16, v177
	v_and_b32_e32 v177, 0xffff0000, v177
	v_lshlrev_b32_e32 v186, 16, v178
	v_and_b32_e32 v187, 0xffff0000, v178
	v_lshlrev_b32_e32 v178, 16, v179
	v_and_b32_e32 v179, 0xffff0000, v179
	s_waitcnt vmcnt(0)
	v_lshlrev_b32_e32 v188, 16, v180
	v_and_b32_e32 v189, 0xffff0000, v180
	v_lshlrev_b32_e32 v180, 16, v181
	v_and_b32_e32 v181, 0xffff0000, v181
	v_lshlrev_b32_e32 v190, 16, v182
	v_and_b32_e32 v191, 0xffff0000, v182
	v_lshlrev_b32_e32 v182, 16, v183
	v_and_b32_e32 v183, 0xffff0000, v183
	v_pk_fma_f32 v[16:17], v[16:17], v[140:141], v[176:177]
	v_pk_fma_f32 v[14:15], v[14:15], v[138:139], v[184:185]
	v_pk_fma_f32 v[12:13], v[12:13], v[144:145], v[178:179]
	v_pk_fma_f32 v[10:11], v[10:11], v[142:143], v[186:187]
	v_pk_fma_f32 v[8:9], v[8:9], v[136:137], v[180:181]
	v_pk_fma_f32 v[6:7], v[6:7], v[134:135], v[188:189]
	v_pk_fma_f32 v[4:5], v[4:5], v[132:133], v[182:183]
	v_pk_fma_f32 v[2:3], v[2:3], v[130:131], v[190:191]
	s_nop 0
	s_and_saveexec_b64 s[6:7], vcc
	s_cbranch_execz .LBB0_1637
	s_lshl_b32 s9, s24, 11
	s_add_i32 s9, s8, s9
	v_mul_f32_e32 v130, 0x3c800000, v172
	s_waitcnt lgkmcnt(0)
	v_add_f32_e32 v131, v173, v174
	v_lshl_add_u32 v132, v167, 5, s9
	ds_write_b64 v132, v[130:131]

; __device__ __forceinline__ float bf_lo(unsigned w) { return __uint_as_float(w << 16); }
; __device__ __forceinline__ float bf_hi(unsigned w) { return __uint_as_float(w & 0xffff0000u); }
;     __device__ __forceinline__ void fused(f32x4 (&acc)[2][2][4][2], const Unit& u, int wr, int wc, int fr, int fq, PG8_LAS unsigned char* lds, int wid, int lane) const {
;     ...
;         const int col0 = u.pn * BM + wc * 32 + 8 * fq, b = u.pm >> 4;
;         {
;             f32x4 gv[2][2];
; #pragma unroll
;             for (int bj = 0; bj < 2; ++bj)
; #pragma unroll
;                 for (int n = 0; n < 2; ++n) gv[bj][n] = *(const f32x4*)(g + (size_t)b * 6144 + col0 + bj * HALF + 4 * n);
; #pragma unroll
;             for (int ai = 0; ai < 2; ++ai)
; #pragma unroll
;                 for (int m = 0; m < 4; ++m) { const int r = ai * HALF + wr * 64 + m * 16 + fr; const size_t off = (size_t)(u.pm * BM + r) * 1024 + col0;
; #pragma unroll
;                     for (int bj = 0; bj < 2; ++bj) { f32x4 b0, b1;
;                         if (XIN_BF16) { const u32x4 w = *(const u32x4*)((const bf16_t*)xin + off + bj * HALF); b0 = (f32x4){bf_lo(w.x), bf_hi(w.x), bf_lo(w.y), bf_hi(w.y)}; b1 = (f32x4){bf_lo(w.z), bf_hi(w.z), bf_lo(w.w), bf_hi(w.w)}; }
;                         else { b0 = *(const f32x4*)((const float*)xin + off + bj * HALF); b1 = *(const f32x4*)((const float*)xin + off + bj * HALF + 4); }
;                         acc[ai][bj][m][0] = b0 + gv[bj][0] * acc[ai][bj][m][0]; acc[ai][bj][m][1] = b1 + gv[bj][1] * acc[ai][bj][m][1]; }
;                     asm volatile("" : "+v"(acc[ai][0][m][0]), "+v"(acc[ai][0][m][1]), "+v"(acc[ai][1][m][0]), "+v"(acc[ai][1][m][1]));
;                     if (m == 3) asm volatile("" ::: "memory"); }
.LBB0_1845:
	s_add_u32 s0, s12, 0xc800000
	s_addc_u32 s1, s13, 0
	s_lshl_b32 s2, s34, 5
	s_lshl_b32 s3, s14, 8
	v_lshrrev_b32_e32 v130, 1, v0
	s_or_b32 s2, s3, s2
	v_and_or_b32 v152, v130, 24, s2
	s_ashr_i32 s2, s31, 4
	s_mul_hi_i32 s3, s2, 0x6000
	s_mulk_i32 s2, 0x6000
	s_add_u32 s4, s12, s2
	s_addc_u32 s5, s13, s3
	s_lshl_b32 s2, s31, 8
	v_add_u32_e32 v146, s2, v166
	v_ashrrev_i32_e32 v147, 31, v146
	v_ashrrev_i32_e32 v153, 31, v152
	v_lshlrev_b64 v[130:131], 11, v[146:147]
	v_lshl_add_u64 v[130:131], s[0:1], 0, v[130:131]
	v_lshlrev_b64 v[164:165], 1, v[152:153]
	v_lshl_add_u64 v[130:131], v[130:131], 0, v[164:165]
	v_lshl_add_u64 v[132:133], v[152:153], 2, s[4:5]
	s_mov_b32 s3, 0x1d000
	s_barrier
	s_mov_b64 s[98:99], 0x8000
	v_lshl_add_u64 v[244:245], v[130:131], 0, s[98:99]
	global_load_dwordx4 v[192:195], v[244:245], off nt
	global_load_dwordx4 v[196:199], v[244:245], off offset:256 nt
	s_mov_b64 s[98:99], 0x10000
	v_lshl_add_u64 v[244:245], v[130:131], 0, s[98:99]
	global_load_dwordx4 v[200:203], v[244:245], off nt
	global_load_dwordx4 v[204:207], v[244:245], off offset:256 nt
	s_mov_b64 s[98:99], 0x18000
	v_lshl_add_u64 v[244:245], v[130:131], 0, s[98:99]
	global_load_dwordx4 v[208:211], v[244:245], off nt
	global_load_dwordx4 v[212:215], v[244:245], off offset:256 nt
	s_mov_b64 s[98:99], 0x40000
	v_lshl_add_u64 v[244:245], v[130:131], 0, s[98:99]
	global_load_dwordx4 v[216:219], v[244:245], off nt
	global_load_dwordx4 v[220:223], v[244:245], off offset:256 nt
	s_mov_b64 s[98:99], 0x48000
	v_lshl_add_u64 v[244:245], v[130:131], 0, s[98:99]
	global_load_dwordx4 v[224:227], v[244:245], off nt
	global_load_dwordx4 v[228:231], v[244:245], off offset:256 nt
	s_mov_b64 s[98:99], 0x50000
	v_lshl_add_u64 v[244:245], v[130:131], 0, s[98:99]
	global_load_dwordx4 v[232:235], v[244:245], off nt
	global_load_dwordx4 v[236:239], v[244:245], off offset:256 nt
	s_mov_b64 s[98:99], 0x58000
	v_lshl_add_u64 v[244:245], v[130:131], 0, s[98:99]
	global_load_dwordx4 v[240:243], v[244:245], off nt
	global_load_dwordx4 v[248:251], v[244:245], off offset:256 nt
	global_load_dwordx4 v[154:157], v[130:131], off nt
	global_load_dwordx4 v[158:161], v[130:131], off offset:256 nt
	v_add_co_u32_e32 v130, vcc, s3, v132
	s_mov_b64 s[4:5], 0x1d000
	s_nop 0
	v_addc_co_u32_e32 v131, vcc, 0, v133, vcc
	global_load_dwordx4 v[138:141], v[130:131], off nt
	v_lshl_add_u64 v[130:131], v[132:133], 0, s[4:5]
	global_load_dwordx4 v[142:145], v[130:131], off offset:16 nt
	global_load_dwordx4 v[134:137], v[130:131], off offset:512 nt
	s_nop 0
	global_load_dwordx4 v[130:133], v[130:131], off offset:528 nt
	v_add_u32_e32 v148, 16, v146
	v_ashrrev_i32_e32 v149, 31, v148
	v_lshlrev_b64 v[150:151], 11, v[148:149]
	v_lshl_add_u64 v[150:151], s[0:1], 0, v[150:151]
	v_lshl_add_u64 v[150:151], v[150:151], 0, v[164:165]
	v_mbcnt_hi_u32_b32 v188, -1, v1
	v_xor_b32_e32 v1, 16, v188
	s_waitcnt vmcnt(0)
	v_lshlrev_b32_e32 v162, 16, v154
	v_and_b32_e32 v163, 0xffff0000, v154
	v_lshlrev_b32_e32 v154, 16, v155
	v_and_b32_e32 v155, 0xffff0000, v155
	v_lshlrev_b32_e32 v168, 16, v156
	v_and_b32_e32 v169, 0xffff0000, v156
	v_lshlrev_b32_e32 v156, 16, v157
	v_and_b32_e32 v157, 0xffff0000, v157
	v_lshlrev_b32_e32 v170, 16, v158
	v_and_b32_e32 v171, 0xffff0000, v158
	v_lshlrev_b32_e32 v158, 16, v159
	v_and_b32_e32 v159, 0xffff0000, v159
	v_lshlrev_b32_e32 v172, 16, v160
	v_and_b32_e32 v173, 0xffff0000, v160
	v_lshlrev_b32_e32 v160, 16, v161
	v_and_b32_e32 v161, 0xffff0000, v161
	v_pk_fma_f32 v[102:103], v[102:103], v[138:139], v[162:163]
	v_pk_fma_f32 v[104:105], v[104:105], v[140:141], v[154:155]
	v_pk_fma_f32 v[108:109], v[108:109], v[144:145], v[156:157]
	v_pk_fma_f32 v[106:107], v[106:107], v[142:143], v[168:169]
	v_pk_fma_f32 v[88:89], v[88:89], v[136:137], v[158:159]
	v_pk_fma_f32 v[86:87], v[86:87], v[134:135], v[170:171]
	v_pk_fma_f32 v[84:85], v[84:85], v[132:133], v[160:161]
	v_pk_fma_f32 v[82:83], v[82:83], v[130:131], v[172:173]
	s_nop 0
	v_mov_b32_e32 v154, v192
	v_mov_b32_e32 v155, v193
	v_mov_b32_e32 v156, v194
	v_mov_b32_e32 v157, v195
	v_mov_b32_e32 v158, v196
	v_mov_b32_e32 v159, v197
	v_mov_b32_e32 v160, v198
	v_mov_b32_e32 v161, v199
	v_add_u32_e32 v150, 32, v146
	v_ashrrev_i32_e32 v151, 31, v150
	v_lshlrev_b64 v[162:163], 11, v[150:151]
	v_lshl_add_u64 v[162:163], s[0:1], 0, v[162:163]
	v_lshl_add_u64 v[162:163], v[162:163], 0, v[164:165]
	s_waitcnt vmcnt(1)
	v_lshlrev_b32_e32 v168, 16, v154
	v_and_b32_e32 v169, 0xffff0000, v154
	v_lshlrev_b32_e32 v154, 16, v155
	v_and_b32_e32 v155, 0xffff0000, v155
	v_lshlrev_b32_e32 v170, 16, v156
	v_and_b32_e32 v171, 0xffff0000, v156
	v_lshlrev_b32_e32 v156, 16, v157
	v_and_b32_e32 v157, 0xffff0000, v157
	s_waitcnt vmcnt(0)
	v_lshlrev_b32_e32 v172, 16, v158
	v_and_b32_e32 v173, 0xffff0000, v158
	v_lshlrev_b32_e32 v158, 16, v159
	v_and_b32_e32 v159, 0xffff0000, v159
	v_lshlrev_b32_e32 v174, 16, v160
	v_and_b32_e32 v175, 0xffff0000, v160
	v_lshlrev_b32_e32 v160, 16, v161
	v_and_b32_e32 v161, 0xffff0000, v161
	v_pk_fma_f32 v[116:117], v[116:117], v[140:141], v[154:155]
	v_pk_fma_f32 v[114:115], v[114:115], v[138:139], v[168:169]
	v_pk_fma_f32 v[120:121], v[120:121], v[144:145], v[156:157]
	v_pk_fma_f32 v[118:119], v[118:119], v[142:143], v[170:171]
	v_pk_fma_f32 v[96:97], v[96:97], v[136:137], v[158:159]
	v_pk_fma_f32 v[94:95], v[94:95], v[134:135], v[172:173]
	v_pk_fma_f32 v[92:93], v[92:93], v[132:133], v[160:161]
	v_pk_fma_f32 v[90:91], v[90:91], v[130:131], v[174:175]
	v_add_u32_e32 v154, 48, v146
	v_mov_b32_e32 v156, v200
	v_mov_b32_e32 v157, v201
	v_mov_b32_e32 v158, v202
	v_mov_b32_e32 v159, v203
	s_nop 0
	v_mov_b32_e32 v160, v204
	v_mov_b32_e32 v161, v205
	v_mov_b32_e32 v162, v206
	v_mov_b32_e32 v163, v207
	v_ashrrev_i32_e32 v155, 31, v154
	v_lshlrev_b64 v[168:169], 11, v[154:155]
	v_lshl_add_u64 v[168:169], s[0:1], 0, v[168:169]
	v_lshl_add_u64 v[168:169], v[168:169], 0, v[164:165]
	s_waitcnt vmcnt(1)
; __device__ __forceinline__ float bf_lo(unsigned w) { return __uint_as_float(w << 16); }
; __device__ __forceinline__ float bf_hi(unsigned w) { return __uint_as_float(w & 0xffff0000u); }
;     __device__ __forceinline__ void fused(f32x4 (&acc)[2][2][4][2], const Unit& u, int wr, int wc, int fr, int fq, PG8_LAS unsigned char* lds, int wid, int lane) const {
;     ...
; #pragma unroll
;             for (int ai = 0; ai < 2; ++ai)
; #pragma unroll
;                 for (int m = 0; m < 4; ++m) { const int r = ai * HALF + wr * 64 + m * 16 + fr; const size_t off = (size_t)(u.pm * BM + r) * 1024 + col0;
; #pragma unroll
;                     for (int bj = 0; bj < 2; ++bj) { f32x4 b0, b1;
;                         if (XIN_BF16) { const u32x4 w = *(const u32x4*)((const bf16_t*)xin + off + bj * HALF); b0 = (f32x4){bf_lo(w.x), bf_hi(w.x), bf_lo(w.y), bf_hi(w.y)}; b1 = (f32x4){bf_lo(w.z), bf_hi(w.z), bf_lo(w.w), bf_hi(w.w)}; }
;                         else { b0 = *(const f32x4*)((const float*)xin + off + bj * HALF); b1 = *(const f32x4*)((const float*)xin + off + bj * HALF + 4); }
;                         acc[ai][bj][m][0] = b0 + gv[bj][0] * acc[ai][bj][m][0]; acc[ai][bj][m][1] = b1 + gv[bj][1] * acc[ai][bj][m][1]; }
;                     asm volatile("" : "+v"(acc[ai][0][m][0]), "+v"(acc[ai][0][m][1]), "+v"(acc[ai][1][m][0]), "+v"(acc[ai][1][m][1]));
;                     if (m == 3) asm volatile("" ::: "memory"); }
	v_lshlrev_b32_e32 v170, 16, v156
	v_and_b32_e32 v171, 0xffff0000, v156
	v_lshlrev_b32_e32 v156, 16, v157
	v_and_b32_e32 v157, 0xffff0000, v157
	v_lshlrev_b32_e32 v172, 16, v158
	v_and_b32_e32 v173, 0xffff0000, v158
	v_lshlrev_b32_e32 v158, 16, v159
	v_and_b32_e32 v159, 0xffff0000, v159
	s_waitcnt vmcnt(0)
	v_lshlrev_b32_e32 v174, 16, v160
	v_and_b32_e32 v175, 0xffff0000, v160
	v_lshlrev_b32_e32 v160, 16, v161
	v_and_b32_e32 v161, 0xffff0000, v161
	v_lshlrev_b32_e32 v176, 16, v162
	v_and_b32_e32 v177, 0xffff0000, v162
	v_lshlrev_b32_e32 v162, 16, v163
	v_and_b32_e32 v163, 0xffff0000, v163
	v_pk_fma_f32 v[128:129], v[128:129], v[140:141], v[156:157]
	v_pk_fma_f32 v[126:127], v[126:127], v[138:139], v[170:171]
	v_pk_fma_f32 v[124:125], v[124:125], v[144:145], v[158:159]
	v_pk_fma_f32 v[122:123], v[122:123], v[142:143], v[172:173]
	v_pk_fma_f32 v[112:113], v[112:113], v[136:137], v[160:161]
	v_pk_fma_f32 v[110:111], v[110:111], v[134:135], v[174:175]
	v_pk_fma_f32 v[100:101], v[100:101], v[132:133], v[162:163]
	v_pk_fma_f32 v[98:99], v[98:99], v[130:131], v[176:177]
	v_add_u32_e32 v156, 0x80, v146
	v_mov_b32_e32 v158, v208
	v_mov_b32_e32 v159, v209
	v_mov_b32_e32 v160, v210
	v_mov_b32_e32 v161, v211
	s_nop 0
	v_mov_b32_e32 v168, v212
	v_mov_b32_e32 v169, v213
	v_mov_b32_e32 v170, v214
	v_mov_b32_e32 v171, v215
	v_ashrrev_i32_e32 v157, 31, v156
	v_lshlrev_b64 v[162:163], 11, v[156:157]
	v_lshl_add_u64 v[162:163], s[0:1], 0, v[162:163]
	v_lshl_add_u64 v[172:173], v[162:163], 0, v[164:165]
	s_waitcnt vmcnt(1)
	v_lshlrev_b32_e32 v162, 16, v158
	v_and_b32_e32 v163, 0xffff0000, v158
	v_lshlrev_b32_e32 v158, 16, v159
	v_and_b32_e32 v159, 0xffff0000, v159
	v_lshlrev_b32_e32 v174, 16, v160
	v_and_b32_e32 v175, 0xffff0000, v160
	v_lshlrev_b32_e32 v160, 16, v161
	v_and_b32_e32 v161, 0xffff0000, v161
	s_waitcnt vmcnt(0)
	v_lshlrev_b32_e32 v176, 16, v168
	v_and_b32_e32 v177, 0xffff0000, v168
	v_lshlrev_b32_e32 v168, 16, v169
	v_and_b32_e32 v169, 0xffff0000, v169
	v_lshlrev_b32_e32 v178, 16, v170
	v_and_b32_e32 v179, 0xffff0000, v170
	v_lshlrev_b32_e32 v170, 16, v171
	v_and_b32_e32 v171, 0xffff0000, v171
	v_pk_fma_f32 v[80:81], v[80:81], v[140:141], v[158:159]
	v_pk_fma_f32 v[78:79], v[78:79], v[138:139], v[162:163]
	v_pk_fma_f32 v[76:77], v[76:77], v[144:145], v[160:161]
	v_pk_fma_f32 v[74:75], v[74:75], v[142:143], v[174:175]
	v_pk_fma_f32 v[72:73], v[72:73], v[136:137], v[168:169]
	v_pk_fma_f32 v[70:71], v[70:71], v[134:135], v[176:177]
	v_pk_fma_f32 v[68:69], v[68:69], v[132:133], v[170:171]
	v_pk_fma_f32 v[66:67], v[66:67], v[130:131], v[178:179]
	v_add_u32_e32 v158, 0x90, v146
	v_mov_b32_e32 v160, v216
	v_mov_b32_e32 v161, v217
	v_mov_b32_e32 v162, v218
	v_mov_b32_e32 v163, v219
	v_mov_b32_e32 v168, v220
	v_mov_b32_e32 v169, v221
	v_mov_b32_e32 v170, v222
	v_mov_b32_e32 v171, v223
	v_ashrrev_i32_e32 v159, 31, v158
	v_lshlrev_b64 v[172:173], 11, v[158:159]
	v_lshl_add_u64 v[172:173], s[0:1], 0, v[172:173]
	v_lshl_add_u64 v[172:173], v[172:173], 0, v[164:165]
	s_waitcnt vmcnt(1)
	v_lshlrev_b32_e32 v174, 16, v160
	v_and_b32_e32 v175, 0xffff0000, v160
	v_lshlrev_b32_e32 v160, 16, v161
	v_and_b32_e32 v161, 0xffff0000, v161
	v_lshlrev_b32_e32 v176, 16, v162
	v_and_b32_e32 v177, 0xffff0000, v162
	v_lshlrev_b32_e32 v162, 16, v163
	v_and_b32_e32 v163, 0xffff0000, v163
	s_waitcnt vmcnt(0)
	v_lshlrev_b32_e32 v178, 16, v168
	v_and_b32_e32 v179, 0xffff0000, v168
	v_lshlrev_b32_e32 v168, 16, v169
	v_and_b32_e32 v169, 0xffff0000, v169
	v_lshlrev_b32_e32 v180, 16, v170
	v_and_b32_e32 v181, 0xffff0000, v170
	v_lshlrev_b32_e32 v170, 16, v171
	v_and_b32_e32 v171, 0xffff0000, v171
	v_pk_fma_f32 v[64:65], v[64:65], v[140:141], v[160:161]
	v_pk_fma_f32 v[62:63], v[62:63], v[138:139], v[174:175]
	v_pk_fma_f32 v[60:61], v[60:61], v[144:145], v[162:163]
	v_pk_fma_f32 v[58:59], v[58:59], v[142:143], v[176:177]
	v_pk_fma_f32 v[56:57], v[56:57], v[136:137], v[168:169]
	v_pk_fma_f32 v[54:55], v[54:55], v[134:135], v[178:179]
	v_pk_fma_f32 v[52:53], v[52:53], v[132:133], v[170:171]
	v_pk_fma_f32 v[50:51], v[50:51], v[130:131], v[180:181]
	v_add_u32_e32 v160, 0xa0, v146
	v_mov_b32_e32 v168, v224
	v_mov_b32_e32 v169, v225
	v_mov_b32_e32 v170, v226
	v_mov_b32_e32 v171, v227
	s_nop 0
	v_mov_b32_e32 v172, v228
	v_mov_b32_e32 v173, v229
	v_mov_b32_e32 v174, v230
	v_mov_b32_e32 v175, v231
	v_ashrrev_i32_e32 v161, 31, v160
	v_lshlrev_b64 v[162:163], 11, v[160:161]
	v_lshl_add_u64 v[162:163], s[0:1], 0, v[162:163]
	v_lshl_add_u64 v[162:163], v[162:163], 0, v[164:165]
	s_waitcnt vmcnt(1)
	v_lshlrev_b32_e32 v176, 16, v168
	v_and_b32_e32 v177, 0xffff0000, v168
	v_lshlrev_b32_e32 v168, 16, v169
	v_and_b32_e32 v169, 0xffff0000, v169
	v_lshlrev_b32_e32 v178, 16, v170
	v_and_b32_e32 v179, 0xffff0000, v170
	v_lshlrev_b32_e32 v170, 16, v171
	v_and_b32_e32 v171, 0xffff0000, v171
	s_waitcnt vmcnt(0)
	v_lshlrev_b32_e32 v180, 16, v172
	v_and_b32_e32 v181, 0xffff0000, v172
	v_lshlrev_b32_e32 v172, 16, v173
	v_and_b32_e32 v173, 0xffff0000, v173
	v_lshlrev_b32_e32 v182, 16, v174
	v_and_b32_e32 v183, 0xffff0000, v174
	v_lshlrev_b32_e32 v174, 16, v175
	v_and_b32_e32 v175, 0xffff0000, v175
	v_pk_fma_f32 v[48:49], v[48:49], v[140:141], v[168:169]
	v_pk_fma_f32 v[46:47], v[46:47], v[138:139], v[176:177]
	v_pk_fma_f32 v[44:45], v[44:45], v[144:145], v[170:171]
	v_pk_fma_f32 v[42:43], v[42:43], v[142:143], v[178:179]
	v_pk_fma_f32 v[40:41], v[40:41], v[136:137], v[172:173]
	v_pk_fma_f32 v[38:39], v[38:39], v[134:135], v[180:181]
	v_pk_fma_f32 v[36:37], v[36:37], v[132:133], v[174:175]
	v_pk_fma_f32 v[34:35], v[34:35], v[130:131], v[182:183]
	v_mov_b32_e32 v180, v103
	v_mov_b32_e32 v168, v232
	v_mov_b32_e32 v169, v233
	v_mov_b32_e32 v170, v234
	v_mov_b32_e32 v171, v235
	v_mov_b32_e32 v172, v236
	v_mov_b32_e32 v173, v237
	v_mov_b32_e32 v174, v238
	v_mov_b32_e32 v175, v239
	v_and_b32_e32 v162, 64, v188
	v_add_u32_e32 v189, 64, v162
	v_add_u32_e32 v162, 0xb0, v146
	v_ashrrev_i32_e32 v163, 31, v162
	v_lshlrev_b64 v[176:177], 11, v[162:163]
	v_lshl_add_u64 v[176:177], s[0:1], 0, v[176:177]
	v_lshl_add_u64 v[164:165], v[176:177], 0, v[164:165]
	v_mov_b32_e32 v181, v104
	v_mov_b32_e32 v182, v102
	v_mov_b32_e32 v183, v105
	v_pk_add_f32 v[180:181], v[180:181], v[182:183]
	v_cmp_lt_i32_e32 vcc, v1, v189
	s_lshl_b32 s0, s34, 3
	s_add_i32 s3, s0, 0
	v_cndmask_b32_e32 v1, v188, v1, vcc
	v_lshlrev_b32_e32 v1, 2, v1
	s_waitcnt vmcnt(1)
;     template <class Mid> __device__ __forceinline__ bool run(const f32x4 (&v)[2][2][4][2], const Unit& u, int wr, int wc, int fr, int fq, PG8_LAS unsigned char* lds, int wid, int lane, const Mid& mid) const {
;     ...
; #pragma unroll
;         for (int ai = 0; ai < 2; ++ai)
; #pragma unroll
;             for (int m = 0; m < 4; ++m) {
;                 float s = 0.f;
; #pragma unroll
;                 for (int bj = 0; bj < 2; ++bj)
; #pragma unroll
;                     for (int n = 0; n < 2; ++n) { const f32x4 x = v[ai][bj][m][n]; s += (x[0] + x[1]) + (x[2] + x[3]); }
;                 s += __shfl_xor(s, 16); s += __shfl_xor(s, 32);
;                 const float mw = s * (1.0f / 64.0f); float q = 0.f;
; #pragma unroll
;                 for (int bj = 0; bj < 2; ++bj)
; #pragma unroll
;                     for (int n = 0; n < 2; ++n) { const f32x4 d = v[ai][bj][m][n] - mw; q += (d[0] * d[0] + d[1] * d[1]) + (d[2] * d[2] + d[3] * d[3]); }
;                 q += __shfl_xor(q, 16); q += __shfl_xor(q, 32);
;                 if (fq == 0) P[(ai * HALF + wr * 64 + m * 16 + fr) * 4 + wc] = (f32x2v){mw, q};
;     __device__ __forceinline__ void fused(f32x4 (&acc)[2][2][4][2], const Unit& u, int wr, int wc, int fr, int fq, PG8_LAS unsigned char* lds, int wid, int lane) const {
;     ...
; #pragma unroll
;             for (int ai = 0; ai < 2; ++ai)
; #pragma unroll
;                 for (int m = 0; m < 4; ++m) { const int r = ai * HALF + wr * 64 + m * 16 + fr; const size_t off = (size_t)(u.pm * BM + r) * 1024 + col0;
; #pragma unroll
;                     for (int bj = 0; bj < 2; ++bj) { f32x4 b0, b1;
;                         if (XIN_BF16) { const u32x4 w = *(const u32x4*)((const bf16_t*)xin + off + bj * HALF); b0 = (f32x4){bf_lo(w.x), bf_hi(w.x), bf_lo(w.y), bf_hi(w.y)}; b1 = (f32x4){bf_lo(w.z), bf_hi(w.z), bf_lo(w.w), bf_hi(w.w)}; }
;                         else { b0 = *(const f32x4*)((const float*)xin + off + bj * HALF); b1 = *(const f32x4*)((const float*)xin + off + bj * HALF + 4); }
;                         acc[ai][bj][m][0] = b0 + gv[bj][0] * acc[ai][bj][m][0]; acc[ai][bj][m][1] = b1 + gv[bj][1] * acc[ai][bj][m][1]; }
;                     asm volatile("" : "+v"(acc[ai][0][m][0]), "+v"(acc[ai][0][m][1]), "+v"(acc[ai][1][m][0]), "+v"(acc[ai][1][m][1]));
;                     if (m == 3) asm volatile("" ::: "memory"); }
	v_lshlrev_b32_e32 v176, 16, v168
	v_and_b32_e32 v177, 0xffff0000, v168
	v_lshlrev_b32_e32 v168, 16, v169
	v_and_b32_e32 v169, 0xffff0000, v169
	v_lshlrev_b32_e32 v178, 16, v170
	v_and_b32_e32 v179, 0xffff0000, v170
	v_lshlrev_b32_e32 v170, 16, v171
	v_and_b32_e32 v171, 0xffff0000, v171
	s_waitcnt vmcnt(0)
	v_lshlrev_b32_e32 v184, 16, v172
	v_and_b32_e32 v185, 0xffff0000, v172
	v_lshlrev_b32_e32 v172, 16, v173
	v_and_b32_e32 v173, 0xffff0000, v173
	v_lshlrev_b32_e32 v186, 16, v174
	v_and_b32_e32 v187, 0xffff0000, v174
	v_lshlrev_b32_e32 v174, 16, v175
	v_and_b32_e32 v175, 0xffff0000, v175
	v_pk_fma_f32 v[32:33], v[32:33], v[140:141], v[168:169]
	v_pk_fma_f32 v[30:31], v[30:31], v[138:139], v[176:177]
	v_pk_fma_f32 v[28:29], v[28:29], v[144:145], v[170:171]
	v_pk_fma_f32 v[26:27], v[26:27], v[142:143], v[178:179]
	v_pk_fma_f32 v[24:25], v[24:25], v[136:137], v[172:173]
	v_pk_fma_f32 v[22:23], v[22:23], v[134:135], v[184:185]
	v_pk_fma_f32 v[20:21], v[20:21], v[132:133], v[174:175]
	v_pk_fma_f32 v[18:19], v[18:19], v[130:131], v[186:187]
	v_mov_b32_e32 v168, v107
	v_mov_b32_e32 v172, v240
	v_mov_b32_e32 v173, v241
	v_mov_b32_e32 v174, v242
	v_mov_b32_e32 v175, v243
	v_mov_b32_e32 v176, v248
	v_mov_b32_e32 v177, v249
	v_mov_b32_e32 v178, v250
	v_mov_b32_e32 v179, v251
	v_mov_b32_e32 v169, v108
	v_mov_b32_e32 v170, v106
	v_mov_b32_e32 v171, v109
	v_pk_add_f32 v[168:169], v[168:169], v[170:171]
	v_add_f32_e32 v165, v180, v181
	v_pk_add_f32 v[168:169], v[168:169], v[168:169] op_sel_hi:[0,1]
	v_add_f32_e32 v185, v86, v87
	v_add_f32_e32 v187, v88, v89
	v_mov_b32_e32 v184, v82
	v_mov_b32_e32 v186, v83
	v_mov_b32_e32 v164, v85
	v_add_f32_e32 v165, 0, v165
	v_mov_b32_e32 v168, v84
	v_pk_add_f32 v[170:171], v[184:185], v[186:187]
	v_pk_add_f32 v[164:165], v[168:169], v[164:165]
	s_nop 0
	v_pk_add_f32 v[164:165], v[170:171], v[164:165]
	s_nop 0
	v_add_f32_e32 v164, v164, v165
	ds_bpermute_b32 v168, v1, v164
	v_xor_b32_e32 v165, 32, v188
	v_cmp_lt_i32_e32 vcc, v165, v189
	s_waitcnt lgkmcnt(0)
	v_add_f32_e32 v164, v164, v168
	v_cndmask_b32_e32 v165, v188, v165, vcc
	v_lshlrev_b32_e32 v165, 2, v165
	ds_bpermute_b32 v168, v165, v164
	s_waitcnt lgkmcnt(0)
	v_add_f32_e32 v168, v164, v168
	v_fmamk_f32 v169, v168, 0xbc800000, v105
	v_fmamk_f32 v171, v168, 0xbc800000, v103
	v_fmamk_f32 v181, v168, 0xbc800000, v109
	v_fmamk_f32 v183, v168, 0xbc800000, v107
	v_fmamk_f32 v164, v168, 0xbc800000, v104
	v_fmamk_f32 v170, v168, 0xbc800000, v102
	v_fmamk_f32 v180, v168, 0xbc800000, v108
	v_fmamk_f32 v182, v168, 0xbc800000, v106
	v_fmamk_f32 v185, v168, 0xbc800000, v89
	v_fmamk_f32 v187, v168, 0xbc800000, v87
	v_mul_f32_e32 v171, v171, v171
	v_mul_f32_e32 v169, v169, v169
	v_mul_f32_e32 v183, v183, v183
	v_mul_f32_e32 v181, v181, v181
	v_fmamk_f32 v184, v168, 0xbc800000, v88
	v_fmamk_f32 v186, v168, 0xbc800000, v86
	v_fmamk_f32 v189, v168, 0xbc800000, v85
	v_fmamk_f32 v191, v168, 0xbc800000, v83
	v_mul_f32_e32 v187, v187, v187
	v_mul_f32_e32 v185, v185, v185
	v_fmac_f32_e32 v171, v170, v170
	v_fmac_f32_e32 v169, v164, v164
	v_fmac_f32_e32 v183, v182, v182
	v_fmac_f32_e32 v181, v180, v180
	v_fmamk_f32 v188, v168, 0xbc800000, v84
	v_fmamk_f32 v190, v168, 0xbc800000, v82
	v_mul_f32_e32 v191, v191, v191
	v_mul_f32_e32 v189, v189, v189
	v_fmac_f32_e32 v187, v186, v186
	v_fmac_f32_e32 v185, v184, v184
	v_add_f32_e32 v164, v171, v169
	v_add_f32_e32 v169, v183, v181
	v_fmac_f32_e32 v191, v190, v190
	v_fmac_f32_e32 v189, v188, v188
	v_add_f32_e32 v170, v187, v185
	v_add_f32_e32 v164, v164, v169
	v_add_f32_e32 v171, v191, v189
	v_add_f32_e32 v164, v170, v164
	v_add_f32_e32 v169, v171, v164
	ds_bpermute_b32 v170, v1, v169
	v_and_b32_e32 v164, 63, v0
	v_cmp_gt_u32_e32 vcc, 16, v164
	s_waitcnt lgkmcnt(0)
	v_add_f32_e32 v169, v169, v170
	ds_bpermute_b32 v170, v165, v169
	s_waitcnt vmcnt(1)
	v_lshlrev_b32_e32 v180, 16, v172
	v_and_b32_e32 v181, 0xffff0000, v172
	v_lshlrev_b32_e32 v172, 16, v173
	v_and_b32_e32 v173, 0xffff0000, v173
	v_lshlrev_b32_e32 v182, 16, v174
	v_and_b32_e32 v183, 0xffff0000, v174
	v_lshlrev_b32_e32 v174, 16, v175
	v_and_b32_e32 v175, 0xffff0000, v175
	s_waitcnt vmcnt(0)
	v_lshlrev_b32_e32 v184, 16, v176
	v_and_b32_e32 v185, 0xffff0000, v176
	v_lshlrev_b32_e32 v176, 16, v177
	v_and_b32_e32 v177, 0xffff0000, v177
	v_lshlrev_b32_e32 v186, 16, v178
	v_and_b32_e32 v187, 0xffff0000, v178
	v_lshlrev_b32_e32 v178, 16, v179
	v_and_b32_e32 v179, 0xffff0000, v179
	v_pk_fma_f32 v[16:17], v[16:17], v[140:141], v[172:173]
	v_pk_fma_f32 v[14:15], v[14:15], v[138:139], v[180:181]
	v_pk_fma_f32 v[12:13], v[12:13], v[144:145], v[174:175]
	v_pk_fma_f32 v[10:11], v[10:11], v[142:143], v[182:183]
	v_pk_fma_f32 v[8:9], v[8:9], v[136:137], v[176:177]
	v_pk_fma_f32 v[6:7], v[6:7], v[134:135], v[184:185]
	v_pk_fma_f32 v[4:5], v[4:5], v[132:133], v[178:179]
	v_pk_fma_f32 v[2:3], v[2:3], v[130:131], v[186:187]
	s_nop 0
	s_and_saveexec_b64 s[0:1], vcc
	s_cbranch_execz .LBB0_1847
	s_lshl_b32 s4, s33, 11
	s_add_i32 s4, s3, s4
	v_mul_f32_e32 v130, 0x3c800000, v168
	s_waitcnt lgkmcnt(0)
	v_add_f32_e32 v131, v169, v170
	v_lshl_add_u32 v132, v167, 5, s4
	ds_write_b64 v132, v[130:131]
